# GEMM1 phases: nt cache policy on the epilogue activation stores (single-use streams) and on the x loads of the conversion loops, to keep re-used operand tiles in L2
# speedup vs baseline: 1.0273x; 1.0143x over previous
.LBB0_7:
	v_ashrrev_i32_e32 v11, 31, v10
	v_add_u32_e32 v16, s4, v10
	v_lshlrev_b64 v[18:19], 12, v[10:11]
	v_ashrrev_i32_e32 v17, 31, v16
	v_lshlrev_b64 v[20:21], 11, v[10:11]
	v_lshl_add_u64 v[32:33], v[6:7], 0, v[18:19]
	v_add_u32_e32 v10, s4, v16
	v_lshlrev_b64 v[34:35], 12, v[16:17]
	v_lshl_add_u64 v[48:49], v[4:5], 0, v[20:21]
	v_lshlrev_b64 v[36:37], 11, v[16:17]
	global_load_dwordx4 v[16:19], v[32:33], off nt
	global_load_dwordx4 v[20:23], v[32:33], off offset:1024 nt
	global_load_dwordx4 v[24:27], v[32:33], off offset:2048 nt
	global_load_dwordx4 v[28:31], v[32:33], off offset:3072 nt
	v_lshl_add_u64 v[50:51], v[6:7], 0, v[34:35]
	v_lshl_add_u64 v[52:53], v[4:5], 0, v[36:37]
	global_load_dwordx4 v[32:35], v[50:51], off nt
	global_load_dwordx4 v[36:39], v[50:51], off offset:1024 nt
	global_load_dwordx4 v[40:43], v[50:51], off offset:2048 nt
	global_load_dwordx4 v[44:47], v[50:51], off offset:3072 nt
	v_cmp_lt_i32_e32 vcc, s3, v10
	s_or_b64 s[16:17], vcc, s[16:17]
	s_waitcnt vmcnt(7)
	v_mov_b32_e32 v54, v17
	s_waitcnt vmcnt(6)
	v_mov_b32_e32 v55, v21
	s_waitcnt vmcnt(5)
	v_mov_b32_e32 v60, v25
	s_waitcnt vmcnt(4)
	v_mov_b32_e32 v61, v29
	v_mov_b32_e32 v50, v16
	v_mov_b32_e32 v51, v20
	v_mov_b32_e32 v58, v24
	v_mov_b32_e32 v59, v28
	v_pk_mul_f32 v[54:55], v[54:55], v[54:55]
	v_pk_mul_f32 v[60:61], v[60:61], v[60:61]
	s_waitcnt vmcnt(3)
	v_mov_b32_e32 v70, v33
	s_waitcnt vmcnt(2)
	v_mov_b32_e32 v71, v37
	v_mov_b32_e32 v56, v18
	v_mov_b32_e32 v57, v22
	v_mov_b32_e32 v68, v32
	v_mov_b32_e32 v69, v36
	s_waitcnt vmcnt(1)
	v_mov_b32_e32 v74, v41
	s_waitcnt vmcnt(0)
	v_mov_b32_e32 v75, v45
	v_pk_fma_f32 v[50:51], v[50:51], v[50:51], v[54:55]
	v_pk_fma_f32 v[54:55], v[58:59], v[58:59], v[60:61]
	v_pk_mul_f32 v[58:59], v[70:71], v[70:71]
	v_mov_b32_e32 v72, v40
	v_mov_b32_e32 v73, v44
	v_mov_b32_e32 v76, v34
	v_mov_b32_e32 v77, v38
	v_pk_mul_f32 v[60:61], v[74:75], v[74:75]
	v_pk_fma_f32 v[50:51], v[56:57], v[56:57], v[50:51]
	v_pk_fma_f32 v[56:57], v[68:69], v[68:69], v[58:59]
	v_mov_b32_e32 v62, v26
	v_mov_b32_e32 v63, v30
	v_mov_b32_e32 v64, v19
	v_mov_b32_e32 v65, v23
	v_mov_b32_e32 v78, v42
	v_mov_b32_e32 v79, v46
	v_mov_b32_e32 v80, v35
	v_mov_b32_e32 v81, v39
	v_pk_fma_f32 v[58:59], v[72:73], v[72:73], v[60:61]
	v_pk_fma_f32 v[56:57], v[76:77], v[76:77], v[56:57]
	v_mov_b32_e32 v66, v27
	v_mov_b32_e32 v67, v31
	v_mov_b32_e32 v82, v43
	v_mov_b32_e32 v83, v47
	v_pk_fma_f32 v[54:55], v[62:63], v[62:63], v[54:55]
	v_pk_fma_f32 v[50:51], v[64:65], v[64:65], v[50:51]
	v_pk_fma_f32 v[58:59], v[78:79], v[78:79], v[58:59]
	v_pk_fma_f32 v[56:57], v[80:81], v[80:81], v[56:57]
	v_pk_fma_f32 v[54:55], v[66:67], v[66:67], v[54:55]
	v_pk_fma_f32 v[58:59], v[82:83], v[82:83], v[58:59]
	v_mov_b32_e32 v61, v50
	v_mov_b32_e32 v60, v56
	v_mov_b32_e32 v50, v57
	v_mov_b32_e32 v63, v54
	v_mov_b32_e32 v62, v58
	v_pk_add_f32 v[50:51], v[60:61], v[50:51]
	v_mov_b32_e32 v54, v59
	v_pk_add_f32 v[50:51], v[50:51], v[62:63]
	s_nop 0
	v_pk_add_f32 v[50:51], v[50:51], v[54:55]
	ds_bpermute_b32 v55, v1, v51
	ds_bpermute_b32 v54, v1, v50
	s_waitcnt lgkmcnt(0)
	v_pk_add_f32 v[50:51], v[50:51], v[54:55]
	ds_bpermute_b32 v55, v3, v51
	ds_bpermute_b32 v54, v3, v50
	s_waitcnt lgkmcnt(0)
	v_pk_add_f32 v[50:51], v[50:51], v[54:55]
	ds_bpermute_b32 v55, v9, v51
	ds_bpermute_b32 v54, v9, v50
	s_waitcnt lgkmcnt(0)
	v_pk_add_f32 v[50:51], v[50:51], v[54:55]
	ds_bpermute_b32 v55, v12, v51
	ds_bpermute_b32 v54, v12, v50
	s_waitcnt lgkmcnt(0)
	v_pk_add_f32 v[50:51], v[50:51], v[54:55]
	ds_bpermute_b32 v55, v13, v51
	ds_bpermute_b32 v54, v13, v50
	s_waitcnt lgkmcnt(0)
	v_pk_add_f32 v[50:51], v[50:51], v[54:55]
	ds_bpermute_b32 v55, v14, v51
	ds_bpermute_b32 v54, v14, v50
	s_waitcnt lgkmcnt(0)
	v_pk_add_f32 v[50:51], v[50:51], v[54:55]
	s_nop 0
	v_pk_fma_f32 v[50:51], v[50:51], s[18:19], v[8:9] op_sel_hi:[1,0,0]
	s_nop 0
	v_mul_f32_e32 v11, 0x4b800000, v51
	v_cmp_gt_f32_e64 s[0:1], s2, v51
	v_mul_f32_e32 v15, 0x4b800000, v50
	v_cmp_gt_f32_e32 vcc, s2, v50
	v_cndmask_b32_e64 v11, v51, v11, s[0:1]
	v_rsq_f32_e32 v11, v11
	v_cndmask_b32_e32 v15, v50, v15, vcc
	v_rsq_f32_e32 v15, v15
	v_mul_f32_e32 v50, 0x45800000, v11
	v_cndmask_b32_e64 v50, v11, v50, s[0:1]
	v_mul_f32_e32 v51, 0x45800000, v15
	v_cndmask_b32_e32 v54, v15, v51, vcc
	v_pk_mul_f32 v[16:17], v[16:17], v[50:51] op_sel_hi:[1,0]
	v_pk_mul_f32 v[18:19], v[18:19], v[50:51] op_sel_hi:[1,0]
	v_pk_mul_f32 v[32:33], v[32:33], v[54:55] op_sel_hi:[1,0]
	v_pk_mul_f32 v[34:35], v[34:35], v[54:55] op_sel_hi:[1,0]
	v_pk_mul_f32 v[20:21], v[20:21], v[50:51] op_sel_hi:[1,0]
	v_pk_mul_f32 v[22:23], v[22:23], v[50:51] op_sel_hi:[1,0]
	v_pk_mul_f32 v[36:37], v[36:37], v[54:55] op_sel_hi:[1,0]
	v_pk_mul_f32 v[38:39], v[38:39], v[54:55] op_sel_hi:[1,0]
	v_pk_mul_f32 v[24:25], v[24:25], v[50:51] op_sel_hi:[1,0]
	v_pk_mul_f32 v[26:27], v[26:27], v[50:51] op_sel_hi:[1,0]
	v_pk_mul_f32 v[40:41], v[40:41], v[54:55] op_sel_hi:[1,0]
	v_pk_mul_f32 v[42:43], v[42:43], v[54:55] op_sel_hi:[1,0]
	v_pk_mul_f32 v[28:29], v[28:29], v[50:51] op_sel_hi:[1,0]
	v_pk_mul_f32 v[30:31], v[30:31], v[50:51] op_sel_hi:[1,0]
	v_pk_mul_f32 v[44:45], v[44:45], v[54:55] op_sel_hi:[1,0]
	v_pk_mul_f32 v[46:47], v[46:47], v[54:55] op_sel_hi:[1,0]
	v_cvt_pk_bf16_f32 v16, v16, v17
	v_cvt_pk_bf16_f32 v17, v18, v19
	v_cvt_pk_bf16_f32 v18, v32, v33
	v_cvt_pk_bf16_f32 v19, v34, v35
	v_cvt_pk_bf16_f32 v20, v20, v21
	v_cvt_pk_bf16_f32 v21, v22, v23
	v_cvt_pk_bf16_f32 v22, v36, v37
	v_cvt_pk_bf16_f32 v23, v38, v39
	v_cvt_pk_bf16_f32 v24, v24, v25
	v_cvt_pk_bf16_f32 v25, v26, v27
	v_cvt_pk_bf16_f32 v26, v40, v41
	v_cvt_pk_bf16_f32 v27, v42, v43
	v_cvt_pk_bf16_f32 v28, v28, v29
	v_cvt_pk_bf16_f32 v29, v30, v31
	v_cvt_pk_bf16_f32 v30, v44, v45
	v_cvt_pk_bf16_f32 v31, v46, v47
	global_store_dwordx2 v[48:49], v[16:17], off
	global_store_dwordx2 v[52:53], v[18:19], off
	global_store_dwordx2 v[48:49], v[20:21], off offset:512
	global_store_dwordx2 v[52:53], v[22:23], off offset:512
	global_store_dwordx2 v[48:49], v[24:25], off offset:1024
	global_store_dwordx2 v[52:53], v[26:27], off offset:1024
	global_store_dwordx2 v[48:49], v[28:29], off offset:1536
	global_store_dwordx2 v[52:53], v[30:31], off offset:1536
	s_andn2_b64 exec, exec, s[16:17]
	s_cbranch_execnz .LBB0_7

.LBB0_111:
	v_lshl_add_u64 v[28:29], s[6:7], 0, v[148:149]
	v_lshl_add_u64 v[36:37], s[8:9], 0, v[148:149]
	global_load_dwordx4 v[8:11], v[28:29], off nt
	global_load_dwordx4 v[12:15], v[28:29], off offset:1024 nt
	global_load_dwordx4 v[16:19], v[36:37], off nt
	global_load_dwordx4 v[20:23], v[36:37], off offset:1024 nt
	global_load_dwordx4 v[24:27], v[28:29], off offset:2048 nt
	s_nop 0
	global_load_dwordx4 v[28:31], v[28:29], off offset:3072 nt
	s_nop 0
	global_load_dwordx4 v[32:35], v[36:37], off offset:2048 nt
	s_nop 0
	global_load_dwordx4 v[36:39], v[36:37], off offset:3072 nt
	s_add_i32 s3, s3, 16
	v_lshl_add_u64 v[42:43], s[4:5], 0, v[146:147]
	s_add_u32 s4, s4, 0x8000
	s_addc_u32 s5, s5, 0
	s_add_u32 s6, s6, 0x10000
	s_addc_u32 s7, s7, 0
	s_add_u32 s8, s8, 0x10000
	s_addc_u32 s9, s9, 0
	v_lshl_add_u64 v[40:41], s[10:11], 0, v[146:147]
	s_add_u32 s10, s10, 0x8000
	s_addc_u32 s11, s11, 0
	s_cmp_lt_i32 s3, s2
	s_waitcnt vmcnt(7)
	v_mov_b32_e32 v46, v9
	s_waitcnt vmcnt(6)
	v_mov_b32_e32 v47, v13
	s_waitcnt vmcnt(5)
	v_mov_b32_e32 v54, v17
	s_waitcnt vmcnt(4)
	v_mov_b32_e32 v55, v21
	v_mov_b32_e32 v44, v8
	v_mov_b32_e32 v45, v12
	v_mov_b32_e32 v52, v16
	v_mov_b32_e32 v53, v20
	s_waitcnt vmcnt(3)
	v_mov_b32_e32 v62, v25
	s_waitcnt vmcnt(2)
	v_mov_b32_e32 v63, v29
	s_waitcnt vmcnt(1)
	v_mov_b32_e32 v68, v33
	s_waitcnt vmcnt(0)
	v_mov_b32_e32 v69, v37
	v_pk_mul_f32 v[46:47], v[46:47], v[46:47]
	v_pk_mul_f32 v[54:55], v[54:55], v[54:55]
	v_mov_b32_e32 v48, v10
	v_mov_b32_e32 v49, v14
	v_mov_b32_e32 v56, v18
	v_mov_b32_e32 v57, v22
	v_mov_b32_e32 v60, v24
	v_mov_b32_e32 v61, v28
	v_mov_b32_e32 v66, v32
	v_mov_b32_e32 v67, v36
	v_pk_mul_f32 v[62:63], v[62:63], v[62:63]
	v_pk_mul_f32 v[68:69], v[68:69], v[68:69]
	v_pk_fma_f32 v[44:45], v[44:45], v[44:45], v[46:47]
	v_pk_fma_f32 v[46:47], v[52:53], v[52:53], v[54:55]
	v_mov_b32_e32 v50, v11
	v_mov_b32_e32 v51, v15
	v_mov_b32_e32 v58, v19
	v_mov_b32_e32 v59, v23
	v_mov_b32_e32 v64, v26
	v_mov_b32_e32 v65, v30
	v_mov_b32_e32 v72, v34
	v_mov_b32_e32 v73, v38
	v_pk_fma_f32 v[52:53], v[60:61], v[60:61], v[62:63]
	v_pk_fma_f32 v[54:55], v[66:67], v[66:67], v[68:69]
	v_pk_fma_f32 v[44:45], v[48:49], v[48:49], v[44:45]
	v_pk_fma_f32 v[46:47], v[56:57], v[56:57], v[46:47]
	v_mov_b32_e32 v70, v27
	v_mov_b32_e32 v71, v31
	v_mov_b32_e32 v74, v35
	v_mov_b32_e32 v75, v39
	v_pk_fma_f32 v[48:49], v[64:65], v[64:65], v[52:53]
	v_pk_fma_f32 v[52:53], v[72:73], v[72:73], v[54:55]
	v_pk_fma_f32 v[44:45], v[50:51], v[50:51], v[44:45]
	v_pk_fma_f32 v[46:47], v[58:59], v[58:59], v[46:47]
	v_pk_fma_f32 v[48:49], v[70:71], v[70:71], v[48:49]
	v_pk_fma_f32 v[50:51], v[74:75], v[74:75], v[52:53]
	v_mov_b32_e32 v52, v46
	v_mov_b32_e32 v53, v44
	v_mov_b32_e32 v44, v47
	v_mov_b32_e32 v46, v50
	v_mov_b32_e32 v47, v48
	v_pk_add_f32 v[44:45], v[52:53], v[44:45]
	v_mov_b32_e32 v48, v51
	v_pk_add_f32 v[44:45], v[44:45], v[46:47]
	s_nop 0
	v_pk_add_f32 v[44:45], v[44:45], v[48:49]
	ds_bpermute_b32 v47, v1, v45
	ds_bpermute_b32 v46, v1, v44
	s_waitcnt lgkmcnt(0)
	v_pk_add_f32 v[44:45], v[44:45], v[46:47]
	ds_bpermute_b32 v47, v3, v45
	ds_bpermute_b32 v46, v3, v44
	s_waitcnt lgkmcnt(0)
	v_pk_add_f32 v[44:45], v[44:45], v[46:47]
	ds_bpermute_b32 v47, v4, v45
	ds_bpermute_b32 v46, v4, v44
	s_waitcnt lgkmcnt(0)
	v_pk_add_f32 v[44:45], v[44:45], v[46:47]
	ds_bpermute_b32 v47, v5, v45
	ds_bpermute_b32 v46, v5, v44
	s_waitcnt lgkmcnt(0)
	v_pk_add_f32 v[44:45], v[44:45], v[46:47]
	ds_bpermute_b32 v47, v6, v45
	ds_bpermute_b32 v46, v6, v44
	s_waitcnt lgkmcnt(0)
	v_pk_add_f32 v[44:45], v[44:45], v[46:47]
	ds_bpermute_b32 v47, v7, v45
	ds_bpermute_b32 v46, v7, v44
	s_waitcnt lgkmcnt(0)
	v_pk_add_f32 v[44:45], v[44:45], v[46:47]
	s_nop 0
	v_pk_fma_f32 v[44:45], v[44:45], s[14:15], v[2:3] op_sel_hi:[1,0,0]
	s_nop 0
	v_mul_f32_e32 v46, 0x4b800000, v45
	v_cmp_gt_f32_e64 s[0:1], s15, v45
	v_mul_f32_e32 v47, 0x4b800000, v44
	v_cmp_gt_f32_e32 vcc, s15, v44
	v_cndmask_b32_e64 v45, v45, v46, s[0:1]
	v_rsq_f32_e32 v45, v45
	v_cndmask_b32_e32 v44, v44, v47, vcc
	v_rsq_f32_e32 v46, v44
	v_mul_f32_e32 v44, 0x45800000, v45
	v_cndmask_b32_e64 v44, v45, v44, s[0:1]
	v_mul_f32_e32 v47, 0x45800000, v46
	v_cndmask_b32_e32 v46, v46, v47, vcc
	v_pk_mul_f32 v[8:9], v[8:9], v[44:45] op_sel_hi:[1,0]
	v_pk_mul_f32 v[10:11], v[10:11], v[44:45] op_sel_hi:[1,0]
	v_pk_mul_f32 v[16:17], v[16:17], v[46:47] op_sel_hi:[1,0]
	v_pk_mul_f32 v[18:19], v[18:19], v[46:47] op_sel_hi:[1,0]
	v_pk_mul_f32 v[12:13], v[12:13], v[44:45] op_sel_hi:[1,0]
	v_pk_mul_f32 v[14:15], v[14:15], v[44:45] op_sel_hi:[1,0]
	v_pk_mul_f32 v[20:21], v[20:21], v[46:47] op_sel_hi:[1,0]
	v_pk_mul_f32 v[22:23], v[22:23], v[46:47] op_sel_hi:[1,0]
	v_pk_mul_f32 v[24:25], v[24:25], v[44:45] op_sel_hi:[1,0]
	v_pk_mul_f32 v[26:27], v[26:27], v[44:45] op_sel_hi:[1,0]
	v_pk_mul_f32 v[32:33], v[32:33], v[46:47] op_sel_hi:[1,0]
	v_pk_mul_f32 v[34:35], v[34:35], v[46:47] op_sel_hi:[1,0]
	v_pk_mul_f32 v[28:29], v[28:29], v[44:45] op_sel_hi:[1,0]
	v_pk_mul_f32 v[30:31], v[30:31], v[44:45] op_sel_hi:[1,0]
	v_pk_mul_f32 v[36:37], v[36:37], v[46:47] op_sel_hi:[1,0]
	v_pk_mul_f32 v[38:39], v[38:39], v[46:47] op_sel_hi:[1,0]
	v_cvt_pk_bf16_f32 v8, v8, v9
	v_cvt_pk_bf16_f32 v9, v10, v11
	v_cvt_pk_bf16_f32 v10, v16, v17
	v_cvt_pk_bf16_f32 v11, v18, v19
	v_cvt_pk_bf16_f32 v12, v12, v13
	v_cvt_pk_bf16_f32 v13, v14, v15
	v_cvt_pk_bf16_f32 v14, v20, v21
	v_cvt_pk_bf16_f32 v15, v22, v23
	v_cvt_pk_bf16_f32 v16, v24, v25
	v_cvt_pk_bf16_f32 v17, v26, v27
	v_cvt_pk_bf16_f32 v18, v32, v33
	v_cvt_pk_bf16_f32 v19, v34, v35
	v_cvt_pk_bf16_f32 v20, v28, v29
	v_cvt_pk_bf16_f32 v21, v30, v31
	v_cvt_pk_bf16_f32 v22, v36, v37
	v_cvt_pk_bf16_f32 v23, v38, v39
	global_store_dwordx2 v[40:41], v[8:9], off
	global_store_dwordx2 v[42:43], v[10:11], off
	global_store_dwordx2 v[40:41], v[12:13], off offset:512
	global_store_dwordx2 v[42:43], v[14:15], off offset:512
	global_store_dwordx2 v[40:41], v[16:17], off offset:1024
	global_store_dwordx2 v[42:43], v[18:19], off offset:1024
	global_store_dwordx2 v[40:41], v[20:21], off offset:1536
	global_store_dwordx2 v[42:43], v[22:23], off offset:1536
	s_cbranch_scc1 .LBB0_111

.LBB0_151:
	ds_read_b128 v[130:133], v169
	ds_read_b128 v[134:137], v169 offset:1024
	ds_read_b128 v[138:141], v169 offset:2048
	ds_read_b128 v[142:145], v169 offset:3072
	s_add_u32 s57, s58, 0xfffc0080
	s_addc_u32 s60, s59, -1
	s_cmp_eq_u32 s55, 12
	s_cselect_b32 s63, s11, s60
	s_cselect_b32 s62, s10, s57
	s_cselect_b32 s61, s9, s3
	s_cselect_b32 s60, s8, s2
	v_lshl_add_u64 v[200:201], s[58:59], 0, v[160:161]
	s_add_i32 m0, s70, 0xc000
	ds_read_b128 v[164:167], v170
	ds_read_b128 v[172:175], v170 offset:1024
	ds_read_b128 v[176:179], v170 offset:2048
	ds_read_b128 v[180:183], v170 offset:3072
	ds_read_b128 v[184:187], v170 offset:4096
	ds_read_b128 v[188:191], v170 offset:5120
	ds_read_b128 v[192:195], v170 offset:6144
	ds_read_b128 v[196:199], v170 offset:7168
	global_load_lds_dwordx4 v[200:201], off
	v_lshl_add_u64 v[200:201], s[58:59], 0, v[162:163]
	s_add_i32 m0, s70, 0xe000
	s_nop 0
	global_load_lds_dwordx4 v[200:201], off
	s_waitcnt lgkmcnt(8)
	s_barrier
	s_waitcnt lgkmcnt(0)
	s_setprio 1
	s_waitcnt lgkmcnt(0)
	v_mfma_f32_16x16x32_bf16 v[126:129], v[130:133], v[164:167], v[126:129]
	v_mfma_f32_16x16x32_bf16 v[122:125], v[138:141], v[164:167], v[122:125]
	v_mfma_f32_16x16x32_bf16 v[114:117], v[130:133], v[176:179], v[114:117]
	v_mfma_f32_16x16x32_bf16 v[106:109], v[138:141], v[176:179], v[106:109]
	v_mfma_f32_16x16x32_bf16 v[98:101], v[130:133], v[184:187], v[98:101]
	v_mfma_f32_16x16x32_bf16 v[90:93], v[138:141], v[184:187], v[90:93]
	v_mfma_f32_16x16x32_bf16 v[82:85], v[130:133], v[192:195], v[82:85]
	v_mfma_f32_16x16x32_bf16 v[74:77], v[138:141], v[192:195], v[74:77]
	v_mfma_f32_16x16x32_bf16 v[126:129], v[134:137], v[172:175], v[126:129]
	v_mfma_f32_16x16x32_bf16 v[122:125], v[142:145], v[172:175], v[122:125]
	v_mfma_f32_16x16x32_bf16 v[114:117], v[134:137], v[180:183], v[114:117]
	v_mfma_f32_16x16x32_bf16 v[106:109], v[142:145], v[180:183], v[106:109]
	v_mfma_f32_16x16x32_bf16 v[98:101], v[134:137], v[188:191], v[98:101]
	v_mfma_f32_16x16x32_bf16 v[90:93], v[142:145], v[188:191], v[90:93]
	v_mfma_f32_16x16x32_bf16 v[82:85], v[134:137], v[196:199], v[82:85]
	v_mfma_f32_16x16x32_bf16 v[74:77], v[142:145], v[196:199], v[74:77]
	s_setprio 0
	s_barrier
	s_add_i32 s57, s96, s69
	v_lshl_add_u64 v[216:217], s[60:61], 0, v[152:153]
	s_mov_b32 m0, s57
	ds_read_b128 v[200:203], v171
	ds_read_b128 v[204:207], v171 offset:1024
	ds_read_b128 v[208:211], v171 offset:2048
	ds_read_b128 v[212:215], v171 offset:3072
	global_load_lds_dwordx4 v[216:217], off
	v_lshl_add_u64 v[218:219], s[60:61], 0, v[156:157]
	s_add_i32 m0, s57, 0x2000
	s_nop 0
	global_load_lds_dwordx4 v[218:219], off
	s_barrier
	s_waitcnt lgkmcnt(0)
	s_setprio 1
	s_waitcnt lgkmcnt(0)
	v_mfma_f32_16x16x32_bf16 v[118:121], v[200:203], v[164:167], v[118:121]
	v_mfma_f32_16x16x32_bf16 v[110:113], v[208:211], v[164:167], v[110:113]
	v_mfma_f32_16x16x32_bf16 v[102:105], v[200:203], v[176:179], v[102:105]
	v_mfma_f32_16x16x32_bf16 v[94:97], v[208:211], v[176:179], v[94:97]
	v_mfma_f32_16x16x32_bf16 v[86:89], v[200:203], v[184:187], v[86:89]
	v_mfma_f32_16x16x32_bf16 v[78:81], v[208:211], v[184:187], v[78:81]
	v_mfma_f32_16x16x32_bf16 v[70:73], v[200:203], v[192:195], v[70:73]
	v_mfma_f32_16x16x32_bf16 v[66:69], v[208:211], v[192:195], v[66:69]
	v_mfma_f32_16x16x32_bf16 v[118:121], v[204:207], v[172:175], v[118:121]
	v_mfma_f32_16x16x32_bf16 v[110:113], v[212:215], v[172:175], v[110:113]
	v_mfma_f32_16x16x32_bf16 v[102:105], v[204:207], v[180:183], v[102:105]
	v_mfma_f32_16x16x32_bf16 v[94:97], v[212:215], v[180:183], v[94:97]
	v_mfma_f32_16x16x32_bf16 v[86:89], v[204:207], v[188:191], v[86:89]
	v_mfma_f32_16x16x32_bf16 v[78:81], v[212:215], v[188:191], v[78:81]
	v_mfma_f32_16x16x32_bf16 v[70:73], v[204:207], v[196:199], v[70:73]
	v_mfma_f32_16x16x32_bf16 v[66:69], v[212:215], v[196:199], v[66:69]
	s_setprio 0
	s_mov_b32 m0, s70
	v_lshl_add_u64 v[220:221], s[62:63], 0, v[150:151]
	s_barrier
	ds_read_b128 v[164:167], v170 offset:16384
	ds_read_b128 v[172:175], v170 offset:17408
	ds_read_b128 v[176:179], v170 offset:18432
	ds_read_b128 v[180:183], v170 offset:19456
	ds_read_b128 v[184:187], v170 offset:20480
	ds_read_b128 v[188:191], v170 offset:21504
	ds_read_b128 v[192:195], v170 offset:22528
	ds_read_b128 v[196:199], v170 offset:23552
	global_load_lds_dwordx4 v[220:221], off
	v_lshl_add_u64 v[222:223], s[62:63], 0, v[154:155]
	s_mov_b32 m0, s71
	s_nop 0
	global_load_lds_dwordx4 v[222:223], off
	s_barrier
	s_waitcnt lgkmcnt(0)
	s_setprio 1
	s_waitcnt lgkmcnt(0)
	v_mfma_f32_16x16x32_bf16 v[62:65], v[130:133], v[164:167], v[62:65]
	v_mfma_f32_16x16x32_bf16 v[58:61], v[138:141], v[164:167], v[58:61]
	v_mfma_f32_16x16x32_bf16 v[50:53], v[130:133], v[176:179], v[50:53]
	v_mfma_f32_16x16x32_bf16 v[42:45], v[138:141], v[176:179], v[42:45]
	v_mfma_f32_16x16x32_bf16 v[34:37], v[130:133], v[184:187], v[34:37]
	v_mfma_f32_16x16x32_bf16 v[26:29], v[138:141], v[184:187], v[26:29]
	v_mfma_f32_16x16x32_bf16 v[18:21], v[130:133], v[192:195], v[18:21]
	v_mfma_f32_16x16x32_bf16 v[10:13], v[138:141], v[192:195], v[10:13]
	v_mfma_f32_16x16x32_bf16 v[62:65], v[134:137], v[172:175], v[62:65]
	v_mfma_f32_16x16x32_bf16 v[58:61], v[142:145], v[172:175], v[58:61]
	v_mfma_f32_16x16x32_bf16 v[50:53], v[134:137], v[180:183], v[50:53]
	v_mfma_f32_16x16x32_bf16 v[42:45], v[142:145], v[180:183], v[42:45]
	v_mfma_f32_16x16x32_bf16 v[34:37], v[134:137], v[188:191], v[34:37]
	v_mfma_f32_16x16x32_bf16 v[26:29], v[142:145], v[188:191], v[26:29]
	v_mfma_f32_16x16x32_bf16 v[18:21], v[134:137], v[196:199], v[18:21]
	v_mfma_f32_16x16x32_bf16 v[10:13], v[142:145], v[196:199], v[10:13]
	s_setprio 0
	s_barrier
	s_add_u32 s64, s60, 0x40000
	s_addc_u32 s65, s61, 0
	s_add_i32 s57, s33, s69
	v_lshl_add_u64 v[130:131], s[64:65], 0, v[152:153]
	s_mov_b32 m0, s57
	s_nop 0
	global_load_lds_dwordx4 v[130:131], off
	v_lshl_add_u64 v[130:131], s[64:65], 0, v[156:157]
	s_add_i32 m0, s57, 0x2000
	s_nop 0
	global_load_lds_dwordx4 v[130:131], off
	s_waitcnt vmcnt(6)
	s_barrier
	s_setprio 1
	v_mfma_f32_16x16x32_bf16 v[54:57], v[200:203], v[164:167], v[54:57]
	v_mfma_f32_16x16x32_bf16 v[46:49], v[208:211], v[164:167], v[46:49]
	v_mfma_f32_16x16x32_bf16 v[38:41], v[200:203], v[176:179], v[38:41]
	v_mfma_f32_16x16x32_bf16 v[30:33], v[208:211], v[176:179], v[30:33]
	v_mfma_f32_16x16x32_bf16 v[22:25], v[200:203], v[184:187], v[22:25]
	v_mfma_f32_16x16x32_bf16 v[14:17], v[208:211], v[184:187], v[14:17]
	v_mfma_f32_16x16x32_bf16 v[6:9], v[200:203], v[192:195], v[6:9]
	v_mfma_f32_16x16x32_bf16 v[2:5], v[208:211], v[192:195], v[2:5]
	v_mfma_f32_16x16x32_bf16 v[54:57], v[204:207], v[172:175], v[54:57]
	v_mfma_f32_16x16x32_bf16 v[46:49], v[212:215], v[172:175], v[46:49]
	v_mfma_f32_16x16x32_bf16 v[38:41], v[204:207], v[180:183], v[38:41]
	v_mfma_f32_16x16x32_bf16 v[30:33], v[212:215], v[180:183], v[30:33]
	v_mfma_f32_16x16x32_bf16 v[22:25], v[204:207], v[188:191], v[22:25]
	v_mfma_f32_16x16x32_bf16 v[14:17], v[212:215], v[188:191], v[14:17]
	v_mfma_f32_16x16x32_bf16 v[6:9], v[204:207], v[196:199], v[6:9]
	v_mfma_f32_16x16x32_bf16 v[2:5], v[212:215], v[196:199], v[2:5]
	s_setprio 0
	s_add_i32 s57, 0, 0x18000
	v_add_u32_e32 v142, s57, v149
	s_barrier
	ds_read_b128 v[130:133], v142
	ds_read_b128 v[134:137], v142 offset:1024
	ds_read_b128 v[138:141], v142 offset:2048
	ds_read_b128 v[142:145], v142 offset:3072
	s_add_u32 s62, s62, 0x40000
	s_addc_u32 s63, s63, 0
	s_mov_b32 m0, s72
	v_lshl_add_u64 v[200:201], s[62:63], 0, v[150:151]
	ds_read_b128 v[164:167], v170 offset:32768
	ds_read_b128 v[172:175], v170 offset:33792
	ds_read_b128 v[176:179], v170 offset:34816
	ds_read_b128 v[180:183], v170 offset:35840
	ds_read_b128 v[184:187], v170 offset:36864
	ds_read_b128 v[188:191], v170 offset:37888
	ds_read_b128 v[192:195], v170 offset:38912
	ds_read_b128 v[196:199], v170 offset:39936
	global_load_lds_dwordx4 v[200:201], off
	v_lshl_add_u64 v[200:201], s[62:63], 0, v[154:155]
	s_mov_b32 m0, s73
	s_nop 0
	global_load_lds_dwordx4 v[200:201], off
	s_waitcnt lgkmcnt(8)
	s_barrier
	s_waitcnt lgkmcnt(0)
	s_setprio 1
	s_waitcnt lgkmcnt(0)
	v_mfma_f32_16x16x32_bf16 v[126:129], v[130:133], v[164:167], v[126:129]
	v_mfma_f32_16x16x32_bf16 v[122:125], v[138:141], v[164:167], v[122:125]
	v_mfma_f32_16x16x32_bf16 v[114:117], v[130:133], v[176:179], v[114:117]
	v_mfma_f32_16x16x32_bf16 v[106:109], v[138:141], v[176:179], v[106:109]
	v_mfma_f32_16x16x32_bf16 v[98:101], v[130:133], v[184:187], v[98:101]
	v_mfma_f32_16x16x32_bf16 v[90:93], v[138:141], v[184:187], v[90:93]
	v_mfma_f32_16x16x32_bf16 v[82:85], v[130:133], v[192:195], v[82:85]
	v_mfma_f32_16x16x32_bf16 v[74:77], v[138:141], v[192:195], v[74:77]
	v_mfma_f32_16x16x32_bf16 v[126:129], v[134:137], v[172:175], v[126:129]
	v_mfma_f32_16x16x32_bf16 v[122:125], v[142:145], v[172:175], v[122:125]
	v_mfma_f32_16x16x32_bf16 v[114:117], v[134:137], v[180:183], v[114:117]
	v_mfma_f32_16x16x32_bf16 v[106:109], v[142:145], v[180:183], v[106:109]
	v_mfma_f32_16x16x32_bf16 v[98:101], v[134:137], v[188:191], v[98:101]
	v_mfma_f32_16x16x32_bf16 v[90:93], v[142:145], v[188:191], v[90:93]
	v_mfma_f32_16x16x32_bf16 v[82:85], v[134:137], v[196:199], v[82:85]
	v_mfma_f32_16x16x32_bf16 v[74:77], v[142:145], v[196:199], v[74:77]
	s_setprio 0
	s_barrier
	s_add_i32 s62, 0, 0x1c000
	s_add_i32 s57, s57, s69
	v_add_u32_e32 v158, s62, v149
	v_lshl_add_u64 v[216:217], v[216:217], 0, s[0:1]
	s_mov_b32 m0, s57
	ds_read_b128 v[200:203], v158
	ds_read_b128 v[204:207], v158 offset:1024
	ds_read_b128 v[208:211], v158 offset:2048
	ds_read_b128 v[212:215], v158 offset:3072
	global_load_lds_dwordx4 v[216:217], off
	v_lshl_add_u64 v[216:217], v[218:219], 0, s[0:1]
	s_add_i32 m0, s57, 0x2000
	s_nop 0
	global_load_lds_dwordx4 v[216:217], off
	s_barrier
	s_waitcnt lgkmcnt(0)
	s_setprio 1
	s_waitcnt lgkmcnt(0)
	v_mfma_f32_16x16x32_bf16 v[118:121], v[200:203], v[164:167], v[118:121]
	v_mfma_f32_16x16x32_bf16 v[110:113], v[208:211], v[164:167], v[110:113]
	v_mfma_f32_16x16x32_bf16 v[102:105], v[200:203], v[176:179], v[102:105]
	v_mfma_f32_16x16x32_bf16 v[94:97], v[208:211], v[176:179], v[94:97]
	v_mfma_f32_16x16x32_bf16 v[86:89], v[200:203], v[184:187], v[86:89]
	v_mfma_f32_16x16x32_bf16 v[78:81], v[208:211], v[184:187], v[78:81]
	v_mfma_f32_16x16x32_bf16 v[70:73], v[200:203], v[192:195], v[70:73]
	v_mfma_f32_16x16x32_bf16 v[66:69], v[208:211], v[192:195], v[66:69]
	v_mfma_f32_16x16x32_bf16 v[118:121], v[204:207], v[172:175], v[118:121]
	v_mfma_f32_16x16x32_bf16 v[110:113], v[212:215], v[172:175], v[110:113]
	v_mfma_f32_16x16x32_bf16 v[102:105], v[204:207], v[180:183], v[102:105]
	v_mfma_f32_16x16x32_bf16 v[94:97], v[212:215], v[180:183], v[94:97]
	v_mfma_f32_16x16x32_bf16 v[86:89], v[204:207], v[188:191], v[86:89]
	v_mfma_f32_16x16x32_bf16 v[78:81], v[212:215], v[188:191], v[78:81]
	v_mfma_f32_16x16x32_bf16 v[70:73], v[204:207], v[196:199], v[70:73]
	v_mfma_f32_16x16x32_bf16 v[66:69], v[212:215], v[196:199], v[66:69]
	s_setprio 0
	s_mov_b32 m0, s90
	v_lshl_add_u64 v[216:217], v[220:221], 0, s[0:1]
	s_barrier
	ds_read_b128 v[164:167], v170 offset:49152
	ds_read_b128 v[172:175], v170 offset:50176
	ds_read_b128 v[176:179], v170 offset:51200
	ds_read_b128 v[180:183], v170 offset:52224
	ds_read_b128 v[184:187], v170 offset:53248
	ds_read_b128 v[188:191], v170 offset:54272
	ds_read_b128 v[192:195], v170 offset:55296
	ds_read_b128 v[196:199], v170 offset:56320
	global_load_lds_dwordx4 v[216:217], off
	v_lshl_add_u64 v[216:217], v[222:223], 0, s[0:1]
	s_mov_b32 m0, s91
	s_nop 0
	global_load_lds_dwordx4 v[216:217], off
	s_barrier
	s_waitcnt lgkmcnt(0)
	s_setprio 1
	s_waitcnt lgkmcnt(0)
	v_mfma_f32_16x16x32_bf16 v[62:65], v[130:133], v[164:167], v[62:65]
	v_mfma_f32_16x16x32_bf16 v[58:61], v[138:141], v[164:167], v[58:61]
	v_mfma_f32_16x16x32_bf16 v[50:53], v[130:133], v[176:179], v[50:53]
	v_mfma_f32_16x16x32_bf16 v[42:45], v[138:141], v[176:179], v[42:45]
	v_mfma_f32_16x16x32_bf16 v[34:37], v[130:133], v[184:187], v[34:37]
	v_mfma_f32_16x16x32_bf16 v[26:29], v[138:141], v[184:187], v[26:29]
	v_mfma_f32_16x16x32_bf16 v[18:21], v[130:133], v[192:195], v[18:21]
	v_mfma_f32_16x16x32_bf16 v[10:13], v[138:141], v[192:195], v[10:13]
	v_mfma_f32_16x16x32_bf16 v[62:65], v[134:137], v[172:175], v[62:65]
	v_mfma_f32_16x16x32_bf16 v[58:61], v[142:145], v[172:175], v[58:61]
	v_mfma_f32_16x16x32_bf16 v[50:53], v[134:137], v[180:183], v[50:53]
	v_mfma_f32_16x16x32_bf16 v[42:45], v[142:145], v[180:183], v[42:45]
	v_mfma_f32_16x16x32_bf16 v[34:37], v[134:137], v[188:191], v[34:37]
	v_mfma_f32_16x16x32_bf16 v[26:29], v[142:145], v[188:191], v[26:29]
	v_mfma_f32_16x16x32_bf16 v[18:21], v[134:137], v[196:199], v[18:21]
	v_mfma_f32_16x16x32_bf16 v[10:13], v[142:145], v[196:199], v[10:13]
	s_setprio 0
	s_barrier
	s_add_u32 s60, s60, 0x40080
	s_addc_u32 s61, s61, 0
	s_add_i32 s57, s62, s69
	v_lshl_add_u64 v[130:131], s[60:61], 0, v[152:153]
	s_mov_b32 m0, s57
	s_nop 0
	global_load_lds_dwordx4 v[130:131], off
	v_lshl_add_u64 v[130:131], s[60:61], 0, v[156:157]
	s_add_i32 m0, s57, 0x2000
	s_nop 0
	global_load_lds_dwordx4 v[130:131], off
	s_waitcnt vmcnt(6)
	s_barrier
	s_setprio 1
	v_mfma_f32_16x16x32_bf16 v[54:57], v[200:203], v[164:167], v[54:57]
	v_mfma_f32_16x16x32_bf16 v[46:49], v[208:211], v[164:167], v[46:49]
	v_mfma_f32_16x16x32_bf16 v[38:41], v[200:203], v[176:179], v[38:41]
	v_mfma_f32_16x16x32_bf16 v[30:33], v[208:211], v[176:179], v[30:33]
	v_mfma_f32_16x16x32_bf16 v[22:25], v[200:203], v[184:187], v[22:25]
	v_mfma_f32_16x16x32_bf16 v[14:17], v[208:211], v[184:187], v[14:17]
	v_mfma_f32_16x16x32_bf16 v[6:9], v[200:203], v[192:195], v[6:9]
	v_mfma_f32_16x16x32_bf16 v[2:5], v[208:211], v[192:195], v[2:5]
	v_mfma_f32_16x16x32_bf16 v[54:57], v[204:207], v[172:175], v[54:57]
	v_mfma_f32_16x16x32_bf16 v[46:49], v[212:215], v[172:175], v[46:49]
	v_mfma_f32_16x16x32_bf16 v[38:41], v[204:207], v[180:183], v[38:41]
	v_mfma_f32_16x16x32_bf16 v[30:33], v[212:215], v[180:183], v[30:33]
	v_mfma_f32_16x16x32_bf16 v[22:25], v[204:207], v[188:191], v[22:25]
	v_mfma_f32_16x16x32_bf16 v[14:17], v[212:215], v[188:191], v[14:17]
	v_mfma_f32_16x16x32_bf16 v[6:9], v[204:207], v[196:199], v[6:9]
	v_mfma_f32_16x16x32_bf16 v[2:5], v[212:215], v[196:199], v[2:5]
	s_setprio 0
	s_add_i32 s55, s55, 2
	s_add_u32 s58, s58, 0x100
	s_addc_u32 s59, s59, 0
	s_add_u32 s2, s2, 0x100
	s_addc_u32 s3, s3, 0
	s_cmp_gt_u32 s55, 13
	s_barrier
	s_cbranch_scc0 .LBB0_151
	v_mov_b32_e32 v130, v147
	v_mov_b32_e32 v173, v1
	s_ashr_i32 s55, s19, 1
	s_mov_b64 s[62:63], -1
	v_lshlrev_b32_e32 v174, 3, v130
	s_mov_b64 s[60:61], 0
	s_cmp_lt_i32 s55, 4
	s_mov_b64 s[58:59], 0
	s_cbranch_scc1 .LBB0_167
	s_cmp_gt_i32 s55, 5
	s_cbranch_scc0 .LBB0_161
	s_cmp_gt_i32 s55, 6
	s_cbranch_scc0 .LBB0_158
	s_cmp_eq_u32 s55, 7
	s_mov_b64 s[58:59], -1
	s_cbranch_scc0 .LBB0_157
	s_lshl_b32 s2, s18, 8
	s_or_b32 s2, s2, s85
	v_add_u32_e32 v140, s2, v174
	s_lshl_b32 s2, s19, 8
	v_ashrrev_i32_e32 v130, 3, v140
	s_and_b32 s2, s2, 0x100
	v_and_b32_e32 v130, 0xfffffe00, v130
	s_add_i32 s2, s2, s84
	v_add3_u32 v134, s2, v173, v130
	v_ashrrev_i32_e32 v135, 31, v134
	v_lshlrev_b64 v[136:137], 13, v[134:135]
	v_and_b32_e32 v135, 0xff8, v140
	v_lshl_add_u64 v[136:137], s[14:15], 0, v[136:137]
	v_lshlrev_b32_e32 v158, 1, v135
	v_cvt_pk_bf16_f32 v130, v126, v127
	v_cvt_pk_bf16_f32 v131, v128, v129
	v_cvt_pk_bf16_f32 v132, v122, v123
	v_cvt_pk_bf16_f32 v133, v124, v125
	v_lshl_add_u64 v[138:139], v[136:137], 0, v[158:159]
	global_store_dwordx4 v[138:139], v[130:133], off nt
	v_mov_b32_e32 v139, v159
	s_mov_b64 s[58:59], 0
	v_add_u32_e32 v130, 0x80, v140
	v_and_b32_e32 v135, 0xff8, v130
	v_lshlrev_b32_e32 v138, 1, v135
	v_cvt_pk_bf16_f32 v130, v118, v119
	v_cvt_pk_bf16_f32 v131, v120, v121
	v_cvt_pk_bf16_f32 v132, v110, v111
	v_cvt_pk_bf16_f32 v133, v112, v113
	v_lshl_add_u64 v[136:137], v[136:137], 0, v[138:139]
	global_store_dwordx4 v[136:137], v[130:133], off nt
	s_nop 1
	v_add_u32_e32 v130, 16, v134
	v_ashrrev_i32_e32 v131, 31, v130
	v_lshlrev_b64 v[136:137], 13, v[130:131]
	v_lshl_add_u64 v[136:137], s[14:15], 0, v[136:137]
	v_cvt_pk_bf16_f32 v130, v114, v115
	v_cvt_pk_bf16_f32 v131, v116, v117
	v_cvt_pk_bf16_f32 v132, v106, v107
	v_cvt_pk_bf16_f32 v133, v108, v109
	v_lshl_add_u64 v[140:141], v[136:137], 0, v[158:159]
	global_store_dwordx4 v[140:141], v[130:133], off nt
	v_lshl_add_u64 v[136:137], v[136:137], 0, v[138:139]
	s_nop 0
	v_cvt_pk_bf16_f32 v130, v102, v103
	v_cvt_pk_bf16_f32 v131, v104, v105
	v_cvt_pk_bf16_f32 v132, v94, v95
	v_cvt_pk_bf16_f32 v133, v96, v97
	global_store_dwordx4 v[136:137], v[130:133], off nt
	s_nop 1
	v_add_u32_e32 v130, 32, v134
	v_ashrrev_i32_e32 v131, 31, v130
	v_lshlrev_b64 v[136:137], 13, v[130:131]
	v_lshl_add_u64 v[136:137], s[14:15], 0, v[136:137]
	v_cvt_pk_bf16_f32 v130, v98, v99
	v_cvt_pk_bf16_f32 v131, v100, v101
	v_cvt_pk_bf16_f32 v132, v90, v91
	v_cvt_pk_bf16_f32 v133, v92, v93
	v_lshl_add_u64 v[140:141], v[136:137], 0, v[158:159]
	global_store_dwordx4 v[140:141], v[130:133], off nt
	v_lshl_add_u64 v[136:137], v[136:137], 0, v[138:139]
	s_nop 0
	v_cvt_pk_bf16_f32 v130, v86, v87
	v_cvt_pk_bf16_f32 v131, v88, v89
	v_cvt_pk_bf16_f32 v132, v78, v79
	v_cvt_pk_bf16_f32 v133, v80, v81
	global_store_dwordx4 v[136:137], v[130:133], off nt
	s_nop 1
	v_add_u32_e32 v130, 48, v134
	v_ashrrev_i32_e32 v131, 31, v130
	v_lshlrev_b64 v[136:137], 13, v[130:131]
	v_lshl_add_u64 v[136:137], s[14:15], 0, v[136:137]
	v_cvt_pk_bf16_f32 v130, v82, v83
	v_cvt_pk_bf16_f32 v131, v84, v85
	v_cvt_pk_bf16_f32 v132, v74, v75
	v_cvt_pk_bf16_f32 v133, v76, v77
	v_lshl_add_u64 v[140:141], v[136:137], 0, v[158:159]
	global_store_dwordx4 v[140:141], v[130:133], off nt
	v_lshl_add_u64 v[136:137], v[136:137], 0, v[138:139]
	s_nop 0
	v_cvt_pk_bf16_f32 v130, v70, v71
	v_cvt_pk_bf16_f32 v131, v72, v73
	v_cvt_pk_bf16_f32 v132, v66, v67
	v_cvt_pk_bf16_f32 v133, v68, v69
	global_store_dwordx4 v[136:137], v[130:133], off nt
	s_nop 1
	v_add_u32_e32 v130, 0x80, v134
	v_ashrrev_i32_e32 v131, 31, v130
	v_lshlrev_b64 v[136:137], 13, v[130:131]
	v_lshl_add_u64 v[136:137], s[14:15], 0, v[136:137]
	v_cvt_pk_bf16_f32 v130, v62, v63
	v_cvt_pk_bf16_f32 v131, v64, v65
	v_cvt_pk_bf16_f32 v132, v58, v59
	v_cvt_pk_bf16_f32 v133, v60, v61
	v_lshl_add_u64 v[140:141], v[136:137], 0, v[158:159]
	global_store_dwordx4 v[140:141], v[130:133], off nt
	v_lshl_add_u64 v[136:137], v[136:137], 0, v[138:139]
	s_nop 0
	v_cvt_pk_bf16_f32 v130, v54, v55
	v_cvt_pk_bf16_f32 v131, v56, v57
	v_cvt_pk_bf16_f32 v132, v46, v47
	v_cvt_pk_bf16_f32 v133, v48, v49
	global_store_dwordx4 v[136:137], v[130:133], off nt
	s_nop 1
	v_add_u32_e32 v130, 0x90, v134
	v_ashrrev_i32_e32 v131, 31, v130
	v_lshlrev_b64 v[136:137], 13, v[130:131]
	v_lshl_add_u64 v[136:137], s[14:15], 0, v[136:137]
	v_cvt_pk_bf16_f32 v130, v50, v51
	v_cvt_pk_bf16_f32 v131, v52, v53
	v_cvt_pk_bf16_f32 v132, v42, v43
	v_cvt_pk_bf16_f32 v133, v44, v45
	v_lshl_add_u64 v[140:141], v[136:137], 0, v[158:159]
	global_store_dwordx4 v[140:141], v[130:133], off nt
	v_lshl_add_u64 v[136:137], v[136:137], 0, v[138:139]
	s_nop 0
	v_cvt_pk_bf16_f32 v130, v38, v39
	v_cvt_pk_bf16_f32 v131, v40, v41
	v_cvt_pk_bf16_f32 v132, v30, v31
	v_cvt_pk_bf16_f32 v133, v32, v33
	global_store_dwordx4 v[136:137], v[130:133], off nt
	s_nop 1
	v_add_u32_e32 v130, 0xa0, v134
	v_ashrrev_i32_e32 v131, 31, v130
	v_lshlrev_b64 v[136:137], 13, v[130:131]
	v_lshl_add_u64 v[136:137], s[14:15], 0, v[136:137]
	v_cvt_pk_bf16_f32 v130, v34, v35
	v_cvt_pk_bf16_f32 v131, v36, v37
	v_cvt_pk_bf16_f32 v132, v26, v27
	v_cvt_pk_bf16_f32 v133, v28, v29
	v_lshl_add_u64 v[140:141], v[136:137], 0, v[158:159]
	global_store_dwordx4 v[140:141], v[130:133], off nt
	v_lshl_add_u64 v[136:137], v[136:137], 0, v[138:139]
	s_nop 0
	v_cvt_pk_bf16_f32 v130, v22, v23
	v_cvt_pk_bf16_f32 v131, v24, v25
	v_cvt_pk_bf16_f32 v132, v14, v15
	v_cvt_pk_bf16_f32 v133, v16, v17
	global_store_dwordx4 v[136:137], v[130:133], off nt
	s_nop 1
	v_add_u32_e32 v130, 0xb0, v134
	v_ashrrev_i32_e32 v131, 31, v130
	v_lshlrev_b64 v[134:135], 13, v[130:131]
	v_lshl_add_u64 v[134:135], s[14:15], 0, v[134:135]
	v_cvt_pk_bf16_f32 v130, v18, v19
	v_cvt_pk_bf16_f32 v131, v20, v21
	v_cvt_pk_bf16_f32 v132, v10, v11
	v_cvt_pk_bf16_f32 v133, v12, v13
	v_lshl_add_u64 v[136:137], v[134:135], 0, v[158:159]
	global_store_dwordx4 v[136:137], v[130:133], off nt
	v_lshl_add_u64 v[134:135], v[134:135], 0, v[138:139]
	s_nop 0
	v_cvt_pk_bf16_f32 v130, v6, v7
	v_cvt_pk_bf16_f32 v131, v8, v9
	v_cvt_pk_bf16_f32 v132, v2, v3
	v_cvt_pk_bf16_f32 v133, v4, v5
	global_store_dwordx4 v[134:135], v[130:133], off nt

.LBB0_158:
	s_and_b64 vcc, exec, s[62:63]
	s_cbranch_vccz .LBB0_160
	s_lshl_b32 s2, s19, 8
	s_and_b32 s2, s2, 0x100
	s_or_b32 s2, s2, s85
	v_add_u32_e32 v164, s2, v174
	v_ashrrev_i32_e32 v165, 31, v164
	v_lshl_add_u64 v[138:139], v[164:165], 2, s[88:89]
	global_load_dwordx4 v[130:133], v[138:139], off offset:512
	global_load_dwordx4 v[142:145], v[138:139], off
	global_load_dwordx4 v[134:137], v[138:139], off offset:16
	v_mul_f32_e32 v140, 0xbfb8aa3b, v126
	v_mul_f32_e32 v141, 0xbfb8aa3b, v127
	v_exp_f32_e32 v179, v140
	v_exp_f32_e32 v180, v141
	global_load_dwordx4 v[138:141], v[138:139], off offset:528
	v_mul_f32_e32 v158, 0xbfb8aa3b, v128
	v_mul_f32_e32 v166, 0xbfb8aa3b, v129
	v_mul_f32_e32 v167, 0xbfb8aa3b, v122
	v_mul_f32_e32 v168, 0xbfb8aa3b, v123
	v_exp_f32_e32 v158, v158
	v_exp_f32_e32 v181, v166
	v_exp_f32_e32 v182, v167
	v_exp_f32_e32 v168, v168
	s_lshl_b32 s2, s18, 8
	v_mul_f32_e32 v172, 0xbfb8aa3b, v124
	v_mul_f32_e32 v175, 0xbfb8aa3b, v125
	v_mul_f32_e32 v176, 0xbfb8aa3b, v118
	v_mul_f32_e32 v177, 0xbfb8aa3b, v119
	v_mul_f32_e32 v178, 0xbfb8aa3b, v120
	s_add_i32 s2, s2, s84
	v_exp_f32_e32 v172, v172
	v_exp_f32_e32 v175, v175
	v_exp_f32_e32 v176, v176
	v_exp_f32_e32 v177, v177
	v_exp_f32_e32 v190, v178
	v_add_u32_e32 v166, s2, v173
	v_add_f32_e32 v178, 1.0, v179
	v_add_f32_e32 v179, 1.0, v180
	v_add_f32_e32 v158, 1.0, v158
	v_add_f32_e32 v180, 1.0, v181
	v_add_f32_e32 v181, 1.0, v182
	v_add_f32_e32 v168, 1.0, v168
	v_ashrrev_i32_e32 v167, 31, v166
	v_rcp_f32_e32 v186, v178
	v_rcp_f32_e32 v187, v179
	v_rcp_f32_e32 v188, v158
	v_rcp_f32_e32 v189, v180
	v_rcp_f32_e32 v191, v181
	v_rcp_f32_e32 v168, v168
	v_lshlrev_b64 v[166:167], 10, v[166:167]
	v_add_f32_e32 v172, 1.0, v172
	v_add_f32_e32 v175, 1.0, v175
	v_lshl_add_u64 v[166:167], s[20:21], 0, v[166:167]
	v_add_f32_e32 v176, 1.0, v176
	v_add_f32_e32 v177, 1.0, v177
	v_rcp_f32_e32 v172, v172
	v_rcp_f32_e32 v175, v175
	v_lshl_add_u64 v[164:165], v[164:165], 1, v[166:167]
	v_rcp_f32_e32 v167, v176
	v_rcp_f32_e32 v176, v177
	s_waitcnt vmcnt(0)
	v_sub_f32_e32 v158, 1.0, v130
	v_sub_f32_e32 v185, 1.0, v142
	v_sub_f32_e32 v184, 1.0, v143
	v_sub_f32_e32 v183, 1.0, v144
	v_sub_f32_e32 v182, 1.0, v145
	v_sub_f32_e32 v181, 1.0, v134
	v_sub_f32_e32 v180, 1.0, v135
	v_fma_f32 v177, v186, v185, v142
	v_fma_f32 v186, v187, v184, v143
	v_fma_f32 v187, v188, v183, v144
	v_fma_f32 v188, v189, v182, v145
	v_fma_f32 v189, v191, v181, v134
	v_fma_f32 v168, v168, v180, v135
	v_log_f32_e32 v187, v187
	v_log_f32_e32 v188, v188
	v_log_f32_e32 v189, v189
	v_log_f32_e32 v168, v168
	v_sub_f32_e32 v179, 1.0, v136
	v_sub_f32_e32 v178, 1.0, v137
	v_fma_f32 v172, v172, v179, v136
	v_fma_f32 v175, v175, v178, v137
	v_fma_f32 v167, v167, v158, v130
	v_log_f32_e32 v172, v172
	v_log_f32_e32 v175, v175
	v_log_f32_e32 v191, v167
	v_mul_f32_e32 v167, 0xbfb8aa3b, v121
	v_cvt_pk_bf16_f32 v187, v187, v188
	v_cvt_pk_bf16_f32 v188, v189, v168
	v_exp_f32_e32 v168, v167
	v_add_f32_e32 v167, 1.0, v190
	v_log_f32_e32 v177, v177
	v_log_f32_e32 v186, v186
	v_cvt_pk_bf16_f32 v189, v172, v175
	v_rcp_f32_e32 v172, v167
	v_add_f32_e32 v168, 1.0, v168
	v_rcp_f32_e32 v168, v168
	v_sub_f32_e32 v167, 1.0, v132
	v_cvt_pk_bf16_f32 v186, v177, v186
	v_fma_f32 v172, v172, v167, v132
	global_store_dwordx4 v[164:165], v[186:189], off nt
	v_mul_f32_e32 v175, 0xbfb8aa3b, v110
	v_exp_f32_e32 v175, v175
	v_log_f32_e32 v187, v172
	v_sub_f32_e32 v172, 1.0, v133
	v_fma_f32 v168, v168, v172, v133
	v_log_f32_e32 v188, v168
	v_mul_f32_e32 v168, 0xbfb8aa3b, v111
	v_exp_f32_e32 v168, v168
	v_sub_f32_e32 v166, 1.0, v131
	v_fma_f32 v176, v176, v166, v131
	v_add_f32_e32 v175, 1.0, v175
	v_log_f32_e32 v192, v176
	v_rcp_f32_e32 v176, v175
	v_add_f32_e32 v168, 1.0, v168
	v_rcp_f32_e32 v177, v168
	v_sub_f32_e32 v175, 1.0, v138
	v_fma_f32 v168, v176, v175, v138
	v_log_f32_e32 v189, v168
	v_sub_f32_e32 v168, 1.0, v139
	v_fma_f32 v176, v177, v168, v139
	v_mul_f32_e32 v177, 0xbfb8aa3b, v112
	v_exp_f32_e32 v177, v177
	v_log_f32_e32 v190, v176
	v_mul_f32_e32 v176, 0xbfb8aa3b, v113
	v_exp_f32_e32 v186, v176
	v_add_f32_e32 v176, 1.0, v177
	v_rcp_f32_e32 v177, v176
	v_sub_f32_e32 v176, 1.0, v140
	v_add_f32_e32 v186, 1.0, v186
	v_rcp_f32_e32 v186, v186
	v_fma_f32 v177, v177, v176, v140
	v_log_f32_e32 v193, v177
	v_sub_f32_e32 v177, 1.0, v141
	v_cvt_pk_bf16_f32 v187, v187, v188
	v_cvt_pk_bf16_f32 v188, v189, v190
	v_mul_f32_e32 v189, 0xbfb8aa3b, v114
	v_fma_f32 v186, v186, v177, v141
	v_exp_f32_e32 v190, v189
	v_mul_f32_e32 v189, 0xbfb8aa3b, v115
	v_log_f32_e32 v194, v186
	v_cvt_pk_bf16_f32 v186, v191, v192
	v_exp_f32_e32 v191, v189
	v_add_f32_e32 v190, 1.0, v190
	v_cvt_pk_bf16_f32 v189, v193, v194
	v_rcp_f32_e32 v190, v190
	v_add_f32_e32 v191, 1.0, v191
	v_rcp_f32_e32 v191, v191
	global_store_dwordx4 v[164:165], v[186:189], off offset:256 nt
	v_mul_f32_e32 v192, 0xbfb8aa3b, v108
	v_mul_f32_e32 v193, 0xbfb8aa3b, v109
	v_mul_f32_e32 v188, 0xbfb8aa3b, v116
	v_mul_f32_e32 v189, 0xbfb8aa3b, v117
	v_exp_f32_e32 v188, v188
	v_exp_f32_e32 v189, v189
	v_exp_f32_e32 v192, v192
	v_exp_f32_e32 v193, v193
	v_fma_f32 v186, v190, v185, v142
	v_fma_f32 v187, v191, v184, v143
	v_mul_f32_e32 v190, 0xbfb8aa3b, v106
	v_mul_f32_e32 v191, 0xbfb8aa3b, v107
	v_exp_f32_e32 v190, v190
	v_exp_f32_e32 v191, v191
	v_add_f32_e32 v188, 1.0, v188
	v_add_f32_e32 v189, 1.0, v189
	v_add_f32_e32 v192, 1.0, v192
	v_add_f32_e32 v193, 1.0, v193
	v_rcp_f32_e32 v188, v188
	v_rcp_f32_e32 v189, v189
	v_rcp_f32_e32 v192, v192
	v_rcp_f32_e32 v193, v193
	v_add_f32_e32 v190, 1.0, v190
	v_add_f32_e32 v191, 1.0, v191
	v_rcp_f32_e32 v190, v190
	v_rcp_f32_e32 v191, v191
	v_fma_f32 v188, v188, v183, v144
	v_fma_f32 v189, v189, v182, v145
	v_fma_f32 v192, v192, v179, v136
	v_fma_f32 v193, v193, v178, v137
	v_log_f32_e32 v186, v186
	v_log_f32_e32 v187, v187
	v_log_f32_e32 v188, v188
	v_log_f32_e32 v189, v189
	v_log_f32_e32 v192, v192
	v_log_f32_e32 v193, v193
	v_fma_f32 v190, v190, v181, v134
	v_fma_f32 v191, v191, v180, v135
	v_log_f32_e32 v190, v190
	v_log_f32_e32 v191, v191
	v_cvt_pk_bf16_f32 v186, v186, v187
	v_cvt_pk_bf16_f32 v187, v188, v189
	v_cvt_pk_bf16_f32 v189, v192, v193
	v_mul_f32_e32 v192, 0xbfb8aa3b, v102
	v_exp_f32_e32 v194, v192
	v_mul_f32_e32 v192, 0xbfb8aa3b, v103
	v_exp_f32_e32 v195, v192
	v_add_co_u32_e32 v192, vcc, s75, v164
	v_cvt_pk_bf16_f32 v188, v190, v191
	s_nop 0
	v_addc_co_u32_e32 v193, vcc, 0, v165, vcc
	global_store_dwordx4 v[192:193], v[186:189], off nt
	v_mul_f32_e32 v192, 0xbfb8aa3b, v94
	v_mul_f32_e32 v193, 0xbfb8aa3b, v95
	v_mul_f32_e32 v188, 0xbfb8aa3b, v104
	v_mul_f32_e32 v189, 0xbfb8aa3b, v105
	v_exp_f32_e32 v188, v188
	v_exp_f32_e32 v189, v189
	v_exp_f32_e32 v192, v192
	v_exp_f32_e32 v193, v193
	v_add_f32_e32 v194, 1.0, v194
	v_add_f32_e32 v195, 1.0, v195
	v_add_f32_e32 v188, 1.0, v188
	v_add_f32_e32 v189, 1.0, v189
	v_rcp_f32_e32 v194, v194
	v_rcp_f32_e32 v195, v195
	v_rcp_f32_e32 v188, v188
	v_rcp_f32_e32 v189, v189
	v_add_f32_e32 v192, 1.0, v192
	v_add_f32_e32 v193, 1.0, v193
	v_rcp_f32_e32 v192, v192
	v_rcp_f32_e32 v193, v193
	v_fma_f32 v186, v194, v158, v130
	v_fma_f32 v187, v195, v166, v131
	v_fma_f32 v188, v188, v167, v132
	v_fma_f32 v189, v189, v172, v133
	v_mul_f32_e32 v194, 0xbfb8aa3b, v96
	v_mul_f32_e32 v195, 0xbfb8aa3b, v97
	v_log_f32_e32 v186, v186
	v_log_f32_e32 v187, v187
	v_log_f32_e32 v188, v188
	v_log_f32_e32 v189, v189
	v_fma_f32 v192, v192, v175, v138
	v_exp_f32_e32 v194, v194
	v_exp_f32_e32 v195, v195
	v_fma_f32 v193, v193, v168, v139
	v_log_f32_e32 v192, v192
	v_log_f32_e32 v193, v193
	v_add_f32_e32 v194, 1.0, v194
	v_add_f32_e32 v195, 1.0, v195
	v_cvt_pk_bf16_f32 v186, v186, v187
	v_cvt_pk_bf16_f32 v187, v188, v189
	v_mul_f32_e32 v189, 0xbfb8aa3b, v98
	v_rcp_f32_e32 v194, v194
	v_rcp_f32_e32 v195, v195
	v_cvt_pk_bf16_f32 v188, v192, v193
	v_exp_f32_e32 v192, v189
	v_mul_f32_e32 v189, 0xbfb8aa3b, v99
	v_exp_f32_e32 v193, v189
	v_fma_f32 v194, v194, v176, v140
	v_fma_f32 v195, v195, v177, v141
	v_log_f32_e32 v194, v194
	v_log_f32_e32 v195, v195
	v_add_f32_e32 v192, 1.0, v192
	v_add_f32_e32 v193, 1.0, v193
	v_rcp_f32_e32 v192, v192
	v_rcp_f32_e32 v193, v193
	v_lshl_add_u64 v[190:191], v[164:165], 0, s[38:39]
	v_cvt_pk_bf16_f32 v189, v194, v195
	global_store_dwordx4 v[190:191], v[186:189], off offset:256 nt
	v_mul_f32_e32 v190, 0xbfb8aa3b, v90
	v_mul_f32_e32 v191, 0xbfb8aa3b, v91
	v_fma_f32 v186, v192, v185, v142
	v_fma_f32 v187, v193, v184, v143
	v_mul_f32_e32 v188, 0xbfb8aa3b, v100
	v_mul_f32_e32 v189, 0xbfb8aa3b, v101
	v_mul_f32_e32 v192, 0xbfb8aa3b, v92
	v_mul_f32_e32 v193, 0xbfb8aa3b, v93
	v_exp_f32_e32 v188, v188
	v_exp_f32_e32 v189, v189
	v_exp_f32_e32 v192, v192
	v_exp_f32_e32 v193, v193
	v_exp_f32_e32 v190, v190
	v_exp_f32_e32 v191, v191
	v_add_f32_e32 v188, 1.0, v188
	v_add_f32_e32 v189, 1.0, v189
	v_add_f32_e32 v192, 1.0, v192
	v_add_f32_e32 v193, 1.0, v193
	v_rcp_f32_e32 v188, v188
	v_rcp_f32_e32 v189, v189
	v_rcp_f32_e32 v192, v192
	v_rcp_f32_e32 v193, v193
	v_add_f32_e32 v190, 1.0, v190
	v_add_f32_e32 v191, 1.0, v191
	v_rcp_f32_e32 v190, v190
	v_rcp_f32_e32 v191, v191
	v_fma_f32 v188, v188, v183, v144
	v_fma_f32 v189, v189, v182, v145
	v_fma_f32 v192, v192, v179, v136
	v_fma_f32 v193, v193, v178, v137
	v_log_f32_e32 v186, v186
	v_log_f32_e32 v187, v187
	v_log_f32_e32 v188, v188
	v_log_f32_e32 v189, v189
	v_log_f32_e32 v192, v192
	v_log_f32_e32 v193, v193
	v_fma_f32 v190, v190, v181, v134
	v_fma_f32 v191, v191, v180, v135
	v_log_f32_e32 v190, v190
	v_log_f32_e32 v191, v191
	v_cvt_pk_bf16_f32 v186, v186, v187
	v_cvt_pk_bf16_f32 v187, v188, v189
	v_cvt_pk_bf16_f32 v189, v192, v193
	v_mul_f32_e32 v192, 0xbfb8aa3b, v86
	v_exp_f32_e32 v194, v192
	v_mul_f32_e32 v192, 0xbfb8aa3b, v87
	v_exp_f32_e32 v195, v192
	v_add_co_u32_e32 v192, vcc, s92, v164
	v_cvt_pk_bf16_f32 v188, v190, v191
	s_nop 0
	v_addc_co_u32_e32 v193, vcc, 0, v165, vcc
	global_store_dwordx4 v[192:193], v[186:189], off nt
	v_mul_f32_e32 v192, 0xbfb8aa3b, v78
	v_mul_f32_e32 v193, 0xbfb8aa3b, v79
	v_mul_f32_e32 v188, 0xbfb8aa3b, v88
	v_mul_f32_e32 v189, 0xbfb8aa3b, v89
	v_exp_f32_e32 v188, v188
	v_exp_f32_e32 v189, v189
	v_exp_f32_e32 v192, v192
	v_exp_f32_e32 v193, v193
	v_add_f32_e32 v194, 1.0, v194
	v_add_f32_e32 v195, 1.0, v195
	v_add_f32_e32 v188, 1.0, v188
	v_add_f32_e32 v189, 1.0, v189
	v_rcp_f32_e32 v194, v194
	v_rcp_f32_e32 v195, v195
	v_rcp_f32_e32 v188, v188
	v_rcp_f32_e32 v189, v189
	v_add_f32_e32 v192, 1.0, v192
	v_add_f32_e32 v193, 1.0, v193
	v_rcp_f32_e32 v192, v192
	v_rcp_f32_e32 v193, v193
	v_fma_f32 v186, v194, v158, v130
	v_fma_f32 v187, v195, v166, v131
	v_fma_f32 v188, v188, v167, v132
	v_fma_f32 v189, v189, v172, v133
	v_mul_f32_e32 v194, 0xbfb8aa3b, v80
	v_mul_f32_e32 v195, 0xbfb8aa3b, v81
	v_log_f32_e32 v186, v186
	v_log_f32_e32 v187, v187
	v_log_f32_e32 v188, v188
	v_log_f32_e32 v189, v189
	v_fma_f32 v192, v192, v175, v138
	v_exp_f32_e32 v194, v194
	v_exp_f32_e32 v195, v195
	v_fma_f32 v193, v193, v168, v139
	v_log_f32_e32 v192, v192
	v_log_f32_e32 v193, v193
	v_add_f32_e32 v194, 1.0, v194
	v_add_f32_e32 v195, 1.0, v195
	v_cvt_pk_bf16_f32 v186, v186, v187
	v_cvt_pk_bf16_f32 v187, v188, v189
	v_mul_f32_e32 v189, 0xbfb8aa3b, v82
	v_rcp_f32_e32 v194, v194
	v_rcp_f32_e32 v195, v195
	v_cvt_pk_bf16_f32 v188, v192, v193
	v_exp_f32_e32 v192, v189
	v_mul_f32_e32 v189, 0xbfb8aa3b, v83
	v_exp_f32_e32 v193, v189
	v_fma_f32 v194, v194, v176, v140
	v_fma_f32 v195, v195, v177, v141
	v_log_f32_e32 v194, v194
	v_log_f32_e32 v195, v195
	v_add_f32_e32 v192, 1.0, v192
	v_add_f32_e32 v193, 1.0, v193
	v_rcp_f32_e32 v192, v192
	v_rcp_f32_e32 v193, v193
	v_lshl_add_u64 v[190:191], v[164:165], 0, s[40:41]
	v_cvt_pk_bf16_f32 v189, v194, v195
	global_store_dwordx4 v[190:191], v[186:189], off offset:256 nt
	v_mul_f32_e32 v190, 0xbfb8aa3b, v74
	v_mul_f32_e32 v191, 0xbfb8aa3b, v75
	v_fma_f32 v186, v192, v185, v142
	v_fma_f32 v187, v193, v184, v143
	v_mul_f32_e32 v188, 0xbfb8aa3b, v84
	v_mul_f32_e32 v189, 0xbfb8aa3b, v85
	v_mul_f32_e32 v192, 0xbfb8aa3b, v76
	v_mul_f32_e32 v193, 0xbfb8aa3b, v77
	v_exp_f32_e32 v188, v188
	v_exp_f32_e32 v189, v189
	v_exp_f32_e32 v192, v192
	v_exp_f32_e32 v193, v193
	v_exp_f32_e32 v190, v190
	v_exp_f32_e32 v191, v191
	v_add_f32_e32 v188, 1.0, v188
	v_add_f32_e32 v189, 1.0, v189
	v_add_f32_e32 v192, 1.0, v192
	v_add_f32_e32 v193, 1.0, v193
	v_rcp_f32_e32 v188, v188
	v_rcp_f32_e32 v189, v189
	v_rcp_f32_e32 v192, v192
	v_rcp_f32_e32 v193, v193
	v_add_f32_e32 v190, 1.0, v190
	v_add_f32_e32 v191, 1.0, v191
	v_rcp_f32_e32 v190, v190
	v_rcp_f32_e32 v191, v191
	v_fma_f32 v188, v188, v183, v144
	v_fma_f32 v189, v189, v182, v145
	v_fma_f32 v192, v192, v179, v136
	v_fma_f32 v193, v193, v178, v137
	v_log_f32_e32 v186, v186
	v_log_f32_e32 v187, v187
	v_log_f32_e32 v188, v188
	v_log_f32_e32 v189, v189
	v_log_f32_e32 v192, v192
	v_log_f32_e32 v193, v193
	v_fma_f32 v190, v190, v181, v134
	v_fma_f32 v191, v191, v180, v135
	v_log_f32_e32 v190, v190
	v_log_f32_e32 v191, v191
	v_cvt_pk_bf16_f32 v186, v186, v187
	v_cvt_pk_bf16_f32 v187, v188, v189
	v_cvt_pk_bf16_f32 v189, v192, v193
	v_mul_f32_e32 v192, 0xbfb8aa3b, v70
	v_exp_f32_e32 v194, v192
	v_mul_f32_e32 v192, 0xbfb8aa3b, v71
	v_exp_f32_e32 v195, v192
	v_add_co_u32_e32 v192, vcc, s97, v164
	v_cvt_pk_bf16_f32 v188, v190, v191
	s_nop 0
	v_addc_co_u32_e32 v193, vcc, 0, v165, vcc
	global_store_dwordx4 v[192:193], v[186:189], off nt
	v_mul_f32_e32 v192, 0xbfb8aa3b, v66
	v_mul_f32_e32 v193, 0xbfb8aa3b, v67
	v_mul_f32_e32 v188, 0xbfb8aa3b, v72
	v_mul_f32_e32 v189, 0xbfb8aa3b, v73
	v_exp_f32_e32 v188, v188
	v_exp_f32_e32 v189, v189
	v_exp_f32_e32 v192, v192
	v_exp_f32_e32 v193, v193
	v_add_f32_e32 v194, 1.0, v194
	v_add_f32_e32 v195, 1.0, v195
	v_add_f32_e32 v188, 1.0, v188
	v_add_f32_e32 v189, 1.0, v189
	v_rcp_f32_e32 v194, v194
	v_rcp_f32_e32 v195, v195
	v_rcp_f32_e32 v188, v188
	v_rcp_f32_e32 v189, v189
	v_add_f32_e32 v192, 1.0, v192
	v_add_f32_e32 v193, 1.0, v193
	v_rcp_f32_e32 v192, v192
	v_rcp_f32_e32 v193, v193
	v_fma_f32 v186, v194, v158, v130
	v_fma_f32 v187, v195, v166, v131
	v_fma_f32 v188, v188, v167, v132
	v_fma_f32 v189, v189, v172, v133
	v_mul_f32_e32 v194, 0xbfb8aa3b, v68
	v_mul_f32_e32 v195, 0xbfb8aa3b, v69
	v_log_f32_e32 v186, v186
	v_log_f32_e32 v187, v187
	v_log_f32_e32 v188, v188
	v_log_f32_e32 v189, v189
	v_fma_f32 v192, v192, v175, v138
	v_exp_f32_e32 v194, v194
	v_exp_f32_e32 v195, v195
	v_fma_f32 v193, v193, v168, v139
	v_log_f32_e32 v192, v192
	v_log_f32_e32 v193, v193
	v_add_f32_e32 v194, 1.0, v194
	v_add_f32_e32 v195, 1.0, v195
	v_cvt_pk_bf16_f32 v186, v186, v187
	v_cvt_pk_bf16_f32 v187, v188, v189
	v_mul_f32_e32 v189, 0xbfb8aa3b, v62
	v_rcp_f32_e32 v194, v194
	v_rcp_f32_e32 v195, v195
	v_cvt_pk_bf16_f32 v188, v192, v193
	v_exp_f32_e32 v192, v189
	v_mul_f32_e32 v189, 0xbfb8aa3b, v63
	v_exp_f32_e32 v193, v189
	v_fma_f32 v194, v194, v176, v140
	v_fma_f32 v195, v195, v177, v141
	v_log_f32_e32 v194, v194
	v_log_f32_e32 v195, v195
	v_add_f32_e32 v192, 1.0, v192
	v_add_f32_e32 v193, 1.0, v193
	v_rcp_f32_e32 v192, v192
	v_rcp_f32_e32 v193, v193
	v_lshl_add_u64 v[190:191], v[164:165], 0, s[42:43]
	v_cvt_pk_bf16_f32 v189, v194, v195
	global_store_dwordx4 v[190:191], v[186:189], off offset:256 nt
	v_mul_f32_e32 v190, 0xbfb8aa3b, v58
	v_mul_f32_e32 v191, 0xbfb8aa3b, v59
	v_fma_f32 v186, v192, v185, v142
	v_fma_f32 v187, v193, v184, v143
	v_mul_f32_e32 v188, 0xbfb8aa3b, v64
	v_mul_f32_e32 v189, 0xbfb8aa3b, v65
	v_mul_f32_e32 v192, 0xbfb8aa3b, v60
	v_mul_f32_e32 v193, 0xbfb8aa3b, v61
	v_exp_f32_e32 v188, v188
	v_exp_f32_e32 v189, v189
	v_exp_f32_e32 v192, v192
	v_exp_f32_e32 v193, v193
	v_exp_f32_e32 v190, v190
	v_exp_f32_e32 v191, v191
	v_add_f32_e32 v188, 1.0, v188
	v_add_f32_e32 v189, 1.0, v189
	v_add_f32_e32 v192, 1.0, v192
	v_add_f32_e32 v193, 1.0, v193
	v_rcp_f32_e32 v188, v188
	v_rcp_f32_e32 v189, v189
	v_rcp_f32_e32 v192, v192
	v_rcp_f32_e32 v193, v193
	v_add_f32_e32 v190, 1.0, v190
	v_add_f32_e32 v191, 1.0, v191
	v_rcp_f32_e32 v190, v190
	v_rcp_f32_e32 v191, v191
	v_fma_f32 v188, v188, v183, v144
	v_fma_f32 v189, v189, v182, v145
	v_fma_f32 v192, v192, v179, v136
	v_fma_f32 v193, v193, v178, v137
	v_log_f32_e32 v186, v186
	v_log_f32_e32 v187, v187
	v_log_f32_e32 v188, v188
	v_log_f32_e32 v189, v189
	v_log_f32_e32 v192, v192
	v_log_f32_e32 v193, v193
	v_fma_f32 v190, v190, v181, v134
	v_fma_f32 v191, v191, v180, v135
	v_log_f32_e32 v190, v190
	v_log_f32_e32 v191, v191
	v_cvt_pk_bf16_f32 v186, v186, v187
	v_cvt_pk_bf16_f32 v187, v188, v189
	v_cvt_pk_bf16_f32 v189, v192, v193
	v_mul_f32_e32 v192, 0xbfb8aa3b, v54
	v_exp_f32_e32 v194, v192
	v_mul_f32_e32 v192, 0xbfb8aa3b, v55
	v_exp_f32_e32 v195, v192
	v_add_co_u32_e32 v192, vcc, s66, v164
	v_cvt_pk_bf16_f32 v188, v190, v191
	s_nop 0
	v_addc_co_u32_e32 v193, vcc, 0, v165, vcc
	global_store_dwordx4 v[192:193], v[186:189], off nt
	v_mul_f32_e32 v192, 0xbfb8aa3b, v46
	v_mul_f32_e32 v193, 0xbfb8aa3b, v47
	v_mul_f32_e32 v188, 0xbfb8aa3b, v56
	v_mul_f32_e32 v189, 0xbfb8aa3b, v57
	v_exp_f32_e32 v188, v188
	v_exp_f32_e32 v189, v189
	v_exp_f32_e32 v192, v192
	v_exp_f32_e32 v193, v193
	v_add_f32_e32 v194, 1.0, v194
	v_add_f32_e32 v195, 1.0, v195
	v_add_f32_e32 v188, 1.0, v188
	v_add_f32_e32 v189, 1.0, v189
	v_rcp_f32_e32 v194, v194
	v_rcp_f32_e32 v195, v195
	v_rcp_f32_e32 v188, v188
	v_rcp_f32_e32 v189, v189
	v_add_f32_e32 v192, 1.0, v192
	v_add_f32_e32 v193, 1.0, v193
	v_rcp_f32_e32 v192, v192
	v_rcp_f32_e32 v193, v193
	v_fma_f32 v186, v194, v158, v130
	v_fma_f32 v187, v195, v166, v131
	v_fma_f32 v188, v188, v167, v132
	v_fma_f32 v189, v189, v172, v133
	v_mul_f32_e32 v194, 0xbfb8aa3b, v48
	v_mul_f32_e32 v195, 0xbfb8aa3b, v49
	v_log_f32_e32 v186, v186
	v_log_f32_e32 v187, v187
	v_log_f32_e32 v188, v188
	v_log_f32_e32 v189, v189
	v_fma_f32 v192, v192, v175, v138
	v_exp_f32_e32 v194, v194
	v_exp_f32_e32 v195, v195
	v_fma_f32 v193, v193, v168, v139
	v_log_f32_e32 v192, v192
	v_log_f32_e32 v193, v193
	v_add_f32_e32 v194, 1.0, v194
	v_add_f32_e32 v195, 1.0, v195
	v_cvt_pk_bf16_f32 v186, v186, v187
	v_cvt_pk_bf16_f32 v187, v188, v189
	v_mul_f32_e32 v189, 0xbfb8aa3b, v50
	v_rcp_f32_e32 v194, v194
	v_rcp_f32_e32 v195, v195
	v_cvt_pk_bf16_f32 v188, v192, v193
	v_exp_f32_e32 v192, v189
	v_mul_f32_e32 v189, 0xbfb8aa3b, v51
	v_exp_f32_e32 v193, v189
	v_fma_f32 v194, v194, v176, v140
	v_fma_f32 v195, v195, v177, v141
	v_log_f32_e32 v194, v194
	v_log_f32_e32 v195, v195
	v_add_f32_e32 v192, 1.0, v192
	v_add_f32_e32 v193, 1.0, v193
	v_rcp_f32_e32 v192, v192
	v_rcp_f32_e32 v193, v193
	v_lshl_add_u64 v[190:191], v[164:165], 0, s[44:45]
	v_cvt_pk_bf16_f32 v189, v194, v195
	global_store_dwordx4 v[190:191], v[186:189], off offset:256 nt
	v_mul_f32_e32 v190, 0xbfb8aa3b, v42
	v_mul_f32_e32 v191, 0xbfb8aa3b, v43
	v_fma_f32 v186, v192, v185, v142
	v_fma_f32 v187, v193, v184, v143
	v_mul_f32_e32 v188, 0xbfb8aa3b, v52
	v_mul_f32_e32 v189, 0xbfb8aa3b, v53
	v_mul_f32_e32 v192, 0xbfb8aa3b, v44
	v_mul_f32_e32 v193, 0xbfb8aa3b, v45
	v_exp_f32_e32 v188, v188
	v_exp_f32_e32 v189, v189
	v_exp_f32_e32 v192, v192
	v_exp_f32_e32 v193, v193
	v_exp_f32_e32 v190, v190
	v_exp_f32_e32 v191, v191
	v_add_f32_e32 v188, 1.0, v188
	v_add_f32_e32 v189, 1.0, v189
	v_add_f32_e32 v192, 1.0, v192
	v_add_f32_e32 v193, 1.0, v193
	v_rcp_f32_e32 v188, v188
	v_rcp_f32_e32 v189, v189
	v_rcp_f32_e32 v192, v192
	v_rcp_f32_e32 v193, v193
	v_add_f32_e32 v190, 1.0, v190
	v_add_f32_e32 v191, 1.0, v191
	v_rcp_f32_e32 v190, v190
	v_rcp_f32_e32 v191, v191
	v_fma_f32 v188, v188, v183, v144
	v_fma_f32 v189, v189, v182, v145
	v_fma_f32 v192, v192, v179, v136
	v_fma_f32 v193, v193, v178, v137
	v_log_f32_e32 v186, v186
	v_log_f32_e32 v187, v187
	v_log_f32_e32 v188, v188
	v_log_f32_e32 v189, v189
	v_log_f32_e32 v192, v192
	v_log_f32_e32 v193, v193
	v_fma_f32 v190, v190, v181, v134
	v_fma_f32 v191, v191, v180, v135
	v_log_f32_e32 v190, v190
	v_log_f32_e32 v191, v191
	v_cvt_pk_bf16_f32 v186, v186, v187
	v_cvt_pk_bf16_f32 v187, v188, v189
	v_cvt_pk_bf16_f32 v189, v192, v193
	v_mul_f32_e32 v192, 0xbfb8aa3b, v38
	v_exp_f32_e32 v194, v192
	v_mul_f32_e32 v192, 0xbfb8aa3b, v39
	v_exp_f32_e32 v195, v192
	v_add_co_u32_e32 v192, vcc, s53, v164
	v_cvt_pk_bf16_f32 v188, v190, v191
	s_nop 0
	v_addc_co_u32_e32 v193, vcc, 0, v165, vcc
	global_store_dwordx4 v[192:193], v[186:189], off nt
	v_mul_f32_e32 v192, 0xbfb8aa3b, v30
	v_mul_f32_e32 v193, 0xbfb8aa3b, v31
	v_mul_f32_e32 v188, 0xbfb8aa3b, v40
	v_mul_f32_e32 v189, 0xbfb8aa3b, v41
	v_exp_f32_e32 v188, v188
	v_exp_f32_e32 v189, v189
	v_exp_f32_e32 v192, v192
	v_exp_f32_e32 v193, v193
	v_add_f32_e32 v194, 1.0, v194
	v_add_f32_e32 v195, 1.0, v195
	v_add_f32_e32 v188, 1.0, v188
	v_add_f32_e32 v189, 1.0, v189
	v_rcp_f32_e32 v194, v194
	v_rcp_f32_e32 v195, v195
	v_rcp_f32_e32 v188, v188
	v_rcp_f32_e32 v189, v189
	v_add_f32_e32 v192, 1.0, v192
	v_add_f32_e32 v193, 1.0, v193
	v_rcp_f32_e32 v192, v192
	v_rcp_f32_e32 v193, v193
	v_fma_f32 v186, v194, v158, v130
	v_fma_f32 v187, v195, v166, v131
	v_fma_f32 v188, v188, v167, v132
	v_fma_f32 v189, v189, v172, v133
	v_mul_f32_e32 v194, 0xbfb8aa3b, v32
	v_mul_f32_e32 v195, 0xbfb8aa3b, v33
	v_log_f32_e32 v186, v186
	v_log_f32_e32 v187, v187
	v_log_f32_e32 v188, v188
	v_log_f32_e32 v189, v189
	v_fma_f32 v192, v192, v175, v138
	v_exp_f32_e32 v194, v194
	v_exp_f32_e32 v195, v195
	v_fma_f32 v193, v193, v168, v139
	v_log_f32_e32 v192, v192
	v_log_f32_e32 v193, v193
	v_add_f32_e32 v194, 1.0, v194
	v_add_f32_e32 v195, 1.0, v195
	v_cvt_pk_bf16_f32 v186, v186, v187
	v_cvt_pk_bf16_f32 v187, v188, v189
	v_mul_f32_e32 v189, 0xbfb8aa3b, v34
	v_rcp_f32_e32 v194, v194
	v_rcp_f32_e32 v195, v195
	v_cvt_pk_bf16_f32 v188, v192, v193
	v_exp_f32_e32 v192, v189
	v_mul_f32_e32 v189, 0xbfb8aa3b, v35
	v_exp_f32_e32 v193, v189
	v_fma_f32 v194, v194, v176, v140
	v_fma_f32 v195, v195, v177, v141
	v_log_f32_e32 v194, v194
	v_log_f32_e32 v195, v195
	v_add_f32_e32 v192, 1.0, v192
	v_add_f32_e32 v193, 1.0, v193
	v_rcp_f32_e32 v192, v192
	v_rcp_f32_e32 v193, v193
	v_lshl_add_u64 v[190:191], v[164:165], 0, s[46:47]
	v_cvt_pk_bf16_f32 v189, v194, v195
	global_store_dwordx4 v[190:191], v[186:189], off offset:256 nt
	v_mul_f32_e32 v190, 0xbfb8aa3b, v26
	v_mul_f32_e32 v191, 0xbfb8aa3b, v27
	v_fma_f32 v186, v192, v185, v142
	v_fma_f32 v187, v193, v184, v143
	v_mul_f32_e32 v188, 0xbfb8aa3b, v36
	v_mul_f32_e32 v189, 0xbfb8aa3b, v37
	v_mul_f32_e32 v192, 0xbfb8aa3b, v28
	v_mul_f32_e32 v193, 0xbfb8aa3b, v29
	v_exp_f32_e32 v188, v188
	v_exp_f32_e32 v189, v189
	v_exp_f32_e32 v192, v192
	v_exp_f32_e32 v193, v193
	v_exp_f32_e32 v190, v190
	v_exp_f32_e32 v191, v191
	v_add_f32_e32 v188, 1.0, v188
	v_add_f32_e32 v189, 1.0, v189
	v_add_f32_e32 v192, 1.0, v192
	v_add_f32_e32 v193, 1.0, v193
	v_rcp_f32_e32 v188, v188
	v_rcp_f32_e32 v189, v189
	v_rcp_f32_e32 v192, v192
	v_rcp_f32_e32 v193, v193
	v_add_f32_e32 v190, 1.0, v190
	v_add_f32_e32 v191, 1.0, v191
	v_rcp_f32_e32 v190, v190
	v_rcp_f32_e32 v191, v191
	v_fma_f32 v188, v188, v183, v144
	v_fma_f32 v189, v189, v182, v145
	v_fma_f32 v192, v192, v179, v136
	v_fma_f32 v193, v193, v178, v137
	v_log_f32_e32 v186, v186
	v_log_f32_e32 v187, v187
	v_log_f32_e32 v188, v188
	v_log_f32_e32 v189, v189
	v_log_f32_e32 v192, v192
	v_log_f32_e32 v193, v193
	v_fma_f32 v190, v190, v181, v134
	v_fma_f32 v191, v191, v180, v135
	v_log_f32_e32 v190, v190
	v_log_f32_e32 v191, v191
	v_cvt_pk_bf16_f32 v186, v186, v187
	v_cvt_pk_bf16_f32 v187, v188, v189
	v_cvt_pk_bf16_f32 v189, v192, v193
	v_mul_f32_e32 v192, 0xbfb8aa3b, v22
	v_exp_f32_e32 v194, v192
	v_mul_f32_e32 v192, 0xbfb8aa3b, v23
	v_exp_f32_e32 v195, v192
	v_add_co_u32_e32 v192, vcc, s68, v164
	v_cvt_pk_bf16_f32 v188, v190, v191
	s_nop 0
	v_addc_co_u32_e32 v193, vcc, 0, v165, vcc
	global_store_dwordx4 v[192:193], v[186:189], off nt
	v_mul_f32_e32 v192, 0xbfb8aa3b, v14
	v_mul_f32_e32 v193, 0xbfb8aa3b, v15
	v_mul_f32_e32 v188, 0xbfb8aa3b, v24
	v_mul_f32_e32 v189, 0xbfb8aa3b, v25
	v_exp_f32_e32 v188, v188
	v_exp_f32_e32 v189, v189
	v_exp_f32_e32 v192, v192
	v_exp_f32_e32 v193, v193
	v_add_f32_e32 v194, 1.0, v194
	v_add_f32_e32 v195, 1.0, v195
	v_add_f32_e32 v188, 1.0, v188
	v_add_f32_e32 v189, 1.0, v189
	v_rcp_f32_e32 v194, v194
	v_rcp_f32_e32 v195, v195
	v_rcp_f32_e32 v188, v188
	v_rcp_f32_e32 v189, v189
	v_add_f32_e32 v192, 1.0, v192
	v_add_f32_e32 v193, 1.0, v193
	v_rcp_f32_e32 v192, v192
	v_rcp_f32_e32 v193, v193
	v_fma_f32 v186, v194, v158, v130
	v_fma_f32 v187, v195, v166, v131
	v_fma_f32 v188, v188, v167, v132
	v_fma_f32 v189, v189, v172, v133
	v_log_f32_e32 v186, v186
	v_log_f32_e32 v187, v187
	v_log_f32_e32 v188, v188
	v_log_f32_e32 v189, v189
	v_fma_f32 v192, v192, v175, v138
	v_fma_f32 v193, v193, v168, v139
	v_log_f32_e32 v192, v192
	v_log_f32_e32 v193, v193
	v_mul_f32_e32 v194, 0xbfb8aa3b, v16
	v_mul_f32_e32 v195, 0xbfb8aa3b, v17
	v_exp_f32_e32 v194, v194
	v_exp_f32_e32 v195, v195
	v_cvt_pk_bf16_f32 v186, v186, v187
	v_cvt_pk_bf16_f32 v187, v188, v189
	v_mul_f32_e32 v189, 0xbfb8aa3b, v18
	v_cvt_pk_bf16_f32 v188, v192, v193
	v_exp_f32_e32 v192, v189
	v_mul_f32_e32 v189, 0xbfb8aa3b, v19
	v_exp_f32_e32 v193, v189
	v_add_f32_e32 v194, 1.0, v194
	v_add_f32_e32 v195, 1.0, v195
	v_rcp_f32_e32 v194, v194
	v_rcp_f32_e32 v195, v195
	v_add_f32_e32 v192, 1.0, v192
	v_rcp_f32_e32 v192, v192
	v_add_f32_e32 v193, 1.0, v193
	v_rcp_f32_e32 v193, v193
	v_fma_f32 v194, v194, v176, v140
	v_fma_f32 v195, v195, v177, v141
	v_log_f32_e32 v194, v194
	v_log_f32_e32 v195, v195
	v_fma_f32 v142, v192, v185, v142
	v_mul_f32_e32 v185, 0xbfb8aa3b, v21
	v_fma_f32 v143, v193, v184, v143
	v_mul_f32_e32 v184, 0xbfb8aa3b, v20
	v_exp_f32_e32 v185, v185
	v_exp_f32_e32 v184, v184
	v_lshl_add_u64 v[190:191], v[164:165], 0, s[48:49]
	v_cvt_pk_bf16_f32 v189, v194, v195
	global_store_dwordx4 v[190:191], v[186:189], off offset:256 nt
	v_add_f32_e32 v185, 1.0, v185
	v_add_f32_e32 v184, 1.0, v184
	v_mul_f32_e32 v186, 0xbfb8aa3b, v10
	v_rcp_f32_e32 v185, v185
	v_exp_f32_e32 v186, v186
	v_rcp_f32_e32 v184, v184
	v_log_f32_e32 v142, v142
	v_fmac_f32_e32 v145, v185, v182
	v_add_f32_e32 v182, 1.0, v186
	v_fma_f32 v144, v184, v183, v144
	v_rcp_f32_e32 v182, v182
	v_mul_f32_e32 v183, 0xbfb8aa3b, v11
	v_exp_f32_e32 v183, v183
	v_log_f32_e32 v144, v144
	v_fma_f32 v134, v182, v181, v134
	v_log_f32_e32 v181, v134
	v_add_f32_e32 v134, 1.0, v183
	v_mul_f32_e32 v182, 0xbfb8aa3b, v12
	v_mul_f32_e32 v183, 0xbfb8aa3b, v13
	v_rcp_f32_e32 v134, v134
	v_exp_f32_e32 v182, v182
	v_exp_f32_e32 v183, v183
	v_log_f32_e32 v145, v145
	v_fma_f32 v134, v134, v180, v135
	v_add_f32_e32 v135, 1.0, v182
	v_add_f32_e32 v180, 1.0, v183
	v_rcp_f32_e32 v135, v135
	v_rcp_f32_e32 v180, v180
	v_log_f32_e32 v182, v134
	v_log_f32_e32 v143, v143
	v_fma_f32 v134, v135, v179, v136
	v_fmac_f32_e32 v137, v180, v178
	v_log_f32_e32 v179, v134
	v_log_f32_e32 v137, v137
	v_cvt_pk_bf16_f32 v135, v144, v145
	v_mul_f32_e32 v144, 0xbfb8aa3b, v6
	v_exp_f32_e32 v178, v144
	v_mul_f32_e32 v144, 0xbfb8aa3b, v7
	v_cvt_pk_bf16_f32 v137, v179, v137
	v_exp_f32_e32 v179, v144
	v_add_co_u32_e32 v144, vcc, s4, v164
	v_cvt_pk_bf16_f32 v134, v142, v143
	v_cvt_pk_bf16_f32 v136, v181, v182
	v_addc_co_u32_e32 v145, vcc, 0, v165, vcc
	global_store_dwordx4 v[144:145], v[134:137], off nt
	v_lshl_add_u64 v[142:143], v[164:165], 0, s[50:51]
	v_add_f32_e32 v164, 1.0, v178
	v_mul_f32_e32 v134, 0xbfb8aa3b, v8
	v_mul_f32_e32 v135, 0xbfb8aa3b, v9
	v_exp_f32_e32 v134, v134
	v_exp_f32_e32 v135, v135
	v_mul_f32_e32 v136, 0xbfb8aa3b, v2
	v_exp_f32_e32 v136, v136
	v_add_f32_e32 v134, 1.0, v134
	v_add_f32_e32 v135, 1.0, v135
	v_rcp_f32_e32 v134, v134
	v_rcp_f32_e32 v135, v135
	v_mul_f32_e32 v137, 0xbfb8aa3b, v5
	v_exp_f32_e32 v137, v137
	v_fma_f32 v132, v134, v167, v132
	v_fmac_f32_e32 v133, v135, v172
	v_add_f32_e32 v134, 1.0, v136
	v_mul_f32_e32 v135, 0xbfb8aa3b, v3
	v_mul_f32_e32 v136, 0xbfb8aa3b, v4
	v_exp_f32_e32 v135, v135
	v_exp_f32_e32 v136, v136
	v_add_f32_e32 v165, 1.0, v179
	v_add_f32_e32 v137, 1.0, v137
	v_add_f32_e32 v135, 1.0, v135
	v_add_f32_e32 v136, 1.0, v136
	v_rcp_f32_e32 v164, v164
	v_rcp_f32_e32 v165, v165
	v_rcp_f32_e32 v134, v134
	v_rcp_f32_e32 v135, v135
	v_rcp_f32_e32 v136, v136
	v_rcp_f32_e32 v137, v137
	v_fma_f32 v130, v164, v158, v130
	v_fma_f32 v131, v165, v166, v131
	v_fma_f32 v134, v134, v175, v138
	v_fma_f32 v135, v135, v168, v139
	v_fma_f32 v136, v136, v176, v140
	v_fmac_f32_e32 v141, v137, v177
	v_log_f32_e32 v130, v130
	v_log_f32_e32 v131, v131
	v_log_f32_e32 v132, v132
	v_log_f32_e32 v133, v133
	v_log_f32_e32 v134, v134
	v_log_f32_e32 v135, v135
	v_log_f32_e32 v136, v136
	v_log_f32_e32 v137, v141
	v_cvt_pk_bf16_f32 v130, v130, v131
	v_cvt_pk_bf16_f32 v131, v132, v133
	v_cvt_pk_bf16_f32 v132, v134, v135
	v_cvt_pk_bf16_f32 v133, v136, v137
	global_store_dwordx4 v[142:143], v[130:133], off offset:256 nt

.LBB0_161:
	s_and_b64 vcc, exec, s[62:63]
	s_cbranch_vccz .LBB0_166
	v_mul_f32_e32 v130, 0xbfb8aa3b, v126
	v_mul_f32_e32 v131, 0xbfb8aa3b, v127
	v_mul_f32_e32 v132, 0xbfb8aa3b, v128
	v_mul_f32_e32 v133, 0xbfb8aa3b, v129
	v_mul_f32_e32 v134, 0xbfb8aa3b, v122
	v_mul_f32_e32 v135, 0xbfb8aa3b, v123
	v_mul_f32_e32 v136, 0xbfb8aa3b, v124
	v_mul_f32_e32 v137, 0xbfb8aa3b, v125
	v_mul_f32_e32 v138, 0xbfb8aa3b, v118
	v_mul_f32_e32 v139, 0xbfb8aa3b, v119
	v_mul_f32_e32 v140, 0xbfb8aa3b, v120
	v_mul_f32_e32 v141, 0xbfb8aa3b, v121
	v_mul_f32_e32 v142, 0xbfb8aa3b, v110
	v_mul_f32_e32 v143, 0xbfb8aa3b, v111
	v_mul_f32_e32 v144, 0xbfb8aa3b, v112
	v_mul_f32_e32 v145, 0xbfb8aa3b, v113
	v_mul_f32_e32 v158, 0xbfb8aa3b, v114
	v_mul_f32_e32 v164, 0xbfb8aa3b, v115
	v_mul_f32_e32 v165, 0xbfb8aa3b, v116
	v_mul_f32_e32 v166, 0xbfb8aa3b, v117
	v_mul_f32_e32 v167, 0xbfb8aa3b, v106
	v_mul_f32_e32 v168, 0xbfb8aa3b, v107
	v_mul_f32_e32 v172, 0xbfb8aa3b, v108
	v_mul_f32_e32 v175, 0xbfb8aa3b, v109
	v_mul_f32_e32 v176, 0xbfb8aa3b, v102
	v_mul_f32_e32 v177, 0xbfb8aa3b, v103
	v_mul_f32_e32 v178, 0xbfb8aa3b, v104
	v_mul_f32_e32 v179, 0xbfb8aa3b, v105
	v_mul_f32_e32 v180, 0xbfb8aa3b, v94
	v_mul_f32_e32 v181, 0xbfb8aa3b, v95
	v_mul_f32_e32 v182, 0xbfb8aa3b, v96
	v_mul_f32_e32 v183, 0xbfb8aa3b, v97
	v_mul_f32_e32 v184, 0xbfb8aa3b, v98
	v_mul_f32_e32 v185, 0xbfb8aa3b, v99
	v_mul_f32_e32 v186, 0xbfb8aa3b, v100
	v_mul_f32_e32 v187, 0xbfb8aa3b, v101
	v_mul_f32_e32 v188, 0xbfb8aa3b, v90
	v_mul_f32_e32 v189, 0xbfb8aa3b, v91
	v_mul_f32_e32 v190, 0xbfb8aa3b, v92
	v_mul_f32_e32 v191, 0xbfb8aa3b, v93
	v_mul_f32_e32 v192, 0xbfb8aa3b, v86
	v_mul_f32_e32 v193, 0xbfb8aa3b, v87
	v_mul_f32_e32 v194, 0xbfb8aa3b, v88
	v_mul_f32_e32 v195, 0xbfb8aa3b, v89
	v_mul_f32_e32 v196, 0xbfb8aa3b, v78
	v_mul_f32_e32 v197, 0xbfb8aa3b, v79
	v_mul_f32_e32 v198, 0xbfb8aa3b, v80
	v_mul_f32_e32 v199, 0xbfb8aa3b, v81
	v_mul_f32_e32 v200, 0xbfb8aa3b, v82
	v_mul_f32_e32 v249, 0xbfb8aa3b, v83
	v_mul_f32_e32 v250, 0xbfb8aa3b, v84
	v_mul_f32_e32 v251, 0xbfb8aa3b, v85
	v_mul_f32_e32 v252, 0xbfb8aa3b, v74
	v_exp_f32_e32 v248, v130
	v_exp_f32_e32 v247, v131
	v_exp_f32_e32 v246, v132
	v_exp_f32_e32 v245, v133
	v_exp_f32_e32 v244, v134
	v_exp_f32_e32 v243, v135
	v_exp_f32_e32 v242, v136
	v_exp_f32_e32 v241, v137
	v_exp_f32_e32 v240, v138
	v_exp_f32_e32 v239, v139
	v_exp_f32_e32 v238, v140
	v_exp_f32_e32 v237, v141
	v_exp_f32_e32 v236, v142
	v_exp_f32_e32 v235, v143
	v_exp_f32_e32 v234, v144
	v_exp_f32_e32 v233, v145
	v_exp_f32_e32 v232, v158
	v_exp_f32_e32 v231, v164
	v_exp_f32_e32 v230, v165
	v_exp_f32_e32 v229, v166
	v_exp_f32_e32 v228, v167
	v_exp_f32_e32 v227, v168
	v_exp_f32_e32 v226, v172
	v_exp_f32_e32 v225, v175
	v_exp_f32_e32 v224, v176
	v_exp_f32_e32 v223, v177
	v_exp_f32_e32 v222, v178
	v_exp_f32_e32 v221, v179
	v_exp_f32_e32 v220, v180
	v_exp_f32_e32 v219, v181
	v_exp_f32_e32 v218, v182
	v_exp_f32_e32 v217, v183
	v_exp_f32_e32 v216, v184
	v_exp_f32_e32 v215, v185
	v_exp_f32_e32 v214, v186
	v_exp_f32_e32 v213, v187
	v_exp_f32_e32 v212, v188
	v_exp_f32_e32 v211, v189
	v_exp_f32_e32 v210, v190
	v_exp_f32_e32 v209, v191
	v_exp_f32_e32 v208, v192
	v_exp_f32_e32 v207, v193
	v_exp_f32_e32 v206, v194
	v_exp_f32_e32 v205, v195
	v_exp_f32_e32 v204, v196
	v_exp_f32_e32 v203, v197
	v_exp_f32_e32 v202, v198
	v_exp_f32_e32 v201, v199
	v_exp_f32_e32 v200, v200
	v_exp_f32_e32 v199, v249
	v_exp_f32_e32 v198, v250
	v_exp_f32_e32 v197, v251
	v_exp_f32_e32 v195, v252
	s_mov_b64 s[62:63], -1
	s_cmp_gt_i32 s55, 4
	v_mul_f32_e32 v196, 0xbfb8aa3b, v75
	v_mul_f32_e32 v194, 0xbfb8aa3b, v76
	v_mul_f32_e32 v193, 0xbfb8aa3b, v77
	v_mul_f32_e32 v192, 0xbfb8aa3b, v70
	v_mul_f32_e32 v191, 0xbfb8aa3b, v71
	v_mul_f32_e32 v190, 0xbfb8aa3b, v72
	s_cbranch_scc0 .LBB0_164
	s_lshl_b32 s2, s19, 8
	s_and_b32 s2, s2, 0x100
	s_or_b32 s2, s2, s85
	v_add_u32_e32 v164, s2, v174
	v_ashrrev_i32_e32 v165, 31, v164
	v_lshl_add_u64 v[134:135], v[164:165], 2, s[12:13]
	global_load_dwordx4 v[138:141], v[134:135], off offset:16
	global_load_dwordx4 v[142:145], v[134:135], off
	global_load_dwordx4 v[130:133], v[134:135], off offset:528
	s_nop 0
	global_load_dwordx4 v[134:137], v[134:135], off offset:512
	v_add_f32_e32 v158, 1.0, v248
	v_rcp_f32_e32 v158, v158
	v_add_f32_e32 v172, 1.0, v243
	v_rcp_f32_e32 v172, v172
	v_add_f32_e32 v187, 1.0, v241
	v_rcp_f32_e32 v187, v187
	s_lshl_b32 s2, s18, 8
	s_add_i32 s2, s2, s84
	v_add_u32_e32 v166, s2, v173
	v_ashrrev_i32_e32 v167, 31, v166
	v_lshlrev_b64 v[166:167], 10, v[166:167]
	v_lshl_add_u64 v[166:167], s[22:23], 0, v[166:167]
	v_lshl_add_u64 v[164:165], v[164:165], 1, v[166:167]
	v_add_f32_e32 v166, 1.0, v240
	v_add_f32_e32 v167, 1.0, v239
	v_rcp_f32_e32 v166, v166
	v_rcp_f32_e32 v167, v167
	v_add_f32_e32 v189, 1.0, v217
	v_rcp_f32_e32 v189, v189
	s_mov_b64 s[62:63], 0
	s_waitcnt vmcnt(0)
	v_sub_f32_e32 v175, 1.0, v138
	v_sub_f32_e32 v179, 1.0, v142
	v_fma_f32 v158, v158, v179, v142
	v_log_f32_e32 v168, v158
	v_add_f32_e32 v158, 1.0, v247
	v_rcp_f32_e32 v158, v158
	v_sub_f32_e32 v180, 1.0, v143
	v_sub_f32_e32 v181, 1.0, v144
	v_sub_f32_e32 v178, 1.0, v145
	v_fma_f32 v158, v158, v180, v143
	v_log_f32_e32 v176, v158
	v_add_f32_e32 v158, 1.0, v246
	v_rcp_f32_e32 v158, v158
	v_sub_f32_e32 v177, 1.0, v140
	v_cvt_pk_bf16_f32 v250, v168, v176
	v_add_f32_e32 v176, 1.0, v238
	v_fma_f32 v158, v158, v181, v144
	v_log_f32_e32 v182, v158
	v_add_f32_e32 v158, 1.0, v245
	v_rcp_f32_e32 v158, v158
	v_rcp_f32_e32 v176, v176
	v_sub_f32_e32 v168, 1.0, v136
	v_sub_f32_e32 v249, 1.0, v134
	v_fma_f32 v158, v158, v178, v145
	v_log_f32_e32 v183, v158
	v_add_f32_e32 v158, 1.0, v244
	v_rcp_f32_e32 v158, v158
	v_fma_f32 v176, v176, v168, v136
	v_cvt_pk_bf16_f32 v251, v182, v183
	v_log_f32_e32 v183, v176
	v_fma_f32 v158, v158, v175, v138
	v_log_f32_e32 v184, v158
	v_sub_f32_e32 v158, 1.0, v139
	v_fma_f32 v172, v172, v158, v139
	v_log_f32_e32 v185, v172
	v_add_f32_e32 v172, 1.0, v242
	v_rcp_f32_e32 v172, v172
	v_add_f32_e32 v176, 1.0, v237
	v_rcp_f32_e32 v176, v176
	v_cvt_pk_bf16_f32 v252, v184, v185
	v_fma_f32 v172, v172, v177, v140
	v_log_f32_e32 v186, v172
	v_sub_f32_e32 v172, 1.0, v141
	v_fma_f32 v187, v187, v172, v141
	v_log_f32_e32 v187, v187
	v_add_f32_e32 v182, 1.0, v233
	v_rcp_f32_e32 v182, v182
	v_sub_f32_e32 v254, 1.0, v135
	v_cvt_pk_bf16_f32 v253, v186, v187
	global_store_dwordx4 v[164:165], v[250:253], off nt
	v_fma_f32 v166, v166, v249, v134
	v_fma_f32 v167, v167, v254, v135
	v_sub_f32_e32 v253, 1.0, v137
	v_fma_f32 v176, v176, v253, v137
	v_log_f32_e32 v184, v176
	v_add_f32_e32 v176, 1.0, v236
	v_rcp_f32_e32 v176, v176
	v_sub_f32_e32 v251, 1.0, v130
	v_sub_f32_e32 v250, 1.0, v131
	v_sub_f32_e32 v252, 1.0, v132
	v_fma_f32 v176, v176, v251, v130
	v_log_f32_e32 v185, v176
	v_add_f32_e32 v176, 1.0, v235
	v_rcp_f32_e32 v176, v176
	v_log_f32_e32 v166, v166
	v_log_f32_e32 v167, v167
	v_cvt_pk_bf16_f32 v183, v183, v184
	v_fma_f32 v176, v176, v250, v131
	v_log_f32_e32 v186, v176
	v_add_f32_e32 v176, 1.0, v234
	v_rcp_f32_e32 v176, v176
	v_cvt_pk_bf16_f32 v184, v185, v186
	v_fma_f32 v176, v176, v252, v132
	v_log_f32_e32 v187, v176
	v_sub_f32_e32 v176, 1.0, v133
	v_fma_f32 v182, v182, v176, v133
	v_log_f32_e32 v188, v182
	v_cvt_pk_bf16_f32 v182, v166, v167
	v_add_f32_e32 v166, 1.0, v232
	v_add_f32_e32 v167, 1.0, v231
	v_cvt_pk_bf16_f32 v185, v187, v188
	global_store_dwordx4 v[164:165], v[182:185], off offset:256 nt
	v_rcp_f32_e32 v166, v166
	v_rcp_f32_e32 v167, v167
	v_add_f32_e32 v182, 1.0, v230
	v_rcp_f32_e32 v182, v182
	v_fma_f32 v166, v166, v179, v142
	v_fma_f32 v167, v167, v180, v143
	v_log_f32_e32 v166, v166
	v_fma_f32 v182, v182, v181, v144
	v_log_f32_e32 v183, v182
	v_add_f32_e32 v182, 1.0, v229
	v_rcp_f32_e32 v182, v182
	v_log_f32_e32 v167, v167
	v_fma_f32 v189, v189, v176, v133
	v_log_f32_e32 v189, v189
	v_fma_f32 v182, v182, v178, v145
	v_log_f32_e32 v184, v182
	v_add_f32_e32 v182, 1.0, v228
	v_rcp_f32_e32 v182, v182
	v_cvt_pk_bf16_f32 v183, v183, v184
	v_fma_f32 v182, v182, v175, v138
	v_log_f32_e32 v185, v182
	v_add_f32_e32 v182, 1.0, v227
	v_rcp_f32_e32 v182, v182
	s_nop 0
	v_fma_f32 v182, v182, v158, v139
	v_log_f32_e32 v186, v182
	v_add_f32_e32 v182, 1.0, v226
	v_rcp_f32_e32 v182, v182
	v_cvt_pk_bf16_f32 v184, v185, v186
	v_add_co_u32_e32 v186, vcc, s75, v164
	v_fma_f32 v182, v182, v177, v140
	v_log_f32_e32 v187, v182
	v_add_f32_e32 v182, 1.0, v225
	v_rcp_f32_e32 v182, v182
	s_nop 0
	v_fma_f32 v182, v182, v172, v141
	v_log_f32_e32 v188, v182
	v_cvt_pk_bf16_f32 v182, v166, v167
	v_lshl_add_u64 v[166:167], v[164:165], 0, s[38:39]
	v_cvt_pk_bf16_f32 v185, v187, v188
	v_addc_co_u32_e32 v187, vcc, 0, v165, vcc
	global_store_dwordx4 v[186:187], v[182:185], off nt
	v_add_f32_e32 v186, 1.0, v220
	v_add_f32_e32 v187, 1.0, v219
	v_add_f32_e32 v182, 1.0, v224
	v_add_f32_e32 v183, 1.0, v223
	v_add_f32_e32 v184, 1.0, v222
	v_add_f32_e32 v185, 1.0, v221
	v_add_f32_e32 v188, 1.0, v218
	v_rcp_f32_e32 v182, v182
	v_rcp_f32_e32 v183, v183
	v_rcp_f32_e32 v184, v184
	v_rcp_f32_e32 v185, v185
	v_rcp_f32_e32 v186, v186
	v_rcp_f32_e32 v187, v187
	v_rcp_f32_e32 v188, v188
	v_fma_f32 v182, v182, v249, v134
	v_fma_f32 v183, v183, v254, v135
	v_fma_f32 v184, v184, v168, v136
	v_fma_f32 v185, v185, v253, v137
	v_fma_f32 v186, v186, v251, v130
	v_fma_f32 v187, v187, v250, v131
	v_fma_f32 v188, v188, v252, v132
	v_log_f32_e32 v182, v182
	v_log_f32_e32 v183, v183
	v_log_f32_e32 v184, v184
	v_log_f32_e32 v185, v185
	v_log_f32_e32 v186, v186
	v_log_f32_e32 v187, v187
	v_log_f32_e32 v188, v188
	v_cvt_pk_bf16_f32 v182, v182, v183
	v_cvt_pk_bf16_f32 v183, v184, v185
	v_cvt_pk_bf16_f32 v184, v186, v187
	v_cvt_pk_bf16_f32 v185, v188, v189
	global_store_dwordx4 v[166:167], v[182:185], off offset:256 nt
	v_add_f32_e32 v166, 1.0, v216
	v_add_f32_e32 v167, 1.0, v215
	v_add_f32_e32 v182, 1.0, v214
	v_rcp_f32_e32 v182, v182
	v_rcp_f32_e32 v166, v166
	v_rcp_f32_e32 v167, v167
	v_add_f32_e32 v189, 1.0, v201
	v_fma_f32 v182, v182, v181, v144
	v_log_f32_e32 v183, v182
	v_add_f32_e32 v182, 1.0, v213
	v_rcp_f32_e32 v182, v182
	v_fma_f32 v166, v166, v179, v142
	v_fma_f32 v167, v167, v180, v143
	v_log_f32_e32 v166, v166
	v_fma_f32 v182, v182, v178, v145
	v_log_f32_e32 v184, v182
	v_add_f32_e32 v182, 1.0, v212
	v_rcp_f32_e32 v182, v182
	v_log_f32_e32 v167, v167
	v_cvt_pk_bf16_f32 v183, v183, v184
	v_rcp_f32_e32 v189, v189
	v_fma_f32 v182, v182, v175, v138
	v_log_f32_e32 v185, v182
	v_add_f32_e32 v182, 1.0, v211
	v_rcp_f32_e32 v182, v182
	v_fma_f32 v189, v189, v176, v133
	v_log_f32_e32 v189, v189
	v_fma_f32 v182, v182, v158, v139
	v_log_f32_e32 v186, v182
	v_add_f32_e32 v182, 1.0, v210
	v_rcp_f32_e32 v182, v182
	v_cvt_pk_bf16_f32 v184, v185, v186
	v_add_co_u32_e32 v186, vcc, s92, v164
	v_fma_f32 v182, v182, v177, v140
	v_log_f32_e32 v187, v182
	v_add_f32_e32 v182, 1.0, v209
	v_rcp_f32_e32 v182, v182
	s_nop 0
	v_fma_f32 v182, v182, v172, v141
	v_log_f32_e32 v188, v182
	v_cvt_pk_bf16_f32 v182, v166, v167
	v_lshl_add_u64 v[166:167], v[164:165], 0, s[40:41]
	v_cvt_pk_bf16_f32 v185, v187, v188
	v_addc_co_u32_e32 v187, vcc, 0, v165, vcc
	global_store_dwordx4 v[186:187], v[182:185], off nt
	v_add_f32_e32 v186, 1.0, v204
	v_add_f32_e32 v187, 1.0, v203
	v_add_f32_e32 v182, 1.0, v208
	v_add_f32_e32 v183, 1.0, v207
	v_add_f32_e32 v184, 1.0, v206
	v_add_f32_e32 v185, 1.0, v205
	v_add_f32_e32 v188, 1.0, v202
	v_rcp_f32_e32 v182, v182
	v_rcp_f32_e32 v183, v183
	v_rcp_f32_e32 v184, v184
	v_rcp_f32_e32 v185, v185
	v_rcp_f32_e32 v186, v186
	v_rcp_f32_e32 v187, v187
	v_rcp_f32_e32 v188, v188
	v_fma_f32 v182, v182, v249, v134
	v_fma_f32 v183, v183, v254, v135
	v_fma_f32 v184, v184, v168, v136
	v_fma_f32 v185, v185, v253, v137
	v_fma_f32 v186, v186, v251, v130
	v_fma_f32 v187, v187, v250, v131
	v_fma_f32 v188, v188, v252, v132
	v_log_f32_e32 v182, v182
	v_log_f32_e32 v183, v183
	v_log_f32_e32 v184, v184
	v_log_f32_e32 v185, v185
	v_log_f32_e32 v186, v186
	v_log_f32_e32 v187, v187
	v_log_f32_e32 v188, v188
	v_cvt_pk_bf16_f32 v182, v182, v183
	v_cvt_pk_bf16_f32 v183, v184, v185
	v_cvt_pk_bf16_f32 v184, v186, v187
	v_cvt_pk_bf16_f32 v185, v188, v189
	global_store_dwordx4 v[166:167], v[182:185], off offset:256 nt
	v_add_f32_e32 v166, 1.0, v200
	v_add_f32_e32 v167, 1.0, v199
	v_add_f32_e32 v182, 1.0, v198
	v_rcp_f32_e32 v182, v182
	v_rcp_f32_e32 v166, v166
	v_rcp_f32_e32 v167, v167
	v_mul_f32_e32 v189, 0xbfb8aa3b, v69
	v_fma_f32 v182, v182, v181, v144
	v_log_f32_e32 v183, v182
	v_add_f32_e32 v182, 1.0, v197
	v_rcp_f32_e32 v182, v182
	v_fma_f32 v166, v166, v179, v142
	v_fma_f32 v167, v167, v180, v143
	v_log_f32_e32 v166, v166
	v_fma_f32 v182, v182, v178, v145
	v_log_f32_e32 v184, v182
	v_add_f32_e32 v182, 1.0, v195
	v_rcp_f32_e32 v182, v182
	v_log_f32_e32 v167, v167
	v_cvt_pk_bf16_f32 v183, v183, v184
	v_exp_f32_e32 v189, v189
	v_fma_f32 v182, v182, v175, v138
	v_log_f32_e32 v185, v182
	v_exp_f32_e32 v182, v196
	v_add_f32_e32 v189, 1.0, v189
	v_rcp_f32_e32 v189, v189
	v_add_f32_e32 v182, 1.0, v182
	v_rcp_f32_e32 v182, v182
	v_fma_f32 v189, v189, v176, v133
	v_log_f32_e32 v189, v189
	v_fma_f32 v182, v182, v158, v139
	v_log_f32_e32 v186, v182
	v_exp_f32_e32 v182, v194
	v_cvt_pk_bf16_f32 v184, v185, v186
	v_add_f32_e32 v182, 1.0, v182
	v_rcp_f32_e32 v182, v182
	v_add_co_u32_e32 v186, vcc, s97, v164
	v_fma_f32 v182, v182, v177, v140
	v_log_f32_e32 v187, v182
	v_exp_f32_e32 v182, v193
	s_nop 0
	v_add_f32_e32 v182, 1.0, v182
	v_rcp_f32_e32 v182, v182
	s_nop 0
	v_fma_f32 v182, v182, v172, v141
	v_log_f32_e32 v188, v182
	v_cvt_pk_bf16_f32 v182, v166, v167
	v_lshl_add_u64 v[166:167], v[164:165], 0, s[42:43]
	v_cvt_pk_bf16_f32 v185, v187, v188
	v_addc_co_u32_e32 v187, vcc, 0, v165, vcc
	global_store_dwordx4 v[186:187], v[182:185], off nt
	v_mul_f32_e32 v186, 0xbfb8aa3b, v66
	v_mul_f32_e32 v187, 0xbfb8aa3b, v67
	v_mul_f32_e32 v185, 0xbfb8aa3b, v73
	v_mul_f32_e32 v188, 0xbfb8aa3b, v68
	v_exp_f32_e32 v182, v192
	v_exp_f32_e32 v183, v191
	v_exp_f32_e32 v184, v190
	v_exp_f32_e32 v185, v185
	v_exp_f32_e32 v186, v186
	v_exp_f32_e32 v187, v187
	v_exp_f32_e32 v188, v188
	v_add_f32_e32 v182, 1.0, v182
	v_add_f32_e32 v183, 1.0, v183
	v_add_f32_e32 v184, 1.0, v184
	v_add_f32_e32 v185, 1.0, v185
	v_add_f32_e32 v186, 1.0, v186
	v_add_f32_e32 v187, 1.0, v187
	v_add_f32_e32 v188, 1.0, v188
	v_rcp_f32_e32 v182, v182
	v_rcp_f32_e32 v183, v183
	v_rcp_f32_e32 v184, v184
	v_rcp_f32_e32 v185, v185
	v_rcp_f32_e32 v186, v186
	v_rcp_f32_e32 v187, v187
	v_rcp_f32_e32 v188, v188
	v_fma_f32 v182, v182, v249, v134
	v_fma_f32 v183, v183, v254, v135
	v_fma_f32 v184, v184, v168, v136
	v_fma_f32 v185, v185, v253, v137
	v_fma_f32 v186, v186, v251, v130
	v_fma_f32 v187, v187, v250, v131
	v_fma_f32 v188, v188, v252, v132
	v_log_f32_e32 v182, v182
	v_log_f32_e32 v183, v183
	v_log_f32_e32 v184, v184
	v_log_f32_e32 v185, v185
	v_log_f32_e32 v186, v186
	v_log_f32_e32 v187, v187
	v_log_f32_e32 v188, v188
	v_cvt_pk_bf16_f32 v182, v182, v183
	v_cvt_pk_bf16_f32 v183, v184, v185
	v_cvt_pk_bf16_f32 v184, v186, v187
	v_cvt_pk_bf16_f32 v185, v188, v189
	global_store_dwordx4 v[166:167], v[182:185], off offset:256 nt
	v_mul_f32_e32 v166, 0xbfb8aa3b, v62
	v_mul_f32_e32 v167, 0xbfb8aa3b, v63
	v_mul_f32_e32 v182, 0xbfb8aa3b, v64
	v_exp_f32_e32 v182, v182
	v_exp_f32_e32 v166, v166
	v_exp_f32_e32 v167, v167
	v_mul_f32_e32 v189, 0xbfb8aa3b, v49
	v_add_f32_e32 v182, 1.0, v182
	v_rcp_f32_e32 v182, v182
	v_add_f32_e32 v166, 1.0, v166
	v_add_f32_e32 v167, 1.0, v167
	v_rcp_f32_e32 v166, v166
	v_fma_f32 v182, v182, v181, v144
	v_log_f32_e32 v183, v182
	v_mul_f32_e32 v182, 0xbfb8aa3b, v65
	v_exp_f32_e32 v182, v182
	v_rcp_f32_e32 v167, v167
	v_fma_f32 v166, v166, v179, v142
	v_log_f32_e32 v166, v166
	v_add_f32_e32 v182, 1.0, v182
	v_rcp_f32_e32 v182, v182
	v_fma_f32 v167, v167, v180, v143
	v_log_f32_e32 v167, v167
	v_exp_f32_e32 v189, v189
	v_fma_f32 v182, v182, v178, v145
	v_log_f32_e32 v184, v182
	v_mul_f32_e32 v182, 0xbfb8aa3b, v58
	v_exp_f32_e32 v182, v182
	v_add_f32_e32 v189, 1.0, v189
	v_cvt_pk_bf16_f32 v183, v183, v184
	v_rcp_f32_e32 v189, v189
	v_add_f32_e32 v182, 1.0, v182
	v_rcp_f32_e32 v182, v182
	v_fma_f32 v189, v189, v176, v133
	v_log_f32_e32 v189, v189
	v_fma_f32 v182, v182, v175, v138
	v_log_f32_e32 v185, v182
	v_mul_f32_e32 v182, 0xbfb8aa3b, v59
	v_exp_f32_e32 v182, v182
	s_nop 0
	v_add_f32_e32 v182, 1.0, v182
	v_rcp_f32_e32 v182, v182
	s_nop 0
	v_fma_f32 v182, v182, v158, v139
	v_log_f32_e32 v186, v182
	v_mul_f32_e32 v182, 0xbfb8aa3b, v60
	v_exp_f32_e32 v182, v182
	v_cvt_pk_bf16_f32 v184, v185, v186
	v_add_co_u32_e32 v186, vcc, s66, v164
	v_add_f32_e32 v182, 1.0, v182
	v_rcp_f32_e32 v182, v182
	s_nop 0
	v_fma_f32 v182, v182, v177, v140
	v_log_f32_e32 v187, v182
	v_mul_f32_e32 v182, 0xbfb8aa3b, v61
	v_exp_f32_e32 v182, v182
	s_nop 0
	v_add_f32_e32 v182, 1.0, v182
	v_rcp_f32_e32 v182, v182
	s_nop 0
	v_fma_f32 v182, v182, v172, v141
	v_log_f32_e32 v188, v182
	v_cvt_pk_bf16_f32 v182, v166, v167
	v_lshl_add_u64 v[166:167], v[164:165], 0, s[44:45]
	v_cvt_pk_bf16_f32 v185, v187, v188
	v_addc_co_u32_e32 v187, vcc, 0, v165, vcc
	global_store_dwordx4 v[186:187], v[182:185], off nt
	v_mul_f32_e32 v186, 0xbfb8aa3b, v46
	v_mul_f32_e32 v187, 0xbfb8aa3b, v47
	v_mul_f32_e32 v182, 0xbfb8aa3b, v54
	v_mul_f32_e32 v183, 0xbfb8aa3b, v55
	v_mul_f32_e32 v184, 0xbfb8aa3b, v56
	v_mul_f32_e32 v185, 0xbfb8aa3b, v57
	v_mul_f32_e32 v188, 0xbfb8aa3b, v48
	v_exp_f32_e32 v182, v182
	v_exp_f32_e32 v183, v183
	v_exp_f32_e32 v184, v184
	v_exp_f32_e32 v185, v185
	v_exp_f32_e32 v186, v186
	v_exp_f32_e32 v187, v187
	v_exp_f32_e32 v188, v188
	v_add_f32_e32 v182, 1.0, v182
	v_add_f32_e32 v183, 1.0, v183
	v_add_f32_e32 v184, 1.0, v184
	v_add_f32_e32 v185, 1.0, v185
	v_add_f32_e32 v186, 1.0, v186
	v_add_f32_e32 v187, 1.0, v187
	v_add_f32_e32 v188, 1.0, v188
	v_rcp_f32_e32 v182, v182
	v_rcp_f32_e32 v183, v183
	v_rcp_f32_e32 v184, v184
	v_rcp_f32_e32 v185, v185
	v_rcp_f32_e32 v186, v186
	v_rcp_f32_e32 v187, v187
	v_rcp_f32_e32 v188, v188
	v_fma_f32 v182, v182, v249, v134
	v_fma_f32 v183, v183, v254, v135
	v_fma_f32 v184, v184, v168, v136
	v_fma_f32 v185, v185, v253, v137
	v_fma_f32 v186, v186, v251, v130
	v_fma_f32 v187, v187, v250, v131
	v_fma_f32 v188, v188, v252, v132
	v_log_f32_e32 v182, v182
	v_log_f32_e32 v183, v183
	v_log_f32_e32 v184, v184
	v_log_f32_e32 v185, v185
	v_log_f32_e32 v186, v186
	v_log_f32_e32 v187, v187
	v_log_f32_e32 v188, v188
	v_cvt_pk_bf16_f32 v182, v182, v183
	v_cvt_pk_bf16_f32 v183, v184, v185
	v_cvt_pk_bf16_f32 v184, v186, v187
	v_cvt_pk_bf16_f32 v185, v188, v189
	global_store_dwordx4 v[166:167], v[182:185], off offset:256 nt
	v_mul_f32_e32 v166, 0xbfb8aa3b, v50
	v_mul_f32_e32 v167, 0xbfb8aa3b, v51
	v_mul_f32_e32 v182, 0xbfb8aa3b, v52
	v_exp_f32_e32 v182, v182
	v_exp_f32_e32 v166, v166
	v_exp_f32_e32 v167, v167
	v_mul_f32_e32 v189, 0xbfb8aa3b, v33
	v_add_f32_e32 v182, 1.0, v182
	v_rcp_f32_e32 v182, v182
	v_add_f32_e32 v166, 1.0, v166
	v_add_f32_e32 v167, 1.0, v167
	v_rcp_f32_e32 v166, v166
	v_fma_f32 v182, v182, v181, v144
	v_log_f32_e32 v183, v182
	v_mul_f32_e32 v182, 0xbfb8aa3b, v53
	v_exp_f32_e32 v182, v182
	v_rcp_f32_e32 v167, v167
	v_fma_f32 v166, v166, v179, v142
	v_log_f32_e32 v166, v166
	v_add_f32_e32 v182, 1.0, v182
	v_rcp_f32_e32 v182, v182
	v_fma_f32 v167, v167, v180, v143
	v_log_f32_e32 v167, v167
	v_exp_f32_e32 v189, v189
	v_fma_f32 v182, v182, v178, v145
	v_log_f32_e32 v184, v182
	v_mul_f32_e32 v182, 0xbfb8aa3b, v42
	v_exp_f32_e32 v182, v182
	v_add_f32_e32 v189, 1.0, v189
	v_cvt_pk_bf16_f32 v183, v183, v184
	v_rcp_f32_e32 v189, v189
	v_add_f32_e32 v182, 1.0, v182
	v_rcp_f32_e32 v182, v182
	v_fma_f32 v189, v189, v176, v133
	v_log_f32_e32 v189, v189
	v_fma_f32 v182, v182, v175, v138
	v_log_f32_e32 v185, v182
	v_mul_f32_e32 v182, 0xbfb8aa3b, v43
	v_exp_f32_e32 v182, v182
	s_nop 0
	v_add_f32_e32 v182, 1.0, v182
	v_rcp_f32_e32 v182, v182
	s_nop 0
	v_fma_f32 v182, v182, v158, v139
	v_log_f32_e32 v186, v182
	v_mul_f32_e32 v182, 0xbfb8aa3b, v44
	v_exp_f32_e32 v182, v182
	v_cvt_pk_bf16_f32 v184, v185, v186
	v_add_co_u32_e32 v186, vcc, s53, v164
	v_add_f32_e32 v182, 1.0, v182
	v_rcp_f32_e32 v182, v182
	s_nop 0
	v_fma_f32 v182, v182, v177, v140
	v_log_f32_e32 v187, v182
	v_mul_f32_e32 v182, 0xbfb8aa3b, v45
	v_exp_f32_e32 v182, v182
	s_nop 0
	v_add_f32_e32 v182, 1.0, v182
	v_rcp_f32_e32 v182, v182
	s_nop 0
	v_fma_f32 v182, v182, v172, v141
	v_log_f32_e32 v188, v182
	v_cvt_pk_bf16_f32 v182, v166, v167
	v_lshl_add_u64 v[166:167], v[164:165], 0, s[46:47]
	v_cvt_pk_bf16_f32 v185, v187, v188
	v_addc_co_u32_e32 v187, vcc, 0, v165, vcc
	global_store_dwordx4 v[186:187], v[182:185], off nt
	v_mul_f32_e32 v186, 0xbfb8aa3b, v30
	v_mul_f32_e32 v187, 0xbfb8aa3b, v31
	v_mul_f32_e32 v182, 0xbfb8aa3b, v38
	v_mul_f32_e32 v183, 0xbfb8aa3b, v39
	v_mul_f32_e32 v184, 0xbfb8aa3b, v40
	v_mul_f32_e32 v185, 0xbfb8aa3b, v41
	v_mul_f32_e32 v188, 0xbfb8aa3b, v32
	v_exp_f32_e32 v182, v182
	v_exp_f32_e32 v183, v183
	v_exp_f32_e32 v184, v184
	v_exp_f32_e32 v185, v185
	v_exp_f32_e32 v186, v186
	v_exp_f32_e32 v187, v187
	v_exp_f32_e32 v188, v188
	v_add_f32_e32 v182, 1.0, v182
	v_add_f32_e32 v183, 1.0, v183
	v_add_f32_e32 v184, 1.0, v184
	v_add_f32_e32 v185, 1.0, v185
	v_add_f32_e32 v186, 1.0, v186
	v_add_f32_e32 v187, 1.0, v187
	v_add_f32_e32 v188, 1.0, v188
	v_rcp_f32_e32 v182, v182
	v_rcp_f32_e32 v183, v183
	v_rcp_f32_e32 v184, v184
	v_rcp_f32_e32 v185, v185
	v_rcp_f32_e32 v186, v186
	v_rcp_f32_e32 v187, v187
	v_rcp_f32_e32 v188, v188
	v_fma_f32 v182, v182, v249, v134
	v_fma_f32 v183, v183, v254, v135
	v_fma_f32 v184, v184, v168, v136
	v_fma_f32 v185, v185, v253, v137
	v_fma_f32 v186, v186, v251, v130
	v_fma_f32 v187, v187, v250, v131
	v_fma_f32 v188, v188, v252, v132
	v_log_f32_e32 v182, v182
	v_log_f32_e32 v183, v183
	v_log_f32_e32 v184, v184
	v_log_f32_e32 v185, v185
	v_log_f32_e32 v186, v186
	v_log_f32_e32 v187, v187
	v_log_f32_e32 v188, v188
	v_cvt_pk_bf16_f32 v182, v182, v183
	v_cvt_pk_bf16_f32 v183, v184, v185
	v_cvt_pk_bf16_f32 v184, v186, v187
	v_cvt_pk_bf16_f32 v185, v188, v189
	global_store_dwordx4 v[166:167], v[182:185], off offset:256 nt
	v_mul_f32_e32 v166, 0xbfb8aa3b, v34
	v_mul_f32_e32 v167, 0xbfb8aa3b, v35
	v_mul_f32_e32 v182, 0xbfb8aa3b, v36
	v_exp_f32_e32 v182, v182
	v_exp_f32_e32 v166, v166
	v_exp_f32_e32 v167, v167
	v_mul_f32_e32 v189, 0xbfb8aa3b, v17
	v_add_f32_e32 v182, 1.0, v182
	v_rcp_f32_e32 v182, v182
	v_add_f32_e32 v166, 1.0, v166
	v_add_f32_e32 v167, 1.0, v167
	v_rcp_f32_e32 v166, v166
	v_fma_f32 v182, v182, v181, v144
	v_log_f32_e32 v183, v182
	v_mul_f32_e32 v182, 0xbfb8aa3b, v37
	v_exp_f32_e32 v182, v182
	v_rcp_f32_e32 v167, v167
	v_fma_f32 v166, v166, v179, v142
	v_log_f32_e32 v166, v166
	v_add_f32_e32 v182, 1.0, v182
	v_rcp_f32_e32 v182, v182
	v_fma_f32 v167, v167, v180, v143
	v_log_f32_e32 v167, v167
	v_exp_f32_e32 v189, v189
	v_fma_f32 v182, v182, v178, v145
	v_log_f32_e32 v184, v182
	v_mul_f32_e32 v182, 0xbfb8aa3b, v26
	v_exp_f32_e32 v182, v182
	v_add_f32_e32 v189, 1.0, v189
	v_cvt_pk_bf16_f32 v183, v183, v184
	v_rcp_f32_e32 v189, v189
	v_add_f32_e32 v182, 1.0, v182
	v_rcp_f32_e32 v182, v182
	v_fma_f32 v189, v189, v176, v133
	v_log_f32_e32 v189, v189
	v_fma_f32 v182, v182, v175, v138
	v_log_f32_e32 v185, v182
	v_mul_f32_e32 v182, 0xbfb8aa3b, v27
	v_exp_f32_e32 v182, v182
	s_nop 0
	v_add_f32_e32 v182, 1.0, v182
	v_rcp_f32_e32 v182, v182
	s_nop 0
	v_fma_f32 v182, v182, v158, v139
	v_log_f32_e32 v186, v182
	v_mul_f32_e32 v182, 0xbfb8aa3b, v28
	v_exp_f32_e32 v182, v182
	v_cvt_pk_bf16_f32 v184, v185, v186
	v_add_co_u32_e32 v186, vcc, s68, v164
	v_add_f32_e32 v182, 1.0, v182
	v_rcp_f32_e32 v182, v182
	s_nop 0
	v_fma_f32 v182, v182, v177, v140
	v_log_f32_e32 v187, v182
	v_mul_f32_e32 v182, 0xbfb8aa3b, v29
	v_exp_f32_e32 v182, v182
	s_nop 0
	v_add_f32_e32 v182, 1.0, v182
	v_rcp_f32_e32 v182, v182
	s_nop 0
	v_fma_f32 v182, v182, v172, v141
	v_log_f32_e32 v188, v182
	v_cvt_pk_bf16_f32 v182, v166, v167
	v_lshl_add_u64 v[166:167], v[164:165], 0, s[48:49]
	v_cvt_pk_bf16_f32 v185, v187, v188
	v_addc_co_u32_e32 v187, vcc, 0, v165, vcc
	global_store_dwordx4 v[186:187], v[182:185], off nt
	v_mul_f32_e32 v186, 0xbfb8aa3b, v14
	v_mul_f32_e32 v187, 0xbfb8aa3b, v15
	v_mul_f32_e32 v182, 0xbfb8aa3b, v22
	v_mul_f32_e32 v183, 0xbfb8aa3b, v23
	v_mul_f32_e32 v184, 0xbfb8aa3b, v24
	v_mul_f32_e32 v185, 0xbfb8aa3b, v25
	v_mul_f32_e32 v188, 0xbfb8aa3b, v16
	v_exp_f32_e32 v182, v182
	v_exp_f32_e32 v183, v183
	v_exp_f32_e32 v184, v184
	v_exp_f32_e32 v185, v185
	v_exp_f32_e32 v186, v186
	v_exp_f32_e32 v187, v187
	v_exp_f32_e32 v188, v188
	v_add_f32_e32 v182, 1.0, v182
	v_add_f32_e32 v183, 1.0, v183
	v_add_f32_e32 v184, 1.0, v184
	v_add_f32_e32 v185, 1.0, v185
	v_add_f32_e32 v186, 1.0, v186
	v_add_f32_e32 v187, 1.0, v187
	v_add_f32_e32 v188, 1.0, v188
	v_rcp_f32_e32 v182, v182
	v_rcp_f32_e32 v183, v183
	v_rcp_f32_e32 v184, v184
	v_rcp_f32_e32 v185, v185
	v_rcp_f32_e32 v186, v186
	v_rcp_f32_e32 v187, v187
	v_rcp_f32_e32 v188, v188
	v_fma_f32 v182, v182, v249, v134
	v_fma_f32 v183, v183, v254, v135
	v_fma_f32 v184, v184, v168, v136
	v_fma_f32 v185, v185, v253, v137
	v_fma_f32 v186, v186, v251, v130
	v_fma_f32 v187, v187, v250, v131
	v_fma_f32 v188, v188, v252, v132
	v_log_f32_e32 v182, v182
	v_log_f32_e32 v183, v183
	v_log_f32_e32 v184, v184
	v_log_f32_e32 v185, v185
	v_log_f32_e32 v186, v186
	v_log_f32_e32 v187, v187
	v_log_f32_e32 v188, v188
	v_cvt_pk_bf16_f32 v182, v182, v183
	v_cvt_pk_bf16_f32 v183, v184, v185
	v_cvt_pk_bf16_f32 v184, v186, v187
	v_cvt_pk_bf16_f32 v185, v188, v189
	global_store_dwordx4 v[166:167], v[182:185], off offset:256 nt
	v_mul_f32_e32 v166, 0xbfb8aa3b, v18
	v_exp_f32_e32 v166, v166
	s_nop 0
	v_add_f32_e32 v166, 1.0, v166
	v_rcp_f32_e32 v166, v166
	s_nop 0
	v_fma_f32 v142, v166, v179, v142
	v_mul_f32_e32 v166, 0xbfb8aa3b, v19
	v_exp_f32_e32 v166, v166
	v_log_f32_e32 v142, v142
	v_add_f32_e32 v166, 1.0, v166
	v_rcp_f32_e32 v166, v166
	s_nop 0
	v_fma_f32 v143, v166, v180, v143
	v_mul_f32_e32 v166, 0xbfb8aa3b, v20
	v_exp_f32_e32 v166, v166
	v_log_f32_e32 v143, v143
	v_add_f32_e32 v166, 1.0, v166
	v_rcp_f32_e32 v166, v166
	s_nop 0
	v_fma_f32 v144, v166, v181, v144
	v_mul_f32_e32 v166, 0xbfb8aa3b, v21
	v_exp_f32_e32 v166, v166
	v_log_f32_e32 v144, v144
	v_add_f32_e32 v166, 1.0, v166
	v_rcp_f32_e32 v166, v166
	s_nop 0
	v_fmac_f32_e32 v145, v166, v178
	v_mul_f32_e32 v166, 0xbfb8aa3b, v10
	v_exp_f32_e32 v166, v166
	v_log_f32_e32 v145, v145
	v_add_f32_e32 v166, 1.0, v166
	v_rcp_f32_e32 v166, v166
	s_nop 0
	v_fma_f32 v138, v166, v175, v138
	v_log_f32_e32 v166, v138
	v_mul_f32_e32 v138, 0xbfb8aa3b, v11
	v_exp_f32_e32 v138, v138
	s_nop 0
	v_add_f32_e32 v138, 1.0, v138
	v_rcp_f32_e32 v138, v138
	s_nop 0
	v_fma_f32 v138, v138, v158, v139
	v_log_f32_e32 v158, v138
	v_mul_f32_e32 v138, 0xbfb8aa3b, v12
	v_exp_f32_e32 v138, v138
	v_cvt_pk_bf16_f32 v139, v144, v145
	v_add_co_u32_e32 v144, vcc, s4, v164
	v_add_f32_e32 v138, 1.0, v138
	v_rcp_f32_e32 v138, v138
	v_addc_co_u32_e32 v145, vcc, 0, v165, vcc
	v_fma_f32 v138, v138, v177, v140
	v_log_f32_e32 v167, v138
	v_mul_f32_e32 v138, 0xbfb8aa3b, v13
	v_exp_f32_e32 v138, v138
	v_cvt_pk_bf16_f32 v140, v166, v158
	v_add_f32_e32 v138, 1.0, v138
	v_rcp_f32_e32 v138, v138
	s_nop 0
	v_fmac_f32_e32 v141, v138, v172
	v_log_f32_e32 v141, v141
	v_cvt_pk_bf16_f32 v138, v142, v143
	v_lshl_add_u64 v[142:143], v[164:165], 0, s[50:51]
	v_cvt_pk_bf16_f32 v141, v167, v141
	global_store_dwordx4 v[144:145], v[138:141], off nt
	s_nop 1
	v_mul_f32_e32 v138, 0xbfb8aa3b, v6
	v_exp_f32_e32 v138, v138
	s_nop 0
	v_add_f32_e32 v138, 1.0, v138
	v_rcp_f32_e32 v138, v138
	s_nop 0
	v_fma_f32 v134, v138, v249, v134
	v_mul_f32_e32 v138, 0xbfb8aa3b, v7
	v_exp_f32_e32 v138, v138
	v_log_f32_e32 v134, v134
	v_add_f32_e32 v138, 1.0, v138
	v_rcp_f32_e32 v138, v138
	s_nop 0
	v_fma_f32 v135, v138, v254, v135
	v_mul_f32_e32 v138, 0xbfb8aa3b, v8
	v_exp_f32_e32 v138, v138
	v_log_f32_e32 v135, v135
	v_add_f32_e32 v138, 1.0, v138
	v_rcp_f32_e32 v138, v138
	s_nop 0
	v_fma_f32 v136, v138, v168, v136
	v_mul_f32_e32 v138, 0xbfb8aa3b, v9
	v_exp_f32_e32 v138, v138
	v_log_f32_e32 v136, v136
	v_add_f32_e32 v138, 1.0, v138
	v_rcp_f32_e32 v138, v138
	s_nop 0
	v_fmac_f32_e32 v137, v138, v253
	v_mul_f32_e32 v138, 0xbfb8aa3b, v2
	v_exp_f32_e32 v138, v138
	v_log_f32_e32 v137, v137
	v_add_f32_e32 v138, 1.0, v138
	v_rcp_f32_e32 v138, v138
	s_nop 0
	v_fma_f32 v130, v138, v251, v130
	v_log_f32_e32 v138, v130
	v_mul_f32_e32 v130, 0xbfb8aa3b, v3
	v_exp_f32_e32 v130, v130
	s_nop 0
	v_add_f32_e32 v130, 1.0, v130
	v_rcp_f32_e32 v130, v130
	s_nop 0
	v_fma_f32 v130, v130, v250, v131
	v_log_f32_e32 v139, v130
	v_mul_f32_e32 v130, 0xbfb8aa3b, v4
	v_exp_f32_e32 v130, v130
	v_cvt_pk_bf16_f32 v131, v136, v137
	v_add_f32_e32 v130, 1.0, v130
	v_rcp_f32_e32 v130, v130
	s_nop 0
	v_fma_f32 v130, v130, v252, v132
	v_log_f32_e32 v140, v130
	v_mul_f32_e32 v130, 0xbfb8aa3b, v5
	v_exp_f32_e32 v130, v130
	v_cvt_pk_bf16_f32 v132, v138, v139
	v_add_f32_e32 v130, 1.0, v130
	v_rcp_f32_e32 v130, v130
	s_nop 0
	v_fmac_f32_e32 v133, v130, v176
	v_log_f32_e32 v133, v133
	v_cvt_pk_bf16_f32 v130, v134, v135
	v_cvt_pk_bf16_f32 v133, v140, v133
	global_store_dwordx4 v[142:143], v[130:133], off offset:256 nt
.LBB0_164:
	s_andn2_b64 vcc, exec, s[62:63]
	s_cbranch_vccnz .LBB0_166
	s_lshl_b32 s2, s19, 8
	s_and_b32 s2, s2, 0x100
	s_or_b32 s2, s2, s85
	v_add_u32_e32 v130, s2, v174
	s_lshl_b32 s2, s18, 8
	s_add_i32 s2, s2, s84
	v_add_u32_e32 v132, s2, v173
	v_ashrrev_i32_e32 v133, 31, v132
	v_add_f32_e32 v131, 1.0, v248
	v_lshlrev_b64 v[136:137], 10, v[132:133]
	v_rcp_f32_e32 v132, v131
	v_add_f32_e32 v131, 1.0, v247
	v_rcp_f32_e32 v133, v131
	v_add_f32_e32 v131, 1.0, v246
	v_rcp_f32_e32 v134, v131
	v_add_f32_e32 v131, 1.0, v245
	v_rcp_f32_e32 v135, v131
	v_add_f32_e32 v131, 1.0, v244
	v_rcp_f32_e32 v138, v131
	v_add_f32_e32 v131, 1.0, v243
	v_rcp_f32_e32 v139, v131
	v_add_f32_e32 v131, 1.0, v242
	v_rcp_f32_e32 v140, v131
	v_add_f32_e32 v131, 1.0, v241
	v_rcp_f32_e32 v141, v131
	v_pk_mul_f32 v[132:133], v[126:127], v[132:133]
	v_pk_mul_f32 v[134:135], v[128:129], v[134:135]
	v_pk_mul_f32 v[138:139], v[122:123], v[138:139]
	v_pk_mul_f32 v[140:141], v[124:125], v[140:141]
	v_lshl_add_u64 v[136:137], s[24:25], 0, v[136:137]
	v_ashrrev_i32_e32 v131, 31, v130
	v_cvt_pk_bf16_f32 v132, v132, v133
	v_cvt_pk_bf16_f32 v133, v134, v135
	v_cvt_pk_bf16_f32 v134, v138, v139
	v_cvt_pk_bf16_f32 v135, v140, v141
	v_lshl_add_u64 v[130:131], v[130:131], 1, v[136:137]
	global_store_dwordx4 v[130:131], v[132:135], off nt
	v_add_f32_e32 v136, 1.0, v236
	v_add_f32_e32 v137, 1.0, v235
	v_add_f32_e32 v132, 1.0, v240
	v_add_f32_e32 v133, 1.0, v239
	v_add_f32_e32 v134, 1.0, v238
	v_add_f32_e32 v135, 1.0, v237
	v_add_f32_e32 v138, 1.0, v234
	v_add_f32_e32 v139, 1.0, v233
	v_rcp_f32_e32 v132, v132
	v_rcp_f32_e32 v133, v133
	v_rcp_f32_e32 v134, v134
	v_rcp_f32_e32 v135, v135
	v_rcp_f32_e32 v136, v136
	v_rcp_f32_e32 v137, v137
	v_rcp_f32_e32 v138, v138
	v_rcp_f32_e32 v139, v139
	v_pk_mul_f32 v[132:133], v[118:119], v[132:133]
	v_pk_mul_f32 v[134:135], v[120:121], v[134:135]
	v_pk_mul_f32 v[136:137], v[110:111], v[136:137]
	v_pk_mul_f32 v[138:139], v[112:113], v[138:139]
	v_cvt_pk_bf16_f32 v132, v132, v133
	v_cvt_pk_bf16_f32 v133, v134, v135
	v_cvt_pk_bf16_f32 v134, v136, v137
	v_cvt_pk_bf16_f32 v135, v138, v139
	global_store_dwordx4 v[130:131], v[132:135], off offset:256 nt
	v_add_f32_e32 v138, 1.0, v226
	v_add_f32_e32 v139, 1.0, v225
	v_add_f32_e32 v132, 1.0, v232
	v_add_f32_e32 v133, 1.0, v231
	v_add_f32_e32 v134, 1.0, v230
	v_add_f32_e32 v135, 1.0, v229
	v_rcp_f32_e32 v132, v132
	v_rcp_f32_e32 v133, v133
	v_rcp_f32_e32 v134, v134
	v_rcp_f32_e32 v135, v135
	v_add_f32_e32 v136, 1.0, v228
	v_add_f32_e32 v137, 1.0, v227
	v_rcp_f32_e32 v138, v138
	v_rcp_f32_e32 v139, v139
	v_rcp_f32_e32 v136, v136
	v_rcp_f32_e32 v137, v137
	v_pk_mul_f32 v[132:133], v[114:115], v[132:133]
	v_pk_mul_f32 v[134:135], v[116:117], v[134:135]
	v_pk_mul_f32 v[138:139], v[108:109], v[138:139]
	v_pk_mul_f32 v[136:137], v[106:107], v[136:137]
	v_cvt_pk_bf16_f32 v132, v132, v133
	v_cvt_pk_bf16_f32 v133, v134, v135
	v_cvt_pk_bf16_f32 v135, v138, v139
	v_add_co_u32_e32 v138, vcc, s75, v130
	v_cvt_pk_bf16_f32 v134, v136, v137
	s_nop 0
	v_addc_co_u32_e32 v139, vcc, 0, v131, vcc
	global_store_dwordx4 v[138:139], v[132:135], off nt
	v_add_f32_e32 v138, 1.0, v220
	v_add_f32_e32 v139, 1.0, v219
	v_add_f32_e32 v132, 1.0, v224
	v_add_f32_e32 v133, 1.0, v223
	v_add_f32_e32 v134, 1.0, v222
	v_add_f32_e32 v135, 1.0, v221
	v_add_f32_e32 v140, 1.0, v218
	v_add_f32_e32 v141, 1.0, v217
	v_rcp_f32_e32 v132, v132
	v_rcp_f32_e32 v133, v133
	v_rcp_f32_e32 v134, v134
	v_rcp_f32_e32 v135, v135
	v_rcp_f32_e32 v138, v138
	v_rcp_f32_e32 v139, v139
	v_rcp_f32_e32 v140, v140
	v_rcp_f32_e32 v141, v141
	v_pk_mul_f32 v[132:133], v[102:103], v[132:133]
	v_pk_mul_f32 v[134:135], v[104:105], v[134:135]
	v_pk_mul_f32 v[138:139], v[94:95], v[138:139]
	v_pk_mul_f32 v[140:141], v[96:97], v[140:141]
	v_lshl_add_u64 v[136:137], v[130:131], 0, s[38:39]
	v_cvt_pk_bf16_f32 v132, v132, v133
	v_cvt_pk_bf16_f32 v133, v134, v135
	v_cvt_pk_bf16_f32 v134, v138, v139
	v_cvt_pk_bf16_f32 v135, v140, v141
	global_store_dwordx4 v[136:137], v[132:135], off offset:256 nt
	v_add_f32_e32 v138, 1.0, v210
	v_add_f32_e32 v139, 1.0, v209
	v_add_f32_e32 v132, 1.0, v216
	v_add_f32_e32 v133, 1.0, v215
	v_add_f32_e32 v134, 1.0, v214
	v_add_f32_e32 v135, 1.0, v213
	v_rcp_f32_e32 v132, v132
	v_rcp_f32_e32 v133, v133
	v_rcp_f32_e32 v134, v134
	v_rcp_f32_e32 v135, v135
	v_add_f32_e32 v136, 1.0, v212
	v_add_f32_e32 v137, 1.0, v211
	v_rcp_f32_e32 v138, v138
	v_rcp_f32_e32 v139, v139
	v_rcp_f32_e32 v136, v136
	v_rcp_f32_e32 v137, v137
	v_pk_mul_f32 v[132:133], v[98:99], v[132:133]
	v_pk_mul_f32 v[134:135], v[100:101], v[134:135]
	v_pk_mul_f32 v[138:139], v[92:93], v[138:139]
	v_pk_mul_f32 v[136:137], v[90:91], v[136:137]
	v_cvt_pk_bf16_f32 v132, v132, v133
	v_cvt_pk_bf16_f32 v133, v134, v135
	v_cvt_pk_bf16_f32 v135, v138, v139
	v_add_co_u32_e32 v138, vcc, s92, v130
	v_cvt_pk_bf16_f32 v134, v136, v137
	s_nop 0
	v_addc_co_u32_e32 v139, vcc, 0, v131, vcc
	global_store_dwordx4 v[138:139], v[132:135], off nt
	v_add_f32_e32 v138, 1.0, v204
	v_add_f32_e32 v139, 1.0, v203
	v_add_f32_e32 v132, 1.0, v208
	v_add_f32_e32 v133, 1.0, v207
	v_add_f32_e32 v134, 1.0, v206
	v_add_f32_e32 v135, 1.0, v205
	v_add_f32_e32 v140, 1.0, v202
	v_add_f32_e32 v141, 1.0, v201
	v_rcp_f32_e32 v132, v132
	v_rcp_f32_e32 v133, v133
	v_rcp_f32_e32 v134, v134
	v_rcp_f32_e32 v135, v135
	v_rcp_f32_e32 v138, v138
	v_rcp_f32_e32 v139, v139
	v_rcp_f32_e32 v140, v140
	v_rcp_f32_e32 v141, v141
	v_pk_mul_f32 v[132:133], v[86:87], v[132:133]
	v_pk_mul_f32 v[134:135], v[88:89], v[134:135]
	v_pk_mul_f32 v[138:139], v[78:79], v[138:139]
	v_pk_mul_f32 v[140:141], v[80:81], v[140:141]
	v_lshl_add_u64 v[136:137], v[130:131], 0, s[40:41]
	v_cvt_pk_bf16_f32 v132, v132, v133
	v_cvt_pk_bf16_f32 v133, v134, v135
	v_cvt_pk_bf16_f32 v134, v138, v139
	v_cvt_pk_bf16_f32 v135, v140, v141
	v_exp_f32_e32 v138, v194
	v_exp_f32_e32 v139, v193
	global_store_dwordx4 v[136:137], v[132:135], off offset:256 nt
	v_exp_f32_e32 v137, v196
	v_add_f32_e32 v138, 1.0, v138
	v_add_f32_e32 v132, 1.0, v200
	v_add_f32_e32 v133, 1.0, v199
	v_add_f32_e32 v134, 1.0, v198
	v_add_f32_e32 v135, 1.0, v197
	v_add_f32_e32 v139, 1.0, v139
	v_rcp_f32_e32 v132, v132
	v_rcp_f32_e32 v133, v133
	v_rcp_f32_e32 v134, v134
	v_rcp_f32_e32 v135, v135
	v_add_f32_e32 v136, 1.0, v195
	v_add_f32_e32 v137, 1.0, v137
	v_rcp_f32_e32 v138, v138
	v_rcp_f32_e32 v139, v139
	v_rcp_f32_e32 v136, v136
	v_rcp_f32_e32 v137, v137
	v_pk_mul_f32 v[132:133], v[82:83], v[132:133]
	v_pk_mul_f32 v[134:135], v[84:85], v[134:135]
	v_pk_mul_f32 v[138:139], v[76:77], v[138:139]
	v_pk_mul_f32 v[136:137], v[74:75], v[136:137]
	v_cvt_pk_bf16_f32 v132, v132, v133
	v_cvt_pk_bf16_f32 v133, v134, v135
	v_cvt_pk_bf16_f32 v135, v138, v139
	v_add_co_u32_e32 v138, vcc, s97, v130
	v_cvt_pk_bf16_f32 v134, v136, v137
	v_exp_f32_e32 v140, v192
	v_addc_co_u32_e32 v139, vcc, 0, v131, vcc
	global_store_dwordx4 v[138:139], v[132:135], off nt
	v_mul_f32_e32 v138, 0xbfb8aa3b, v66
	v_mul_f32_e32 v139, 0xbfb8aa3b, v67
	v_mul_f32_e32 v135, 0xbfb8aa3b, v73
	v_exp_f32_e32 v133, v191
	v_exp_f32_e32 v134, v190
	v_exp_f32_e32 v135, v135
	v_exp_f32_e32 v138, v138
	v_exp_f32_e32 v139, v139
	v_add_f32_e32 v132, 1.0, v140
	v_mul_f32_e32 v140, 0xbfb8aa3b, v68
	v_mul_f32_e32 v141, 0xbfb8aa3b, v69
	v_exp_f32_e32 v140, v140
	v_exp_f32_e32 v141, v141
	v_add_f32_e32 v133, 1.0, v133
	v_add_f32_e32 v134, 1.0, v134
	v_add_f32_e32 v135, 1.0, v135
	v_rcp_f32_e32 v132, v132
	v_rcp_f32_e32 v133, v133
	v_rcp_f32_e32 v134, v134
	v_rcp_f32_e32 v135, v135
	v_add_f32_e32 v138, 1.0, v138
	v_add_f32_e32 v139, 1.0, v139
	v_rcp_f32_e32 v138, v138
	v_rcp_f32_e32 v139, v139
	v_add_f32_e32 v140, 1.0, v140
	v_add_f32_e32 v141, 1.0, v141
	v_rcp_f32_e32 v140, v140
	v_rcp_f32_e32 v141, v141
	v_pk_mul_f32 v[132:133], v[70:71], v[132:133]
	v_pk_mul_f32 v[134:135], v[72:73], v[134:135]
	v_pk_mul_f32 v[138:139], v[66:67], v[138:139]
	v_cvt_pk_bf16_f32 v132, v132, v133
	v_cvt_pk_bf16_f32 v133, v134, v135
	v_mul_f32_e32 v135, 0xbfb8aa3b, v62
	v_cvt_pk_bf16_f32 v134, v138, v139
	v_exp_f32_e32 v138, v135
	v_pk_mul_f32 v[140:141], v[68:69], v[140:141]
	v_lshl_add_u64 v[136:137], v[130:131], 0, s[42:43]
	v_cvt_pk_bf16_f32 v135, v140, v141
	global_store_dwordx4 v[136:137], v[132:135], off offset:256 nt
	v_mul_f32_e32 v139, 0xbfb8aa3b, v61
	v_exp_f32_e32 v139, v139
	v_mul_f32_e32 v132, 0xbfb8aa3b, v63
	v_exp_f32_e32 v133, v132
	v_add_f32_e32 v132, 1.0, v138
	v_mul_f32_e32 v134, 0xbfb8aa3b, v64
	v_mul_f32_e32 v135, 0xbfb8aa3b, v65
	v_mul_f32_e32 v138, 0xbfb8aa3b, v60
	v_exp_f32_e32 v134, v134
	v_exp_f32_e32 v135, v135
	v_exp_f32_e32 v138, v138
	v_mul_f32_e32 v136, 0xbfb8aa3b, v58
	v_mul_f32_e32 v137, 0xbfb8aa3b, v59
	v_exp_f32_e32 v136, v136
	v_exp_f32_e32 v137, v137
	v_add_f32_e32 v133, 1.0, v133
	v_add_f32_e32 v134, 1.0, v134
	v_add_f32_e32 v135, 1.0, v135
	v_add_f32_e32 v138, 1.0, v138
	v_add_f32_e32 v139, 1.0, v139
	v_rcp_f32_e32 v132, v132
	v_rcp_f32_e32 v133, v133
	v_rcp_f32_e32 v134, v134
	v_rcp_f32_e32 v135, v135
	v_rcp_f32_e32 v138, v138
	v_rcp_f32_e32 v139, v139
	v_add_f32_e32 v136, 1.0, v136
	v_add_f32_e32 v137, 1.0, v137
	v_rcp_f32_e32 v136, v136
	v_rcp_f32_e32 v137, v137
	v_pk_mul_f32 v[132:133], v[62:63], v[132:133]
	v_pk_mul_f32 v[134:135], v[64:65], v[134:135]
	v_pk_mul_f32 v[138:139], v[60:61], v[138:139]
	v_cvt_pk_bf16_f32 v132, v132, v133
	v_cvt_pk_bf16_f32 v133, v134, v135
	v_cvt_pk_bf16_f32 v135, v138, v139
	v_mul_f32_e32 v138, 0xbfb8aa3b, v54
	v_pk_mul_f32 v[136:137], v[58:59], v[136:137]
	v_exp_f32_e32 v140, v138
	v_add_co_u32_e32 v138, vcc, s66, v130
	v_cvt_pk_bf16_f32 v134, v136, v137
	s_nop 0
	v_addc_co_u32_e32 v139, vcc, 0, v131, vcc
	v_mul_f32_e32 v141, 0xbfb8aa3b, v55
	v_exp_f32_e32 v141, v141
	global_store_dwordx4 v[138:139], v[132:135], off nt
	v_mul_f32_e32 v138, 0xbfb8aa3b, v46
	v_mul_f32_e32 v139, 0xbfb8aa3b, v47
	v_mul_f32_e32 v134, 0xbfb8aa3b, v56
	v_mul_f32_e32 v135, 0xbfb8aa3b, v57
	v_exp_f32_e32 v134, v134
	v_exp_f32_e32 v135, v135
	v_exp_f32_e32 v138, v138
	v_exp_f32_e32 v139, v139
	v_add_f32_e32 v132, 1.0, v140
	v_add_f32_e32 v133, 1.0, v141
	v_mul_f32_e32 v140, 0xbfb8aa3b, v48
	v_mul_f32_e32 v141, 0xbfb8aa3b, v49
	v_add_f32_e32 v134, 1.0, v134
	v_add_f32_e32 v135, 1.0, v135
	v_add_f32_e32 v138, 1.0, v138
	v_add_f32_e32 v139, 1.0, v139
	v_exp_f32_e32 v140, v140
	v_exp_f32_e32 v141, v141
	v_rcp_f32_e32 v132, v132
	v_rcp_f32_e32 v133, v133
	v_rcp_f32_e32 v134, v134
	v_rcp_f32_e32 v135, v135
	v_rcp_f32_e32 v138, v138
	v_rcp_f32_e32 v139, v139
	v_add_f32_e32 v140, 1.0, v140
	v_add_f32_e32 v141, 1.0, v141
	v_rcp_f32_e32 v140, v140
	v_rcp_f32_e32 v141, v141
	v_pk_mul_f32 v[132:133], v[54:55], v[132:133]
	v_pk_mul_f32 v[134:135], v[56:57], v[134:135]
	v_pk_mul_f32 v[138:139], v[46:47], v[138:139]
	v_cvt_pk_bf16_f32 v132, v132, v133
	v_cvt_pk_bf16_f32 v133, v134, v135
	v_cvt_pk_bf16_f32 v134, v138, v139
	v_mul_f32_e32 v138, 0xbfb8aa3b, v50
	v_mul_f32_e32 v139, 0xbfb8aa3b, v51
	v_exp_f32_e32 v138, v138
	v_exp_f32_e32 v139, v139
	v_pk_mul_f32 v[140:141], v[48:49], v[140:141]
	v_lshl_add_u64 v[136:137], v[130:131], 0, s[44:45]
	v_cvt_pk_bf16_f32 v135, v140, v141
	global_store_dwordx4 v[136:137], v[132:135], off offset:256 nt
	v_mul_f32_e32 v136, 0xbfb8aa3b, v42
	v_mul_f32_e32 v137, 0xbfb8aa3b, v43
	v_add_f32_e32 v132, 1.0, v138
	v_add_f32_e32 v133, 1.0, v139
	v_mul_f32_e32 v134, 0xbfb8aa3b, v52
	v_mul_f32_e32 v135, 0xbfb8aa3b, v53
	v_mul_f32_e32 v138, 0xbfb8aa3b, v44
	v_mul_f32_e32 v139, 0xbfb8aa3b, v45
	v_exp_f32_e32 v134, v134
	v_exp_f32_e32 v135, v135
	v_exp_f32_e32 v138, v138
	v_exp_f32_e32 v139, v139
	v_exp_f32_e32 v136, v136
	v_exp_f32_e32 v137, v137
	v_add_f32_e32 v134, 1.0, v134
	v_add_f32_e32 v135, 1.0, v135
	v_add_f32_e32 v138, 1.0, v138
	v_add_f32_e32 v139, 1.0, v139
	v_rcp_f32_e32 v132, v132
	v_rcp_f32_e32 v133, v133
	v_rcp_f32_e32 v134, v134
	v_rcp_f32_e32 v135, v135
	v_add_f32_e32 v136, 1.0, v136
	v_add_f32_e32 v137, 1.0, v137
	v_rcp_f32_e32 v138, v138
	v_rcp_f32_e32 v139, v139
	v_rcp_f32_e32 v136, v136
	v_rcp_f32_e32 v137, v137
	v_pk_mul_f32 v[132:133], v[50:51], v[132:133]
	v_pk_mul_f32 v[134:135], v[52:53], v[134:135]
	v_pk_mul_f32 v[138:139], v[44:45], v[138:139]
	v_pk_mul_f32 v[136:137], v[42:43], v[136:137]
	v_cvt_pk_bf16_f32 v132, v132, v133
	v_cvt_pk_bf16_f32 v133, v134, v135
	v_cvt_pk_bf16_f32 v135, v138, v139
	v_add_co_u32_e32 v138, vcc, s53, v130
	v_cvt_pk_bf16_f32 v134, v136, v137
	s_nop 0
	v_addc_co_u32_e32 v139, vcc, 0, v131, vcc
	v_mul_f32_e32 v140, 0xbfb8aa3b, v38
	v_mul_f32_e32 v141, 0xbfb8aa3b, v39
	v_exp_f32_e32 v140, v140
	v_exp_f32_e32 v141, v141
	global_store_dwordx4 v[138:139], v[132:135], off nt
	v_mul_f32_e32 v138, 0xbfb8aa3b, v30
	v_mul_f32_e32 v139, 0xbfb8aa3b, v31
	v_mul_f32_e32 v134, 0xbfb8aa3b, v40
	v_mul_f32_e32 v135, 0xbfb8aa3b, v41
	v_exp_f32_e32 v134, v134
	v_exp_f32_e32 v135, v135
	v_exp_f32_e32 v138, v138
	v_exp_f32_e32 v139, v139
	v_add_f32_e32 v132, 1.0, v140
	v_add_f32_e32 v133, 1.0, v141
	v_mul_f32_e32 v140, 0xbfb8aa3b, v32
	v_mul_f32_e32 v141, 0xbfb8aa3b, v33
	v_add_f32_e32 v134, 1.0, v134
	v_add_f32_e32 v135, 1.0, v135
	v_add_f32_e32 v138, 1.0, v138
	v_add_f32_e32 v139, 1.0, v139
	v_exp_f32_e32 v140, v140
	v_exp_f32_e32 v141, v141
	v_rcp_f32_e32 v132, v132
	v_rcp_f32_e32 v133, v133
	v_rcp_f32_e32 v134, v134
	v_rcp_f32_e32 v135, v135
	v_rcp_f32_e32 v138, v138
	v_rcp_f32_e32 v139, v139
	v_add_f32_e32 v140, 1.0, v140
	v_add_f32_e32 v141, 1.0, v141
	v_rcp_f32_e32 v140, v140
	v_rcp_f32_e32 v141, v141
	v_pk_mul_f32 v[132:133], v[38:39], v[132:133]
	v_pk_mul_f32 v[134:135], v[40:41], v[134:135]
	v_pk_mul_f32 v[138:139], v[30:31], v[138:139]
	v_cvt_pk_bf16_f32 v132, v132, v133
	v_cvt_pk_bf16_f32 v133, v134, v135
	v_cvt_pk_bf16_f32 v134, v138, v139
	v_mul_f32_e32 v138, 0xbfb8aa3b, v34
	v_mul_f32_e32 v139, 0xbfb8aa3b, v35
	v_exp_f32_e32 v138, v138
	v_exp_f32_e32 v139, v139
	v_pk_mul_f32 v[140:141], v[32:33], v[140:141]
	v_lshl_add_u64 v[136:137], v[130:131], 0, s[46:47]
	v_cvt_pk_bf16_f32 v135, v140, v141
	global_store_dwordx4 v[136:137], v[132:135], off offset:256 nt
	v_mul_f32_e32 v136, 0xbfb8aa3b, v26
	v_mul_f32_e32 v137, 0xbfb8aa3b, v27
	v_add_f32_e32 v132, 1.0, v138
	v_add_f32_e32 v133, 1.0, v139
	v_mul_f32_e32 v134, 0xbfb8aa3b, v36
	v_mul_f32_e32 v135, 0xbfb8aa3b, v37
	v_mul_f32_e32 v138, 0xbfb8aa3b, v28
	v_mul_f32_e32 v139, 0xbfb8aa3b, v29
	v_exp_f32_e32 v134, v134
	v_exp_f32_e32 v135, v135
	v_exp_f32_e32 v138, v138
	v_exp_f32_e32 v139, v139
	v_exp_f32_e32 v136, v136
	v_exp_f32_e32 v137, v137
	v_add_f32_e32 v134, 1.0, v134
	v_add_f32_e32 v135, 1.0, v135
	v_add_f32_e32 v138, 1.0, v138
	v_add_f32_e32 v139, 1.0, v139
	v_rcp_f32_e32 v132, v132
	v_rcp_f32_e32 v133, v133
	v_rcp_f32_e32 v134, v134
	v_rcp_f32_e32 v135, v135
	v_add_f32_e32 v136, 1.0, v136
	v_add_f32_e32 v137, 1.0, v137
	v_rcp_f32_e32 v138, v138
	v_rcp_f32_e32 v139, v139
	v_rcp_f32_e32 v136, v136
	v_rcp_f32_e32 v137, v137
	v_pk_mul_f32 v[132:133], v[34:35], v[132:133]
	v_pk_mul_f32 v[134:135], v[36:37], v[134:135]
	v_pk_mul_f32 v[138:139], v[28:29], v[138:139]
	v_pk_mul_f32 v[136:137], v[26:27], v[136:137]
	v_cvt_pk_bf16_f32 v132, v132, v133
	v_cvt_pk_bf16_f32 v133, v134, v135
	v_cvt_pk_bf16_f32 v135, v138, v139
	v_add_co_u32_e32 v138, vcc, s68, v130
	v_cvt_pk_bf16_f32 v134, v136, v137
	s_nop 0
	v_addc_co_u32_e32 v139, vcc, 0, v131, vcc
	v_mul_f32_e32 v140, 0xbfb8aa3b, v22
	v_mul_f32_e32 v141, 0xbfb8aa3b, v23
	v_exp_f32_e32 v140, v140
	v_exp_f32_e32 v141, v141
	global_store_dwordx4 v[138:139], v[132:135], off nt
	v_mul_f32_e32 v138, 0xbfb8aa3b, v14
	v_mul_f32_e32 v139, 0xbfb8aa3b, v15
	v_mul_f32_e32 v134, 0xbfb8aa3b, v24
	v_mul_f32_e32 v135, 0xbfb8aa3b, v25
	v_exp_f32_e32 v134, v134
	v_exp_f32_e32 v135, v135
	v_exp_f32_e32 v138, v138
	v_exp_f32_e32 v139, v139
	v_add_f32_e32 v132, 1.0, v140
	v_add_f32_e32 v133, 1.0, v141
	v_mul_f32_e32 v140, 0xbfb8aa3b, v16
	v_mul_f32_e32 v141, 0xbfb8aa3b, v17
	v_add_f32_e32 v134, 1.0, v134
	v_add_f32_e32 v135, 1.0, v135
	v_add_f32_e32 v138, 1.0, v138
	v_add_f32_e32 v139, 1.0, v139
	v_exp_f32_e32 v140, v140
	v_exp_f32_e32 v141, v141
	v_rcp_f32_e32 v132, v132
	v_rcp_f32_e32 v133, v133
	v_rcp_f32_e32 v134, v134
	v_rcp_f32_e32 v135, v135
	v_rcp_f32_e32 v138, v138
	v_rcp_f32_e32 v139, v139
	v_add_f32_e32 v140, 1.0, v140
	v_add_f32_e32 v141, 1.0, v141
	v_rcp_f32_e32 v140, v140
	v_rcp_f32_e32 v141, v141
	v_pk_mul_f32 v[132:133], v[22:23], v[132:133]
	v_pk_mul_f32 v[134:135], v[24:25], v[134:135]
	v_pk_mul_f32 v[138:139], v[14:15], v[138:139]
	v_cvt_pk_bf16_f32 v132, v132, v133
	v_cvt_pk_bf16_f32 v133, v134, v135
	v_cvt_pk_bf16_f32 v134, v138, v139
	v_mul_f32_e32 v138, 0xbfb8aa3b, v18
	v_mul_f32_e32 v139, 0xbfb8aa3b, v19
	v_exp_f32_e32 v138, v138
	v_exp_f32_e32 v139, v139
	v_pk_mul_f32 v[140:141], v[16:17], v[140:141]
	v_lshl_add_u64 v[136:137], v[130:131], 0, s[48:49]
	v_cvt_pk_bf16_f32 v135, v140, v141
	global_store_dwordx4 v[136:137], v[132:135], off offset:256 nt
	v_mul_f32_e32 v136, 0xbfb8aa3b, v10
	v_mul_f32_e32 v137, 0xbfb8aa3b, v11
	v_add_f32_e32 v132, 1.0, v138
	v_add_f32_e32 v133, 1.0, v139
	v_mul_f32_e32 v134, 0xbfb8aa3b, v20
	v_mul_f32_e32 v135, 0xbfb8aa3b, v21
	v_mul_f32_e32 v138, 0xbfb8aa3b, v12
	v_mul_f32_e32 v139, 0xbfb8aa3b, v13
	v_exp_f32_e32 v134, v134
	v_exp_f32_e32 v135, v135
	v_exp_f32_e32 v138, v138
	v_exp_f32_e32 v139, v139
	v_exp_f32_e32 v136, v136
	v_exp_f32_e32 v137, v137
	v_add_f32_e32 v134, 1.0, v134
	v_add_f32_e32 v135, 1.0, v135
	v_add_f32_e32 v138, 1.0, v138
	v_add_f32_e32 v139, 1.0, v139
	v_rcp_f32_e32 v132, v132
	v_rcp_f32_e32 v133, v133
	v_rcp_f32_e32 v134, v134
	v_rcp_f32_e32 v135, v135
	v_rcp_f32_e32 v138, v138
	v_rcp_f32_e32 v139, v139
	v_add_f32_e32 v136, 1.0, v136
	v_add_f32_e32 v137, 1.0, v137
	v_rcp_f32_e32 v136, v136
	v_rcp_f32_e32 v137, v137
	v_pk_mul_f32 v[132:133], v[18:19], v[132:133]
	v_pk_mul_f32 v[134:135], v[20:21], v[134:135]
	v_pk_mul_f32 v[138:139], v[12:13], v[138:139]
	v_cvt_pk_bf16_f32 v132, v132, v133
	v_cvt_pk_bf16_f32 v133, v134, v135
	v_cvt_pk_bf16_f32 v135, v138, v139
	v_mul_f32_e32 v138, 0xbfb8aa3b, v6
	v_mul_f32_e32 v139, 0xbfb8aa3b, v7
	v_exp_f32_e32 v138, v138
	v_exp_f32_e32 v139, v139
	v_pk_mul_f32 v[136:137], v[10:11], v[136:137]
	s_nop 0
	v_cvt_pk_bf16_f32 v134, v136, v137
	v_lshl_add_u64 v[136:137], v[130:131], 0, s[50:51]
	v_add_co_u32_e32 v130, vcc, s4, v130
	s_nop 1
	v_addc_co_u32_e32 v131, vcc, 0, v131, vcc
	global_store_dwordx4 v[130:131], v[132:135], off nt
	v_add_f32_e32 v130, 1.0, v138
	v_add_f32_e32 v131, 1.0, v139
	v_mul_f32_e32 v132, 0xbfb8aa3b, v8
	v_mul_f32_e32 v133, 0xbfb8aa3b, v9
	v_mul_f32_e32 v134, 0xbfb8aa3b, v2
	v_mul_f32_e32 v135, 0xbfb8aa3b, v3
	v_mul_f32_e32 v138, 0xbfb8aa3b, v4
	v_mul_f32_e32 v139, 0xbfb8aa3b, v5
	v_exp_f32_e32 v132, v132
	v_exp_f32_e32 v133, v133
	v_exp_f32_e32 v134, v134
	v_exp_f32_e32 v135, v135
	v_exp_f32_e32 v138, v138
	v_exp_f32_e32 v139, v139
	v_add_f32_e32 v132, 1.0, v132
	v_add_f32_e32 v133, 1.0, v133
	v_add_f32_e32 v134, 1.0, v134
	v_add_f32_e32 v135, 1.0, v135
	v_add_f32_e32 v138, 1.0, v138
	v_add_f32_e32 v139, 1.0, v139
	v_rcp_f32_e32 v130, v130
	v_rcp_f32_e32 v131, v131
	v_rcp_f32_e32 v132, v132
	v_rcp_f32_e32 v133, v133
	v_rcp_f32_e32 v134, v134
	v_rcp_f32_e32 v135, v135
	v_rcp_f32_e32 v138, v138
	v_rcp_f32_e32 v139, v139
	v_pk_mul_f32 v[130:131], v[6:7], v[130:131]
	v_pk_mul_f32 v[132:133], v[8:9], v[132:133]
	v_pk_mul_f32 v[134:135], v[2:3], v[134:135]
	v_pk_mul_f32 v[138:139], v[4:5], v[138:139]
	v_cvt_pk_bf16_f32 v130, v130, v131
	v_cvt_pk_bf16_f32 v131, v132, v133
	v_cvt_pk_bf16_f32 v132, v134, v135
	v_cvt_pk_bf16_f32 v133, v138, v139
	global_store_dwordx4 v[136:137], v[130:133], off offset:256 nt

.LBB0_167:
	s_and_b64 vcc, exec, s[62:63]
	s_cbranch_vccz .LBB0_179
	s_cmp_gt_i32 s55, 1
	s_mov_b64 s[60:61], -1
	s_cbranch_scc0 .LBB0_174
	s_cmp_gt_i32 s55, 2
	s_cbranch_scc0 .LBB0_171
	s_lshl_b32 s2, s19, 8
	s_and_b32 s2, s2, 0x100
	s_or_b32 s2, s2, s85
	v_add_u32_e32 v134, s2, v174
	s_lshl_b32 s2, s18, 8
	s_add_i32 s2, s2, s84
	v_add_u32_e32 v130, s2, v173
	v_ashrrev_i32_e32 v131, 31, v130
	v_lshlrev_b64 v[136:137], 10, v[130:131]
	v_lshl_add_u64 v[136:137], s[26:27], 0, v[136:137]
	v_ashrrev_i32_e32 v135, 31, v134
	v_cvt_pk_bf16_f32 v130, v126, v127
	v_cvt_pk_bf16_f32 v131, v128, v129
	v_cvt_pk_bf16_f32 v132, v122, v123
	v_cvt_pk_bf16_f32 v133, v124, v125
	v_lshl_add_u64 v[134:135], v[134:135], 1, v[136:137]
	global_store_dwordx4 v[134:135], v[130:133], off nt
	v_add_co_u32_e32 v138, vcc, s75, v134
	s_nop 0
	v_cvt_pk_bf16_f32 v130, v118, v119
	v_cvt_pk_bf16_f32 v131, v120, v121
	v_cvt_pk_bf16_f32 v132, v110, v111
	v_cvt_pk_bf16_f32 v133, v112, v113
	global_store_dwordx4 v[134:135], v[130:133], off offset:256 nt
	v_addc_co_u32_e32 v139, vcc, 0, v135, vcc
	s_nop 0
	v_cvt_pk_bf16_f32 v130, v114, v115
	v_cvt_pk_bf16_f32 v131, v116, v117
	v_cvt_pk_bf16_f32 v132, v106, v107
	v_cvt_pk_bf16_f32 v133, v108, v109
	v_lshl_add_u64 v[136:137], v[134:135], 0, s[38:39]
	global_store_dwordx4 v[138:139], v[130:133], off nt
	v_add_co_u32_e32 v138, vcc, s92, v134
	s_nop 0
	v_cvt_pk_bf16_f32 v130, v102, v103
	v_cvt_pk_bf16_f32 v131, v104, v105
	v_cvt_pk_bf16_f32 v132, v94, v95
	v_cvt_pk_bf16_f32 v133, v96, v97
	global_store_dwordx4 v[136:137], v[130:133], off offset:256 nt
	v_addc_co_u32_e32 v139, vcc, 0, v135, vcc
	s_nop 0
	v_cvt_pk_bf16_f32 v130, v98, v99
	v_cvt_pk_bf16_f32 v131, v100, v101
	v_cvt_pk_bf16_f32 v132, v90, v91
	v_cvt_pk_bf16_f32 v133, v92, v93
	v_lshl_add_u64 v[136:137], v[134:135], 0, s[40:41]
	global_store_dwordx4 v[138:139], v[130:133], off nt
	v_add_co_u32_e32 v138, vcc, s97, v134
	s_nop 0
	v_cvt_pk_bf16_f32 v130, v86, v87
	v_cvt_pk_bf16_f32 v131, v88, v89
	v_cvt_pk_bf16_f32 v132, v78, v79
	v_cvt_pk_bf16_f32 v133, v80, v81
	global_store_dwordx4 v[136:137], v[130:133], off offset:256 nt
	v_addc_co_u32_e32 v139, vcc, 0, v135, vcc
	s_nop 0
	v_cvt_pk_bf16_f32 v130, v82, v83
	v_cvt_pk_bf16_f32 v131, v84, v85
	v_cvt_pk_bf16_f32 v132, v74, v75
	v_cvt_pk_bf16_f32 v133, v76, v77
	v_lshl_add_u64 v[136:137], v[134:135], 0, s[42:43]
	global_store_dwordx4 v[138:139], v[130:133], off nt
	v_add_co_u32_e32 v138, vcc, s66, v134
	s_nop 0
	v_cvt_pk_bf16_f32 v130, v70, v71
	v_cvt_pk_bf16_f32 v131, v72, v73
	v_cvt_pk_bf16_f32 v132, v66, v67
	v_cvt_pk_bf16_f32 v133, v68, v69
	global_store_dwordx4 v[136:137], v[130:133], off offset:256 nt
	v_addc_co_u32_e32 v139, vcc, 0, v135, vcc
	s_nop 0
	v_cvt_pk_bf16_f32 v130, v62, v63
	v_cvt_pk_bf16_f32 v131, v64, v65
	v_cvt_pk_bf16_f32 v132, v58, v59
	v_cvt_pk_bf16_f32 v133, v60, v61
	v_lshl_add_u64 v[136:137], v[134:135], 0, s[44:45]
	global_store_dwordx4 v[138:139], v[130:133], off nt
	v_add_co_u32_e32 v138, vcc, s53, v134
	s_nop 0
	v_cvt_pk_bf16_f32 v130, v54, v55
	v_cvt_pk_bf16_f32 v131, v56, v57
	v_cvt_pk_bf16_f32 v132, v46, v47
	v_cvt_pk_bf16_f32 v133, v48, v49
	global_store_dwordx4 v[136:137], v[130:133], off offset:256 nt
	v_addc_co_u32_e32 v139, vcc, 0, v135, vcc
	s_nop 0
	v_cvt_pk_bf16_f32 v130, v50, v51
	v_cvt_pk_bf16_f32 v131, v52, v53
	v_cvt_pk_bf16_f32 v132, v42, v43
	v_cvt_pk_bf16_f32 v133, v44, v45
	v_lshl_add_u64 v[136:137], v[134:135], 0, s[46:47]
	global_store_dwordx4 v[138:139], v[130:133], off nt
	v_add_co_u32_e32 v138, vcc, s68, v134
	s_nop 0
	v_cvt_pk_bf16_f32 v130, v38, v39
	v_cvt_pk_bf16_f32 v131, v40, v41
	v_cvt_pk_bf16_f32 v132, v30, v31
	v_cvt_pk_bf16_f32 v133, v32, v33
	global_store_dwordx4 v[136:137], v[130:133], off offset:256 nt
	v_addc_co_u32_e32 v139, vcc, 0, v135, vcc
	s_nop 0
	v_cvt_pk_bf16_f32 v130, v34, v35
	v_cvt_pk_bf16_f32 v131, v36, v37
	v_cvt_pk_bf16_f32 v132, v26, v27
	v_cvt_pk_bf16_f32 v133, v28, v29
	v_lshl_add_u64 v[136:137], v[134:135], 0, s[48:49]
	global_store_dwordx4 v[138:139], v[130:133], off nt
	s_mov_b64 s[60:61], 0
	s_nop 0
	v_cvt_pk_bf16_f32 v130, v22, v23
	v_cvt_pk_bf16_f32 v131, v24, v25
	v_cvt_pk_bf16_f32 v132, v14, v15
	v_cvt_pk_bf16_f32 v133, v16, v17
	global_store_dwordx4 v[136:137], v[130:133], off offset:256 nt
	v_lshl_add_u64 v[136:137], v[134:135], 0, s[50:51]
	v_add_co_u32_e32 v134, vcc, s4, v134
	v_cvt_pk_bf16_f32 v130, v18, v19
	v_cvt_pk_bf16_f32 v131, v20, v21
	v_cvt_pk_bf16_f32 v132, v10, v11
	v_cvt_pk_bf16_f32 v133, v12, v13
	v_addc_co_u32_e32 v135, vcc, 0, v135, vcc
	global_store_dwordx4 v[134:135], v[130:133], off nt
	s_nop 1
	v_cvt_pk_bf16_f32 v130, v6, v7
	v_cvt_pk_bf16_f32 v131, v8, v9
	v_cvt_pk_bf16_f32 v132, v2, v3
	v_cvt_pk_bf16_f32 v133, v4, v5
	global_store_dwordx4 v[136:137], v[130:133], off offset:256 nt
.LBB0_171:
	s_andn2_b64 vcc, exec, s[60:61]
	s_cbranch_vccnz .LBB0_173
	v_add_u32_e32 v130, s85, v174
	v_lshl_add_u32 v138, s18, 8, v130
	v_ashrrev_i32_e32 v131, 3, v138
	s_lshl_b32 s2, s19, 8
	v_and_b32_e32 v131, 0xfffffe00, v131
	s_and_b32 s2, s2, 0x100
	v_add_u32_e32 v140, s84, v173
	v_or_b32_e32 v141, s2, v131
	v_add_u32_e32 v142, v141, v140
	v_lshrrev_b32_e32 v144, 6, v138
	v_and_b32_e32 v139, 56, v130
	v_bfi_b32 v130, s5, v142, v144
	v_ashrrev_i32_e32 v131, 31, v130
	v_lshlrev_b64 v[130:131], 13, v[130:131]
	v_lshlrev_b32_e32 v136, 7, v173
	v_lshl_add_u64 v[130:131], s[28:29], 0, v[130:131]
	v_and_b32_e32 v158, 0x1f80, v136
	v_lshl_add_u64 v[136:137], v[130:131], 0, v[158:159]
	v_lshlrev_b32_e32 v130, 1, v139
	v_mov_b32_e32 v131, v159
	v_cvt_pk_bf16_f32 v132, v126, v127
	v_cvt_pk_bf16_f32 v133, v128, v129
	v_cvt_pk_bf16_f32 v134, v122, v123
	v_cvt_pk_bf16_f32 v135, v124, v125
	v_lshl_add_u64 v[136:137], v[136:137], 0, v[130:131]
	global_store_dwordx4 v[136:137], v[132:135], off nt
	v_add_u32_e32 v136, 0x80, v138
	v_lshrrev_b32_e32 v164, 6, v136
	v_bfe_u32 v165, v136, 6, 6
	v_bfi_b32 v136, s5, v142, v164
	v_ashrrev_i32_e32 v137, 31, v136
	v_lshlrev_b64 v[136:137], 13, v[136:137]
	v_lshl_add_u64 v[136:137], s[28:29], 0, v[136:137]
	v_bfe_u32 v145, v138, 6, 6
	v_lshl_add_u64 v[136:137], v[136:137], 0, v[158:159]
	v_add_u32_e32 v138, 16, v140
	v_and_b32_e32 v143, 0xffffffc0, v142
	v_cvt_pk_bf16_f32 v132, v118, v119
	v_cvt_pk_bf16_f32 v133, v120, v121
	v_cvt_pk_bf16_f32 v134, v110, v111
	v_cvt_pk_bf16_f32 v135, v112, v113
	v_lshl_add_u64 v[136:137], v[136:137], 0, v[130:131]
	v_add_u32_e32 v142, v141, v138
	global_store_dwordx4 v[136:137], v[132:135], off nt
	v_bfi_b32 v136, s5, v142, v144
	v_ashrrev_i32_e32 v137, 31, v136
	v_lshlrev_b64 v[136:137], 13, v[136:137]
	v_lshlrev_b32_e32 v138, 7, v138
	v_lshl_add_u64 v[136:137], s[28:29], 0, v[136:137]
	v_and_b32_e32 v138, 0x1f80, v138
	v_mov_b32_e32 v139, v159
	v_lshl_add_u64 v[136:137], v[136:137], 0, v[138:139]
	v_cvt_pk_bf16_f32 v132, v114, v115
	v_cvt_pk_bf16_f32 v133, v116, v117
	v_cvt_pk_bf16_f32 v134, v106, v107
	v_cvt_pk_bf16_f32 v135, v108, v109
	v_lshl_add_u64 v[136:137], v[136:137], 0, v[130:131]
	global_store_dwordx4 v[136:137], v[132:135], off nt
	v_bfi_b32 v136, s5, v142, v164
	v_ashrrev_i32_e32 v137, 31, v136
	v_lshlrev_b64 v[136:137], 13, v[136:137]
	v_lshl_add_u64 v[136:137], s[28:29], 0, v[136:137]
	v_lshl_add_u64 v[136:137], v[136:137], 0, v[138:139]
	v_add_u32_e32 v138, 32, v140
	v_cvt_pk_bf16_f32 v132, v102, v103
	v_cvt_pk_bf16_f32 v133, v104, v105
	v_cvt_pk_bf16_f32 v134, v94, v95
	v_cvt_pk_bf16_f32 v135, v96, v97
	v_lshl_add_u64 v[136:137], v[136:137], 0, v[130:131]
	v_add_u32_e32 v142, v141, v138
	global_store_dwordx4 v[136:137], v[132:135], off nt
	v_bfi_b32 v136, s5, v142, v144
	v_ashrrev_i32_e32 v137, 31, v136
	v_lshlrev_b64 v[136:137], 13, v[136:137]
	v_lshlrev_b32_e32 v138, 7, v138
	v_lshl_add_u64 v[136:137], s[28:29], 0, v[136:137]
	v_and_b32_e32 v138, 0x1f80, v138
	v_lshl_add_u64 v[136:137], v[136:137], 0, v[138:139]
	v_cvt_pk_bf16_f32 v132, v98, v99
	v_cvt_pk_bf16_f32 v133, v100, v101
	v_cvt_pk_bf16_f32 v134, v90, v91
	v_cvt_pk_bf16_f32 v135, v92, v93
	v_lshl_add_u64 v[136:137], v[136:137], 0, v[130:131]
	global_store_dwordx4 v[136:137], v[132:135], off nt
	v_bfi_b32 v136, s5, v142, v164
	v_ashrrev_i32_e32 v137, 31, v136
	v_lshlrev_b64 v[136:137], 13, v[136:137]
	v_lshl_add_u64 v[136:137], s[28:29], 0, v[136:137]
	v_lshl_add_u64 v[136:137], v[136:137], 0, v[138:139]
	v_add_u32_e32 v138, 48, v140
	v_cvt_pk_bf16_f32 v132, v86, v87
	v_cvt_pk_bf16_f32 v133, v88, v89
	v_cvt_pk_bf16_f32 v134, v78, v79
	v_cvt_pk_bf16_f32 v135, v80, v81
	v_lshl_add_u64 v[136:137], v[136:137], 0, v[130:131]
	v_add_u32_e32 v142, v141, v138
	global_store_dwordx4 v[136:137], v[132:135], off nt
	v_bfi_b32 v136, s5, v142, v144
	v_ashrrev_i32_e32 v137, 31, v136
	v_lshlrev_b64 v[136:137], 13, v[136:137]
	v_lshlrev_b32_e32 v138, 7, v138
	v_lshl_add_u64 v[136:137], s[28:29], 0, v[136:137]
	v_and_b32_e32 v138, 0x1f80, v138
	v_lshl_add_u64 v[136:137], v[136:137], 0, v[138:139]
	v_cvt_pk_bf16_f32 v132, v82, v83
	v_cvt_pk_bf16_f32 v133, v84, v85
	v_cvt_pk_bf16_f32 v134, v74, v75
	v_cvt_pk_bf16_f32 v135, v76, v77
	v_lshl_add_u64 v[136:137], v[136:137], 0, v[130:131]
	global_store_dwordx4 v[136:137], v[132:135], off nt
	v_bfi_b32 v136, s5, v142, v164
	v_ashrrev_i32_e32 v137, 31, v136
	v_lshlrev_b64 v[136:137], 13, v[136:137]
	v_lshl_add_u64 v[136:137], s[28:29], 0, v[136:137]
	v_lshl_add_u64 v[136:137], v[136:137], 0, v[138:139]
	v_cvt_pk_bf16_f32 v132, v70, v71
	v_cvt_pk_bf16_f32 v133, v72, v73
	v_cvt_pk_bf16_f32 v134, v66, v67
	v_cvt_pk_bf16_f32 v135, v68, v69
	v_lshl_add_u64 v[136:137], v[136:137], 0, v[130:131]
	v_add_u32_e32 v138, 0x80, v143
	global_store_dwordx4 v[136:137], v[132:135], off nt
	v_or_b32_e32 v136, v145, v138
	v_ashrrev_i32_e32 v137, 31, v136
	v_lshlrev_b64 v[136:137], 13, v[136:137]
	v_lshl_add_u64 v[136:137], s[28:29], 0, v[136:137]
	v_lshl_add_u64 v[136:137], v[136:137], 0, v[158:159]
	v_cvt_pk_bf16_f32 v132, v62, v63
	v_cvt_pk_bf16_f32 v133, v64, v65
	v_cvt_pk_bf16_f32 v134, v58, v59
	v_cvt_pk_bf16_f32 v135, v60, v61
	v_lshl_add_u64 v[136:137], v[136:137], 0, v[130:131]
	global_store_dwordx4 v[136:137], v[132:135], off nt
	v_or_b32_e32 v136, v165, v138
	v_ashrrev_i32_e32 v137, 31, v136
	v_lshlrev_b64 v[136:137], 13, v[136:137]
	v_lshl_add_u64 v[136:137], s[28:29], 0, v[136:137]
	v_lshl_add_u64 v[136:137], v[136:137], 0, v[158:159]
	v_add_u32_e32 v138, 0x90, v140
	v_cvt_pk_bf16_f32 v132, v54, v55
	v_cvt_pk_bf16_f32 v133, v56, v57
	v_cvt_pk_bf16_f32 v134, v46, v47
	v_cvt_pk_bf16_f32 v135, v48, v49
	v_lshl_add_u64 v[136:137], v[136:137], 0, v[130:131]
	v_add_u32_e32 v139, v141, v138
	global_store_dwordx4 v[136:137], v[132:135], off nt
	v_bfi_b32 v136, s5, v139, v144
	v_ashrrev_i32_e32 v137, 31, v136
	v_lshlrev_b64 v[136:137], 13, v[136:137]
	v_lshlrev_b32_e32 v138, 7, v138
	v_lshl_add_u64 v[136:137], s[28:29], 0, v[136:137]
	v_and_b32_e32 v158, 0x1f80, v138
	v_lshl_add_u64 v[136:137], v[136:137], 0, v[158:159]
	v_cvt_pk_bf16_f32 v132, v50, v51
	v_cvt_pk_bf16_f32 v133, v52, v53
	v_cvt_pk_bf16_f32 v134, v42, v43
	v_cvt_pk_bf16_f32 v135, v44, v45
	v_lshl_add_u64 v[136:137], v[136:137], 0, v[130:131]
	global_store_dwordx4 v[136:137], v[132:135], off nt
	v_bfi_b32 v136, s5, v139, v164
	v_ashrrev_i32_e32 v137, 31, v136
	v_lshlrev_b64 v[136:137], 13, v[136:137]
	v_lshl_add_u64 v[136:137], s[28:29], 0, v[136:137]
	v_lshl_add_u64 v[136:137], v[136:137], 0, v[158:159]
	v_add_u32_e32 v138, 0xa0, v140
	v_cvt_pk_bf16_f32 v132, v38, v39
	v_cvt_pk_bf16_f32 v133, v40, v41
	v_cvt_pk_bf16_f32 v134, v30, v31
	v_cvt_pk_bf16_f32 v135, v32, v33
	v_lshl_add_u64 v[136:137], v[136:137], 0, v[130:131]
	v_add_u32_e32 v139, v141, v138
	global_store_dwordx4 v[136:137], v[132:135], off nt
	v_bfi_b32 v136, s5, v139, v144
	v_ashrrev_i32_e32 v137, 31, v136
	v_lshlrev_b64 v[136:137], 13, v[136:137]
	v_lshlrev_b32_e32 v138, 7, v138
	v_lshl_add_u64 v[136:137], s[28:29], 0, v[136:137]
	v_and_b32_e32 v158, 0x1f80, v138
	v_lshl_add_u64 v[136:137], v[136:137], 0, v[158:159]
	v_cvt_pk_bf16_f32 v132, v34, v35
	v_cvt_pk_bf16_f32 v133, v36, v37
	v_cvt_pk_bf16_f32 v134, v26, v27
	v_cvt_pk_bf16_f32 v135, v28, v29
	v_lshl_add_u64 v[136:137], v[136:137], 0, v[130:131]
	global_store_dwordx4 v[136:137], v[132:135], off nt
	v_bfi_b32 v136, s5, v139, v164
	v_ashrrev_i32_e32 v137, 31, v136
	v_lshlrev_b64 v[136:137], 13, v[136:137]
	v_lshl_add_u64 v[136:137], s[28:29], 0, v[136:137]
	v_lshl_add_u64 v[136:137], v[136:137], 0, v[158:159]
	v_add_u32_e32 v138, 0xb0, v140
	v_cvt_pk_bf16_f32 v132, v22, v23
	v_cvt_pk_bf16_f32 v133, v24, v25
	v_cvt_pk_bf16_f32 v134, v14, v15
	v_cvt_pk_bf16_f32 v135, v16, v17
	v_lshl_add_u64 v[136:137], v[136:137], 0, v[130:131]
	v_add_u32_e32 v139, v141, v138
	global_store_dwordx4 v[136:137], v[132:135], off nt
	v_bfi_b32 v136, s5, v139, v144
	v_ashrrev_i32_e32 v137, 31, v136
	v_lshlrev_b64 v[136:137], 13, v[136:137]
	v_lshlrev_b32_e32 v138, 7, v138
	v_lshl_add_u64 v[136:137], s[28:29], 0, v[136:137]
	v_and_b32_e32 v158, 0x1f80, v138
	v_lshl_add_u64 v[136:137], v[136:137], 0, v[158:159]
	v_cvt_pk_bf16_f32 v132, v18, v19
	v_cvt_pk_bf16_f32 v133, v20, v21
	v_cvt_pk_bf16_f32 v134, v10, v11
	v_cvt_pk_bf16_f32 v135, v12, v13
	v_lshl_add_u64 v[136:137], v[136:137], 0, v[130:131]
	global_store_dwordx4 v[136:137], v[132:135], off nt
	v_bfi_b32 v136, s5, v139, v164
	v_ashrrev_i32_e32 v137, 31, v136
	v_lshlrev_b64 v[136:137], 13, v[136:137]
	v_lshl_add_u64 v[136:137], s[28:29], 0, v[136:137]
	v_lshl_add_u64 v[136:137], v[136:137], 0, v[158:159]
	v_cvt_pk_bf16_f32 v132, v6, v7
	v_cvt_pk_bf16_f32 v133, v8, v9
	v_cvt_pk_bf16_f32 v134, v2, v3
	v_cvt_pk_bf16_f32 v135, v4, v5
	v_lshl_add_u64 v[130:131], v[136:137], 0, v[130:131]
	global_store_dwordx4 v[130:131], v[132:135], off nt

.LBB0_174:
	s_andn2_b64 vcc, exec, s[60:61]
	s_mov_b64 s[60:61], 0
	s_cbranch_vccnz .LBB0_179
	s_cmp_gt_i32 s55, 0
	s_mov_b64 s[60:61], -1
	s_cbranch_scc0 .LBB0_177
	s_lshl_b32 s2, s19, 8
	s_and_b32 s2, s2, 0x100
	s_or_b32 s2, s2, s85
	v_add_u32_e32 v138, s2, v174
	s_lshl_b32 s2, s18, 8
	s_add_i32 s2, s2, s84
	v_add_u32_e32 v139, s2, v173
	v_ashrrev_i32_e32 v130, 9, v139
	v_and_b32_e32 v141, -8, v130
	v_ashrrev_i32_e32 v142, 6, v138
	v_add_u32_e32 v130, v141, v142
	v_ashrrev_i32_e32 v131, 31, v130
	v_lshlrev_b64 v[130:131], 19, v[130:131]
	v_lshlrev_b32_e32 v136, 7, v139
	v_and_b32_e32 v140, 56, v138
	v_lshl_add_u64 v[130:131], s[30:31], 0, v[130:131]
	v_and_b32_e32 v158, 0x7ff80, v136
	v_lshl_add_u64 v[136:137], v[130:131], 0, v[158:159]
	v_lshlrev_b32_e32 v130, 1, v140
	v_mov_b32_e32 v131, v159
	v_cvt_pk_bf16_f32 v132, v126, v127
	v_cvt_pk_bf16_f32 v133, v128, v129
	v_cvt_pk_bf16_f32 v134, v122, v123
	v_cvt_pk_bf16_f32 v135, v124, v125
	v_lshl_add_u64 v[136:137], v[136:137], 0, v[130:131]
	global_store_dwordx4 v[136:137], v[132:135], off nt
	v_add_u32_e32 v136, 0x80, v138
	v_ashrrev_i32_e32 v138, 6, v136
	v_add_u32_e32 v136, v138, v141
	v_ashrrev_i32_e32 v137, 31, v136
	v_lshlrev_b64 v[136:137], 19, v[136:137]
	v_lshl_add_u64 v[136:137], s[30:31], 0, v[136:137]
	v_lshl_add_u64 v[136:137], v[136:137], 0, v[158:159]
	v_cvt_pk_bf16_f32 v132, v118, v119
	v_cvt_pk_bf16_f32 v133, v120, v121
	v_cvt_pk_bf16_f32 v134, v110, v111
	v_cvt_pk_bf16_f32 v135, v112, v113
	v_lshl_add_u64 v[136:137], v[136:137], 0, v[130:131]
	v_add_u32_e32 v140, 16, v139
	global_store_dwordx4 v[136:137], v[132:135], off nt
	s_mov_b64 s[60:61], 0
	s_nop 0
	v_ashrrev_i32_e32 v132, 9, v140
	v_and_b32_e32 v141, -8, v132
	v_add_u32_e32 v136, v141, v142
	v_ashrrev_i32_e32 v137, 31, v136
	v_lshlrev_b64 v[136:137], 19, v[136:137]
	v_lshlrev_b32_e32 v140, 7, v140
	v_lshl_add_u64 v[136:137], s[30:31], 0, v[136:137]
	v_and_b32_e32 v158, 0x7ff80, v140
	v_lshl_add_u64 v[136:137], v[136:137], 0, v[158:159]
	v_cvt_pk_bf16_f32 v132, v114, v115
	v_cvt_pk_bf16_f32 v133, v116, v117
	v_cvt_pk_bf16_f32 v134, v106, v107
	v_cvt_pk_bf16_f32 v135, v108, v109
	v_lshl_add_u64 v[136:137], v[136:137], 0, v[130:131]
	global_store_dwordx4 v[136:137], v[132:135], off nt
	v_add_u32_e32 v136, v141, v138
	v_ashrrev_i32_e32 v137, 31, v136
	v_lshlrev_b64 v[136:137], 19, v[136:137]
	v_lshl_add_u64 v[136:137], s[30:31], 0, v[136:137]
	v_lshl_add_u64 v[136:137], v[136:137], 0, v[158:159]
	v_cvt_pk_bf16_f32 v132, v102, v103
	v_cvt_pk_bf16_f32 v133, v104, v105
	v_cvt_pk_bf16_f32 v134, v94, v95
	v_cvt_pk_bf16_f32 v135, v96, v97
	v_lshl_add_u64 v[136:137], v[136:137], 0, v[130:131]
	v_add_u32_e32 v140, 32, v139
	global_store_dwordx4 v[136:137], v[132:135], off nt
	s_nop 1
	v_ashrrev_i32_e32 v132, 9, v140
	v_and_b32_e32 v141, -8, v132
	v_add_u32_e32 v136, v141, v142
	v_ashrrev_i32_e32 v137, 31, v136
	v_lshlrev_b64 v[136:137], 19, v[136:137]
	v_lshlrev_b32_e32 v140, 7, v140
	v_lshl_add_u64 v[136:137], s[30:31], 0, v[136:137]
	v_and_b32_e32 v158, 0x7ff80, v140
	v_lshl_add_u64 v[136:137], v[136:137], 0, v[158:159]
	v_cvt_pk_bf16_f32 v132, v98, v99
	v_cvt_pk_bf16_f32 v133, v100, v101
	v_cvt_pk_bf16_f32 v134, v90, v91
	v_cvt_pk_bf16_f32 v135, v92, v93
	v_lshl_add_u64 v[136:137], v[136:137], 0, v[130:131]
	global_store_dwordx4 v[136:137], v[132:135], off nt
	v_add_u32_e32 v136, v141, v138
	v_ashrrev_i32_e32 v137, 31, v136
	v_lshlrev_b64 v[136:137], 19, v[136:137]
	v_lshl_add_u64 v[136:137], s[30:31], 0, v[136:137]
	v_lshl_add_u64 v[136:137], v[136:137], 0, v[158:159]
	v_cvt_pk_bf16_f32 v132, v86, v87
	v_cvt_pk_bf16_f32 v133, v88, v89
	v_cvt_pk_bf16_f32 v134, v78, v79
	v_cvt_pk_bf16_f32 v135, v80, v81
	v_lshl_add_u64 v[136:137], v[136:137], 0, v[130:131]
	v_add_u32_e32 v140, 48, v139
	global_store_dwordx4 v[136:137], v[132:135], off nt
	s_nop 1
	v_ashrrev_i32_e32 v132, 9, v140
	v_and_b32_e32 v141, -8, v132
	v_add_u32_e32 v136, v141, v142
	v_ashrrev_i32_e32 v137, 31, v136
	v_lshlrev_b64 v[136:137], 19, v[136:137]
	v_lshlrev_b32_e32 v140, 7, v140
	v_lshl_add_u64 v[136:137], s[30:31], 0, v[136:137]
	v_and_b32_e32 v158, 0x7ff80, v140
	v_lshl_add_u64 v[136:137], v[136:137], 0, v[158:159]
	v_cvt_pk_bf16_f32 v132, v82, v83
	v_cvt_pk_bf16_f32 v133, v84, v85
	v_cvt_pk_bf16_f32 v134, v74, v75
	v_cvt_pk_bf16_f32 v135, v76, v77
	v_lshl_add_u64 v[136:137], v[136:137], 0, v[130:131]
	global_store_dwordx4 v[136:137], v[132:135], off nt
	v_add_u32_e32 v136, v141, v138
	v_ashrrev_i32_e32 v137, 31, v136
	v_lshlrev_b64 v[136:137], 19, v[136:137]
	v_lshl_add_u64 v[136:137], s[30:31], 0, v[136:137]
	v_lshl_add_u64 v[136:137], v[136:137], 0, v[158:159]
	v_cvt_pk_bf16_f32 v132, v70, v71
	v_cvt_pk_bf16_f32 v133, v72, v73
	v_cvt_pk_bf16_f32 v134, v66, v67
	v_cvt_pk_bf16_f32 v135, v68, v69
	v_lshl_add_u64 v[136:137], v[136:137], 0, v[130:131]
	v_add_u32_e32 v140, 0x80, v139
	global_store_dwordx4 v[136:137], v[132:135], off nt
	s_nop 1
	v_ashrrev_i32_e32 v132, 9, v140
	v_and_b32_e32 v141, -8, v132
	v_add_u32_e32 v136, v141, v142
	v_ashrrev_i32_e32 v137, 31, v136
	v_lshlrev_b64 v[136:137], 19, v[136:137]
	v_lshlrev_b32_e32 v140, 7, v140
	v_lshl_add_u64 v[136:137], s[30:31], 0, v[136:137]
	v_and_b32_e32 v158, 0x7ff80, v140
	v_lshl_add_u64 v[136:137], v[136:137], 0, v[158:159]
	v_cvt_pk_bf16_f32 v132, v62, v63
	v_cvt_pk_bf16_f32 v133, v64, v65
	v_cvt_pk_bf16_f32 v134, v58, v59
	v_cvt_pk_bf16_f32 v135, v60, v61
	v_lshl_add_u64 v[136:137], v[136:137], 0, v[130:131]
	global_store_dwordx4 v[136:137], v[132:135], off nt
	v_add_u32_e32 v136, v141, v138
	v_ashrrev_i32_e32 v137, 31, v136
	v_lshlrev_b64 v[136:137], 19, v[136:137]
	v_lshl_add_u64 v[136:137], s[30:31], 0, v[136:137]
	v_lshl_add_u64 v[136:137], v[136:137], 0, v[158:159]
	v_cvt_pk_bf16_f32 v132, v54, v55
	v_cvt_pk_bf16_f32 v133, v56, v57
	v_cvt_pk_bf16_f32 v134, v46, v47
	v_cvt_pk_bf16_f32 v135, v48, v49
	v_lshl_add_u64 v[136:137], v[136:137], 0, v[130:131]
	v_add_u32_e32 v140, 0x90, v139
	global_store_dwordx4 v[136:137], v[132:135], off nt
	s_nop 1
	v_ashrrev_i32_e32 v132, 9, v140
	v_and_b32_e32 v141, -8, v132
	v_add_u32_e32 v136, v141, v142
	v_ashrrev_i32_e32 v137, 31, v136
	v_lshlrev_b64 v[136:137], 19, v[136:137]
	v_lshlrev_b32_e32 v140, 7, v140
	v_lshl_add_u64 v[136:137], s[30:31], 0, v[136:137]
	v_and_b32_e32 v158, 0x7ff80, v140
	v_lshl_add_u64 v[136:137], v[136:137], 0, v[158:159]
	v_cvt_pk_bf16_f32 v132, v50, v51
	v_cvt_pk_bf16_f32 v133, v52, v53
	v_cvt_pk_bf16_f32 v134, v42, v43
	v_cvt_pk_bf16_f32 v135, v44, v45
	v_lshl_add_u64 v[136:137], v[136:137], 0, v[130:131]
	global_store_dwordx4 v[136:137], v[132:135], off nt
	v_add_u32_e32 v136, v141, v138
	v_ashrrev_i32_e32 v137, 31, v136
	v_lshlrev_b64 v[136:137], 19, v[136:137]
	v_lshl_add_u64 v[136:137], s[30:31], 0, v[136:137]
	v_lshl_add_u64 v[136:137], v[136:137], 0, v[158:159]
	v_cvt_pk_bf16_f32 v132, v38, v39
	v_cvt_pk_bf16_f32 v133, v40, v41
	v_cvt_pk_bf16_f32 v134, v30, v31
	v_cvt_pk_bf16_f32 v135, v32, v33
	v_lshl_add_u64 v[136:137], v[136:137], 0, v[130:131]
	v_add_u32_e32 v140, 0xa0, v139
	global_store_dwordx4 v[136:137], v[132:135], off nt
	v_add_u32_e32 v139, 0xb0, v139
	s_nop 0
	v_ashrrev_i32_e32 v132, 9, v140
	v_and_b32_e32 v141, -8, v132
	v_add_u32_e32 v136, v141, v142
	v_ashrrev_i32_e32 v137, 31, v136
	v_lshlrev_b64 v[136:137], 19, v[136:137]
	v_lshlrev_b32_e32 v140, 7, v140
	v_lshl_add_u64 v[136:137], s[30:31], 0, v[136:137]
	v_and_b32_e32 v158, 0x7ff80, v140
	v_lshl_add_u64 v[136:137], v[136:137], 0, v[158:159]
	v_cvt_pk_bf16_f32 v132, v34, v35
	v_cvt_pk_bf16_f32 v133, v36, v37
	v_cvt_pk_bf16_f32 v134, v26, v27
	v_cvt_pk_bf16_f32 v135, v28, v29
	v_lshl_add_u64 v[136:137], v[136:137], 0, v[130:131]
	global_store_dwordx4 v[136:137], v[132:135], off nt
	v_add_u32_e32 v136, v141, v138
	v_ashrrev_i32_e32 v137, 31, v136
	v_lshlrev_b64 v[136:137], 19, v[136:137]
	v_lshl_add_u64 v[136:137], s[30:31], 0, v[136:137]
	v_lshl_add_u64 v[136:137], v[136:137], 0, v[158:159]
	v_cvt_pk_bf16_f32 v132, v22, v23
	v_cvt_pk_bf16_f32 v133, v24, v25
	v_cvt_pk_bf16_f32 v134, v14, v15
	v_cvt_pk_bf16_f32 v135, v16, v17
	v_lshl_add_u64 v[136:137], v[136:137], 0, v[130:131]
	global_store_dwordx4 v[136:137], v[132:135], off nt
	s_nop 1
	v_ashrrev_i32_e32 v132, 9, v139
	v_and_b32_e32 v140, -8, v132
	v_add_u32_e32 v136, v140, v142
	v_ashrrev_i32_e32 v137, 31, v136
	v_lshlrev_b64 v[136:137], 19, v[136:137]
	v_lshlrev_b32_e32 v139, 7, v139
	v_lshl_add_u64 v[136:137], s[30:31], 0, v[136:137]
	v_and_b32_e32 v158, 0x7ff80, v139
	v_lshl_add_u64 v[136:137], v[136:137], 0, v[158:159]
	v_cvt_pk_bf16_f32 v132, v18, v19
	v_cvt_pk_bf16_f32 v133, v20, v21
	v_cvt_pk_bf16_f32 v134, v10, v11
	v_cvt_pk_bf16_f32 v135, v12, v13
	v_lshl_add_u64 v[136:137], v[136:137], 0, v[130:131]
	global_store_dwordx4 v[136:137], v[132:135], off nt
	v_add_u32_e32 v136, v140, v138
	v_ashrrev_i32_e32 v137, 31, v136
	v_lshlrev_b64 v[136:137], 19, v[136:137]
	v_lshl_add_u64 v[136:137], s[30:31], 0, v[136:137]
	v_lshl_add_u64 v[136:137], v[136:137], 0, v[158:159]
	v_cvt_pk_bf16_f32 v132, v6, v7
	v_cvt_pk_bf16_f32 v133, v8, v9
	v_cvt_pk_bf16_f32 v134, v2, v3
	v_cvt_pk_bf16_f32 v135, v4, v5
	v_lshl_add_u64 v[130:131], v[136:137], 0, v[130:131]
	global_store_dwordx4 v[130:131], v[132:135], off nt

.LBB0_179:
	s_and_b64 vcc, exec, s[58:59]
	s_cbranch_vccz .LBB0_181
	s_lshl_b32 s2, s19, 8
	s_and_b32 s2, s2, 0x100
	s_or_b32 s2, s2, s85
	v_add_u32_e32 v134, s2, v174
	s_lshl_b32 s2, s18, 8
	s_add_i32 s2, s2, s84
	v_add_u32_e32 v130, s2, v173
	v_ashrrev_i32_e32 v131, 31, v130
	v_lshlrev_b64 v[136:137], 10, v[130:131]
	v_lshl_add_u64 v[136:137], s[36:37], 0, v[136:137]
	v_ashrrev_i32_e32 v135, 31, v134
	v_cvt_pk_bf16_f32 v130, v126, v127
	v_cvt_pk_bf16_f32 v131, v128, v129
	v_cvt_pk_bf16_f32 v132, v122, v123
	v_cvt_pk_bf16_f32 v133, v124, v125
	v_lshl_add_u64 v[134:135], v[134:135], 1, v[136:137]
	global_store_dwordx4 v[134:135], v[130:133], off nt
	v_add_co_u32_e32 v138, vcc, s75, v134
	s_nop 0
	v_cvt_pk_bf16_f32 v130, v118, v119
	v_cvt_pk_bf16_f32 v131, v120, v121
	v_cvt_pk_bf16_f32 v132, v110, v111
	v_cvt_pk_bf16_f32 v133, v112, v113
	global_store_dwordx4 v[134:135], v[130:133], off offset:256 nt
	v_addc_co_u32_e32 v139, vcc, 0, v135, vcc
	s_nop 0
	v_cvt_pk_bf16_f32 v130, v114, v115
	v_cvt_pk_bf16_f32 v131, v116, v117
	v_cvt_pk_bf16_f32 v132, v106, v107
	v_cvt_pk_bf16_f32 v133, v108, v109
	v_lshl_add_u64 v[136:137], v[134:135], 0, s[38:39]
	global_store_dwordx4 v[138:139], v[130:133], off nt
	v_add_co_u32_e32 v138, vcc, s92, v134
	s_nop 0
	v_cvt_pk_bf16_f32 v130, v102, v103
	v_cvt_pk_bf16_f32 v131, v104, v105
	v_cvt_pk_bf16_f32 v132, v94, v95
	v_cvt_pk_bf16_f32 v133, v96, v97
	global_store_dwordx4 v[136:137], v[130:133], off offset:256 nt
	v_addc_co_u32_e32 v139, vcc, 0, v135, vcc
	s_nop 0
	v_cvt_pk_bf16_f32 v130, v98, v99
	v_cvt_pk_bf16_f32 v131, v100, v101
	v_cvt_pk_bf16_f32 v132, v90, v91
	v_cvt_pk_bf16_f32 v133, v92, v93
	v_lshl_add_u64 v[136:137], v[134:135], 0, s[40:41]
	global_store_dwordx4 v[138:139], v[130:133], off nt
	v_add_co_u32_e32 v138, vcc, s97, v134
	s_nop 0
	v_cvt_pk_bf16_f32 v130, v86, v87
	v_cvt_pk_bf16_f32 v131, v88, v89
	v_cvt_pk_bf16_f32 v132, v78, v79
	v_cvt_pk_bf16_f32 v133, v80, v81
	global_store_dwordx4 v[136:137], v[130:133], off offset:256 nt
	v_addc_co_u32_e32 v139, vcc, 0, v135, vcc
	s_nop 0
	v_cvt_pk_bf16_f32 v130, v82, v83
	v_cvt_pk_bf16_f32 v131, v84, v85
	v_cvt_pk_bf16_f32 v132, v74, v75
	v_cvt_pk_bf16_f32 v133, v76, v77
	v_lshl_add_u64 v[136:137], v[134:135], 0, s[42:43]
	global_store_dwordx4 v[138:139], v[130:133], off nt
	v_add_co_u32_e32 v138, vcc, s66, v134
	s_nop 0
	v_cvt_pk_bf16_f32 v130, v70, v71
	v_cvt_pk_bf16_f32 v131, v72, v73
	v_cvt_pk_bf16_f32 v132, v66, v67
	v_cvt_pk_bf16_f32 v133, v68, v69
	global_store_dwordx4 v[136:137], v[130:133], off offset:256 nt
	v_addc_co_u32_e32 v139, vcc, 0, v135, vcc
	s_nop 0
	v_cvt_pk_bf16_f32 v130, v62, v63
	v_cvt_pk_bf16_f32 v131, v64, v65
	v_cvt_pk_bf16_f32 v132, v58, v59
	v_cvt_pk_bf16_f32 v133, v60, v61
	v_lshl_add_u64 v[136:137], v[134:135], 0, s[44:45]
	global_store_dwordx4 v[138:139], v[130:133], off nt
	v_add_co_u32_e32 v138, vcc, s53, v134
	s_nop 0
	v_cvt_pk_bf16_f32 v130, v54, v55
	v_cvt_pk_bf16_f32 v131, v56, v57
	v_cvt_pk_bf16_f32 v132, v46, v47
	v_cvt_pk_bf16_f32 v133, v48, v49
	global_store_dwordx4 v[136:137], v[130:133], off offset:256 nt
	v_addc_co_u32_e32 v139, vcc, 0, v135, vcc
	s_nop 0
	v_cvt_pk_bf16_f32 v130, v50, v51
	v_cvt_pk_bf16_f32 v131, v52, v53
	v_cvt_pk_bf16_f32 v132, v42, v43
	v_cvt_pk_bf16_f32 v133, v44, v45
	v_lshl_add_u64 v[136:137], v[134:135], 0, s[46:47]
	global_store_dwordx4 v[138:139], v[130:133], off nt
	v_add_co_u32_e32 v138, vcc, s68, v134
	s_nop 0
	v_cvt_pk_bf16_f32 v130, v38, v39
	v_cvt_pk_bf16_f32 v131, v40, v41
	v_cvt_pk_bf16_f32 v132, v30, v31
	v_cvt_pk_bf16_f32 v133, v32, v33
	global_store_dwordx4 v[136:137], v[130:133], off offset:256 nt
	v_addc_co_u32_e32 v139, vcc, 0, v135, vcc
	s_nop 0
	v_cvt_pk_bf16_f32 v130, v34, v35
	v_cvt_pk_bf16_f32 v131, v36, v37
	v_cvt_pk_bf16_f32 v132, v26, v27
	v_cvt_pk_bf16_f32 v133, v28, v29
	v_lshl_add_u64 v[136:137], v[134:135], 0, s[48:49]
	global_store_dwordx4 v[138:139], v[130:133], off nt
	s_mov_b64 s[60:61], 0
	s_nop 0
	v_cvt_pk_bf16_f32 v130, v22, v23
	v_cvt_pk_bf16_f32 v131, v24, v25
	v_cvt_pk_bf16_f32 v132, v14, v15
	v_cvt_pk_bf16_f32 v133, v16, v17
	global_store_dwordx4 v[136:137], v[130:133], off offset:256 nt
	v_lshl_add_u64 v[136:137], v[134:135], 0, s[50:51]
	v_add_co_u32_e32 v134, vcc, s4, v134
	v_cvt_pk_bf16_f32 v130, v18, v19
	v_cvt_pk_bf16_f32 v131, v20, v21
	v_cvt_pk_bf16_f32 v132, v10, v11
	v_cvt_pk_bf16_f32 v133, v12, v13
	v_addc_co_u32_e32 v135, vcc, 0, v135, vcc
	global_store_dwordx4 v[134:135], v[130:133], off nt
	s_nop 1
	v_cvt_pk_bf16_f32 v130, v6, v7
	v_cvt_pk_bf16_f32 v131, v8, v9
	v_cvt_pk_bf16_f32 v132, v2, v3
	v_cvt_pk_bf16_f32 v133, v4, v5
	global_store_dwordx4 v[136:137], v[130:133], off offset:256 nt
.LBB0_181:
	s_andn2_b64 vcc, exec, s[60:61]
	s_cbranch_vccnz .LBB0_130
	s_lshl_b32 s2, s19, 8
	s_and_b32 s2, s2, 0x100
	s_or_b32 s2, s2, s85
	v_add_u32_e32 v132, s2, v174
	s_lshl_b32 s2, s18, 8
	s_add_i32 s2, s2, s84
	v_add_u32_e32 v133, s2, v173
	v_ashrrev_i32_e32 v130, 9, v133
	v_and_b32_e32 v135, -8, v130
	v_pk_mul_f32 v[126:127], v[126:127], s[52:53] op_sel_hi:[1,0]
	v_pk_mul_f32 v[130:131], v[124:125], s[52:53] op_sel_hi:[1,0]
	v_pk_mul_f32 v[122:123], v[122:123], s[52:53] op_sel_hi:[1,0]
	v_cvt_pk_bf16_f32 v124, v126, v127
	v_cvt_pk_bf16_f32 v127, v130, v131
	v_ashrrev_i32_e32 v130, 6, v132
	v_cvt_pk_bf16_f32 v126, v122, v123
	v_add_u32_e32 v122, v135, v130
	v_pk_mul_f32 v[128:129], v[128:129], s[52:53] op_sel_hi:[1,0]
	v_ashrrev_i32_e32 v123, 31, v122
	v_cvt_pk_bf16_f32 v125, v128, v129
	v_lshlrev_b64 v[122:123], 19, v[122:123]
	v_lshlrev_b32_e32 v128, 7, v133
	v_and_b32_e32 v134, 56, v132
	v_lshl_add_u64 v[122:123], s[34:35], 0, v[122:123]
	v_and_b32_e32 v158, 0x7ff80, v128
	v_lshl_add_u64 v[128:129], v[122:123], 0, v[158:159]
	v_lshlrev_b32_e32 v122, 1, v134
	v_mov_b32_e32 v123, v159
	v_lshl_add_u64 v[128:129], v[128:129], 0, v[122:123]
	global_store_dwordx4 v[128:129], v[124:127], off nt
	v_pk_mul_f32 v[120:121], v[120:121], s[52:53] op_sel_hi:[1,0]
	v_add_u32_e32 v128, 0x80, v132
	v_pk_mul_f32 v[118:119], v[118:119], s[52:53] op_sel_hi:[1,0]
	v_pk_mul_f32 v[124:125], v[110:111], s[52:53] op_sel_hi:[1,0]
	v_cvt_pk_bf16_f32 v111, v120, v121
	v_ashrrev_i32_e32 v120, 6, v128
	v_cvt_pk_bf16_f32 v110, v118, v119
	v_add_u32_e32 v118, v120, v135
	v_ashrrev_i32_e32 v119, 31, v118
	v_lshlrev_b64 v[118:119], 19, v[118:119]
	v_lshl_add_u64 v[118:119], s[34:35], 0, v[118:119]
	v_pk_mul_f32 v[126:127], v[112:113], s[52:53] op_sel_hi:[1,0]
	v_lshl_add_u64 v[118:119], v[118:119], 0, v[158:159]
	v_cvt_pk_bf16_f32 v112, v124, v125
	v_cvt_pk_bf16_f32 v113, v126, v127
	v_lshl_add_u64 v[118:119], v[118:119], 0, v[122:123]
	global_store_dwordx4 v[118:119], v[110:113], off nt
	v_add_u32_e32 v118, 16, v133
	v_pk_mul_f32 v[102:103], v[102:103], s[52:53] op_sel_hi:[1,0]
	v_ashrrev_i32_e32 v110, 9, v118
	v_and_b32_e32 v119, -8, v110
	v_pk_mul_f32 v[110:111], v[114:115], s[52:53] op_sel_hi:[1,0]
	v_pk_mul_f32 v[114:115], v[106:107], s[52:53] op_sel_hi:[1,0]
	v_cvt_pk_bf16_f32 v106, v110, v111
	v_add_u32_e32 v110, v119, v130
	v_pk_mul_f32 v[112:113], v[116:117], s[52:53] op_sel_hi:[1,0]
	v_ashrrev_i32_e32 v111, 31, v110
	v_cvt_pk_bf16_f32 v107, v112, v113
	v_lshlrev_b64 v[110:111], 19, v[110:111]
	v_lshlrev_b32_e32 v112, 7, v118
	v_lshl_add_u64 v[110:111], s[34:35], 0, v[110:111]
	v_and_b32_e32 v158, 0x7ff80, v112
	v_pk_mul_f32 v[116:117], v[108:109], s[52:53] op_sel_hi:[1,0]
	v_lshl_add_u64 v[110:111], v[110:111], 0, v[158:159]
	v_cvt_pk_bf16_f32 v108, v114, v115
	v_cvt_pk_bf16_f32 v109, v116, v117
	v_lshl_add_u64 v[110:111], v[110:111], 0, v[122:123]
	global_store_dwordx4 v[110:111], v[106:109], off nt
	v_pk_mul_f32 v[104:105], v[104:105], s[52:53] op_sel_hi:[1,0]
	v_pk_mul_f32 v[86:87], v[86:87], s[52:53] op_sel_hi:[1,0]
	v_pk_mul_f32 v[106:107], v[94:95], s[52:53] op_sel_hi:[1,0]
	v_cvt_pk_bf16_f32 v94, v102, v103
	v_add_u32_e32 v102, v119, v120
	v_ashrrev_i32_e32 v103, 31, v102
	v_lshlrev_b64 v[102:103], 19, v[102:103]
	v_lshl_add_u64 v[102:103], s[34:35], 0, v[102:103]
	v_pk_mul_f32 v[108:109], v[96:97], s[52:53] op_sel_hi:[1,0]
	v_lshl_add_u64 v[102:103], v[102:103], 0, v[158:159]
	v_cvt_pk_bf16_f32 v95, v104, v105
	v_cvt_pk_bf16_f32 v96, v106, v107
	v_cvt_pk_bf16_f32 v97, v108, v109
	v_lshl_add_u64 v[102:103], v[102:103], 0, v[122:123]
	global_store_dwordx4 v[102:103], v[94:97], off nt
	v_add_u32_e32 v102, 32, v133
	v_pk_mul_f32 v[88:89], v[88:89], s[52:53] op_sel_hi:[1,0]
	v_ashrrev_i32_e32 v94, 9, v102
	v_and_b32_e32 v103, -8, v94
	v_pk_mul_f32 v[94:95], v[98:99], s[52:53] op_sel_hi:[1,0]
	v_pk_mul_f32 v[98:99], v[90:91], s[52:53] op_sel_hi:[1,0]
	v_cvt_pk_bf16_f32 v90, v94, v95
	v_add_u32_e32 v94, v103, v130
	v_pk_mul_f32 v[96:97], v[100:101], s[52:53] op_sel_hi:[1,0]
	v_ashrrev_i32_e32 v95, 31, v94
	v_cvt_pk_bf16_f32 v91, v96, v97
	v_lshlrev_b64 v[94:95], 19, v[94:95]
	v_lshlrev_b32_e32 v96, 7, v102
	v_lshl_add_u64 v[94:95], s[34:35], 0, v[94:95]
	v_and_b32_e32 v158, 0x7ff80, v96
	v_pk_mul_f32 v[100:101], v[92:93], s[52:53] op_sel_hi:[1,0]
	v_lshl_add_u64 v[94:95], v[94:95], 0, v[158:159]
	v_cvt_pk_bf16_f32 v92, v98, v99
	v_cvt_pk_bf16_f32 v93, v100, v101
	v_lshl_add_u64 v[94:95], v[94:95], 0, v[122:123]
	global_store_dwordx4 v[94:95], v[90:93], off nt
	v_pk_mul_f32 v[70:71], v[70:71], s[52:53] op_sel_hi:[1,0]
	v_pk_mul_f32 v[72:73], v[72:73], s[52:53] op_sel_hi:[1,0]
	v_pk_mul_f32 v[90:91], v[78:79], s[52:53] op_sel_hi:[1,0]
	v_cvt_pk_bf16_f32 v78, v86, v87
	v_add_u32_e32 v86, v103, v120
	v_ashrrev_i32_e32 v87, 31, v86
	v_lshlrev_b64 v[86:87], 19, v[86:87]
	v_lshl_add_u64 v[86:87], s[34:35], 0, v[86:87]
	v_pk_mul_f32 v[92:93], v[80:81], s[52:53] op_sel_hi:[1,0]
	v_lshl_add_u64 v[86:87], v[86:87], 0, v[158:159]
	v_cvt_pk_bf16_f32 v79, v88, v89
	v_cvt_pk_bf16_f32 v80, v90, v91
	v_cvt_pk_bf16_f32 v81, v92, v93
	v_lshl_add_u64 v[86:87], v[86:87], 0, v[122:123]
	global_store_dwordx4 v[86:87], v[78:81], off nt
	v_add_u32_e32 v86, 48, v133
	v_pk_mul_f32 v[62:63], v[62:63], s[52:53] op_sel_hi:[1,0]
	v_ashrrev_i32_e32 v78, 9, v86
	v_and_b32_e32 v87, -8, v78
	v_pk_mul_f32 v[78:79], v[82:83], s[52:53] op_sel_hi:[1,0]
	v_pk_mul_f32 v[82:83], v[74:75], s[52:53] op_sel_hi:[1,0]
	v_cvt_pk_bf16_f32 v74, v78, v79
	v_add_u32_e32 v78, v87, v130
	v_pk_mul_f32 v[80:81], v[84:85], s[52:53] op_sel_hi:[1,0]
	v_ashrrev_i32_e32 v79, 31, v78
	v_cvt_pk_bf16_f32 v75, v80, v81
	v_lshlrev_b64 v[78:79], 19, v[78:79]
	v_lshlrev_b32_e32 v80, 7, v86
	v_lshl_add_u64 v[78:79], s[34:35], 0, v[78:79]
	v_and_b32_e32 v158, 0x7ff80, v80
	v_pk_mul_f32 v[84:85], v[76:77], s[52:53] op_sel_hi:[1,0]
	v_lshl_add_u64 v[78:79], v[78:79], 0, v[158:159]
	v_cvt_pk_bf16_f32 v76, v82, v83
	v_cvt_pk_bf16_f32 v77, v84, v85
	v_lshl_add_u64 v[78:79], v[78:79], 0, v[122:123]
	global_store_dwordx4 v[78:79], v[74:77], off nt
	v_pk_mul_f32 v[64:65], v[64:65], s[52:53] op_sel_hi:[1,0]
	v_pk_mul_f32 v[54:55], v[54:55], s[52:53] op_sel_hi:[1,0]
	v_pk_mul_f32 v[74:75], v[66:67], s[52:53] op_sel_hi:[1,0]
	v_cvt_pk_bf16_f32 v66, v70, v71
	v_add_u32_e32 v70, v87, v120
	v_ashrrev_i32_e32 v71, 31, v70
	v_lshlrev_b64 v[70:71], 19, v[70:71]
	v_lshl_add_u64 v[70:71], s[34:35], 0, v[70:71]
	v_pk_mul_f32 v[76:77], v[68:69], s[52:53] op_sel_hi:[1,0]
	v_lshl_add_u64 v[70:71], v[70:71], 0, v[158:159]
	v_cvt_pk_bf16_f32 v67, v72, v73
	v_cvt_pk_bf16_f32 v68, v74, v75
	v_cvt_pk_bf16_f32 v69, v76, v77
	v_lshl_add_u64 v[70:71], v[70:71], 0, v[122:123]
	global_store_dwordx4 v[70:71], v[66:69], off nt
	v_add_u32_e32 v70, 0x80, v133
	v_pk_mul_f32 v[56:57], v[56:57], s[52:53] op_sel_hi:[1,0]
	v_ashrrev_i32_e32 v66, 9, v70
	v_and_b32_e32 v71, -8, v66
	v_pk_mul_f32 v[66:67], v[58:59], s[52:53] op_sel_hi:[1,0]
	v_cvt_pk_bf16_f32 v58, v62, v63
	v_add_u32_e32 v62, v71, v130
	v_ashrrev_i32_e32 v63, 31, v62
	v_cvt_pk_bf16_f32 v59, v64, v65
	v_lshlrev_b64 v[62:63], 19, v[62:63]
	v_lshlrev_b32_e32 v64, 7, v70
	v_lshl_add_u64 v[62:63], s[34:35], 0, v[62:63]
	v_and_b32_e32 v158, 0x7ff80, v64
	v_pk_mul_f32 v[68:69], v[60:61], s[52:53] op_sel_hi:[1,0]
	v_lshl_add_u64 v[62:63], v[62:63], 0, v[158:159]
	v_cvt_pk_bf16_f32 v60, v66, v67
	v_cvt_pk_bf16_f32 v61, v68, v69
	v_lshl_add_u64 v[62:63], v[62:63], 0, v[122:123]
	global_store_dwordx4 v[62:63], v[58:61], off nt
	v_pk_mul_f32 v[38:39], v[38:39], s[52:53] op_sel_hi:[1,0]
	v_pk_mul_f32 v[40:41], v[40:41], s[52:53] op_sel_hi:[1,0]
	v_pk_mul_f32 v[58:59], v[46:47], s[52:53] op_sel_hi:[1,0]
	v_cvt_pk_bf16_f32 v46, v54, v55
	v_add_u32_e32 v54, v71, v120
	v_ashrrev_i32_e32 v55, 31, v54
	v_lshlrev_b64 v[54:55], 19, v[54:55]
	v_lshl_add_u64 v[54:55], s[34:35], 0, v[54:55]
	v_pk_mul_f32 v[60:61], v[48:49], s[52:53] op_sel_hi:[1,0]
	v_lshl_add_u64 v[54:55], v[54:55], 0, v[158:159]
	v_cvt_pk_bf16_f32 v47, v56, v57
	v_cvt_pk_bf16_f32 v48, v58, v59
	v_cvt_pk_bf16_f32 v49, v60, v61
	v_lshl_add_u64 v[54:55], v[54:55], 0, v[122:123]
	global_store_dwordx4 v[54:55], v[46:49], off nt
	v_add_u32_e32 v54, 0x90, v133
	v_pk_mul_f32 v[22:23], v[22:23], s[52:53] op_sel_hi:[1,0]
	v_ashrrev_i32_e32 v46, 9, v54
	v_and_b32_e32 v55, -8, v46
	v_pk_mul_f32 v[46:47], v[50:51], s[52:53] op_sel_hi:[1,0]
	v_pk_mul_f32 v[50:51], v[42:43], s[52:53] op_sel_hi:[1,0]
	v_cvt_pk_bf16_f32 v42, v46, v47
	v_add_u32_e32 v46, v55, v130
	v_pk_mul_f32 v[48:49], v[52:53], s[52:53] op_sel_hi:[1,0]
	v_ashrrev_i32_e32 v47, 31, v46
	v_cvt_pk_bf16_f32 v43, v48, v49
	v_lshlrev_b64 v[46:47], 19, v[46:47]
	v_lshlrev_b32_e32 v48, 7, v54
	v_lshl_add_u64 v[46:47], s[34:35], 0, v[46:47]
	v_and_b32_e32 v158, 0x7ff80, v48
	v_pk_mul_f32 v[52:53], v[44:45], s[52:53] op_sel_hi:[1,0]
	v_lshl_add_u64 v[46:47], v[46:47], 0, v[158:159]
	v_cvt_pk_bf16_f32 v44, v50, v51
	v_cvt_pk_bf16_f32 v45, v52, v53
	v_lshl_add_u64 v[46:47], v[46:47], 0, v[122:123]
	global_store_dwordx4 v[46:47], v[42:45], off nt
	v_pk_mul_f32 v[24:25], v[24:25], s[52:53] op_sel_hi:[1,0]
	v_pk_mul_f32 v[6:7], v[6:7], s[52:53] op_sel_hi:[1,0]
	v_pk_mul_f32 v[42:43], v[30:31], s[52:53] op_sel_hi:[1,0]
	v_cvt_pk_bf16_f32 v30, v38, v39
	v_add_u32_e32 v38, v55, v120
	v_ashrrev_i32_e32 v39, 31, v38
	v_lshlrev_b64 v[38:39], 19, v[38:39]
	v_lshl_add_u64 v[38:39], s[34:35], 0, v[38:39]
	v_pk_mul_f32 v[44:45], v[32:33], s[52:53] op_sel_hi:[1,0]
	v_lshl_add_u64 v[38:39], v[38:39], 0, v[158:159]
	v_cvt_pk_bf16_f32 v31, v40, v41
	v_cvt_pk_bf16_f32 v32, v42, v43
	v_cvt_pk_bf16_f32 v33, v44, v45
	v_lshl_add_u64 v[38:39], v[38:39], 0, v[122:123]
	global_store_dwordx4 v[38:39], v[30:33], off nt
	v_add_u32_e32 v38, 0xa0, v133
	v_pk_mul_f32 v[8:9], v[8:9], s[52:53] op_sel_hi:[1,0]
	v_ashrrev_i32_e32 v30, 9, v38
	v_and_b32_e32 v39, -8, v30
	v_pk_mul_f32 v[30:31], v[34:35], s[52:53] op_sel_hi:[1,0]
	v_pk_mul_f32 v[34:35], v[26:27], s[52:53] op_sel_hi:[1,0]
	v_cvt_pk_bf16_f32 v26, v30, v31
	v_add_u32_e32 v30, v39, v130
	v_pk_mul_f32 v[32:33], v[36:37], s[52:53] op_sel_hi:[1,0]
	v_ashrrev_i32_e32 v31, 31, v30
	v_cvt_pk_bf16_f32 v27, v32, v33
	v_lshlrev_b64 v[30:31], 19, v[30:31]
	v_lshlrev_b32_e32 v32, 7, v38
	v_lshl_add_u64 v[30:31], s[34:35], 0, v[30:31]
	v_and_b32_e32 v158, 0x7ff80, v32
	v_pk_mul_f32 v[36:37], v[28:29], s[52:53] op_sel_hi:[1,0]
	v_lshl_add_u64 v[30:31], v[30:31], 0, v[158:159]
	v_cvt_pk_bf16_f32 v28, v34, v35
	v_cvt_pk_bf16_f32 v29, v36, v37
	v_lshl_add_u64 v[30:31], v[30:31], 0, v[122:123]
	global_store_dwordx4 v[30:31], v[26:29], off nt
	s_nop 1
	v_pk_mul_f32 v[26:27], v[14:15], s[52:53] op_sel_hi:[1,0]
	v_cvt_pk_bf16_f32 v14, v22, v23
	v_add_u32_e32 v22, v39, v120
	v_ashrrev_i32_e32 v23, 31, v22
	v_lshlrev_b64 v[22:23], 19, v[22:23]
	v_lshl_add_u64 v[22:23], s[34:35], 0, v[22:23]
	v_pk_mul_f32 v[28:29], v[16:17], s[52:53] op_sel_hi:[1,0]
	v_lshl_add_u64 v[22:23], v[22:23], 0, v[158:159]
	v_cvt_pk_bf16_f32 v15, v24, v25
	v_cvt_pk_bf16_f32 v16, v26, v27
	v_cvt_pk_bf16_f32 v17, v28, v29
	v_lshl_add_u64 v[22:23], v[22:23], 0, v[122:123]
	global_store_dwordx4 v[22:23], v[14:17], off nt
	v_add_u32_e32 v22, 0xb0, v133
	s_nop 0
	v_ashrrev_i32_e32 v14, 9, v22
	v_and_b32_e32 v23, -8, v14
	v_pk_mul_f32 v[14:15], v[18:19], s[52:53] op_sel_hi:[1,0]
	v_pk_mul_f32 v[18:19], v[10:11], s[52:53] op_sel_hi:[1,0]
	v_cvt_pk_bf16_f32 v10, v14, v15
	v_add_u32_e32 v14, v23, v130
	v_pk_mul_f32 v[16:17], v[20:21], s[52:53] op_sel_hi:[1,0]
	v_ashrrev_i32_e32 v15, 31, v14
	v_cvt_pk_bf16_f32 v11, v16, v17
	v_lshlrev_b64 v[14:15], 19, v[14:15]
	v_lshlrev_b32_e32 v16, 7, v22
	v_lshl_add_u64 v[14:15], s[34:35], 0, v[14:15]
	v_and_b32_e32 v158, 0x7ff80, v16
	v_pk_mul_f32 v[20:21], v[12:13], s[52:53] op_sel_hi:[1,0]
	v_lshl_add_u64 v[14:15], v[14:15], 0, v[158:159]
	v_cvt_pk_bf16_f32 v12, v18, v19
	v_cvt_pk_bf16_f32 v13, v20, v21
	v_lshl_add_u64 v[14:15], v[14:15], 0, v[122:123]
	global_store_dwordx4 v[14:15], v[10:13], off nt
	s_nop 1
	v_pk_mul_f32 v[10:11], v[2:3], s[52:53] op_sel_hi:[1,0]
	v_cvt_pk_bf16_f32 v2, v6, v7
	v_add_u32_e32 v6, v23, v120
	v_ashrrev_i32_e32 v7, 31, v6
	v_lshlrev_b64 v[6:7], 19, v[6:7]
	v_lshl_add_u64 v[6:7], s[34:35], 0, v[6:7]
	v_pk_mul_f32 v[12:13], v[4:5], s[52:53] op_sel_hi:[1,0]
	v_lshl_add_u64 v[6:7], v[6:7], 0, v[158:159]
	v_cvt_pk_bf16_f32 v3, v8, v9
	v_cvt_pk_bf16_f32 v4, v10, v11
	v_cvt_pk_bf16_f32 v5, v12, v13
	v_lshl_add_u64 v[6:7], v[6:7], 0, v[122:123]
	global_store_dwordx4 v[6:7], v[2:5], off nt
	s_branch .LBB0_130

.LBB0_189:
	v_lshl_add_u64 v[28:29], s[8:9], 0, v[148:149]
	v_lshl_add_u64 v[36:37], s[10:11], 0, v[148:149]
	global_load_dwordx4 v[8:11], v[28:29], off nt
	global_load_dwordx4 v[12:15], v[28:29], off offset:1024 nt
	global_load_dwordx4 v[16:19], v[36:37], off nt
	global_load_dwordx4 v[20:23], v[36:37], off offset:1024 nt
	global_load_dwordx4 v[24:27], v[28:29], off offset:2048 nt
	s_nop 0
	global_load_dwordx4 v[28:31], v[28:29], off offset:3072 nt
	s_nop 0
	global_load_dwordx4 v[32:35], v[36:37], off offset:2048 nt
	s_nop 0
	global_load_dwordx4 v[36:39], v[36:37], off offset:3072 nt
	s_add_i32 s3, s3, 16
	v_lshl_add_u64 v[42:43], s[6:7], 0, v[146:147]
	s_add_u32 s6, s6, 0x8000
	s_addc_u32 s7, s7, 0
	s_add_u32 s8, s8, 0x10000
	s_addc_u32 s9, s9, 0
	s_add_u32 s10, s10, 0x10000
	s_addc_u32 s11, s11, 0
	v_lshl_add_u64 v[40:41], s[14:15], 0, v[146:147]
	s_add_u32 s14, s14, 0x8000
	s_addc_u32 s15, s15, 0
	s_cmp_lt_i32 s3, s2
	s_waitcnt vmcnt(0)
	v_mov_b32_e32 v46, v9
	v_mov_b32_e32 v47, v13
	v_mov_b32_e32 v54, v17
	v_mov_b32_e32 v55, v21
	v_mov_b32_e32 v44, v8
	v_mov_b32_e32 v45, v12
	v_mov_b32_e32 v52, v16
	v_mov_b32_e32 v53, v20
	v_mov_b32_e32 v62, v25
	v_mov_b32_e32 v63, v29
	v_mov_b32_e32 v70, v33
	v_mov_b32_e32 v71, v37
	v_pk_mul_f32 v[46:47], v[46:47], v[46:47]
	v_pk_mul_f32 v[54:55], v[54:55], v[54:55]
	v_mov_b32_e32 v48, v10
	v_mov_b32_e32 v49, v14
	v_mov_b32_e32 v56, v18
	v_mov_b32_e32 v57, v22
	v_mov_b32_e32 v60, v24
	v_mov_b32_e32 v61, v28
	v_mov_b32_e32 v68, v32
	v_mov_b32_e32 v69, v36
	v_pk_mul_f32 v[62:63], v[62:63], v[62:63]
	v_pk_mul_f32 v[70:71], v[70:71], v[70:71]
	v_pk_fma_f32 v[44:45], v[44:45], v[44:45], v[46:47]
	v_pk_fma_f32 v[46:47], v[52:53], v[52:53], v[54:55]
	v_mov_b32_e32 v50, v11
	v_mov_b32_e32 v51, v15
	v_mov_b32_e32 v58, v19
	v_mov_b32_e32 v59, v23
	v_mov_b32_e32 v64, v26
	v_mov_b32_e32 v65, v30
	v_mov_b32_e32 v72, v34
	v_mov_b32_e32 v73, v38
	v_pk_fma_f32 v[52:53], v[60:61], v[60:61], v[62:63]
	v_pk_fma_f32 v[54:55], v[68:69], v[68:69], v[70:71]
	v_pk_fma_f32 v[44:45], v[48:49], v[48:49], v[44:45]
	v_pk_fma_f32 v[46:47], v[56:57], v[56:57], v[46:47]
	v_mov_b32_e32 v66, v27
	v_mov_b32_e32 v67, v31
	v_mov_b32_e32 v74, v35
	v_mov_b32_e32 v75, v39
	v_pk_fma_f32 v[48:49], v[64:65], v[64:65], v[52:53]
	v_pk_fma_f32 v[52:53], v[72:73], v[72:73], v[54:55]
	v_pk_fma_f32 v[44:45], v[50:51], v[50:51], v[44:45]
	v_pk_fma_f32 v[46:47], v[58:59], v[58:59], v[46:47]
	v_pk_fma_f32 v[48:49], v[66:67], v[66:67], v[48:49]
	v_pk_fma_f32 v[50:51], v[74:75], v[74:75], v[52:53]
	v_mov_b32_e32 v52, v46
	v_mov_b32_e32 v53, v44
	v_mov_b32_e32 v44, v47
	v_mov_b32_e32 v46, v50
	v_mov_b32_e32 v47, v48
	v_pk_add_f32 v[44:45], v[52:53], v[44:45]
	v_mov_b32_e32 v48, v51
	v_pk_add_f32 v[44:45], v[44:45], v[46:47]
	s_nop 0
	v_pk_add_f32 v[44:45], v[44:45], v[48:49]
	ds_bpermute_b32 v47, v1, v45
	ds_bpermute_b32 v46, v1, v44
	s_waitcnt lgkmcnt(0)
	v_pk_add_f32 v[44:45], v[44:45], v[46:47]
	ds_bpermute_b32 v47, v3, v45
	ds_bpermute_b32 v46, v3, v44
	s_waitcnt lgkmcnt(0)
	v_pk_add_f32 v[44:45], v[44:45], v[46:47]
	ds_bpermute_b32 v47, v4, v45
	ds_bpermute_b32 v46, v4, v44
	s_waitcnt lgkmcnt(0)
	v_pk_add_f32 v[44:45], v[44:45], v[46:47]
	ds_bpermute_b32 v47, v5, v45
	ds_bpermute_b32 v46, v5, v44
	s_waitcnt lgkmcnt(0)
	v_pk_add_f32 v[44:45], v[44:45], v[46:47]
	ds_bpermute_b32 v47, v6, v45
	ds_bpermute_b32 v46, v6, v44
	s_waitcnt lgkmcnt(0)
	v_pk_add_f32 v[44:45], v[44:45], v[46:47]
	ds_bpermute_b32 v47, v7, v45
	ds_bpermute_b32 v46, v7, v44
	s_waitcnt lgkmcnt(0)
	v_pk_add_f32 v[44:45], v[44:45], v[46:47]
	s_nop 0
	v_pk_fma_f32 v[44:45], v[44:45], s[18:19], v[2:3] op_sel_hi:[1,0,0]
	s_nop 0
	v_mul_f32_e32 v46, 0x4b800000, v45
	v_cmp_gt_f32_e64 s[0:1], s4, v45
	v_mul_f32_e32 v47, 0x4b800000, v44
	v_cmp_gt_f32_e32 vcc, s4, v44
	v_cndmask_b32_e64 v45, v45, v46, s[0:1]
	v_rsq_f32_e32 v45, v45
	v_cndmask_b32_e32 v44, v44, v47, vcc
	v_rsq_f32_e32 v46, v44
	v_mul_f32_e32 v44, 0x45800000, v45
	v_cndmask_b32_e64 v44, v45, v44, s[0:1]
	v_mul_f32_e32 v47, 0x45800000, v46
	v_cndmask_b32_e32 v46, v46, v47, vcc
	v_pk_mul_f32 v[8:9], v[8:9], v[44:45] op_sel_hi:[1,0]
	v_pk_mul_f32 v[10:11], v[10:11], v[44:45] op_sel_hi:[1,0]
	v_pk_mul_f32 v[16:17], v[16:17], v[46:47] op_sel_hi:[1,0]
	v_pk_mul_f32 v[18:19], v[18:19], v[46:47] op_sel_hi:[1,0]
	v_pk_mul_f32 v[12:13], v[12:13], v[44:45] op_sel_hi:[1,0]
	v_pk_mul_f32 v[14:15], v[14:15], v[44:45] op_sel_hi:[1,0]
	v_pk_mul_f32 v[20:21], v[20:21], v[46:47] op_sel_hi:[1,0]
	v_pk_mul_f32 v[22:23], v[22:23], v[46:47] op_sel_hi:[1,0]
	v_pk_mul_f32 v[24:25], v[24:25], v[44:45] op_sel_hi:[1,0]
	v_pk_mul_f32 v[26:27], v[26:27], v[44:45] op_sel_hi:[1,0]
	v_pk_mul_f32 v[32:33], v[32:33], v[46:47] op_sel_hi:[1,0]
	v_pk_mul_f32 v[34:35], v[34:35], v[46:47] op_sel_hi:[1,0]
	v_pk_mul_f32 v[28:29], v[28:29], v[44:45] op_sel_hi:[1,0]
	v_pk_mul_f32 v[30:31], v[30:31], v[44:45] op_sel_hi:[1,0]
	v_pk_mul_f32 v[36:37], v[36:37], v[46:47] op_sel_hi:[1,0]
	v_pk_mul_f32 v[38:39], v[38:39], v[46:47] op_sel_hi:[1,0]
	v_cvt_pk_bf16_f32 v8, v8, v9
	v_cvt_pk_bf16_f32 v9, v10, v11
	v_cvt_pk_bf16_f32 v10, v16, v17
	v_cvt_pk_bf16_f32 v11, v18, v19
	v_cvt_pk_bf16_f32 v12, v12, v13
	v_cvt_pk_bf16_f32 v13, v14, v15
	v_cvt_pk_bf16_f32 v14, v20, v21
	v_cvt_pk_bf16_f32 v15, v22, v23
	v_cvt_pk_bf16_f32 v16, v24, v25
	v_cvt_pk_bf16_f32 v17, v26, v27
	v_cvt_pk_bf16_f32 v18, v32, v33
	v_cvt_pk_bf16_f32 v19, v34, v35
	v_cvt_pk_bf16_f32 v20, v28, v29
	v_cvt_pk_bf16_f32 v21, v30, v31
	v_cvt_pk_bf16_f32 v22, v36, v37
	v_cvt_pk_bf16_f32 v23, v38, v39
	global_store_dwordx2 v[40:41], v[8:9], off
	global_store_dwordx2 v[42:43], v[10:11], off
	global_store_dwordx2 v[40:41], v[12:13], off offset:512
	global_store_dwordx2 v[42:43], v[14:15], off offset:512
	global_store_dwordx2 v[40:41], v[16:17], off offset:1024
	global_store_dwordx2 v[42:43], v[18:19], off offset:1024
	global_store_dwordx2 v[40:41], v[20:21], off offset:1536
	global_store_dwordx2 v[42:43], v[22:23], off offset:1536
	s_cbranch_scc1 .LBB0_189

.LBB0_281:
	ds_read_b128 v[130:133], v167
	ds_read_b128 v[134:137], v167 offset:1024
	ds_read_b128 v[138:141], v167 offset:2048
	ds_read_b128 v[142:145], v167 offset:3072
	s_add_u32 s43, s44, 0xfffc0080
	s_addc_u32 s46, s45, -1
	s_cmp_eq_u32 s41, 12
	s_cselect_b32 s49, s9, s46
	s_cselect_b32 s48, s8, s43
	s_cselect_b32 s47, s7, s3
	s_cselect_b32 s46, s6, s2
	v_lshl_add_u64 v[200:201], s[44:45], 0, v[158:159]
	s_add_i32 m0, s53, 0xc000
	ds_read_b128 v[162:165], v169
	ds_read_b128 v[172:175], v169 offset:1024
	ds_read_b128 v[176:179], v169 offset:2048
	ds_read_b128 v[180:183], v169 offset:3072
	ds_read_b128 v[184:187], v169 offset:4096
	ds_read_b128 v[188:191], v169 offset:5120
	ds_read_b128 v[192:195], v169 offset:6144
	ds_read_b128 v[196:199], v169 offset:7168
	global_load_lds_dwordx4 v[200:201], off
	v_lshl_add_u64 v[200:201], s[44:45], 0, v[160:161]
	s_add_i32 m0, s53, 0xe000
	s_nop 0
	global_load_lds_dwordx4 v[200:201], off
	s_waitcnt lgkmcnt(8)
	s_barrier
	s_waitcnt lgkmcnt(0)
	s_setprio 1
	s_waitcnt lgkmcnt(0)
	v_mfma_f32_16x16x32_bf16 v[126:129], v[130:133], v[162:165], v[126:129]
	v_mfma_f32_16x16x32_bf16 v[122:125], v[138:141], v[162:165], v[122:125]
	v_mfma_f32_16x16x32_bf16 v[114:117], v[130:133], v[176:179], v[114:117]
	v_mfma_f32_16x16x32_bf16 v[106:109], v[138:141], v[176:179], v[106:109]
	v_mfma_f32_16x16x32_bf16 v[98:101], v[130:133], v[184:187], v[98:101]
	v_mfma_f32_16x16x32_bf16 v[90:93], v[138:141], v[184:187], v[90:93]
	v_mfma_f32_16x16x32_bf16 v[82:85], v[130:133], v[192:195], v[82:85]
	v_mfma_f32_16x16x32_bf16 v[74:77], v[138:141], v[192:195], v[74:77]
	v_mfma_f32_16x16x32_bf16 v[126:129], v[134:137], v[172:175], v[126:129]
	v_mfma_f32_16x16x32_bf16 v[122:125], v[142:145], v[172:175], v[122:125]
	v_mfma_f32_16x16x32_bf16 v[114:117], v[134:137], v[180:183], v[114:117]
	v_mfma_f32_16x16x32_bf16 v[106:109], v[142:145], v[180:183], v[106:109]
	v_mfma_f32_16x16x32_bf16 v[98:101], v[134:137], v[188:191], v[98:101]
	v_mfma_f32_16x16x32_bf16 v[90:93], v[142:145], v[188:191], v[90:93]
	v_mfma_f32_16x16x32_bf16 v[82:85], v[134:137], v[196:199], v[82:85]
	v_mfma_f32_16x16x32_bf16 v[74:77], v[142:145], v[196:199], v[74:77]
	s_setprio 0
	s_barrier
	s_add_i32 s43, s67, s52
	v_lshl_add_u64 v[216:217], s[46:47], 0, v[150:151]
	s_mov_b32 m0, s43
	ds_read_b128 v[200:203], v170
	ds_read_b128 v[204:207], v170 offset:1024
	ds_read_b128 v[208:211], v170 offset:2048
	ds_read_b128 v[212:215], v170 offset:3072
	global_load_lds_dwordx4 v[216:217], off
	v_lshl_add_u64 v[218:219], s[46:47], 0, v[154:155]
	s_add_i32 m0, s43, 0x2000
	s_nop 0
	global_load_lds_dwordx4 v[218:219], off
	s_barrier
	s_waitcnt lgkmcnt(0)
	s_setprio 1
	s_waitcnt lgkmcnt(0)
	v_mfma_f32_16x16x32_bf16 v[118:121], v[200:203], v[162:165], v[118:121]
	v_mfma_f32_16x16x32_bf16 v[110:113], v[208:211], v[162:165], v[110:113]
	v_mfma_f32_16x16x32_bf16 v[102:105], v[200:203], v[176:179], v[102:105]
	v_mfma_f32_16x16x32_bf16 v[94:97], v[208:211], v[176:179], v[94:97]
	v_mfma_f32_16x16x32_bf16 v[86:89], v[200:203], v[184:187], v[86:89]
	v_mfma_f32_16x16x32_bf16 v[78:81], v[208:211], v[184:187], v[78:81]
	v_mfma_f32_16x16x32_bf16 v[70:73], v[200:203], v[192:195], v[70:73]
	v_mfma_f32_16x16x32_bf16 v[66:69], v[208:211], v[192:195], v[66:69]
	v_mfma_f32_16x16x32_bf16 v[118:121], v[204:207], v[172:175], v[118:121]
	v_mfma_f32_16x16x32_bf16 v[110:113], v[212:215], v[172:175], v[110:113]
	v_mfma_f32_16x16x32_bf16 v[102:105], v[204:207], v[180:183], v[102:105]
	v_mfma_f32_16x16x32_bf16 v[94:97], v[212:215], v[180:183], v[94:97]
	v_mfma_f32_16x16x32_bf16 v[86:89], v[204:207], v[188:191], v[86:89]
	v_mfma_f32_16x16x32_bf16 v[78:81], v[212:215], v[188:191], v[78:81]
	v_mfma_f32_16x16x32_bf16 v[70:73], v[204:207], v[196:199], v[70:73]
	v_mfma_f32_16x16x32_bf16 v[66:69], v[212:215], v[196:199], v[66:69]
	s_setprio 0
	s_mov_b32 m0, s53
	v_lshl_add_u64 v[220:221], s[48:49], 0, v[148:149]
	s_barrier
	ds_read_b128 v[162:165], v169 offset:16384
	ds_read_b128 v[172:175], v169 offset:17408
	ds_read_b128 v[176:179], v169 offset:18432
	ds_read_b128 v[180:183], v169 offset:19456
	ds_read_b128 v[184:187], v169 offset:20480
	ds_read_b128 v[188:191], v169 offset:21504
	ds_read_b128 v[192:195], v169 offset:22528
	ds_read_b128 v[196:199], v169 offset:23552
	global_load_lds_dwordx4 v[220:221], off
	v_lshl_add_u64 v[222:223], s[48:49], 0, v[152:153]
	s_mov_b32 m0, s54
	s_nop 0
	global_load_lds_dwordx4 v[222:223], off
	s_barrier
	s_waitcnt lgkmcnt(0)
	s_setprio 1
	s_waitcnt lgkmcnt(0)
	v_mfma_f32_16x16x32_bf16 v[62:65], v[130:133], v[162:165], v[62:65]
	v_mfma_f32_16x16x32_bf16 v[58:61], v[138:141], v[162:165], v[58:61]
	v_mfma_f32_16x16x32_bf16 v[50:53], v[130:133], v[176:179], v[50:53]
	v_mfma_f32_16x16x32_bf16 v[42:45], v[138:141], v[176:179], v[42:45]
	v_mfma_f32_16x16x32_bf16 v[34:37], v[130:133], v[184:187], v[34:37]
	v_mfma_f32_16x16x32_bf16 v[26:29], v[138:141], v[184:187], v[26:29]
	v_mfma_f32_16x16x32_bf16 v[18:21], v[130:133], v[192:195], v[18:21]
	v_mfma_f32_16x16x32_bf16 v[10:13], v[138:141], v[192:195], v[10:13]
	v_mfma_f32_16x16x32_bf16 v[62:65], v[134:137], v[172:175], v[62:65]
	v_mfma_f32_16x16x32_bf16 v[58:61], v[142:145], v[172:175], v[58:61]
	v_mfma_f32_16x16x32_bf16 v[50:53], v[134:137], v[180:183], v[50:53]
	v_mfma_f32_16x16x32_bf16 v[42:45], v[142:145], v[180:183], v[42:45]
	v_mfma_f32_16x16x32_bf16 v[34:37], v[134:137], v[188:191], v[34:37]
	v_mfma_f32_16x16x32_bf16 v[26:29], v[142:145], v[188:191], v[26:29]
	v_mfma_f32_16x16x32_bf16 v[18:21], v[134:137], v[196:199], v[18:21]
	v_mfma_f32_16x16x32_bf16 v[10:13], v[142:145], v[196:199], v[10:13]
	s_setprio 0
	s_barrier
	s_add_u32 s50, s46, 0x40000
	s_addc_u32 s51, s47, 0
	s_add_i32 s43, s68, s52
	v_lshl_add_u64 v[130:131], s[50:51], 0, v[150:151]
	s_mov_b32 m0, s43
	s_nop 0
	global_load_lds_dwordx4 v[130:131], off
	v_lshl_add_u64 v[130:131], s[50:51], 0, v[154:155]
	s_add_i32 m0, s43, 0x2000
	s_nop 0
	global_load_lds_dwordx4 v[130:131], off
	s_waitcnt vmcnt(6)
	s_barrier
	s_setprio 1
	v_mfma_f32_16x16x32_bf16 v[54:57], v[200:203], v[162:165], v[54:57]
	v_mfma_f32_16x16x32_bf16 v[46:49], v[208:211], v[162:165], v[46:49]
	v_mfma_f32_16x16x32_bf16 v[38:41], v[200:203], v[176:179], v[38:41]
	v_mfma_f32_16x16x32_bf16 v[30:33], v[208:211], v[176:179], v[30:33]
	v_mfma_f32_16x16x32_bf16 v[22:25], v[200:203], v[184:187], v[22:25]
	v_mfma_f32_16x16x32_bf16 v[14:17], v[208:211], v[184:187], v[14:17]
	v_mfma_f32_16x16x32_bf16 v[6:9], v[200:203], v[192:195], v[6:9]
	v_mfma_f32_16x16x32_bf16 v[2:5], v[208:211], v[192:195], v[2:5]
	v_mfma_f32_16x16x32_bf16 v[54:57], v[204:207], v[172:175], v[54:57]
	v_mfma_f32_16x16x32_bf16 v[46:49], v[212:215], v[172:175], v[46:49]
	v_mfma_f32_16x16x32_bf16 v[38:41], v[204:207], v[180:183], v[38:41]
	v_mfma_f32_16x16x32_bf16 v[30:33], v[212:215], v[180:183], v[30:33]
	v_mfma_f32_16x16x32_bf16 v[22:25], v[204:207], v[188:191], v[22:25]
	v_mfma_f32_16x16x32_bf16 v[14:17], v[212:215], v[188:191], v[14:17]
	v_mfma_f32_16x16x32_bf16 v[6:9], v[204:207], v[196:199], v[6:9]
	v_mfma_f32_16x16x32_bf16 v[2:5], v[212:215], v[196:199], v[2:5]
	s_setprio 0
	s_add_i32 s43, 0, 0x18000
	v_add_u32_e32 v142, s43, v166
	s_barrier
	ds_read_b128 v[130:133], v142
	ds_read_b128 v[134:137], v142 offset:1024
	ds_read_b128 v[138:141], v142 offset:2048
	ds_read_b128 v[142:145], v142 offset:3072
	s_add_u32 s48, s48, 0x40000
	s_addc_u32 s49, s49, 0
	s_mov_b32 m0, s55
	v_lshl_add_u64 v[200:201], s[48:49], 0, v[148:149]
	ds_read_b128 v[162:165], v169 offset:32768
	ds_read_b128 v[172:175], v169 offset:33792
	ds_read_b128 v[176:179], v169 offset:34816
	ds_read_b128 v[180:183], v169 offset:35840
	ds_read_b128 v[184:187], v169 offset:36864
	ds_read_b128 v[188:191], v169 offset:37888
	ds_read_b128 v[192:195], v169 offset:38912
	ds_read_b128 v[196:199], v169 offset:39936
	global_load_lds_dwordx4 v[200:201], off
	v_lshl_add_u64 v[200:201], s[48:49], 0, v[152:153]
	s_mov_b32 m0, s56
	s_nop 0
	global_load_lds_dwordx4 v[200:201], off
	s_waitcnt lgkmcnt(8)
	s_barrier
	s_waitcnt lgkmcnt(0)
	s_setprio 1
	s_waitcnt lgkmcnt(0)
	v_mfma_f32_16x16x32_bf16 v[126:129], v[130:133], v[162:165], v[126:129]
	v_mfma_f32_16x16x32_bf16 v[122:125], v[138:141], v[162:165], v[122:125]
	v_mfma_f32_16x16x32_bf16 v[114:117], v[130:133], v[176:179], v[114:117]
	v_mfma_f32_16x16x32_bf16 v[106:109], v[138:141], v[176:179], v[106:109]
	v_mfma_f32_16x16x32_bf16 v[98:101], v[130:133], v[184:187], v[98:101]
	v_mfma_f32_16x16x32_bf16 v[90:93], v[138:141], v[184:187], v[90:93]
	v_mfma_f32_16x16x32_bf16 v[82:85], v[130:133], v[192:195], v[82:85]
	v_mfma_f32_16x16x32_bf16 v[74:77], v[138:141], v[192:195], v[74:77]
	v_mfma_f32_16x16x32_bf16 v[126:129], v[134:137], v[172:175], v[126:129]
	v_mfma_f32_16x16x32_bf16 v[122:125], v[142:145], v[172:175], v[122:125]
	v_mfma_f32_16x16x32_bf16 v[114:117], v[134:137], v[180:183], v[114:117]
	v_mfma_f32_16x16x32_bf16 v[106:109], v[142:145], v[180:183], v[106:109]
	v_mfma_f32_16x16x32_bf16 v[98:101], v[134:137], v[188:191], v[98:101]
	v_mfma_f32_16x16x32_bf16 v[90:93], v[142:145], v[188:191], v[90:93]
	v_mfma_f32_16x16x32_bf16 v[82:85], v[134:137], v[196:199], v[82:85]
	v_mfma_f32_16x16x32_bf16 v[74:77], v[142:145], v[196:199], v[74:77]
	s_setprio 0
	s_barrier
	s_add_i32 s48, 0, 0x1c000
	s_add_i32 s43, s43, s52
	v_add_u32_e32 v156, s48, v166
	v_lshl_add_u64 v[216:217], v[216:217], 0, s[10:11]
	s_mov_b32 m0, s43
	ds_read_b128 v[200:203], v156
	ds_read_b128 v[204:207], v156 offset:1024
	ds_read_b128 v[208:211], v156 offset:2048
	ds_read_b128 v[212:215], v156 offset:3072
	global_load_lds_dwordx4 v[216:217], off
	v_lshl_add_u64 v[216:217], v[218:219], 0, s[10:11]
	s_add_i32 m0, s43, 0x2000
	s_nop 0
	global_load_lds_dwordx4 v[216:217], off
	s_barrier
	s_waitcnt lgkmcnt(0)
	s_setprio 1
	s_waitcnt lgkmcnt(0)
	v_mfma_f32_16x16x32_bf16 v[118:121], v[200:203], v[162:165], v[118:121]
	v_mfma_f32_16x16x32_bf16 v[110:113], v[208:211], v[162:165], v[110:113]
	v_mfma_f32_16x16x32_bf16 v[102:105], v[200:203], v[176:179], v[102:105]
	v_mfma_f32_16x16x32_bf16 v[94:97], v[208:211], v[176:179], v[94:97]
	v_mfma_f32_16x16x32_bf16 v[86:89], v[200:203], v[184:187], v[86:89]
	v_mfma_f32_16x16x32_bf16 v[78:81], v[208:211], v[184:187], v[78:81]
	v_mfma_f32_16x16x32_bf16 v[70:73], v[200:203], v[192:195], v[70:73]
	v_mfma_f32_16x16x32_bf16 v[66:69], v[208:211], v[192:195], v[66:69]
	v_mfma_f32_16x16x32_bf16 v[118:121], v[204:207], v[172:175], v[118:121]
	v_mfma_f32_16x16x32_bf16 v[110:113], v[212:215], v[172:175], v[110:113]
	v_mfma_f32_16x16x32_bf16 v[102:105], v[204:207], v[180:183], v[102:105]
	v_mfma_f32_16x16x32_bf16 v[94:97], v[212:215], v[180:183], v[94:97]
	v_mfma_f32_16x16x32_bf16 v[86:89], v[204:207], v[188:191], v[86:89]
	v_mfma_f32_16x16x32_bf16 v[78:81], v[212:215], v[188:191], v[78:81]
	v_mfma_f32_16x16x32_bf16 v[70:73], v[204:207], v[196:199], v[70:73]
	v_mfma_f32_16x16x32_bf16 v[66:69], v[212:215], v[196:199], v[66:69]
	s_setprio 0
	s_mov_b32 m0, s60
	v_lshl_add_u64 v[216:217], v[220:221], 0, s[10:11]
	s_barrier
	ds_read_b128 v[162:165], v169 offset:49152
	ds_read_b128 v[172:175], v169 offset:50176
	ds_read_b128 v[176:179], v169 offset:51200
	ds_read_b128 v[180:183], v169 offset:52224
	ds_read_b128 v[184:187], v169 offset:53248
	ds_read_b128 v[188:191], v169 offset:54272
	ds_read_b128 v[192:195], v169 offset:55296
	ds_read_b128 v[196:199], v169 offset:56320
	global_load_lds_dwordx4 v[216:217], off
	v_lshl_add_u64 v[216:217], v[222:223], 0, s[10:11]
	s_mov_b32 m0, s61
	s_nop 0
	global_load_lds_dwordx4 v[216:217], off
	s_barrier
	s_waitcnt lgkmcnt(0)
	s_setprio 1
	s_waitcnt lgkmcnt(0)
	v_mfma_f32_16x16x32_bf16 v[62:65], v[130:133], v[162:165], v[62:65]
	v_mfma_f32_16x16x32_bf16 v[58:61], v[138:141], v[162:165], v[58:61]
	v_mfma_f32_16x16x32_bf16 v[50:53], v[130:133], v[176:179], v[50:53]
	v_mfma_f32_16x16x32_bf16 v[42:45], v[138:141], v[176:179], v[42:45]
	v_mfma_f32_16x16x32_bf16 v[34:37], v[130:133], v[184:187], v[34:37]
	v_mfma_f32_16x16x32_bf16 v[26:29], v[138:141], v[184:187], v[26:29]
	v_mfma_f32_16x16x32_bf16 v[18:21], v[130:133], v[192:195], v[18:21]
	v_mfma_f32_16x16x32_bf16 v[10:13], v[138:141], v[192:195], v[10:13]
	v_mfma_f32_16x16x32_bf16 v[62:65], v[134:137], v[172:175], v[62:65]
	v_mfma_f32_16x16x32_bf16 v[58:61], v[142:145], v[172:175], v[58:61]
	v_mfma_f32_16x16x32_bf16 v[50:53], v[134:137], v[180:183], v[50:53]
	v_mfma_f32_16x16x32_bf16 v[42:45], v[142:145], v[180:183], v[42:45]
	v_mfma_f32_16x16x32_bf16 v[34:37], v[134:137], v[188:191], v[34:37]
	v_mfma_f32_16x16x32_bf16 v[26:29], v[142:145], v[188:191], v[26:29]
	v_mfma_f32_16x16x32_bf16 v[18:21], v[134:137], v[196:199], v[18:21]
	v_mfma_f32_16x16x32_bf16 v[10:13], v[142:145], v[196:199], v[10:13]
	s_setprio 0
	s_barrier
	s_add_u32 s46, s46, 0x40080
	s_addc_u32 s47, s47, 0
	s_add_i32 s43, s48, s52
	v_lshl_add_u64 v[130:131], s[46:47], 0, v[150:151]
	s_mov_b32 m0, s43
	s_nop 0
	global_load_lds_dwordx4 v[130:131], off
	v_lshl_add_u64 v[130:131], s[46:47], 0, v[154:155]
	s_add_i32 m0, s43, 0x2000
	s_nop 0
	global_load_lds_dwordx4 v[130:131], off
	s_waitcnt vmcnt(6)
	s_barrier
	s_setprio 1
	v_mfma_f32_16x16x32_bf16 v[54:57], v[200:203], v[162:165], v[54:57]
	v_mfma_f32_16x16x32_bf16 v[46:49], v[208:211], v[162:165], v[46:49]
	v_mfma_f32_16x16x32_bf16 v[38:41], v[200:203], v[176:179], v[38:41]
	v_mfma_f32_16x16x32_bf16 v[30:33], v[208:211], v[176:179], v[30:33]
	v_mfma_f32_16x16x32_bf16 v[22:25], v[200:203], v[184:187], v[22:25]
	v_mfma_f32_16x16x32_bf16 v[14:17], v[208:211], v[184:187], v[14:17]
	v_mfma_f32_16x16x32_bf16 v[6:9], v[200:203], v[192:195], v[6:9]
	v_mfma_f32_16x16x32_bf16 v[2:5], v[208:211], v[192:195], v[2:5]
	v_mfma_f32_16x16x32_bf16 v[54:57], v[204:207], v[172:175], v[54:57]
	v_mfma_f32_16x16x32_bf16 v[46:49], v[212:215], v[172:175], v[46:49]
	v_mfma_f32_16x16x32_bf16 v[38:41], v[204:207], v[180:183], v[38:41]
	v_mfma_f32_16x16x32_bf16 v[30:33], v[212:215], v[180:183], v[30:33]
	v_mfma_f32_16x16x32_bf16 v[22:25], v[204:207], v[188:191], v[22:25]
	v_mfma_f32_16x16x32_bf16 v[14:17], v[212:215], v[188:191], v[14:17]
	v_mfma_f32_16x16x32_bf16 v[6:9], v[204:207], v[196:199], v[6:9]
	v_mfma_f32_16x16x32_bf16 v[2:5], v[212:215], v[196:199], v[2:5]
	s_setprio 0
	s_add_i32 s41, s41, 2
	s_add_u32 s44, s44, 0x100
	s_addc_u32 s45, s45, 0
	s_add_u32 s2, s2, 0x100
	s_addc_u32 s3, s3, 0
	s_cmp_gt_u32 s41, 13
	s_barrier
	s_cbranch_scc0 .LBB0_281
	v_mov_b32_e32 v130, v147
	v_mov_b32_e32 v171, v1
	s_ashr_i32 s41, s66, 1
	s_mov_b64 s[48:49], -1
	v_lshlrev_b32_e32 v173, 3, v130
	s_mov_b64 s[46:47], 0
	s_cmp_lt_i32 s41, 4
	s_mov_b64 s[44:45], 0
	s_cbranch_scc1 .LBB0_297
	s_cmp_gt_i32 s41, 5
	s_cbranch_scc0 .LBB0_291
	s_cmp_gt_i32 s41, 6
	s_cbranch_scc0 .LBB0_288
	s_cmp_eq_u32 s41, 7
	s_mov_b64 s[44:45], -1
	s_cbranch_scc0 .LBB0_287
	s_lshl_b32 s2, s33, 8
	s_or_b32 s2, s2, s59
	v_add_u32_e32 v140, s2, v173
	v_add_u32_e32 v130, 0x8000, v140
	s_lshl_b32 s2, s66, 8
	v_ashrrev_i32_e32 v130, 3, v130
	s_and_b32 s2, s2, 0x100
	v_and_b32_e32 v130, 0xfffffe00, v130
	s_add_i32 s2, s2, s58
	v_add3_u32 v134, s2, v171, v130
	v_ashrrev_i32_e32 v135, 31, v134
	v_lshlrev_b64 v[136:137], 13, v[134:135]
	v_and_b32_e32 v135, 0xff8, v140
	v_lshl_add_u64 v[136:137], s[14:15], 0, v[136:137]
	v_lshlrev_b32_e32 v156, 1, v135
	v_cvt_pk_bf16_f32 v130, v126, v127
	v_cvt_pk_bf16_f32 v131, v128, v129
	v_cvt_pk_bf16_f32 v132, v122, v123
	v_cvt_pk_bf16_f32 v133, v124, v125
	v_lshl_add_u64 v[138:139], v[136:137], 0, v[156:157]
	global_store_dwordx4 v[138:139], v[130:133], off nt
	v_mov_b32_e32 v139, v157
	s_mov_b64 s[44:45], 0
	v_add_u32_e32 v130, 0x80, v140
	v_and_b32_e32 v135, 0xff8, v130
	v_lshlrev_b32_e32 v138, 1, v135
	v_cvt_pk_bf16_f32 v130, v118, v119
	v_cvt_pk_bf16_f32 v131, v120, v121
	v_cvt_pk_bf16_f32 v132, v110, v111
	v_cvt_pk_bf16_f32 v133, v112, v113
	v_lshl_add_u64 v[136:137], v[136:137], 0, v[138:139]
	global_store_dwordx4 v[136:137], v[130:133], off nt
	s_nop 1
	v_add_u32_e32 v130, 16, v134
	v_ashrrev_i32_e32 v131, 31, v130
	v_lshlrev_b64 v[136:137], 13, v[130:131]
	v_lshl_add_u64 v[136:137], s[14:15], 0, v[136:137]
	v_cvt_pk_bf16_f32 v130, v114, v115
	v_cvt_pk_bf16_f32 v131, v116, v117
	v_cvt_pk_bf16_f32 v132, v106, v107
	v_cvt_pk_bf16_f32 v133, v108, v109
	v_lshl_add_u64 v[140:141], v[136:137], 0, v[156:157]
	global_store_dwordx4 v[140:141], v[130:133], off nt
	v_lshl_add_u64 v[136:137], v[136:137], 0, v[138:139]
	s_nop 0
	v_cvt_pk_bf16_f32 v130, v102, v103
	v_cvt_pk_bf16_f32 v131, v104, v105
	v_cvt_pk_bf16_f32 v132, v94, v95
	v_cvt_pk_bf16_f32 v133, v96, v97
	global_store_dwordx4 v[136:137], v[130:133], off nt
	s_nop 1
	v_add_u32_e32 v130, 32, v134
	v_ashrrev_i32_e32 v131, 31, v130
	v_lshlrev_b64 v[136:137], 13, v[130:131]
	v_lshl_add_u64 v[136:137], s[14:15], 0, v[136:137]
	v_cvt_pk_bf16_f32 v130, v98, v99
	v_cvt_pk_bf16_f32 v131, v100, v101
	v_cvt_pk_bf16_f32 v132, v90, v91
	v_cvt_pk_bf16_f32 v133, v92, v93
	v_lshl_add_u64 v[140:141], v[136:137], 0, v[156:157]
	global_store_dwordx4 v[140:141], v[130:133], off nt
	v_lshl_add_u64 v[136:137], v[136:137], 0, v[138:139]
	s_nop 0
	v_cvt_pk_bf16_f32 v130, v86, v87
	v_cvt_pk_bf16_f32 v131, v88, v89
	v_cvt_pk_bf16_f32 v132, v78, v79
	v_cvt_pk_bf16_f32 v133, v80, v81
	global_store_dwordx4 v[136:137], v[130:133], off nt
	s_nop 1
	v_add_u32_e32 v130, 48, v134
	v_ashrrev_i32_e32 v131, 31, v130
	v_lshlrev_b64 v[136:137], 13, v[130:131]
	v_lshl_add_u64 v[136:137], s[14:15], 0, v[136:137]
	v_cvt_pk_bf16_f32 v130, v82, v83
	v_cvt_pk_bf16_f32 v131, v84, v85
	v_cvt_pk_bf16_f32 v132, v74, v75
	v_cvt_pk_bf16_f32 v133, v76, v77
	v_lshl_add_u64 v[140:141], v[136:137], 0, v[156:157]
	global_store_dwordx4 v[140:141], v[130:133], off nt
	v_lshl_add_u64 v[136:137], v[136:137], 0, v[138:139]
	s_nop 0
	v_cvt_pk_bf16_f32 v130, v70, v71
	v_cvt_pk_bf16_f32 v131, v72, v73
	v_cvt_pk_bf16_f32 v132, v66, v67
	v_cvt_pk_bf16_f32 v133, v68, v69
	global_store_dwordx4 v[136:137], v[130:133], off nt
	s_nop 1
	v_add_u32_e32 v130, 0x80, v134
	v_ashrrev_i32_e32 v131, 31, v130
	v_lshlrev_b64 v[136:137], 13, v[130:131]
	v_lshl_add_u64 v[136:137], s[14:15], 0, v[136:137]
	v_cvt_pk_bf16_f32 v130, v62, v63
	v_cvt_pk_bf16_f32 v131, v64, v65
	v_cvt_pk_bf16_f32 v132, v58, v59
	v_cvt_pk_bf16_f32 v133, v60, v61
	v_lshl_add_u64 v[140:141], v[136:137], 0, v[156:157]
	global_store_dwordx4 v[140:141], v[130:133], off nt
	v_lshl_add_u64 v[136:137], v[136:137], 0, v[138:139]
	s_nop 0
	v_cvt_pk_bf16_f32 v130, v54, v55
	v_cvt_pk_bf16_f32 v131, v56, v57
	v_cvt_pk_bf16_f32 v132, v46, v47
	v_cvt_pk_bf16_f32 v133, v48, v49
	global_store_dwordx4 v[136:137], v[130:133], off nt
	s_nop 1
	v_add_u32_e32 v130, 0x90, v134
	v_ashrrev_i32_e32 v131, 31, v130
	v_lshlrev_b64 v[136:137], 13, v[130:131]
	v_lshl_add_u64 v[136:137], s[14:15], 0, v[136:137]
	v_cvt_pk_bf16_f32 v130, v50, v51
	v_cvt_pk_bf16_f32 v131, v52, v53
	v_cvt_pk_bf16_f32 v132, v42, v43
	v_cvt_pk_bf16_f32 v133, v44, v45
	v_lshl_add_u64 v[140:141], v[136:137], 0, v[156:157]
	global_store_dwordx4 v[140:141], v[130:133], off nt
	v_lshl_add_u64 v[136:137], v[136:137], 0, v[138:139]
	s_nop 0
	v_cvt_pk_bf16_f32 v130, v38, v39
	v_cvt_pk_bf16_f32 v131, v40, v41
	v_cvt_pk_bf16_f32 v132, v30, v31
	v_cvt_pk_bf16_f32 v133, v32, v33
	global_store_dwordx4 v[136:137], v[130:133], off nt
	s_nop 1
	v_add_u32_e32 v130, 0xa0, v134
	v_ashrrev_i32_e32 v131, 31, v130
	v_lshlrev_b64 v[136:137], 13, v[130:131]
	v_lshl_add_u64 v[136:137], s[14:15], 0, v[136:137]
	v_cvt_pk_bf16_f32 v130, v34, v35
	v_cvt_pk_bf16_f32 v131, v36, v37
	v_cvt_pk_bf16_f32 v132, v26, v27
	v_cvt_pk_bf16_f32 v133, v28, v29
	v_lshl_add_u64 v[140:141], v[136:137], 0, v[156:157]
	global_store_dwordx4 v[140:141], v[130:133], off nt
	v_lshl_add_u64 v[136:137], v[136:137], 0, v[138:139]
	s_nop 0
	v_cvt_pk_bf16_f32 v130, v22, v23
	v_cvt_pk_bf16_f32 v131, v24, v25
	v_cvt_pk_bf16_f32 v132, v14, v15
	v_cvt_pk_bf16_f32 v133, v16, v17
	global_store_dwordx4 v[136:137], v[130:133], off nt
	s_nop 1
	v_add_u32_e32 v130, 0xb0, v134
	v_ashrrev_i32_e32 v131, 31, v130
	v_lshlrev_b64 v[134:135], 13, v[130:131]
	v_lshl_add_u64 v[134:135], s[14:15], 0, v[134:135]
	v_cvt_pk_bf16_f32 v130, v18, v19
	v_cvt_pk_bf16_f32 v131, v20, v21
	v_cvt_pk_bf16_f32 v132, v10, v11
	v_cvt_pk_bf16_f32 v133, v12, v13
	v_lshl_add_u64 v[136:137], v[134:135], 0, v[156:157]
	global_store_dwordx4 v[136:137], v[130:133], off nt
	v_lshl_add_u64 v[134:135], v[134:135], 0, v[138:139]
	s_nop 0
	v_cvt_pk_bf16_f32 v130, v6, v7
	v_cvt_pk_bf16_f32 v131, v8, v9
	v_cvt_pk_bf16_f32 v132, v2, v3
	v_cvt_pk_bf16_f32 v133, v4, v5
	global_store_dwordx4 v[134:135], v[130:133], off nt

.LBB0_288:
	s_and_b64 vcc, exec, s[48:49]
	s_cbranch_vccz .LBB0_290
	s_lshl_b32 s2, s66, 8
	s_and_b32 s2, s2, 0x100
	s_or_b32 s2, s2, s59
	v_add_u32_e32 v162, s2, v173
	v_ashrrev_i32_e32 v163, 31, v162
	v_lshl_add_u64 v[142:143], v[162:163], 2, s[18:19]
	global_load_dwordx4 v[130:133], v[142:143], off offset:512
	global_load_dwordx4 v[138:141], v[142:143], off
	global_load_dwordx4 v[134:137], v[142:143], off offset:16
	v_mul_f32_e32 v144, 0xbfb8aa3b, v126
	v_mul_f32_e32 v145, 0xbfb8aa3b, v127
	v_exp_f32_e32 v177, v144
	v_exp_f32_e32 v179, v145
	global_load_dwordx4 v[142:145], v[142:143], off offset:528
	v_mul_f32_e32 v156, 0xbfb8aa3b, v128
	v_mul_f32_e32 v164, 0xbfb8aa3b, v129
	v_mul_f32_e32 v165, 0xbfb8aa3b, v122
	v_mul_f32_e32 v168, 0xbfb8aa3b, v123
	v_exp_f32_e32 v156, v156
	v_exp_f32_e32 v180, v164
	v_exp_f32_e32 v181, v165
	v_exp_f32_e32 v168, v168
	s_lshl_b32 s2, s33, 8
	s_add_i32 s2, s2, s58
	v_mul_f32_e32 v172, 0xbfb8aa3b, v124
	v_mul_f32_e32 v174, 0xbfb8aa3b, v125
	v_add_u32_e32 v183, s2, v171
	v_add_f32_e32 v177, 1.0, v177
	v_add_f32_e32 v179, 1.0, v179
	v_exp_f32_e32 v172, v172
	v_exp_f32_e32 v174, v174
	v_add_u32_e32 v164, 0x8000, v183
	v_add_f32_e32 v156, 1.0, v156
	v_add_f32_e32 v180, 1.0, v180
	v_add_f32_e32 v181, 1.0, v181
	v_add_f32_e32 v168, 1.0, v168
	v_rcp_f32_e32 v186, v177
	v_rcp_f32_e32 v187, v179
	v_ashrrev_i32_e32 v165, 31, v164
	v_rcp_f32_e32 v188, v156
	v_rcp_f32_e32 v189, v180
	v_rcp_f32_e32 v192, v181
	v_rcp_f32_e32 v168, v168
	v_mul_f32_e32 v175, 0xbfb8aa3b, v118
	v_lshlrev_b64 v[164:165], 10, v[164:165]
	v_exp_f32_e32 v175, v175
	v_lshlrev_b64 v[162:163], 1, v[162:163]
	v_lshl_add_u64 v[164:165], s[20:21], 0, v[164:165]
	v_add_f32_e32 v172, 1.0, v172
	v_add_f32_e32 v174, 1.0, v174
	v_lshl_add_u64 v[190:191], v[164:165], 0, v[162:163]
	v_rcp_f32_e32 v172, v172
	v_rcp_f32_e32 v174, v174
	v_add_f32_e32 v175, 1.0, v175
	v_mul_f32_e32 v178, 0xbfb8aa3b, v120
	v_rcp_f32_e32 v193, v175
	v_mul_f32_e32 v176, 0xbfb8aa3b, v119
	v_exp_f32_e32 v176, v176
	s_waitcnt vmcnt(0)
	v_sub_f32_e32 v164, 1.0, v131
	v_sub_f32_e32 v185, 1.0, v138
	v_sub_f32_e32 v184, 1.0, v139
	v_sub_f32_e32 v182, 1.0, v140
	v_sub_f32_e32 v181, 1.0, v141
	v_sub_f32_e32 v180, 1.0, v134
	v_sub_f32_e32 v179, 1.0, v135
	v_fma_f32 v165, v186, v185, v138
	v_fma_f32 v186, v187, v184, v139
	v_fma_f32 v187, v188, v182, v140
	v_fma_f32 v188, v189, v181, v141
	v_fma_f32 v189, v192, v180, v134
	v_fma_f32 v168, v168, v179, v135
	v_log_f32_e32 v165, v165
	v_log_f32_e32 v186, v186
	v_log_f32_e32 v187, v187
	v_log_f32_e32 v188, v188
	v_log_f32_e32 v189, v189
	v_log_f32_e32 v168, v168
	v_sub_f32_e32 v177, 1.0, v136
	v_sub_f32_e32 v175, 1.0, v137
	v_fma_f32 v172, v172, v177, v136
	v_fma_f32 v174, v174, v175, v137
	v_cvt_pk_bf16_f32 v186, v165, v186
	v_exp_f32_e32 v165, v178
	v_log_f32_e32 v172, v172
	v_log_f32_e32 v174, v174
	v_cvt_pk_bf16_f32 v187, v187, v188
	v_cvt_pk_bf16_f32 v188, v189, v168
	v_mul_f32_e32 v168, 0xbfb8aa3b, v121
	v_exp_f32_e32 v168, v168
	v_add_f32_e32 v165, 1.0, v165
	v_cvt_pk_bf16_f32 v189, v172, v174
	v_rcp_f32_e32 v172, v165
	v_add_f32_e32 v168, 1.0, v168
	v_rcp_f32_e32 v168, v168
	v_sub_f32_e32 v165, 1.0, v132
	v_fma_f32 v172, v172, v165, v132
	v_add_f32_e32 v176, 1.0, v176
	global_store_dwordx4 v[190:191], v[186:189], off nt
	v_mul_f32_e32 v174, 0xbfb8aa3b, v110
	v_rcp_f32_e32 v176, v176
	v_log_f32_e32 v187, v172
	v_sub_f32_e32 v172, 1.0, v133
	v_fma_f32 v168, v168, v172, v133
	v_exp_f32_e32 v174, v174
	v_log_f32_e32 v188, v168
	v_mul_f32_e32 v168, 0xbfb8aa3b, v111
	v_exp_f32_e32 v168, v168
	v_fma_f32 v176, v176, v164, v131
	v_add_f32_e32 v174, 1.0, v174
	v_log_f32_e32 v186, v176
	v_rcp_f32_e32 v176, v174
	v_add_f32_e32 v168, 1.0, v168
	v_rcp_f32_e32 v178, v168
	v_sub_f32_e32 v174, 1.0, v142
	v_fma_f32 v168, v176, v174, v142
	v_log_f32_e32 v189, v168
	v_sub_f32_e32 v168, 1.0, v143
	v_fma_f32 v176, v178, v168, v143
	v_mul_f32_e32 v178, 0xbfb8aa3b, v112
	v_sub_f32_e32 v156, 1.0, v130
	v_exp_f32_e32 v178, v178
	v_fma_f32 v192, v193, v156, v130
	v_log_f32_e32 v193, v176
	v_mul_f32_e32 v176, 0xbfb8aa3b, v113
	v_exp_f32_e32 v194, v176
	v_add_f32_e32 v176, 1.0, v178
	v_rcp_f32_e32 v178, v176
	v_sub_f32_e32 v176, 1.0, v144
	v_add_f32_e32 v194, 1.0, v194
	v_rcp_f32_e32 v194, v194
	v_fma_f32 v178, v178, v176, v144
	v_log_f32_e32 v195, v178
	v_sub_f32_e32 v178, 1.0, v145
	v_fma_f32 v194, v194, v178, v145
	v_log_f32_e32 v192, v192
	v_log_f32_e32 v194, v194
	v_cvt_pk_bf16_f32 v187, v187, v188
	v_cvt_pk_bf16_f32 v188, v189, v193
	v_cvt_pk_bf16_f32 v186, v192, v186
	v_cvt_pk_bf16_f32 v189, v195, v194
	global_store_dwordx4 v[190:191], v[186:189], off offset:256 nt
	v_mul_f32_e32 v192, 0xbfb8aa3b, v106
	v_mul_f32_e32 v193, 0xbfb8aa3b, v107
	v_mul_f32_e32 v187, 0xbfb8aa3b, v114
	v_exp_f32_e32 v188, v187
	v_mul_f32_e32 v187, 0xbfb8aa3b, v115
	v_exp_f32_e32 v189, v187
	v_add_u32_e32 v186, 0x8010, v183
	v_add_f32_e32 v188, 1.0, v188
	v_rcp_f32_e32 v188, v188
	v_add_f32_e32 v189, 1.0, v189
	v_rcp_f32_e32 v189, v189
	v_ashrrev_i32_e32 v187, 31, v186
	v_lshlrev_b64 v[190:191], 10, v[186:187]
	v_fma_f32 v186, v188, v185, v138
	v_fma_f32 v187, v189, v184, v139
	v_mul_f32_e32 v188, 0xbfb8aa3b, v116
	v_mul_f32_e32 v189, 0xbfb8aa3b, v117
	v_exp_f32_e32 v188, v188
	v_exp_f32_e32 v189, v189
	v_exp_f32_e32 v192, v192
	v_exp_f32_e32 v193, v193
	v_add_f32_e32 v188, 1.0, v188
	v_add_f32_e32 v189, 1.0, v189
	v_add_f32_e32 v192, 1.0, v192
	v_add_f32_e32 v193, 1.0, v193
	v_rcp_f32_e32 v188, v188
	v_rcp_f32_e32 v189, v189
	v_rcp_f32_e32 v192, v192
	v_rcp_f32_e32 v193, v193
	v_mul_f32_e32 v194, 0xbfb8aa3b, v108
	v_mul_f32_e32 v195, 0xbfb8aa3b, v109
	v_fma_f32 v188, v188, v182, v140
	v_fma_f32 v189, v189, v181, v141
	v_fma_f32 v192, v192, v180, v134
	v_exp_f32_e32 v194, v194
	v_exp_f32_e32 v195, v195
	v_fma_f32 v193, v193, v179, v135
	v_log_f32_e32 v186, v186
	v_log_f32_e32 v187, v187
	v_log_f32_e32 v188, v188
	v_log_f32_e32 v189, v189
	v_log_f32_e32 v192, v192
	v_log_f32_e32 v193, v193
	v_add_f32_e32 v194, 1.0, v194
	v_add_f32_e32 v195, 1.0, v195
	v_rcp_f32_e32 v194, v194
	v_rcp_f32_e32 v195, v195
	v_cvt_pk_bf16_f32 v186, v186, v187
	v_cvt_pk_bf16_f32 v187, v188, v189
	v_cvt_pk_bf16_f32 v188, v192, v193
	v_mul_f32_e32 v192, 0xbfb8aa3b, v102
	v_mul_f32_e32 v193, 0xbfb8aa3b, v103
	v_exp_f32_e32 v192, v192
	v_exp_f32_e32 v193, v193
	v_fma_f32 v194, v194, v177, v136
	v_fma_f32 v195, v195, v175, v137
	v_log_f32_e32 v194, v194
	v_log_f32_e32 v195, v195
	v_add_f32_e32 v192, 1.0, v192
	v_add_f32_e32 v193, 1.0, v193
	v_rcp_f32_e32 v192, v192
	v_rcp_f32_e32 v193, v193
	v_lshl_add_u64 v[190:191], s[20:21], 0, v[190:191]
	v_cvt_pk_bf16_f32 v189, v194, v195
	v_lshl_add_u64 v[190:191], v[190:191], 0, v[162:163]
	global_store_dwordx4 v[190:191], v[186:189], off nt
	v_mul_f32_e32 v194, 0xbfb8aa3b, v96
	v_mul_f32_e32 v195, 0xbfb8aa3b, v97
	v_fma_f32 v186, v192, v156, v130
	v_fma_f32 v187, v193, v164, v131
	v_mul_f32_e32 v188, 0xbfb8aa3b, v104
	v_mul_f32_e32 v189, 0xbfb8aa3b, v105
	v_mul_f32_e32 v192, 0xbfb8aa3b, v94
	v_mul_f32_e32 v193, 0xbfb8aa3b, v95
	v_exp_f32_e32 v188, v188
	v_exp_f32_e32 v189, v189
	v_exp_f32_e32 v192, v192
	v_exp_f32_e32 v193, v193
	v_exp_f32_e32 v194, v194
	v_exp_f32_e32 v195, v195
	v_add_f32_e32 v188, 1.0, v188
	v_add_f32_e32 v189, 1.0, v189
	v_add_f32_e32 v192, 1.0, v192
	v_add_f32_e32 v193, 1.0, v193
	v_add_f32_e32 v194, 1.0, v194
	v_add_f32_e32 v195, 1.0, v195
	v_rcp_f32_e32 v188, v188
	v_rcp_f32_e32 v189, v189
	v_rcp_f32_e32 v192, v192
	v_rcp_f32_e32 v193, v193
	v_rcp_f32_e32 v194, v194
	v_rcp_f32_e32 v195, v195
	v_fma_f32 v188, v188, v165, v132
	v_fma_f32 v189, v189, v172, v133
	v_fma_f32 v192, v192, v174, v142
	v_fma_f32 v193, v193, v168, v143
	v_fma_f32 v194, v194, v176, v144
	v_fma_f32 v195, v195, v178, v145
	v_log_f32_e32 v186, v186
	v_log_f32_e32 v187, v187
	v_log_f32_e32 v188, v188
	v_log_f32_e32 v189, v189
	v_log_f32_e32 v192, v192
	v_log_f32_e32 v193, v193
	v_log_f32_e32 v194, v194
	v_log_f32_e32 v195, v195
	v_cvt_pk_bf16_f32 v186, v186, v187
	v_cvt_pk_bf16_f32 v187, v188, v189
	v_cvt_pk_bf16_f32 v188, v192, v193
	v_cvt_pk_bf16_f32 v189, v194, v195
	global_store_dwordx4 v[190:191], v[186:189], off offset:256 nt
	v_mul_f32_e32 v192, 0xbfb8aa3b, v90
	v_mul_f32_e32 v193, 0xbfb8aa3b, v91
	v_mul_f32_e32 v187, 0xbfb8aa3b, v98
	v_exp_f32_e32 v188, v187
	v_mul_f32_e32 v187, 0xbfb8aa3b, v99
	v_exp_f32_e32 v189, v187
	v_add_u32_e32 v186, 0x8020, v183
	v_add_f32_e32 v188, 1.0, v188
	v_rcp_f32_e32 v188, v188
	v_add_f32_e32 v189, 1.0, v189
	v_rcp_f32_e32 v189, v189
	v_ashrrev_i32_e32 v187, 31, v186
	v_lshlrev_b64 v[190:191], 10, v[186:187]
	v_fma_f32 v186, v188, v185, v138
	v_fma_f32 v187, v189, v184, v139
	v_mul_f32_e32 v188, 0xbfb8aa3b, v100
	v_mul_f32_e32 v189, 0xbfb8aa3b, v101
	v_exp_f32_e32 v188, v188
	v_exp_f32_e32 v189, v189
	v_exp_f32_e32 v192, v192
	v_exp_f32_e32 v193, v193
	v_add_f32_e32 v188, 1.0, v188
	v_add_f32_e32 v189, 1.0, v189
	v_add_f32_e32 v192, 1.0, v192
	v_add_f32_e32 v193, 1.0, v193
	v_rcp_f32_e32 v188, v188
	v_rcp_f32_e32 v189, v189
	v_rcp_f32_e32 v192, v192
	v_rcp_f32_e32 v193, v193
	v_mul_f32_e32 v194, 0xbfb8aa3b, v92
	v_mul_f32_e32 v195, 0xbfb8aa3b, v93
	v_fma_f32 v188, v188, v182, v140
	v_fma_f32 v189, v189, v181, v141
	v_fma_f32 v192, v192, v180, v134
	v_exp_f32_e32 v194, v194
	v_exp_f32_e32 v195, v195
	v_fma_f32 v193, v193, v179, v135
	v_log_f32_e32 v186, v186
	v_log_f32_e32 v187, v187
	v_log_f32_e32 v188, v188
	v_log_f32_e32 v189, v189
	v_log_f32_e32 v192, v192
	v_log_f32_e32 v193, v193
	v_add_f32_e32 v194, 1.0, v194
	v_add_f32_e32 v195, 1.0, v195
	v_rcp_f32_e32 v194, v194
	v_rcp_f32_e32 v195, v195
	v_cvt_pk_bf16_f32 v186, v186, v187
	v_cvt_pk_bf16_f32 v187, v188, v189
	v_cvt_pk_bf16_f32 v188, v192, v193
	v_mul_f32_e32 v192, 0xbfb8aa3b, v86
	v_mul_f32_e32 v193, 0xbfb8aa3b, v87
	v_exp_f32_e32 v192, v192
	v_exp_f32_e32 v193, v193
	v_fma_f32 v194, v194, v177, v136
	v_fma_f32 v195, v195, v175, v137
	v_log_f32_e32 v194, v194
	v_log_f32_e32 v195, v195
	v_add_f32_e32 v192, 1.0, v192
	v_add_f32_e32 v193, 1.0, v193
	v_rcp_f32_e32 v192, v192
	v_rcp_f32_e32 v193, v193
	v_lshl_add_u64 v[190:191], s[20:21], 0, v[190:191]
	v_cvt_pk_bf16_f32 v189, v194, v195
	v_lshl_add_u64 v[190:191], v[190:191], 0, v[162:163]
	global_store_dwordx4 v[190:191], v[186:189], off nt
	v_mul_f32_e32 v194, 0xbfb8aa3b, v80
	v_mul_f32_e32 v195, 0xbfb8aa3b, v81
	v_fma_f32 v186, v192, v156, v130
	v_fma_f32 v187, v193, v164, v131
	v_mul_f32_e32 v188, 0xbfb8aa3b, v88
	v_mul_f32_e32 v189, 0xbfb8aa3b, v89
	v_mul_f32_e32 v192, 0xbfb8aa3b, v78
	v_mul_f32_e32 v193, 0xbfb8aa3b, v79
	v_exp_f32_e32 v188, v188
	v_exp_f32_e32 v189, v189
	v_exp_f32_e32 v192, v192
	v_exp_f32_e32 v193, v193
	v_exp_f32_e32 v194, v194
	v_exp_f32_e32 v195, v195
	v_add_f32_e32 v188, 1.0, v188
	v_add_f32_e32 v189, 1.0, v189
	v_add_f32_e32 v192, 1.0, v192
	v_add_f32_e32 v193, 1.0, v193
	v_add_f32_e32 v194, 1.0, v194
	v_add_f32_e32 v195, 1.0, v195
	v_rcp_f32_e32 v188, v188
	v_rcp_f32_e32 v189, v189
	v_rcp_f32_e32 v192, v192
	v_rcp_f32_e32 v193, v193
	v_rcp_f32_e32 v194, v194
	v_rcp_f32_e32 v195, v195
	v_fma_f32 v188, v188, v165, v132
	v_fma_f32 v189, v189, v172, v133
	v_fma_f32 v192, v192, v174, v142
	v_fma_f32 v193, v193, v168, v143
	v_fma_f32 v194, v194, v176, v144
	v_fma_f32 v195, v195, v178, v145
	v_log_f32_e32 v186, v186
	v_log_f32_e32 v187, v187
	v_log_f32_e32 v188, v188
	v_log_f32_e32 v189, v189
	v_log_f32_e32 v192, v192
	v_log_f32_e32 v193, v193
	v_log_f32_e32 v194, v194
	v_log_f32_e32 v195, v195
	v_cvt_pk_bf16_f32 v186, v186, v187
	v_cvt_pk_bf16_f32 v187, v188, v189
	v_cvt_pk_bf16_f32 v188, v192, v193
	v_cvt_pk_bf16_f32 v189, v194, v195
	global_store_dwordx4 v[190:191], v[186:189], off offset:256 nt
	v_mul_f32_e32 v192, 0xbfb8aa3b, v74
	v_mul_f32_e32 v193, 0xbfb8aa3b, v75
	v_mul_f32_e32 v187, 0xbfb8aa3b, v82
	v_exp_f32_e32 v188, v187
	v_mul_f32_e32 v187, 0xbfb8aa3b, v83
	v_exp_f32_e32 v189, v187
	v_add_u32_e32 v186, 0x8030, v183
	v_add_f32_e32 v188, 1.0, v188
	v_rcp_f32_e32 v188, v188
	v_add_f32_e32 v189, 1.0, v189
	v_rcp_f32_e32 v189, v189
	v_ashrrev_i32_e32 v187, 31, v186
	v_lshlrev_b64 v[190:191], 10, v[186:187]
	v_fma_f32 v186, v188, v185, v138
	v_fma_f32 v187, v189, v184, v139
	v_mul_f32_e32 v188, 0xbfb8aa3b, v84
	v_mul_f32_e32 v189, 0xbfb8aa3b, v85
	v_exp_f32_e32 v188, v188
	v_exp_f32_e32 v189, v189
	v_exp_f32_e32 v192, v192
	v_exp_f32_e32 v193, v193
	v_add_f32_e32 v188, 1.0, v188
	v_add_f32_e32 v189, 1.0, v189
	v_add_f32_e32 v192, 1.0, v192
	v_add_f32_e32 v193, 1.0, v193
	v_rcp_f32_e32 v188, v188
	v_rcp_f32_e32 v189, v189
	v_rcp_f32_e32 v192, v192
	v_rcp_f32_e32 v193, v193
	v_mul_f32_e32 v194, 0xbfb8aa3b, v76
	v_mul_f32_e32 v195, 0xbfb8aa3b, v77
	v_fma_f32 v188, v188, v182, v140
	v_fma_f32 v189, v189, v181, v141
	v_fma_f32 v192, v192, v180, v134
	v_exp_f32_e32 v194, v194
	v_exp_f32_e32 v195, v195
	v_fma_f32 v193, v193, v179, v135
	v_log_f32_e32 v186, v186
	v_log_f32_e32 v187, v187
	v_log_f32_e32 v188, v188
	v_log_f32_e32 v189, v189
	v_log_f32_e32 v192, v192
	v_log_f32_e32 v193, v193
	v_add_f32_e32 v194, 1.0, v194
	v_add_f32_e32 v195, 1.0, v195
	v_rcp_f32_e32 v194, v194
	v_rcp_f32_e32 v195, v195
	v_cvt_pk_bf16_f32 v186, v186, v187
	v_cvt_pk_bf16_f32 v187, v188, v189
	v_cvt_pk_bf16_f32 v188, v192, v193
	v_mul_f32_e32 v192, 0xbfb8aa3b, v70
	v_mul_f32_e32 v193, 0xbfb8aa3b, v71
	v_exp_f32_e32 v192, v192
	v_exp_f32_e32 v193, v193
	v_fma_f32 v194, v194, v177, v136
	v_fma_f32 v195, v195, v175, v137
	v_log_f32_e32 v194, v194
	v_log_f32_e32 v195, v195
	v_add_f32_e32 v192, 1.0, v192
	v_add_f32_e32 v193, 1.0, v193
	v_rcp_f32_e32 v192, v192
	v_rcp_f32_e32 v193, v193
	v_lshl_add_u64 v[190:191], s[20:21], 0, v[190:191]
	v_cvt_pk_bf16_f32 v189, v194, v195
	v_lshl_add_u64 v[190:191], v[190:191], 0, v[162:163]
	global_store_dwordx4 v[190:191], v[186:189], off nt
	v_mul_f32_e32 v194, 0xbfb8aa3b, v68
	v_mul_f32_e32 v195, 0xbfb8aa3b, v69
	v_fma_f32 v186, v192, v156, v130
	v_fma_f32 v187, v193, v164, v131
	v_mul_f32_e32 v188, 0xbfb8aa3b, v72
	v_mul_f32_e32 v189, 0xbfb8aa3b, v73
	v_mul_f32_e32 v192, 0xbfb8aa3b, v66
	v_mul_f32_e32 v193, 0xbfb8aa3b, v67
	v_exp_f32_e32 v188, v188
	v_exp_f32_e32 v189, v189
	v_exp_f32_e32 v192, v192
	v_exp_f32_e32 v193, v193
	v_exp_f32_e32 v194, v194
	v_exp_f32_e32 v195, v195
	v_add_f32_e32 v188, 1.0, v188
	v_add_f32_e32 v189, 1.0, v189
	v_add_f32_e32 v192, 1.0, v192
	v_add_f32_e32 v193, 1.0, v193
	v_add_f32_e32 v194, 1.0, v194
	v_add_f32_e32 v195, 1.0, v195
	v_rcp_f32_e32 v188, v188
	v_rcp_f32_e32 v189, v189
	v_rcp_f32_e32 v192, v192
	v_rcp_f32_e32 v193, v193
	v_rcp_f32_e32 v194, v194
	v_rcp_f32_e32 v195, v195
	v_fma_f32 v188, v188, v165, v132
	v_fma_f32 v189, v189, v172, v133
	v_fma_f32 v192, v192, v174, v142
	v_fma_f32 v193, v193, v168, v143
	v_fma_f32 v194, v194, v176, v144
	v_fma_f32 v195, v195, v178, v145
	v_log_f32_e32 v186, v186
	v_log_f32_e32 v187, v187
	v_log_f32_e32 v188, v188
	v_log_f32_e32 v189, v189
	v_log_f32_e32 v192, v192
	v_log_f32_e32 v193, v193
	v_log_f32_e32 v194, v194
	v_log_f32_e32 v195, v195
	v_cvt_pk_bf16_f32 v186, v186, v187
	v_cvt_pk_bf16_f32 v187, v188, v189
	v_cvt_pk_bf16_f32 v188, v192, v193
	v_cvt_pk_bf16_f32 v189, v194, v195
	global_store_dwordx4 v[190:191], v[186:189], off offset:256 nt
	v_mul_f32_e32 v192, 0xbfb8aa3b, v58
	v_mul_f32_e32 v193, 0xbfb8aa3b, v59
	v_mul_f32_e32 v187, 0xbfb8aa3b, v62
	v_exp_f32_e32 v188, v187
	v_mul_f32_e32 v187, 0xbfb8aa3b, v63
	v_exp_f32_e32 v189, v187
	v_add_u32_e32 v186, 0x8080, v183
	v_add_f32_e32 v188, 1.0, v188
	v_rcp_f32_e32 v188, v188
	v_add_f32_e32 v189, 1.0, v189
	v_rcp_f32_e32 v189, v189
	v_ashrrev_i32_e32 v187, 31, v186
	v_lshlrev_b64 v[190:191], 10, v[186:187]
	v_fma_f32 v186, v188, v185, v138
	v_fma_f32 v187, v189, v184, v139
	v_mul_f32_e32 v188, 0xbfb8aa3b, v64
	v_mul_f32_e32 v189, 0xbfb8aa3b, v65
	v_exp_f32_e32 v188, v188
	v_exp_f32_e32 v189, v189
	v_exp_f32_e32 v192, v192
	v_exp_f32_e32 v193, v193
	v_add_f32_e32 v188, 1.0, v188
	v_add_f32_e32 v189, 1.0, v189
	v_add_f32_e32 v192, 1.0, v192
	v_add_f32_e32 v193, 1.0, v193
	v_rcp_f32_e32 v188, v188
	v_rcp_f32_e32 v189, v189
	v_rcp_f32_e32 v192, v192
	v_rcp_f32_e32 v193, v193
	v_mul_f32_e32 v194, 0xbfb8aa3b, v60
	v_mul_f32_e32 v195, 0xbfb8aa3b, v61
	v_fma_f32 v188, v188, v182, v140
	v_fma_f32 v189, v189, v181, v141
	v_fma_f32 v192, v192, v180, v134
	v_exp_f32_e32 v194, v194
	v_exp_f32_e32 v195, v195
	v_fma_f32 v193, v193, v179, v135
	v_log_f32_e32 v186, v186
	v_log_f32_e32 v187, v187
	v_log_f32_e32 v188, v188
	v_log_f32_e32 v189, v189
	v_log_f32_e32 v192, v192
	v_log_f32_e32 v193, v193
	v_add_f32_e32 v194, 1.0, v194
	v_add_f32_e32 v195, 1.0, v195
	v_rcp_f32_e32 v194, v194
	v_rcp_f32_e32 v195, v195
	v_cvt_pk_bf16_f32 v186, v186, v187
	v_cvt_pk_bf16_f32 v187, v188, v189
	v_cvt_pk_bf16_f32 v188, v192, v193
	v_mul_f32_e32 v192, 0xbfb8aa3b, v54
	v_mul_f32_e32 v193, 0xbfb8aa3b, v55
	v_exp_f32_e32 v192, v192
	v_exp_f32_e32 v193, v193
	v_fma_f32 v194, v194, v177, v136
	v_fma_f32 v195, v195, v175, v137
	v_log_f32_e32 v194, v194
	v_log_f32_e32 v195, v195
	v_add_f32_e32 v192, 1.0, v192
	v_add_f32_e32 v193, 1.0, v193
	v_rcp_f32_e32 v192, v192
	v_rcp_f32_e32 v193, v193
	v_lshl_add_u64 v[190:191], s[20:21], 0, v[190:191]
	v_cvt_pk_bf16_f32 v189, v194, v195
	v_lshl_add_u64 v[190:191], v[190:191], 0, v[162:163]
	global_store_dwordx4 v[190:191], v[186:189], off nt
	v_mul_f32_e32 v194, 0xbfb8aa3b, v48
	v_mul_f32_e32 v195, 0xbfb8aa3b, v49
	v_fma_f32 v186, v192, v156, v130
	v_fma_f32 v187, v193, v164, v131
	v_mul_f32_e32 v188, 0xbfb8aa3b, v56
	v_mul_f32_e32 v189, 0xbfb8aa3b, v57
	v_mul_f32_e32 v192, 0xbfb8aa3b, v46
	v_mul_f32_e32 v193, 0xbfb8aa3b, v47
	v_exp_f32_e32 v188, v188
	v_exp_f32_e32 v189, v189
	v_exp_f32_e32 v192, v192
	v_exp_f32_e32 v193, v193
	v_exp_f32_e32 v194, v194
	v_exp_f32_e32 v195, v195
	v_add_f32_e32 v188, 1.0, v188
	v_add_f32_e32 v189, 1.0, v189
	v_add_f32_e32 v192, 1.0, v192
	v_add_f32_e32 v193, 1.0, v193
	v_add_f32_e32 v194, 1.0, v194
	v_add_f32_e32 v195, 1.0, v195
	v_rcp_f32_e32 v188, v188
	v_rcp_f32_e32 v189, v189
	v_rcp_f32_e32 v192, v192
	v_rcp_f32_e32 v193, v193
	v_rcp_f32_e32 v194, v194
	v_rcp_f32_e32 v195, v195
	v_fma_f32 v188, v188, v165, v132
	v_fma_f32 v189, v189, v172, v133
	v_fma_f32 v192, v192, v174, v142
	v_fma_f32 v193, v193, v168, v143
	v_fma_f32 v194, v194, v176, v144
	v_fma_f32 v195, v195, v178, v145
	v_log_f32_e32 v186, v186
	v_log_f32_e32 v187, v187
	v_log_f32_e32 v188, v188
	v_log_f32_e32 v189, v189
	v_log_f32_e32 v192, v192
	v_log_f32_e32 v193, v193
	v_log_f32_e32 v194, v194
	v_log_f32_e32 v195, v195
	v_cvt_pk_bf16_f32 v186, v186, v187
	v_cvt_pk_bf16_f32 v187, v188, v189
	v_cvt_pk_bf16_f32 v188, v192, v193
	v_cvt_pk_bf16_f32 v189, v194, v195
	global_store_dwordx4 v[190:191], v[186:189], off offset:256 nt
	v_mul_f32_e32 v192, 0xbfb8aa3b, v42
	v_mul_f32_e32 v193, 0xbfb8aa3b, v43
	v_mul_f32_e32 v187, 0xbfb8aa3b, v50
	v_exp_f32_e32 v188, v187
	v_mul_f32_e32 v187, 0xbfb8aa3b, v51
	v_exp_f32_e32 v189, v187
	v_add_u32_e32 v186, 0x8090, v183
	v_add_f32_e32 v188, 1.0, v188
	v_rcp_f32_e32 v188, v188
	v_add_f32_e32 v189, 1.0, v189
	v_rcp_f32_e32 v189, v189
	v_ashrrev_i32_e32 v187, 31, v186
	v_lshlrev_b64 v[190:191], 10, v[186:187]
	v_fma_f32 v186, v188, v185, v138
	v_fma_f32 v187, v189, v184, v139
	v_mul_f32_e32 v188, 0xbfb8aa3b, v52
	v_mul_f32_e32 v189, 0xbfb8aa3b, v53
	v_exp_f32_e32 v188, v188
	v_exp_f32_e32 v189, v189
	v_exp_f32_e32 v192, v192
	v_exp_f32_e32 v193, v193
	v_add_f32_e32 v188, 1.0, v188
	v_add_f32_e32 v189, 1.0, v189
	v_add_f32_e32 v192, 1.0, v192
	v_add_f32_e32 v193, 1.0, v193
	v_rcp_f32_e32 v188, v188
	v_rcp_f32_e32 v189, v189
	v_rcp_f32_e32 v192, v192
	v_rcp_f32_e32 v193, v193
	v_mul_f32_e32 v194, 0xbfb8aa3b, v44
	v_mul_f32_e32 v195, 0xbfb8aa3b, v45
	v_fma_f32 v188, v188, v182, v140
	v_fma_f32 v189, v189, v181, v141
	v_fma_f32 v192, v192, v180, v134
	v_exp_f32_e32 v194, v194
	v_exp_f32_e32 v195, v195
	v_fma_f32 v193, v193, v179, v135
	v_log_f32_e32 v186, v186
	v_log_f32_e32 v187, v187
	v_log_f32_e32 v188, v188
	v_log_f32_e32 v189, v189
	v_log_f32_e32 v192, v192
	v_log_f32_e32 v193, v193
	v_add_f32_e32 v194, 1.0, v194
	v_add_f32_e32 v195, 1.0, v195
	v_rcp_f32_e32 v194, v194
	v_rcp_f32_e32 v195, v195
	v_cvt_pk_bf16_f32 v186, v186, v187
	v_cvt_pk_bf16_f32 v187, v188, v189
	v_cvt_pk_bf16_f32 v188, v192, v193
	v_mul_f32_e32 v192, 0xbfb8aa3b, v38
	v_mul_f32_e32 v193, 0xbfb8aa3b, v39
	v_exp_f32_e32 v192, v192
	v_exp_f32_e32 v193, v193
	v_fma_f32 v194, v194, v177, v136
	v_fma_f32 v195, v195, v175, v137
	v_log_f32_e32 v194, v194
	v_log_f32_e32 v195, v195
	v_add_f32_e32 v192, 1.0, v192
	v_add_f32_e32 v193, 1.0, v193
	v_rcp_f32_e32 v192, v192
	v_rcp_f32_e32 v193, v193
	v_lshl_add_u64 v[190:191], s[20:21], 0, v[190:191]
	v_cvt_pk_bf16_f32 v189, v194, v195
	v_lshl_add_u64 v[190:191], v[190:191], 0, v[162:163]
	global_store_dwordx4 v[190:191], v[186:189], off nt
	v_mul_f32_e32 v194, 0xbfb8aa3b, v32
	v_mul_f32_e32 v195, 0xbfb8aa3b, v33
	v_fma_f32 v186, v192, v156, v130
	v_fma_f32 v187, v193, v164, v131
	v_mul_f32_e32 v188, 0xbfb8aa3b, v40
	v_mul_f32_e32 v189, 0xbfb8aa3b, v41
	v_mul_f32_e32 v192, 0xbfb8aa3b, v30
	v_mul_f32_e32 v193, 0xbfb8aa3b, v31
	v_exp_f32_e32 v188, v188
	v_exp_f32_e32 v189, v189
	v_exp_f32_e32 v192, v192
	v_exp_f32_e32 v193, v193
	v_exp_f32_e32 v194, v194
	v_exp_f32_e32 v195, v195
	v_add_f32_e32 v188, 1.0, v188
	v_add_f32_e32 v189, 1.0, v189
	v_add_f32_e32 v192, 1.0, v192
	v_add_f32_e32 v193, 1.0, v193
	v_add_f32_e32 v194, 1.0, v194
	v_add_f32_e32 v195, 1.0, v195
	v_rcp_f32_e32 v188, v188
	v_rcp_f32_e32 v189, v189
	v_rcp_f32_e32 v192, v192
	v_rcp_f32_e32 v193, v193
	v_rcp_f32_e32 v194, v194
	v_rcp_f32_e32 v195, v195
	v_fma_f32 v188, v188, v165, v132
	v_fma_f32 v189, v189, v172, v133
	v_fma_f32 v192, v192, v174, v142
	v_fma_f32 v193, v193, v168, v143
	v_fma_f32 v194, v194, v176, v144
	v_fma_f32 v195, v195, v178, v145
	v_log_f32_e32 v186, v186
	v_log_f32_e32 v187, v187
	v_log_f32_e32 v188, v188
	v_log_f32_e32 v189, v189
	v_log_f32_e32 v192, v192
	v_log_f32_e32 v193, v193
	v_log_f32_e32 v194, v194
	v_log_f32_e32 v195, v195
	v_cvt_pk_bf16_f32 v186, v186, v187
	v_cvt_pk_bf16_f32 v187, v188, v189
	v_cvt_pk_bf16_f32 v188, v192, v193
	v_cvt_pk_bf16_f32 v189, v194, v195
	global_store_dwordx4 v[190:191], v[186:189], off offset:256 nt
	v_mul_f32_e32 v192, 0xbfb8aa3b, v26
	v_mul_f32_e32 v193, 0xbfb8aa3b, v27
	v_mul_f32_e32 v187, 0xbfb8aa3b, v34
	v_exp_f32_e32 v188, v187
	v_mul_f32_e32 v187, 0xbfb8aa3b, v35
	v_exp_f32_e32 v189, v187
	v_add_u32_e32 v186, 0x80a0, v183
	v_add_f32_e32 v188, 1.0, v188
	v_rcp_f32_e32 v188, v188
	v_add_f32_e32 v189, 1.0, v189
	v_rcp_f32_e32 v189, v189
	v_ashrrev_i32_e32 v187, 31, v186
	v_lshlrev_b64 v[190:191], 10, v[186:187]
	v_fma_f32 v186, v188, v185, v138
	v_fma_f32 v187, v189, v184, v139
	v_mul_f32_e32 v188, 0xbfb8aa3b, v36
	v_mul_f32_e32 v189, 0xbfb8aa3b, v37
	v_exp_f32_e32 v188, v188
	v_exp_f32_e32 v189, v189
	v_exp_f32_e32 v192, v192
	v_exp_f32_e32 v193, v193
	v_add_f32_e32 v188, 1.0, v188
	v_add_f32_e32 v189, 1.0, v189
	v_add_f32_e32 v192, 1.0, v192
	v_add_f32_e32 v193, 1.0, v193
	v_rcp_f32_e32 v188, v188
	v_rcp_f32_e32 v189, v189
	v_rcp_f32_e32 v192, v192
	v_rcp_f32_e32 v193, v193
	v_mul_f32_e32 v194, 0xbfb8aa3b, v28
	v_mul_f32_e32 v195, 0xbfb8aa3b, v29
	v_fma_f32 v188, v188, v182, v140
	v_fma_f32 v189, v189, v181, v141
	v_fma_f32 v192, v192, v180, v134
	v_exp_f32_e32 v194, v194
	v_exp_f32_e32 v195, v195
	v_fma_f32 v193, v193, v179, v135
	v_log_f32_e32 v186, v186
	v_log_f32_e32 v187, v187
	v_log_f32_e32 v188, v188
	v_log_f32_e32 v189, v189
	v_log_f32_e32 v192, v192
	v_log_f32_e32 v193, v193
	v_add_f32_e32 v194, 1.0, v194
	v_add_f32_e32 v195, 1.0, v195
	v_rcp_f32_e32 v194, v194
	v_rcp_f32_e32 v195, v195
	v_cvt_pk_bf16_f32 v186, v186, v187
	v_cvt_pk_bf16_f32 v187, v188, v189
	v_cvt_pk_bf16_f32 v188, v192, v193
	v_mul_f32_e32 v192, 0xbfb8aa3b, v22
	v_mul_f32_e32 v193, 0xbfb8aa3b, v23
	v_exp_f32_e32 v192, v192
	v_exp_f32_e32 v193, v193
	v_fma_f32 v194, v194, v177, v136
	v_fma_f32 v195, v195, v175, v137
	v_log_f32_e32 v194, v194
	v_log_f32_e32 v195, v195
	v_add_f32_e32 v192, 1.0, v192
	v_add_f32_e32 v193, 1.0, v193
	v_rcp_f32_e32 v192, v192
	v_rcp_f32_e32 v193, v193
	v_lshl_add_u64 v[190:191], s[20:21], 0, v[190:191]
	v_cvt_pk_bf16_f32 v189, v194, v195
	v_lshl_add_u64 v[190:191], v[190:191], 0, v[162:163]
	global_store_dwordx4 v[190:191], v[186:189], off nt
	v_mul_f32_e32 v194, 0xbfb8aa3b, v16
	v_mul_f32_e32 v195, 0xbfb8aa3b, v17
	v_fma_f32 v186, v192, v156, v130
	v_fma_f32 v187, v193, v164, v131
	v_mul_f32_e32 v188, 0xbfb8aa3b, v24
	v_mul_f32_e32 v189, 0xbfb8aa3b, v25
	v_mul_f32_e32 v192, 0xbfb8aa3b, v14
	v_mul_f32_e32 v193, 0xbfb8aa3b, v15
	v_exp_f32_e32 v188, v188
	v_exp_f32_e32 v189, v189
	v_exp_f32_e32 v192, v192
	v_exp_f32_e32 v193, v193
	v_exp_f32_e32 v194, v194
	v_exp_f32_e32 v195, v195
	v_add_f32_e32 v188, 1.0, v188
	v_add_f32_e32 v189, 1.0, v189
	v_add_f32_e32 v192, 1.0, v192
	v_add_f32_e32 v193, 1.0, v193
	v_add_f32_e32 v194, 1.0, v194
	v_add_f32_e32 v195, 1.0, v195
	v_rcp_f32_e32 v188, v188
	v_rcp_f32_e32 v189, v189
	v_rcp_f32_e32 v192, v192
	v_rcp_f32_e32 v193, v193
	v_rcp_f32_e32 v194, v194
	v_rcp_f32_e32 v195, v195
	v_fma_f32 v188, v188, v165, v132
	v_fma_f32 v189, v189, v172, v133
	v_fma_f32 v192, v192, v174, v142
	v_fma_f32 v193, v193, v168, v143
	v_fma_f32 v194, v194, v176, v144
	v_fma_f32 v195, v195, v178, v145
	v_log_f32_e32 v186, v186
	v_log_f32_e32 v187, v187
	v_log_f32_e32 v188, v188
	v_log_f32_e32 v189, v189
	v_log_f32_e32 v192, v192
	v_log_f32_e32 v193, v193
	v_log_f32_e32 v194, v194
	v_log_f32_e32 v195, v195
	v_cvt_pk_bf16_f32 v186, v186, v187
	v_cvt_pk_bf16_f32 v187, v188, v189
	v_cvt_pk_bf16_f32 v188, v192, v193
	v_cvt_pk_bf16_f32 v189, v194, v195
	global_store_dwordx4 v[190:191], v[186:189], off offset:256 nt
	s_nop 1
	v_mul_f32_e32 v187, 0xbfb8aa3b, v19
	v_add_u32_e32 v186, 0x80b0, v183
	v_mul_f32_e32 v183, 0xbfb8aa3b, v18
	v_exp_f32_e32 v188, v187
	v_exp_f32_e32 v183, v183
	v_ashrrev_i32_e32 v187, 31, v186
	v_lshlrev_b64 v[186:187], 10, v[186:187]
	v_add_f32_e32 v188, 1.0, v188
	v_add_f32_e32 v183, 1.0, v183
	v_rcp_f32_e32 v188, v188
	v_rcp_f32_e32 v183, v183
	v_fma_f32 v139, v188, v184, v139
	v_mul_f32_e32 v184, 0xbfb8aa3b, v21
	v_fma_f32 v138, v183, v185, v138
	v_mul_f32_e32 v183, 0xbfb8aa3b, v20
	v_exp_f32_e32 v184, v184
	v_exp_f32_e32 v183, v183
	v_mul_f32_e32 v185, 0xbfb8aa3b, v10
	v_exp_f32_e32 v185, v185
	v_add_f32_e32 v184, 1.0, v184
	v_add_f32_e32 v183, 1.0, v183
	v_rcp_f32_e32 v184, v184
	v_rcp_f32_e32 v183, v183
	v_log_f32_e32 v138, v138
	v_log_f32_e32 v139, v139
	v_fmac_f32_e32 v141, v184, v181
	v_add_f32_e32 v181, 1.0, v185
	v_fma_f32 v140, v183, v182, v140
	v_rcp_f32_e32 v181, v181
	v_mul_f32_e32 v182, 0xbfb8aa3b, v11
	v_exp_f32_e32 v182, v182
	v_log_f32_e32 v140, v140
	v_fma_f32 v134, v181, v180, v134
	v_log_f32_e32 v180, v134
	v_add_f32_e32 v134, 1.0, v182
	v_mul_f32_e32 v181, 0xbfb8aa3b, v12
	v_mul_f32_e32 v182, 0xbfb8aa3b, v13
	v_rcp_f32_e32 v134, v134
	v_exp_f32_e32 v181, v181
	v_exp_f32_e32 v182, v182
	v_log_f32_e32 v141, v141
	v_fma_f32 v134, v134, v179, v135
	v_add_f32_e32 v135, 1.0, v181
	v_add_f32_e32 v179, 1.0, v182
	v_rcp_f32_e32 v135, v135
	v_rcp_f32_e32 v179, v179
	v_log_f32_e32 v181, v134
	v_fma_f32 v134, v135, v177, v136
	v_fmac_f32_e32 v137, v179, v175
	v_log_f32_e32 v177, v134
	v_log_f32_e32 v137, v137
	v_cvt_pk_bf16_f32 v134, v138, v139
	v_lshl_add_u64 v[138:139], s[20:21], 0, v[186:187]
	v_cvt_pk_bf16_f32 v135, v140, v141
	v_cvt_pk_bf16_f32 v136, v180, v181
	v_cvt_pk_bf16_f32 v137, v177, v137
	v_lshl_add_u64 v[138:139], v[138:139], 0, v[162:163]
	global_store_dwordx4 v[138:139], v[134:137], off nt
	v_mul_f32_e32 v140, 0xbfb8aa3b, v6
	v_mul_f32_e32 v141, 0xbfb8aa3b, v7
	v_mul_f32_e32 v134, 0xbfb8aa3b, v8
	v_mul_f32_e32 v135, 0xbfb8aa3b, v9
	v_exp_f32_e32 v134, v134
	v_exp_f32_e32 v135, v135
	v_mul_f32_e32 v136, 0xbfb8aa3b, v2
	v_exp_f32_e32 v136, v136
	v_add_f32_e32 v134, 1.0, v134
	v_add_f32_e32 v135, 1.0, v135
	v_rcp_f32_e32 v134, v134
	v_rcp_f32_e32 v135, v135
	v_mul_f32_e32 v137, 0xbfb8aa3b, v5
	v_exp_f32_e32 v140, v140
	v_fma_f32 v132, v134, v165, v132
	v_fmac_f32_e32 v133, v135, v172
	v_add_f32_e32 v134, 1.0, v136
	v_mul_f32_e32 v135, 0xbfb8aa3b, v3
	v_mul_f32_e32 v136, 0xbfb8aa3b, v4
	v_exp_f32_e32 v141, v141
	v_exp_f32_e32 v135, v135
	v_exp_f32_e32 v136, v136
	v_exp_f32_e32 v137, v137
	v_add_f32_e32 v140, 1.0, v140
	v_add_f32_e32 v141, 1.0, v141
	v_add_f32_e32 v135, 1.0, v135
	v_add_f32_e32 v136, 1.0, v136
	v_add_f32_e32 v137, 1.0, v137
	v_rcp_f32_e32 v140, v140
	v_rcp_f32_e32 v141, v141
	v_rcp_f32_e32 v134, v134
	v_rcp_f32_e32 v135, v135
	v_rcp_f32_e32 v136, v136
	v_rcp_f32_e32 v137, v137
	v_fma_f32 v130, v140, v156, v130
	v_fma_f32 v131, v141, v164, v131
	v_fma_f32 v134, v134, v174, v142
	v_fma_f32 v135, v135, v168, v143
	v_fma_f32 v136, v136, v176, v144
	v_fmac_f32_e32 v145, v137, v178
	v_log_f32_e32 v130, v130
	v_log_f32_e32 v131, v131
	v_log_f32_e32 v132, v132
	v_log_f32_e32 v133, v133
	v_log_f32_e32 v134, v134
	v_log_f32_e32 v135, v135
	v_log_f32_e32 v136, v136
	v_log_f32_e32 v137, v145
	v_cvt_pk_bf16_f32 v130, v130, v131
	v_cvt_pk_bf16_f32 v131, v132, v133
	v_cvt_pk_bf16_f32 v132, v134, v135
	v_cvt_pk_bf16_f32 v133, v136, v137
	global_store_dwordx4 v[138:139], v[130:133], off offset:256 nt

.LBB0_291:
	s_and_b64 vcc, exec, s[48:49]
	s_cbranch_vccz .LBB0_296
	v_mul_f32_e32 v130, 0xbfb8aa3b, v126
	v_mul_f32_e32 v131, 0xbfb8aa3b, v127
	v_mul_f32_e32 v132, 0xbfb8aa3b, v128
	v_mul_f32_e32 v133, 0xbfb8aa3b, v129
	v_mul_f32_e32 v134, 0xbfb8aa3b, v122
	v_mul_f32_e32 v135, 0xbfb8aa3b, v123
	v_mul_f32_e32 v136, 0xbfb8aa3b, v124
	v_mul_f32_e32 v137, 0xbfb8aa3b, v125
	v_mul_f32_e32 v138, 0xbfb8aa3b, v118
	v_mul_f32_e32 v139, 0xbfb8aa3b, v119
	v_mul_f32_e32 v140, 0xbfb8aa3b, v120
	v_mul_f32_e32 v141, 0xbfb8aa3b, v121
	v_mul_f32_e32 v142, 0xbfb8aa3b, v110
	v_mul_f32_e32 v143, 0xbfb8aa3b, v111
	v_mul_f32_e32 v144, 0xbfb8aa3b, v112
	v_mul_f32_e32 v145, 0xbfb8aa3b, v113
	v_mul_f32_e32 v156, 0xbfb8aa3b, v114
	v_mul_f32_e32 v162, 0xbfb8aa3b, v115
	v_mul_f32_e32 v163, 0xbfb8aa3b, v116
	v_mul_f32_e32 v164, 0xbfb8aa3b, v117
	v_mul_f32_e32 v165, 0xbfb8aa3b, v106
	v_mul_f32_e32 v168, 0xbfb8aa3b, v107
	v_mul_f32_e32 v172, 0xbfb8aa3b, v108
	v_mul_f32_e32 v174, 0xbfb8aa3b, v109
	v_mul_f32_e32 v175, 0xbfb8aa3b, v102
	v_mul_f32_e32 v176, 0xbfb8aa3b, v103
	v_mul_f32_e32 v177, 0xbfb8aa3b, v104
	v_mul_f32_e32 v178, 0xbfb8aa3b, v105
	v_mul_f32_e32 v179, 0xbfb8aa3b, v94
	v_mul_f32_e32 v180, 0xbfb8aa3b, v95
	v_mul_f32_e32 v181, 0xbfb8aa3b, v96
	v_mul_f32_e32 v182, 0xbfb8aa3b, v97
	v_mul_f32_e32 v183, 0xbfb8aa3b, v98
	v_mul_f32_e32 v184, 0xbfb8aa3b, v99
	v_mul_f32_e32 v185, 0xbfb8aa3b, v100
	v_mul_f32_e32 v186, 0xbfb8aa3b, v101
	v_mul_f32_e32 v187, 0xbfb8aa3b, v90
	v_mul_f32_e32 v188, 0xbfb8aa3b, v91
	v_mul_f32_e32 v189, 0xbfb8aa3b, v92
	v_mul_f32_e32 v190, 0xbfb8aa3b, v93
	v_mul_f32_e32 v191, 0xbfb8aa3b, v86
	v_mul_f32_e32 v192, 0xbfb8aa3b, v87
	v_mul_f32_e32 v193, 0xbfb8aa3b, v88
	v_mul_f32_e32 v194, 0xbfb8aa3b, v89
	v_mul_f32_e32 v195, 0xbfb8aa3b, v78
	v_mul_f32_e32 v196, 0xbfb8aa3b, v79
	v_mul_f32_e32 v197, 0xbfb8aa3b, v80
	v_mul_f32_e32 v198, 0xbfb8aa3b, v81
	v_mul_f32_e32 v246, 0xbfb8aa3b, v82
	v_mul_f32_e32 v247, 0xbfb8aa3b, v83
	v_mul_f32_e32 v248, 0xbfb8aa3b, v84
	v_mul_f32_e32 v249, 0xbfb8aa3b, v85
	v_exp_f32_e32 v245, v130
	v_exp_f32_e32 v244, v131
	v_exp_f32_e32 v243, v132
	v_exp_f32_e32 v242, v133
	v_exp_f32_e32 v241, v134
	v_exp_f32_e32 v240, v135
	v_exp_f32_e32 v239, v136
	v_exp_f32_e32 v238, v137
	v_exp_f32_e32 v237, v138
	v_exp_f32_e32 v236, v139
	v_exp_f32_e32 v235, v140
	v_exp_f32_e32 v234, v141
	v_exp_f32_e32 v233, v142
	v_exp_f32_e32 v232, v143
	v_exp_f32_e32 v231, v144
	v_exp_f32_e32 v230, v145
	v_exp_f32_e32 v229, v156
	v_exp_f32_e32 v228, v162
	v_exp_f32_e32 v227, v163
	v_exp_f32_e32 v226, v164
	v_exp_f32_e32 v225, v165
	v_exp_f32_e32 v224, v168
	v_exp_f32_e32 v223, v172
	v_exp_f32_e32 v222, v174
	v_exp_f32_e32 v221, v175
	v_exp_f32_e32 v220, v176
	v_exp_f32_e32 v219, v177
	v_exp_f32_e32 v218, v178
	v_exp_f32_e32 v217, v179
	v_exp_f32_e32 v216, v180
	v_exp_f32_e32 v215, v181
	v_exp_f32_e32 v214, v182
	v_exp_f32_e32 v213, v183
	v_exp_f32_e32 v212, v184
	v_exp_f32_e32 v211, v185
	v_exp_f32_e32 v210, v186
	v_exp_f32_e32 v209, v187
	v_exp_f32_e32 v208, v188
	v_exp_f32_e32 v207, v189
	v_exp_f32_e32 v206, v190
	v_exp_f32_e32 v205, v191
	v_exp_f32_e32 v204, v192
	v_exp_f32_e32 v203, v193
	v_exp_f32_e32 v202, v194
	v_exp_f32_e32 v201, v195
	v_exp_f32_e32 v200, v196
	v_exp_f32_e32 v199, v197
	v_exp_f32_e32 v198, v198
	v_exp_f32_e32 v197, v246
	v_exp_f32_e32 v196, v247
	v_exp_f32_e32 v195, v248
	v_exp_f32_e32 v193, v249
	s_mov_b64 s[48:49], -1
	s_cmp_gt_i32 s41, 4
	v_mul_f32_e32 v194, 0xbfb8aa3b, v74
	v_mul_f32_e32 v192, 0xbfb8aa3b, v75
	v_mul_f32_e32 v191, 0xbfb8aa3b, v76
	v_mul_f32_e32 v190, 0xbfb8aa3b, v77
	v_mul_f32_e32 v189, 0xbfb8aa3b, v70
	v_mul_f32_e32 v188, 0xbfb8aa3b, v71
	v_mul_f32_e32 v187, 0xbfb8aa3b, v72
	s_cbranch_scc0 .LBB0_294
	s_lshl_b32 s2, s66, 8
	s_and_b32 s2, s2, 0x100
	s_or_b32 s2, s2, s59
	v_add_u32_e32 v162, s2, v173
	v_ashrrev_i32_e32 v163, 31, v162
	v_lshl_add_u64 v[134:135], v[162:163], 2, s[12:13]
	global_load_dwordx4 v[138:141], v[134:135], off offset:16
	global_load_dwordx4 v[142:145], v[134:135], off
	global_load_dwordx4 v[130:133], v[134:135], off offset:528
	s_nop 0
	global_load_dwordx4 v[134:137], v[134:135], off offset:512
	v_add_f32_e32 v156, 1.0, v245
	v_rcp_f32_e32 v156, v156
	v_add_f32_e32 v168, 1.0, v242
	v_rcp_f32_e32 v168, v168
	v_add_f32_e32 v178, 1.0, v240
	v_rcp_f32_e32 v178, v178
	s_lshl_b32 s2, s33, 8
	s_add_i32 s2, s2, s58
	v_add_u32_e32 v175, s2, v171
	v_add_u32_e32 v164, 0x8000, v175
	v_ashrrev_i32_e32 v165, 31, v164
	v_lshlrev_b64 v[164:165], 10, v[164:165]
	v_lshl_add_u64 v[164:165], s[22:23], 0, v[164:165]
	v_lshlrev_b64 v[162:163], 1, v[162:163]
	v_lshl_add_u64 v[164:165], v[164:165], 0, v[162:163]
	v_add_f32_e32 v186, 1.0, v230
	v_rcp_f32_e32 v186, v186
	s_mov_b64 s[48:49], 0
	s_waitcnt vmcnt(0)
	v_sub_f32_e32 v252, 1.0, v138
	v_sub_f32_e32 v254, 1.0, v142
	v_fma_f32 v156, v156, v254, v142
	v_log_f32_e32 v172, v156
	v_add_f32_e32 v156, 1.0, v244
	v_rcp_f32_e32 v156, v156
	v_sub_f32_e32 v174, 1.0, v143
	v_sub_f32_e32 v176, 1.0, v144
	v_sub_f32_e32 v253, 1.0, v140
	v_fma_f32 v156, v156, v174, v143
	v_log_f32_e32 v177, v156
	v_add_f32_e32 v156, 1.0, v243
	v_rcp_f32_e32 v156, v156
	v_sub_f32_e32 v248, 1.0, v141
	v_sub_f32_e32 v246, 1.0, v134
	v_sub_f32_e32 v251, 1.0, v135
	v_fma_f32 v156, v156, v176, v144
	v_log_f32_e32 v179, v156
	v_sub_f32_e32 v156, 1.0, v145
	v_fma_f32 v168, v168, v156, v145
	v_log_f32_e32 v180, v168
	v_add_f32_e32 v168, 1.0, v241
	v_rcp_f32_e32 v168, v168
	v_sub_f32_e32 v250, 1.0, v137
	v_cvt_pk_bf16_f32 v179, v179, v180
	v_sub_f32_e32 v249, 1.0, v130
	v_fma_f32 v168, v168, v252, v138
	v_log_f32_e32 v181, v168
	v_sub_f32_e32 v168, 1.0, v139
	v_fma_f32 v178, v178, v168, v139
	v_log_f32_e32 v182, v178
	v_add_f32_e32 v178, 1.0, v239
	v_rcp_f32_e32 v178, v178
	v_cvt_pk_bf16_f32 v180, v181, v182
	v_fma_f32 v178, v178, v253, v140
	v_log_f32_e32 v183, v178
	v_add_f32_e32 v178, 1.0, v238
	v_rcp_f32_e32 v178, v178
	s_nop 0
	v_fma_f32 v178, v178, v248, v141
	v_log_f32_e32 v247, v178
	v_cvt_pk_bf16_f32 v178, v172, v177
	v_add_f32_e32 v172, 1.0, v237
	v_rcp_f32_e32 v172, v172
	v_cvt_pk_bf16_f32 v181, v183, v247
	global_store_dwordx4 v[164:165], v[178:181], off nt
	v_add_f32_e32 v177, 1.0, v235
	v_fma_f32 v172, v172, v246, v134
	v_log_f32_e32 v179, v172
	v_add_f32_e32 v172, 1.0, v236
	v_rcp_f32_e32 v172, v172
	v_rcp_f32_e32 v177, v177
	v_sub_f32_e32 v247, 1.0, v131
	v_sub_f32_e32 v178, 1.0, v132
	v_fma_f32 v172, v172, v251, v135
	v_log_f32_e32 v180, v172
	v_sub_f32_e32 v172, 1.0, v136
	v_fma_f32 v177, v177, v172, v136
	v_log_f32_e32 v181, v177
	v_add_f32_e32 v177, 1.0, v234
	v_rcp_f32_e32 v177, v177
	v_cvt_pk_bf16_f32 v180, v179, v180
	v_add_f32_e32 v179, 1.0, v229
	v_rcp_f32_e32 v179, v179
	v_fma_f32 v177, v177, v250, v137
	v_log_f32_e32 v182, v177
	v_add_f32_e32 v177, 1.0, v233
	v_rcp_f32_e32 v177, v177
	v_fma_f32 v179, v179, v254, v142
	v_cvt_pk_bf16_f32 v181, v181, v182
	v_log_f32_e32 v179, v179
	v_fma_f32 v177, v177, v249, v130
	v_log_f32_e32 v183, v177
	v_add_f32_e32 v177, 1.0, v232
	v_rcp_f32_e32 v177, v177
	s_nop 0
	v_fma_f32 v177, v177, v247, v131
	v_log_f32_e32 v184, v177
	v_add_f32_e32 v177, 1.0, v231
	v_rcp_f32_e32 v177, v177
	v_cvt_pk_bf16_f32 v182, v183, v184
	v_add_f32_e32 v184, 1.0, v224
	v_fma_f32 v177, v177, v178, v132
	v_log_f32_e32 v185, v177
	v_sub_f32_e32 v177, 1.0, v133
	v_fma_f32 v186, v186, v177, v133
	v_log_f32_e32 v186, v186
	v_rcp_f32_e32 v184, v184
	v_cvt_pk_bf16_f32 v183, v185, v186
	global_store_dwordx4 v[164:165], v[180:183], off offset:256 nt
	v_add_f32_e32 v185, 1.0, v223
	v_add_f32_e32 v186, 1.0, v222
	v_add_f32_e32 v180, 1.0, v228
	v_add_f32_e32 v181, 1.0, v227
	v_add_f32_e32 v182, 1.0, v226
	v_add_f32_e32 v183, 1.0, v225
	v_rcp_f32_e32 v180, v180
	v_rcp_f32_e32 v181, v181
	v_rcp_f32_e32 v182, v182
	v_rcp_f32_e32 v183, v183
	v_rcp_f32_e32 v185, v185
	v_rcp_f32_e32 v186, v186
	v_fma_f32 v180, v180, v174, v143
	v_fma_f32 v181, v181, v176, v144
	v_fma_f32 v182, v182, v156, v145
	v_fma_f32 v183, v183, v252, v138
	v_fma_f32 v184, v184, v168, v139
	v_fma_f32 v185, v185, v253, v140
	v_fma_f32 v186, v186, v248, v141
	v_add_u32_e32 v164, 0x8010, v175
	v_log_f32_e32 v180, v180
	v_log_f32_e32 v181, v181
	v_log_f32_e32 v182, v182
	v_log_f32_e32 v183, v183
	v_log_f32_e32 v184, v184
	v_log_f32_e32 v185, v185
	v_log_f32_e32 v186, v186
	v_ashrrev_i32_e32 v165, 31, v164
	v_lshlrev_b64 v[164:165], 10, v[164:165]
	v_lshl_add_u64 v[164:165], s[22:23], 0, v[164:165]
	v_cvt_pk_bf16_f32 v180, v179, v180
	v_cvt_pk_bf16_f32 v181, v181, v182
	v_cvt_pk_bf16_f32 v182, v183, v184
	v_cvt_pk_bf16_f32 v183, v185, v186
	v_lshl_add_u64 v[164:165], v[164:165], 0, v[162:163]
	global_store_dwordx4 v[164:165], v[180:183], off nt
	v_add_f32_e32 v179, 1.0, v221
	v_add_f32_e32 v184, 1.0, v216
	v_add_f32_e32 v180, 1.0, v220
	v_add_f32_e32 v181, 1.0, v219
	v_add_f32_e32 v182, 1.0, v218
	v_add_f32_e32 v183, 1.0, v217
	v_add_f32_e32 v185, 1.0, v215
	v_add_f32_e32 v186, 1.0, v214
	v_rcp_f32_e32 v179, v179
	v_rcp_f32_e32 v180, v180
	v_rcp_f32_e32 v181, v181
	v_rcp_f32_e32 v182, v182
	v_rcp_f32_e32 v183, v183
	v_rcp_f32_e32 v184, v184
	v_rcp_f32_e32 v185, v185
	v_rcp_f32_e32 v186, v186
	v_fma_f32 v179, v179, v246, v134
	v_fma_f32 v180, v180, v251, v135
	v_fma_f32 v181, v181, v172, v136
	v_fma_f32 v182, v182, v250, v137
	v_fma_f32 v183, v183, v249, v130
	v_fma_f32 v184, v184, v247, v131
	v_fma_f32 v185, v185, v178, v132
	v_fma_f32 v186, v186, v177, v133
	v_log_f32_e32 v179, v179
	v_log_f32_e32 v180, v180
	v_log_f32_e32 v181, v181
	v_log_f32_e32 v182, v182
	v_log_f32_e32 v183, v183
	v_log_f32_e32 v184, v184
	v_log_f32_e32 v185, v185
	v_log_f32_e32 v186, v186
	v_cvt_pk_bf16_f32 v180, v179, v180
	v_cvt_pk_bf16_f32 v181, v181, v182
	v_cvt_pk_bf16_f32 v182, v183, v184
	v_cvt_pk_bf16_f32 v183, v185, v186
	global_store_dwordx4 v[164:165], v[180:183], off offset:256 nt
	v_add_f32_e32 v179, 1.0, v213
	v_add_f32_e32 v184, 1.0, v208
	v_add_f32_e32 v180, 1.0, v212
	v_add_f32_e32 v181, 1.0, v211
	v_add_f32_e32 v182, 1.0, v210
	v_add_f32_e32 v183, 1.0, v209
	v_add_f32_e32 v185, 1.0, v207
	v_add_f32_e32 v186, 1.0, v206
	v_rcp_f32_e32 v179, v179
	v_rcp_f32_e32 v180, v180
	v_rcp_f32_e32 v181, v181
	v_rcp_f32_e32 v182, v182
	v_rcp_f32_e32 v183, v183
	v_rcp_f32_e32 v184, v184
	v_rcp_f32_e32 v185, v185
	v_rcp_f32_e32 v186, v186
	v_fma_f32 v179, v179, v254, v142
	v_fma_f32 v180, v180, v174, v143
	v_fma_f32 v181, v181, v176, v144
	v_fma_f32 v182, v182, v156, v145
	v_fma_f32 v183, v183, v252, v138
	v_fma_f32 v184, v184, v168, v139
	v_fma_f32 v185, v185, v253, v140
	v_fma_f32 v186, v186, v248, v141
	v_add_u32_e32 v164, 0x8020, v175
	v_log_f32_e32 v179, v179
	v_log_f32_e32 v180, v180
	v_log_f32_e32 v181, v181
	v_log_f32_e32 v182, v182
	v_log_f32_e32 v183, v183
	v_log_f32_e32 v184, v184
	v_log_f32_e32 v185, v185
	v_log_f32_e32 v186, v186
	v_ashrrev_i32_e32 v165, 31, v164
	v_lshlrev_b64 v[164:165], 10, v[164:165]
	v_lshl_add_u64 v[164:165], s[22:23], 0, v[164:165]
	v_cvt_pk_bf16_f32 v180, v179, v180
	v_cvt_pk_bf16_f32 v181, v181, v182
	v_cvt_pk_bf16_f32 v182, v183, v184
	v_cvt_pk_bf16_f32 v183, v185, v186
	v_lshl_add_u64 v[164:165], v[164:165], 0, v[162:163]
	global_store_dwordx4 v[164:165], v[180:183], off nt
	v_add_f32_e32 v179, 1.0, v205
	v_add_f32_e32 v184, 1.0, v200
	v_add_f32_e32 v180, 1.0, v204
	v_add_f32_e32 v181, 1.0, v203
	v_add_f32_e32 v182, 1.0, v202
	v_add_f32_e32 v183, 1.0, v201
	v_add_f32_e32 v185, 1.0, v199
	v_add_f32_e32 v186, 1.0, v198
	v_rcp_f32_e32 v179, v179
	v_rcp_f32_e32 v180, v180
	v_rcp_f32_e32 v181, v181
	v_rcp_f32_e32 v182, v182
	v_rcp_f32_e32 v183, v183
	v_rcp_f32_e32 v184, v184
	v_rcp_f32_e32 v185, v185
	v_rcp_f32_e32 v186, v186
	v_fma_f32 v179, v179, v246, v134
	v_fma_f32 v180, v180, v251, v135
	v_fma_f32 v181, v181, v172, v136
	v_fma_f32 v182, v182, v250, v137
	v_fma_f32 v183, v183, v249, v130
	v_fma_f32 v184, v184, v247, v131
	v_fma_f32 v185, v185, v178, v132
	v_fma_f32 v186, v186, v177, v133
	v_log_f32_e32 v179, v179
	v_log_f32_e32 v180, v180
	v_log_f32_e32 v181, v181
	v_log_f32_e32 v182, v182
	v_log_f32_e32 v183, v183
	v_log_f32_e32 v184, v184
	v_log_f32_e32 v185, v185
	v_log_f32_e32 v186, v186
	v_cvt_pk_bf16_f32 v180, v179, v180
	v_cvt_pk_bf16_f32 v181, v181, v182
	v_cvt_pk_bf16_f32 v182, v183, v184
	v_cvt_pk_bf16_f32 v183, v185, v186
	global_store_dwordx4 v[164:165], v[180:183], off offset:256 nt
	v_exp_f32_e32 v184, v192
	v_exp_f32_e32 v185, v191
	v_exp_f32_e32 v183, v194
	v_exp_f32_e32 v186, v190
	v_add_f32_e32 v179, 1.0, v197
	v_add_f32_e32 v180, 1.0, v196
	v_add_f32_e32 v181, 1.0, v195
	v_add_f32_e32 v182, 1.0, v193
	v_add_f32_e32 v183, 1.0, v183
	v_add_f32_e32 v184, 1.0, v184
	v_add_f32_e32 v185, 1.0, v185
	v_add_f32_e32 v186, 1.0, v186
	v_rcp_f32_e32 v179, v179
	v_rcp_f32_e32 v180, v180
	v_rcp_f32_e32 v181, v181
	v_rcp_f32_e32 v182, v182
	v_rcp_f32_e32 v183, v183
	v_rcp_f32_e32 v184, v184
	v_rcp_f32_e32 v185, v185
	v_rcp_f32_e32 v186, v186
	v_fma_f32 v179, v179, v254, v142
	v_fma_f32 v180, v180, v174, v143
	v_fma_f32 v181, v181, v176, v144
	v_fma_f32 v182, v182, v156, v145
	v_fma_f32 v183, v183, v252, v138
	v_fma_f32 v184, v184, v168, v139
	v_fma_f32 v185, v185, v253, v140
	v_fma_f32 v186, v186, v248, v141
	v_add_u32_e32 v164, 0x8030, v175
	v_log_f32_e32 v179, v179
	v_log_f32_e32 v180, v180
	v_log_f32_e32 v181, v181
	v_log_f32_e32 v182, v182
	v_log_f32_e32 v183, v183
	v_log_f32_e32 v184, v184
	v_log_f32_e32 v185, v185
	v_log_f32_e32 v186, v186
	v_ashrrev_i32_e32 v165, 31, v164
	v_lshlrev_b64 v[164:165], 10, v[164:165]
	v_lshl_add_u64 v[164:165], s[22:23], 0, v[164:165]
	v_cvt_pk_bf16_f32 v180, v179, v180
	v_cvt_pk_bf16_f32 v181, v181, v182
	v_cvt_pk_bf16_f32 v182, v183, v184
	v_cvt_pk_bf16_f32 v183, v185, v186
	v_lshl_add_u64 v[164:165], v[164:165], 0, v[162:163]
	global_store_dwordx4 v[164:165], v[180:183], off nt
	v_mul_f32_e32 v184, 0xbfb8aa3b, v67
	v_mul_f32_e32 v185, 0xbfb8aa3b, v68
	v_mul_f32_e32 v182, 0xbfb8aa3b, v73
	v_mul_f32_e32 v183, 0xbfb8aa3b, v66
	v_mul_f32_e32 v186, 0xbfb8aa3b, v69
	v_exp_f32_e32 v179, v189
	v_exp_f32_e32 v180, v188
	v_exp_f32_e32 v181, v187
	v_exp_f32_e32 v182, v182
	v_exp_f32_e32 v183, v183
	v_exp_f32_e32 v184, v184
	v_exp_f32_e32 v185, v185
	v_exp_f32_e32 v186, v186
	v_add_f32_e32 v179, 1.0, v179
	v_add_f32_e32 v180, 1.0, v180
	v_add_f32_e32 v181, 1.0, v181
	v_add_f32_e32 v182, 1.0, v182
	v_add_f32_e32 v183, 1.0, v183
	v_add_f32_e32 v184, 1.0, v184
	v_add_f32_e32 v185, 1.0, v185
	v_add_f32_e32 v186, 1.0, v186
	v_rcp_f32_e32 v179, v179
	v_rcp_f32_e32 v180, v180
	v_rcp_f32_e32 v181, v181
	v_rcp_f32_e32 v182, v182
	v_rcp_f32_e32 v183, v183
	v_rcp_f32_e32 v184, v184
	v_rcp_f32_e32 v185, v185
	v_rcp_f32_e32 v186, v186
	v_fma_f32 v179, v179, v246, v134
	v_fma_f32 v180, v180, v251, v135
	v_fma_f32 v181, v181, v172, v136
	v_fma_f32 v182, v182, v250, v137
	v_fma_f32 v183, v183, v249, v130
	v_fma_f32 v184, v184, v247, v131
	v_fma_f32 v185, v185, v178, v132
	v_fma_f32 v186, v186, v177, v133
	v_log_f32_e32 v179, v179
	v_log_f32_e32 v180, v180
	v_log_f32_e32 v181, v181
	v_log_f32_e32 v182, v182
	v_log_f32_e32 v183, v183
	v_log_f32_e32 v184, v184
	v_log_f32_e32 v185, v185
	v_log_f32_e32 v186, v186
	v_cvt_pk_bf16_f32 v180, v179, v180
	v_cvt_pk_bf16_f32 v181, v181, v182
	v_cvt_pk_bf16_f32 v182, v183, v184
	v_cvt_pk_bf16_f32 v183, v185, v186
	global_store_dwordx4 v[164:165], v[180:183], off offset:256 nt
	v_mul_f32_e32 v179, 0xbfb8aa3b, v62
	v_mul_f32_e32 v184, 0xbfb8aa3b, v59
	v_mul_f32_e32 v180, 0xbfb8aa3b, v63
	v_mul_f32_e32 v181, 0xbfb8aa3b, v64
	v_mul_f32_e32 v182, 0xbfb8aa3b, v65
	v_mul_f32_e32 v183, 0xbfb8aa3b, v58
	v_mul_f32_e32 v185, 0xbfb8aa3b, v60
	v_mul_f32_e32 v186, 0xbfb8aa3b, v61
	v_exp_f32_e32 v179, v179
	v_exp_f32_e32 v180, v180
	v_exp_f32_e32 v181, v181
	v_exp_f32_e32 v182, v182
	v_exp_f32_e32 v183, v183
	v_exp_f32_e32 v184, v184
	v_exp_f32_e32 v185, v185
	v_exp_f32_e32 v186, v186
	v_add_f32_e32 v179, 1.0, v179
	v_add_f32_e32 v180, 1.0, v180
	v_add_f32_e32 v181, 1.0, v181
	v_add_f32_e32 v182, 1.0, v182
	v_add_f32_e32 v183, 1.0, v183
	v_add_f32_e32 v184, 1.0, v184
	v_add_f32_e32 v185, 1.0, v185
	v_add_f32_e32 v186, 1.0, v186
	v_rcp_f32_e32 v179, v179
	v_rcp_f32_e32 v180, v180
	v_rcp_f32_e32 v181, v181
	v_rcp_f32_e32 v182, v182
	v_rcp_f32_e32 v183, v183
	v_rcp_f32_e32 v184, v184
	v_rcp_f32_e32 v185, v185
	v_rcp_f32_e32 v186, v186
	v_fma_f32 v179, v179, v254, v142
	v_fma_f32 v180, v180, v174, v143
	v_fma_f32 v181, v181, v176, v144
	v_fma_f32 v182, v182, v156, v145
	v_fma_f32 v183, v183, v252, v138
	v_fma_f32 v184, v184, v168, v139
	v_fma_f32 v185, v185, v253, v140
	v_fma_f32 v186, v186, v248, v141
	v_add_u32_e32 v164, 0x8080, v175
	v_log_f32_e32 v179, v179
	v_log_f32_e32 v180, v180
	v_log_f32_e32 v181, v181
	v_log_f32_e32 v182, v182
	v_log_f32_e32 v183, v183
	v_log_f32_e32 v184, v184
	v_log_f32_e32 v185, v185
	v_log_f32_e32 v186, v186
	v_ashrrev_i32_e32 v165, 31, v164
	v_lshlrev_b64 v[164:165], 10, v[164:165]
	v_lshl_add_u64 v[164:165], s[22:23], 0, v[164:165]
	v_cvt_pk_bf16_f32 v180, v179, v180
	v_cvt_pk_bf16_f32 v181, v181, v182
	v_cvt_pk_bf16_f32 v182, v183, v184
	v_cvt_pk_bf16_f32 v183, v185, v186
	v_lshl_add_u64 v[164:165], v[164:165], 0, v[162:163]
	global_store_dwordx4 v[164:165], v[180:183], off nt
	v_mul_f32_e32 v179, 0xbfb8aa3b, v54
	v_mul_f32_e32 v184, 0xbfb8aa3b, v47
	v_mul_f32_e32 v180, 0xbfb8aa3b, v55
	v_mul_f32_e32 v181, 0xbfb8aa3b, v56
	v_mul_f32_e32 v182, 0xbfb8aa3b, v57
	v_mul_f32_e32 v183, 0xbfb8aa3b, v46
	v_mul_f32_e32 v185, 0xbfb8aa3b, v48
	v_mul_f32_e32 v186, 0xbfb8aa3b, v49
	v_exp_f32_e32 v179, v179
	v_exp_f32_e32 v180, v180
	v_exp_f32_e32 v181, v181
	v_exp_f32_e32 v182, v182
	v_exp_f32_e32 v183, v183
	v_exp_f32_e32 v184, v184
	v_exp_f32_e32 v185, v185
	v_exp_f32_e32 v186, v186
	v_add_f32_e32 v179, 1.0, v179
	v_add_f32_e32 v180, 1.0, v180
	v_add_f32_e32 v181, 1.0, v181
	v_add_f32_e32 v182, 1.0, v182
	v_add_f32_e32 v183, 1.0, v183
	v_add_f32_e32 v184, 1.0, v184
	v_add_f32_e32 v185, 1.0, v185
	v_add_f32_e32 v186, 1.0, v186
	v_rcp_f32_e32 v179, v179
	v_rcp_f32_e32 v180, v180
	v_rcp_f32_e32 v181, v181
	v_rcp_f32_e32 v182, v182
	v_rcp_f32_e32 v183, v183
	v_rcp_f32_e32 v184, v184
	v_rcp_f32_e32 v185, v185
	v_rcp_f32_e32 v186, v186
	v_fma_f32 v179, v179, v246, v134
	v_fma_f32 v180, v180, v251, v135
	v_fma_f32 v181, v181, v172, v136
	v_fma_f32 v182, v182, v250, v137
	v_fma_f32 v183, v183, v249, v130
	v_fma_f32 v184, v184, v247, v131
	v_fma_f32 v185, v185, v178, v132
	v_fma_f32 v186, v186, v177, v133
	v_log_f32_e32 v179, v179
	v_log_f32_e32 v180, v180
	v_log_f32_e32 v181, v181
	v_log_f32_e32 v182, v182
	v_log_f32_e32 v183, v183
	v_log_f32_e32 v184, v184
	v_log_f32_e32 v185, v185
	v_log_f32_e32 v186, v186
	v_cvt_pk_bf16_f32 v180, v179, v180
	v_cvt_pk_bf16_f32 v181, v181, v182
	v_cvt_pk_bf16_f32 v182, v183, v184
	v_cvt_pk_bf16_f32 v183, v185, v186
	global_store_dwordx4 v[164:165], v[180:183], off offset:256 nt
	v_mul_f32_e32 v179, 0xbfb8aa3b, v50
	v_mul_f32_e32 v184, 0xbfb8aa3b, v43
	v_mul_f32_e32 v180, 0xbfb8aa3b, v51
	v_mul_f32_e32 v181, 0xbfb8aa3b, v52
	v_mul_f32_e32 v182, 0xbfb8aa3b, v53
	v_mul_f32_e32 v183, 0xbfb8aa3b, v42
	v_mul_f32_e32 v185, 0xbfb8aa3b, v44
	v_mul_f32_e32 v186, 0xbfb8aa3b, v45
	v_exp_f32_e32 v179, v179
	v_exp_f32_e32 v180, v180
	v_exp_f32_e32 v181, v181
	v_exp_f32_e32 v182, v182
	v_exp_f32_e32 v183, v183
	v_exp_f32_e32 v184, v184
	v_exp_f32_e32 v185, v185
	v_exp_f32_e32 v186, v186
	v_add_f32_e32 v179, 1.0, v179
	v_add_f32_e32 v180, 1.0, v180
	v_add_f32_e32 v181, 1.0, v181
	v_add_f32_e32 v182, 1.0, v182
	v_add_f32_e32 v183, 1.0, v183
	v_add_f32_e32 v184, 1.0, v184
	v_add_f32_e32 v185, 1.0, v185
	v_add_f32_e32 v186, 1.0, v186
	v_rcp_f32_e32 v179, v179
	v_rcp_f32_e32 v180, v180
	v_rcp_f32_e32 v181, v181
	v_rcp_f32_e32 v182, v182
	v_rcp_f32_e32 v183, v183
	v_rcp_f32_e32 v184, v184
	v_rcp_f32_e32 v185, v185
	v_rcp_f32_e32 v186, v186
	v_fma_f32 v179, v179, v254, v142
	v_fma_f32 v180, v180, v174, v143
	v_fma_f32 v181, v181, v176, v144
	v_fma_f32 v182, v182, v156, v145
	v_fma_f32 v183, v183, v252, v138
	v_fma_f32 v184, v184, v168, v139
	v_fma_f32 v185, v185, v253, v140
	v_fma_f32 v186, v186, v248, v141
	v_add_u32_e32 v164, 0x8090, v175
	v_log_f32_e32 v179, v179
	v_log_f32_e32 v180, v180
	v_log_f32_e32 v181, v181
	v_log_f32_e32 v182, v182
	v_log_f32_e32 v183, v183
	v_log_f32_e32 v184, v184
	v_log_f32_e32 v185, v185
	v_log_f32_e32 v186, v186
	v_ashrrev_i32_e32 v165, 31, v164
	v_lshlrev_b64 v[164:165], 10, v[164:165]
	v_lshl_add_u64 v[164:165], s[22:23], 0, v[164:165]
	v_cvt_pk_bf16_f32 v180, v179, v180
	v_cvt_pk_bf16_f32 v181, v181, v182
	v_cvt_pk_bf16_f32 v182, v183, v184
	v_cvt_pk_bf16_f32 v183, v185, v186
	v_lshl_add_u64 v[164:165], v[164:165], 0, v[162:163]
	global_store_dwordx4 v[164:165], v[180:183], off nt
	v_mul_f32_e32 v179, 0xbfb8aa3b, v38
	v_mul_f32_e32 v184, 0xbfb8aa3b, v31
	v_mul_f32_e32 v180, 0xbfb8aa3b, v39
	v_mul_f32_e32 v181, 0xbfb8aa3b, v40
	v_mul_f32_e32 v182, 0xbfb8aa3b, v41
	v_mul_f32_e32 v183, 0xbfb8aa3b, v30
	v_mul_f32_e32 v185, 0xbfb8aa3b, v32
	v_mul_f32_e32 v186, 0xbfb8aa3b, v33
	v_exp_f32_e32 v179, v179
	v_exp_f32_e32 v180, v180
	v_exp_f32_e32 v181, v181
	v_exp_f32_e32 v182, v182
	v_exp_f32_e32 v183, v183
	v_exp_f32_e32 v184, v184
	v_exp_f32_e32 v185, v185
	v_exp_f32_e32 v186, v186
	v_add_f32_e32 v179, 1.0, v179
	v_add_f32_e32 v180, 1.0, v180
	v_add_f32_e32 v181, 1.0, v181
	v_add_f32_e32 v182, 1.0, v182
	v_add_f32_e32 v183, 1.0, v183
	v_add_f32_e32 v184, 1.0, v184
	v_add_f32_e32 v185, 1.0, v185
	v_add_f32_e32 v186, 1.0, v186
	v_rcp_f32_e32 v179, v179
	v_rcp_f32_e32 v180, v180
	v_rcp_f32_e32 v181, v181
	v_rcp_f32_e32 v182, v182
	v_rcp_f32_e32 v183, v183
	v_rcp_f32_e32 v184, v184
	v_rcp_f32_e32 v185, v185
	v_rcp_f32_e32 v186, v186
	v_fma_f32 v179, v179, v246, v134
	v_fma_f32 v180, v180, v251, v135
	v_fma_f32 v181, v181, v172, v136
	v_fma_f32 v182, v182, v250, v137
	v_fma_f32 v183, v183, v249, v130
	v_fma_f32 v184, v184, v247, v131
	v_fma_f32 v185, v185, v178, v132
	v_fma_f32 v186, v186, v177, v133
	v_log_f32_e32 v179, v179
	v_log_f32_e32 v180, v180
	v_log_f32_e32 v181, v181
	v_log_f32_e32 v182, v182
	v_log_f32_e32 v183, v183
	v_log_f32_e32 v184, v184
	v_log_f32_e32 v185, v185
	v_log_f32_e32 v186, v186
	v_cvt_pk_bf16_f32 v180, v179, v180
	v_cvt_pk_bf16_f32 v181, v181, v182
	v_cvt_pk_bf16_f32 v182, v183, v184
	v_cvt_pk_bf16_f32 v183, v185, v186
	global_store_dwordx4 v[164:165], v[180:183], off offset:256 nt
	v_mul_f32_e32 v179, 0xbfb8aa3b, v34
	v_mul_f32_e32 v184, 0xbfb8aa3b, v27
	v_mul_f32_e32 v180, 0xbfb8aa3b, v35
	v_mul_f32_e32 v181, 0xbfb8aa3b, v36
	v_mul_f32_e32 v182, 0xbfb8aa3b, v37
	v_mul_f32_e32 v183, 0xbfb8aa3b, v26
	v_mul_f32_e32 v185, 0xbfb8aa3b, v28
	v_mul_f32_e32 v186, 0xbfb8aa3b, v29
	v_exp_f32_e32 v179, v179
	v_exp_f32_e32 v180, v180
	v_exp_f32_e32 v181, v181
	v_exp_f32_e32 v182, v182
	v_exp_f32_e32 v183, v183
	v_exp_f32_e32 v184, v184
	v_exp_f32_e32 v185, v185
	v_exp_f32_e32 v186, v186
	v_add_f32_e32 v179, 1.0, v179
	v_add_f32_e32 v180, 1.0, v180
	v_add_f32_e32 v181, 1.0, v181
	v_add_f32_e32 v182, 1.0, v182
	v_add_f32_e32 v183, 1.0, v183
	v_add_f32_e32 v184, 1.0, v184
	v_add_f32_e32 v185, 1.0, v185
	v_add_f32_e32 v186, 1.0, v186
	v_rcp_f32_e32 v179, v179
	v_rcp_f32_e32 v180, v180
	v_rcp_f32_e32 v181, v181
	v_rcp_f32_e32 v182, v182
	v_rcp_f32_e32 v183, v183
	v_rcp_f32_e32 v184, v184
	v_rcp_f32_e32 v185, v185
	v_rcp_f32_e32 v186, v186
	v_fma_f32 v179, v179, v254, v142
	v_fma_f32 v180, v180, v174, v143
	v_fma_f32 v181, v181, v176, v144
	v_fma_f32 v182, v182, v156, v145
	v_fma_f32 v183, v183, v252, v138
	v_fma_f32 v184, v184, v168, v139
	v_fma_f32 v185, v185, v253, v140
	v_fma_f32 v186, v186, v248, v141
	v_add_u32_e32 v164, 0x80a0, v175
	v_log_f32_e32 v179, v179
	v_log_f32_e32 v180, v180
	v_log_f32_e32 v181, v181
	v_log_f32_e32 v182, v182
	v_log_f32_e32 v183, v183
	v_log_f32_e32 v184, v184
	v_log_f32_e32 v185, v185
	v_log_f32_e32 v186, v186
	v_ashrrev_i32_e32 v165, 31, v164
	v_lshlrev_b64 v[164:165], 10, v[164:165]
	v_lshl_add_u64 v[164:165], s[22:23], 0, v[164:165]
	v_cvt_pk_bf16_f32 v180, v179, v180
	v_cvt_pk_bf16_f32 v181, v181, v182
	v_cvt_pk_bf16_f32 v182, v183, v184
	v_cvt_pk_bf16_f32 v183, v185, v186
	v_lshl_add_u64 v[164:165], v[164:165], 0, v[162:163]
	global_store_dwordx4 v[164:165], v[180:183], off nt
	v_mul_f32_e32 v179, 0xbfb8aa3b, v22
	v_mul_f32_e32 v184, 0xbfb8aa3b, v15
	v_mul_f32_e32 v180, 0xbfb8aa3b, v23
	v_mul_f32_e32 v181, 0xbfb8aa3b, v24
	v_mul_f32_e32 v182, 0xbfb8aa3b, v25
	v_mul_f32_e32 v183, 0xbfb8aa3b, v14
	v_mul_f32_e32 v185, 0xbfb8aa3b, v16
	v_mul_f32_e32 v186, 0xbfb8aa3b, v17
	v_exp_f32_e32 v179, v179
	v_exp_f32_e32 v180, v180
	v_exp_f32_e32 v181, v181
	v_exp_f32_e32 v182, v182
	v_exp_f32_e32 v183, v183
	v_exp_f32_e32 v184, v184
	v_exp_f32_e32 v185, v185
	v_exp_f32_e32 v186, v186
	v_add_f32_e32 v179, 1.0, v179
	v_add_f32_e32 v180, 1.0, v180
	v_add_f32_e32 v181, 1.0, v181
	v_add_f32_e32 v182, 1.0, v182
	v_add_f32_e32 v183, 1.0, v183
	v_add_f32_e32 v184, 1.0, v184
	v_add_f32_e32 v185, 1.0, v185
	v_add_f32_e32 v186, 1.0, v186
	v_rcp_f32_e32 v179, v179
	v_rcp_f32_e32 v180, v180
	v_rcp_f32_e32 v181, v181
	v_rcp_f32_e32 v182, v182
	v_rcp_f32_e32 v183, v183
	v_rcp_f32_e32 v184, v184
	v_rcp_f32_e32 v185, v185
	v_rcp_f32_e32 v186, v186
	v_fma_f32 v179, v179, v246, v134
	v_fma_f32 v180, v180, v251, v135
	v_fma_f32 v181, v181, v172, v136
	v_fma_f32 v182, v182, v250, v137
	v_fma_f32 v183, v183, v249, v130
	v_fma_f32 v184, v184, v247, v131
	v_fma_f32 v185, v185, v178, v132
	v_fma_f32 v186, v186, v177, v133
	v_log_f32_e32 v179, v179
	v_log_f32_e32 v180, v180
	v_log_f32_e32 v181, v181
	v_log_f32_e32 v182, v182
	v_log_f32_e32 v183, v183
	v_log_f32_e32 v184, v184
	v_log_f32_e32 v185, v185
	v_log_f32_e32 v186, v186
	v_cvt_pk_bf16_f32 v180, v179, v180
	v_cvt_pk_bf16_f32 v181, v181, v182
	v_cvt_pk_bf16_f32 v182, v183, v184
	v_cvt_pk_bf16_f32 v183, v185, v186
	global_store_dwordx4 v[164:165], v[180:183], off offset:256 nt
	v_add_u32_e32 v164, 0x80b0, v175
	v_mul_f32_e32 v175, 0xbfb8aa3b, v18
	v_exp_f32_e32 v175, v175
	v_ashrrev_i32_e32 v165, 31, v164
	v_lshlrev_b64 v[164:165], 10, v[164:165]
	v_add_f32_e32 v175, 1.0, v175
	v_rcp_f32_e32 v175, v175
	s_nop 0
	v_fma_f32 v142, v175, v254, v142
	v_mul_f32_e32 v175, 0xbfb8aa3b, v19
	v_exp_f32_e32 v175, v175
	v_log_f32_e32 v142, v142
	v_add_f32_e32 v175, 1.0, v175
	v_rcp_f32_e32 v175, v175
	s_nop 0
	v_fma_f32 v143, v175, v174, v143
	v_mul_f32_e32 v174, 0xbfb8aa3b, v20
	v_exp_f32_e32 v174, v174
	v_log_f32_e32 v143, v143
	v_add_f32_e32 v174, 1.0, v174
	v_rcp_f32_e32 v174, v174
	s_nop 0
	v_fma_f32 v144, v174, v176, v144
	v_mul_f32_e32 v174, 0xbfb8aa3b, v21
	v_exp_f32_e32 v174, v174
	v_log_f32_e32 v144, v144
	v_add_f32_e32 v174, 1.0, v174
	v_rcp_f32_e32 v174, v174
	s_nop 0
	v_fmac_f32_e32 v145, v174, v156
	v_mul_f32_e32 v156, 0xbfb8aa3b, v10
	v_exp_f32_e32 v156, v156
	v_log_f32_e32 v145, v145
	v_add_f32_e32 v156, 1.0, v156
	v_rcp_f32_e32 v156, v156
	s_nop 0
	v_fma_f32 v138, v156, v252, v138
	v_log_f32_e32 v156, v138
	v_mul_f32_e32 v138, 0xbfb8aa3b, v11
	v_exp_f32_e32 v138, v138
	s_nop 0
	v_add_f32_e32 v138, 1.0, v138
	v_rcp_f32_e32 v138, v138
	s_nop 0
	v_fma_f32 v138, v138, v168, v139
	v_log_f32_e32 v168, v138
	v_mul_f32_e32 v138, 0xbfb8aa3b, v12
	v_exp_f32_e32 v138, v138
	v_cvt_pk_bf16_f32 v139, v144, v145
	v_add_f32_e32 v138, 1.0, v138
	v_rcp_f32_e32 v138, v138
	s_nop 0
	v_fma_f32 v138, v138, v253, v140
	v_log_f32_e32 v174, v138
	v_mul_f32_e32 v138, 0xbfb8aa3b, v13
	v_exp_f32_e32 v138, v138
	v_cvt_pk_bf16_f32 v140, v156, v168
	v_add_f32_e32 v138, 1.0, v138
	v_rcp_f32_e32 v138, v138
	s_nop 0
	v_fmac_f32_e32 v141, v138, v248
	v_log_f32_e32 v141, v141
	v_cvt_pk_bf16_f32 v138, v142, v143
	v_lshl_add_u64 v[142:143], s[22:23], 0, v[164:165]
	v_lshl_add_u64 v[142:143], v[142:143], 0, v[162:163]
	v_cvt_pk_bf16_f32 v141, v174, v141
	global_store_dwordx4 v[142:143], v[138:141], off nt
	s_nop 1
	v_mul_f32_e32 v138, 0xbfb8aa3b, v6
	v_exp_f32_e32 v138, v138
	s_nop 0
	v_add_f32_e32 v138, 1.0, v138
	v_rcp_f32_e32 v138, v138
	s_nop 0
	v_fma_f32 v134, v138, v246, v134
	v_mul_f32_e32 v138, 0xbfb8aa3b, v7
	v_exp_f32_e32 v138, v138
	v_log_f32_e32 v134, v134
	v_add_f32_e32 v138, 1.0, v138
	v_rcp_f32_e32 v138, v138
	s_nop 0
	v_fma_f32 v135, v138, v251, v135
	v_mul_f32_e32 v138, 0xbfb8aa3b, v8
	v_exp_f32_e32 v138, v138
	v_log_f32_e32 v135, v135
	v_add_f32_e32 v138, 1.0, v138
	v_rcp_f32_e32 v138, v138
	s_nop 0
	v_fma_f32 v136, v138, v172, v136
	v_mul_f32_e32 v138, 0xbfb8aa3b, v9
	v_exp_f32_e32 v138, v138
	v_log_f32_e32 v136, v136
	v_add_f32_e32 v138, 1.0, v138
	v_rcp_f32_e32 v138, v138
	s_nop 0
	v_fmac_f32_e32 v137, v138, v250
	v_mul_f32_e32 v138, 0xbfb8aa3b, v2
	v_exp_f32_e32 v138, v138
	v_log_f32_e32 v137, v137
	v_add_f32_e32 v138, 1.0, v138
	v_rcp_f32_e32 v138, v138
	s_nop 0
	v_fma_f32 v130, v138, v249, v130
	v_log_f32_e32 v138, v130
	v_mul_f32_e32 v130, 0xbfb8aa3b, v3
	v_exp_f32_e32 v130, v130
	s_nop 0
	v_add_f32_e32 v130, 1.0, v130
	v_rcp_f32_e32 v130, v130
	s_nop 0
	v_fma_f32 v130, v130, v247, v131
	v_log_f32_e32 v139, v130
	v_mul_f32_e32 v130, 0xbfb8aa3b, v4
	v_exp_f32_e32 v130, v130
	v_cvt_pk_bf16_f32 v131, v136, v137
	v_add_f32_e32 v130, 1.0, v130
	v_rcp_f32_e32 v130, v130
	s_nop 0
	v_fma_f32 v130, v130, v178, v132
	v_log_f32_e32 v140, v130
	v_mul_f32_e32 v130, 0xbfb8aa3b, v5
	v_exp_f32_e32 v130, v130
	v_cvt_pk_bf16_f32 v132, v138, v139
	v_add_f32_e32 v130, 1.0, v130
	v_rcp_f32_e32 v130, v130
	s_nop 0
	v_fmac_f32_e32 v133, v130, v177
	v_log_f32_e32 v133, v133
	v_cvt_pk_bf16_f32 v130, v134, v135
	v_cvt_pk_bf16_f32 v133, v140, v133
	global_store_dwordx4 v[142:143], v[130:133], off offset:256 nt
.LBB0_294:
	s_andn2_b64 vcc, exec, s[48:49]
	s_cbranch_vccnz .LBB0_296
	s_lshl_b32 s2, s66, 8
	s_and_b32 s2, s2, 0x100
	s_or_b32 s2, s2, s59
	v_add_u32_e32 v130, s2, v173
	s_lshl_b32 s2, s33, 8
	s_add_i32 s2, s2, s58
	v_add_u32_e32 v132, s2, v171
	v_add_u32_e32 v134, 0x8000, v132
	v_ashrrev_i32_e32 v135, 31, v134
	v_add_f32_e32 v131, 1.0, v245
	v_lshlrev_b64 v[138:139], 10, v[134:135]
	v_rcp_f32_e32 v134, v131
	v_add_f32_e32 v131, 1.0, v244
	v_rcp_f32_e32 v135, v131
	v_add_f32_e32 v131, 1.0, v243
	v_rcp_f32_e32 v136, v131
	v_add_f32_e32 v131, 1.0, v242
	v_rcp_f32_e32 v137, v131
	v_add_f32_e32 v131, 1.0, v241
	v_rcp_f32_e32 v140, v131
	v_add_f32_e32 v131, 1.0, v240
	v_rcp_f32_e32 v141, v131
	v_add_f32_e32 v131, 1.0, v239
	v_rcp_f32_e32 v142, v131
	v_add_f32_e32 v131, 1.0, v238
	v_rcp_f32_e32 v143, v131
	v_ashrrev_i32_e32 v131, 31, v130
	v_pk_mul_f32 v[134:135], v[126:127], v[134:135]
	v_pk_mul_f32 v[136:137], v[128:129], v[136:137]
	v_pk_mul_f32 v[140:141], v[122:123], v[140:141]
	v_pk_mul_f32 v[142:143], v[124:125], v[142:143]
	v_lshl_add_u64 v[138:139], s[24:25], 0, v[138:139]
	v_lshlrev_b64 v[130:131], 1, v[130:131]
	v_cvt_pk_bf16_f32 v134, v134, v135
	v_cvt_pk_bf16_f32 v135, v136, v137
	v_cvt_pk_bf16_f32 v136, v140, v141
	v_cvt_pk_bf16_f32 v137, v142, v143
	v_lshl_add_u64 v[138:139], v[138:139], 0, v[130:131]
	v_add_f32_e32 v133, 1.0, v237
	global_store_dwordx4 v[138:139], v[134:137], off nt
	s_nop 1
	v_rcp_f32_e32 v134, v133
	v_add_f32_e32 v133, 1.0, v236
	v_rcp_f32_e32 v135, v133
	v_add_f32_e32 v133, 1.0, v235
	v_rcp_f32_e32 v136, v133
	v_add_f32_e32 v133, 1.0, v234
	v_rcp_f32_e32 v137, v133
	v_add_f32_e32 v133, 1.0, v233
	v_rcp_f32_e32 v140, v133
	v_add_f32_e32 v133, 1.0, v232
	v_rcp_f32_e32 v141, v133
	v_add_f32_e32 v133, 1.0, v231
	v_rcp_f32_e32 v142, v133
	v_add_f32_e32 v133, 1.0, v230
	v_rcp_f32_e32 v143, v133
	v_pk_mul_f32 v[134:135], v[118:119], v[134:135]
	v_pk_mul_f32 v[136:137], v[120:121], v[136:137]
	v_pk_mul_f32 v[140:141], v[110:111], v[140:141]
	v_pk_mul_f32 v[142:143], v[112:113], v[142:143]
	v_cvt_pk_bf16_f32 v134, v134, v135
	v_cvt_pk_bf16_f32 v135, v136, v137
	v_cvt_pk_bf16_f32 v136, v140, v141
	v_cvt_pk_bf16_f32 v137, v142, v143
	global_store_dwordx4 v[138:139], v[134:137], off offset:256 nt
	v_add_f32_e32 v133, 1.0, v229
	s_nop 0
	v_add_u32_e32 v134, 0x8010, v132
	v_ashrrev_i32_e32 v135, 31, v134
	v_lshlrev_b64 v[138:139], 10, v[134:135]
	v_rcp_f32_e32 v134, v133
	v_add_f32_e32 v133, 1.0, v228
	v_rcp_f32_e32 v135, v133
	v_add_f32_e32 v133, 1.0, v227
	v_rcp_f32_e32 v136, v133
	v_add_f32_e32 v133, 1.0, v226
	v_rcp_f32_e32 v137, v133
	v_add_f32_e32 v133, 1.0, v225
	v_rcp_f32_e32 v140, v133
	v_add_f32_e32 v133, 1.0, v224
	v_rcp_f32_e32 v141, v133
	v_add_f32_e32 v133, 1.0, v223
	v_rcp_f32_e32 v142, v133
	v_add_f32_e32 v133, 1.0, v222
	v_rcp_f32_e32 v143, v133
	v_pk_mul_f32 v[134:135], v[114:115], v[134:135]
	v_pk_mul_f32 v[136:137], v[116:117], v[136:137]
	v_pk_mul_f32 v[140:141], v[106:107], v[140:141]
	v_pk_mul_f32 v[142:143], v[108:109], v[142:143]
	v_lshl_add_u64 v[138:139], s[24:25], 0, v[138:139]
	v_cvt_pk_bf16_f32 v134, v134, v135
	v_cvt_pk_bf16_f32 v135, v136, v137
	v_cvt_pk_bf16_f32 v136, v140, v141
	v_cvt_pk_bf16_f32 v137, v142, v143
	v_lshl_add_u64 v[138:139], v[138:139], 0, v[130:131]
	v_add_f32_e32 v133, 1.0, v221
	global_store_dwordx4 v[138:139], v[134:137], off nt
	s_nop 1
	v_rcp_f32_e32 v134, v133
	v_add_f32_e32 v133, 1.0, v220
	v_rcp_f32_e32 v135, v133
	v_add_f32_e32 v133, 1.0, v219
	v_rcp_f32_e32 v136, v133
	v_add_f32_e32 v133, 1.0, v218
	v_rcp_f32_e32 v137, v133
	v_add_f32_e32 v133, 1.0, v217
	v_rcp_f32_e32 v140, v133
	v_add_f32_e32 v133, 1.0, v216
	v_rcp_f32_e32 v141, v133
	v_add_f32_e32 v133, 1.0, v215
	v_rcp_f32_e32 v142, v133
	v_add_f32_e32 v133, 1.0, v214
	v_rcp_f32_e32 v143, v133
	v_pk_mul_f32 v[134:135], v[102:103], v[134:135]
	v_pk_mul_f32 v[136:137], v[104:105], v[136:137]
	v_pk_mul_f32 v[140:141], v[94:95], v[140:141]
	v_pk_mul_f32 v[142:143], v[96:97], v[142:143]
	v_cvt_pk_bf16_f32 v134, v134, v135
	v_cvt_pk_bf16_f32 v135, v136, v137
	v_cvt_pk_bf16_f32 v136, v140, v141
	v_cvt_pk_bf16_f32 v137, v142, v143
	global_store_dwordx4 v[138:139], v[134:137], off offset:256 nt
	v_add_f32_e32 v133, 1.0, v213
	s_nop 0
	v_add_u32_e32 v134, 0x8020, v132
	v_ashrrev_i32_e32 v135, 31, v134
	v_lshlrev_b64 v[138:139], 10, v[134:135]
	v_rcp_f32_e32 v134, v133
	v_add_f32_e32 v133, 1.0, v212
	v_rcp_f32_e32 v135, v133
	v_add_f32_e32 v133, 1.0, v211
	v_rcp_f32_e32 v136, v133
	v_add_f32_e32 v133, 1.0, v210
	v_rcp_f32_e32 v137, v133
	v_add_f32_e32 v133, 1.0, v209
	v_rcp_f32_e32 v140, v133
	v_add_f32_e32 v133, 1.0, v208
	v_rcp_f32_e32 v141, v133
	v_add_f32_e32 v133, 1.0, v207
	v_rcp_f32_e32 v142, v133
	v_add_f32_e32 v133, 1.0, v206
	v_rcp_f32_e32 v143, v133
	v_pk_mul_f32 v[134:135], v[98:99], v[134:135]
	v_pk_mul_f32 v[136:137], v[100:101], v[136:137]
	v_pk_mul_f32 v[140:141], v[90:91], v[140:141]
	v_pk_mul_f32 v[142:143], v[92:93], v[142:143]
	v_lshl_add_u64 v[138:139], s[24:25], 0, v[138:139]
	v_cvt_pk_bf16_f32 v134, v134, v135
	v_cvt_pk_bf16_f32 v135, v136, v137
	v_cvt_pk_bf16_f32 v136, v140, v141
	v_cvt_pk_bf16_f32 v137, v142, v143
	v_lshl_add_u64 v[138:139], v[138:139], 0, v[130:131]
	v_add_f32_e32 v133, 1.0, v205
	global_store_dwordx4 v[138:139], v[134:137], off nt
	s_nop 1
	v_rcp_f32_e32 v134, v133
	v_add_f32_e32 v133, 1.0, v204
	v_rcp_f32_e32 v135, v133
	v_add_f32_e32 v133, 1.0, v203
	v_rcp_f32_e32 v136, v133
	v_add_f32_e32 v133, 1.0, v202
	v_rcp_f32_e32 v137, v133
	v_add_f32_e32 v133, 1.0, v201
	v_rcp_f32_e32 v140, v133
	v_add_f32_e32 v133, 1.0, v200
	v_rcp_f32_e32 v141, v133
	v_add_f32_e32 v133, 1.0, v199
	v_rcp_f32_e32 v142, v133
	v_add_f32_e32 v133, 1.0, v198
	v_rcp_f32_e32 v143, v133
	v_pk_mul_f32 v[134:135], v[86:87], v[134:135]
	v_pk_mul_f32 v[136:137], v[88:89], v[136:137]
	v_pk_mul_f32 v[140:141], v[78:79], v[140:141]
	v_pk_mul_f32 v[142:143], v[80:81], v[142:143]
	v_cvt_pk_bf16_f32 v134, v134, v135
	v_cvt_pk_bf16_f32 v135, v136, v137
	v_cvt_pk_bf16_f32 v136, v140, v141
	v_cvt_pk_bf16_f32 v137, v142, v143
	global_store_dwordx4 v[138:139], v[134:137], off offset:256 nt
	v_add_f32_e32 v133, 1.0, v197
	v_exp_f32_e32 v141, v192
	v_add_u32_e32 v134, 0x8030, v132
	v_ashrrev_i32_e32 v135, 31, v134
	v_lshlrev_b64 v[138:139], 10, v[134:135]
	v_rcp_f32_e32 v134, v133
	v_add_f32_e32 v133, 1.0, v196
	v_rcp_f32_e32 v135, v133
	v_add_f32_e32 v133, 1.0, v195
	v_rcp_f32_e32 v136, v133
	v_exp_f32_e32 v133, v194
	v_exp_f32_e32 v143, v190
	v_add_f32_e32 v137, 1.0, v193
	v_add_f32_e32 v141, 1.0, v141
	v_add_f32_e32 v133, 1.0, v133
	v_rcp_f32_e32 v140, v133
	v_exp_f32_e32 v133, v191
	v_rcp_f32_e32 v137, v137
	v_rcp_f32_e32 v141, v141
	v_pk_mul_f32 v[134:135], v[82:83], v[134:135]
	v_add_f32_e32 v133, 1.0, v133
	v_rcp_f32_e32 v142, v133
	v_add_f32_e32 v133, 1.0, v143
	v_rcp_f32_e32 v143, v133
	v_exp_f32_e32 v133, v189
	v_pk_mul_f32 v[136:137], v[84:85], v[136:137]
	v_pk_mul_f32 v[140:141], v[74:75], v[140:141]
	v_pk_mul_f32 v[142:143], v[76:77], v[142:143]
	v_lshl_add_u64 v[138:139], s[24:25], 0, v[138:139]
	v_cvt_pk_bf16_f32 v134, v134, v135
	v_cvt_pk_bf16_f32 v135, v136, v137
	v_cvt_pk_bf16_f32 v136, v140, v141
	v_cvt_pk_bf16_f32 v137, v142, v143
	v_lshl_add_u64 v[138:139], v[138:139], 0, v[130:131]
	v_add_f32_e32 v133, 1.0, v133
	global_store_dwordx4 v[138:139], v[134:137], off nt
	v_mul_f32_e32 v140, 0xbfb8aa3b, v67
	v_exp_f32_e32 v141, v140
	v_rcp_f32_e32 v134, v133
	v_exp_f32_e32 v133, v187
	v_mul_f32_e32 v136, 0xbfb8aa3b, v73
	v_exp_f32_e32 v137, v136
	v_mul_f32_e32 v142, 0xbfb8aa3b, v69
	v_add_f32_e32 v133, 1.0, v133
	v_rcp_f32_e32 v136, v133
	v_mul_f32_e32 v133, 0xbfb8aa3b, v66
	v_exp_f32_e32 v133, v133
	v_exp_f32_e32 v135, v188
	v_exp_f32_e32 v143, v142
	v_add_f32_e32 v137, 1.0, v137
	v_add_f32_e32 v133, 1.0, v133
	v_rcp_f32_e32 v140, v133
	v_mul_f32_e32 v133, 0xbfb8aa3b, v68
	v_exp_f32_e32 v133, v133
	v_add_f32_e32 v135, 1.0, v135
	v_add_f32_e32 v141, 1.0, v141
	v_rcp_f32_e32 v135, v135
	v_add_f32_e32 v133, 1.0, v133
	v_rcp_f32_e32 v142, v133
	v_add_f32_e32 v133, 1.0, v143
	v_rcp_f32_e32 v137, v137
	v_rcp_f32_e32 v141, v141
	v_rcp_f32_e32 v143, v133
	v_mul_f32_e32 v133, 0xbfb8aa3b, v62
	v_pk_mul_f32 v[134:135], v[70:71], v[134:135]
	v_pk_mul_f32 v[136:137], v[72:73], v[136:137]
	v_pk_mul_f32 v[140:141], v[66:67], v[140:141]
	v_pk_mul_f32 v[142:143], v[68:69], v[142:143]
	v_exp_f32_e32 v133, v133
	v_cvt_pk_bf16_f32 v134, v134, v135
	v_cvt_pk_bf16_f32 v135, v136, v137
	v_cvt_pk_bf16_f32 v136, v140, v141
	v_cvt_pk_bf16_f32 v137, v142, v143
	global_store_dwordx4 v[138:139], v[134:137], off offset:256 nt
	v_add_f32_e32 v133, 1.0, v133
	v_mul_f32_e32 v140, 0xbfb8aa3b, v59
	v_add_u32_e32 v134, 0x8080, v132
	v_ashrrev_i32_e32 v135, 31, v134
	v_lshlrev_b64 v[138:139], 10, v[134:135]
	v_mul_f32_e32 v134, 0xbfb8aa3b, v63
	v_exp_f32_e32 v135, v134
	v_rcp_f32_e32 v134, v133
	v_mul_f32_e32 v133, 0xbfb8aa3b, v64
	v_exp_f32_e32 v133, v133
	v_mul_f32_e32 v136, 0xbfb8aa3b, v65
	v_exp_f32_e32 v137, v136
	v_exp_f32_e32 v141, v140
	v_add_f32_e32 v133, 1.0, v133
	v_rcp_f32_e32 v136, v133
	v_mul_f32_e32 v133, 0xbfb8aa3b, v58
	v_exp_f32_e32 v133, v133
	v_mul_f32_e32 v142, 0xbfb8aa3b, v61
	v_exp_f32_e32 v143, v142
	v_add_f32_e32 v135, 1.0, v135
	v_add_f32_e32 v133, 1.0, v133
	v_rcp_f32_e32 v140, v133
	v_mul_f32_e32 v133, 0xbfb8aa3b, v60
	v_exp_f32_e32 v133, v133
	v_add_f32_e32 v137, 1.0, v137
	v_add_f32_e32 v141, 1.0, v141
	v_rcp_f32_e32 v135, v135
	v_add_f32_e32 v133, 1.0, v133
	v_rcp_f32_e32 v142, v133
	v_add_f32_e32 v133, 1.0, v143
	v_rcp_f32_e32 v137, v137
	v_rcp_f32_e32 v141, v141
	v_rcp_f32_e32 v143, v133
	v_pk_mul_f32 v[134:135], v[62:63], v[134:135]
	v_pk_mul_f32 v[136:137], v[64:65], v[136:137]
	v_pk_mul_f32 v[140:141], v[58:59], v[140:141]
	v_pk_mul_f32 v[142:143], v[60:61], v[142:143]
	v_lshl_add_u64 v[138:139], s[24:25], 0, v[138:139]
	v_mul_f32_e32 v133, 0xbfb8aa3b, v54
	v_cvt_pk_bf16_f32 v134, v134, v135
	v_cvt_pk_bf16_f32 v135, v136, v137
	v_cvt_pk_bf16_f32 v136, v140, v141
	v_cvt_pk_bf16_f32 v137, v142, v143
	v_lshl_add_u64 v[138:139], v[138:139], 0, v[130:131]
	v_exp_f32_e32 v133, v133
	v_mul_f32_e32 v140, 0xbfb8aa3b, v55
	v_exp_f32_e32 v140, v140
	global_store_dwordx4 v[138:139], v[134:137], off nt
	v_add_f32_e32 v133, 1.0, v133
	s_nop 0
	v_mul_f32_e32 v135, 0xbfb8aa3b, v56
	v_exp_f32_e32 v136, v135
	v_mul_f32_e32 v135, 0xbfb8aa3b, v57
	v_exp_f32_e32 v137, v135
	v_rcp_f32_e32 v134, v133
	v_add_f32_e32 v133, 1.0, v140
	v_rcp_f32_e32 v135, v133
	v_add_f32_e32 v133, 1.0, v136
	v_rcp_f32_e32 v136, v133
	v_add_f32_e32 v133, 1.0, v137
	v_mul_f32_e32 v137, 0xbfb8aa3b, v46
	v_exp_f32_e32 v140, v137
	v_mul_f32_e32 v137, 0xbfb8aa3b, v47
	v_exp_f32_e32 v141, v137
	v_rcp_f32_e32 v137, v133
	v_add_f32_e32 v133, 1.0, v140
	v_rcp_f32_e32 v140, v133
	v_add_f32_e32 v133, 1.0, v141
	v_mul_f32_e32 v141, 0xbfb8aa3b, v48
	v_exp_f32_e32 v142, v141
	v_mul_f32_e32 v141, 0xbfb8aa3b, v49
	v_exp_f32_e32 v143, v141
	v_rcp_f32_e32 v141, v133
	v_add_f32_e32 v133, 1.0, v142
	v_rcp_f32_e32 v142, v133
	v_add_f32_e32 v133, 1.0, v143
	v_rcp_f32_e32 v143, v133
	v_pk_mul_f32 v[134:135], v[54:55], v[134:135]
	v_pk_mul_f32 v[136:137], v[56:57], v[136:137]
	v_pk_mul_f32 v[140:141], v[46:47], v[140:141]
	v_pk_mul_f32 v[142:143], v[48:49], v[142:143]
	v_cvt_pk_bf16_f32 v134, v134, v135
	v_cvt_pk_bf16_f32 v135, v136, v137
	v_cvt_pk_bf16_f32 v136, v140, v141
	v_cvt_pk_bf16_f32 v137, v142, v143
	v_mul_f32_e32 v133, 0xbfb8aa3b, v50
	global_store_dwordx4 v[138:139], v[134:137], off offset:256 nt
	v_exp_f32_e32 v133, v133
	s_nop 0
	v_mul_f32_e32 v136, 0xbfb8aa3b, v51
	v_exp_f32_e32 v136, v136
	v_add_u32_e32 v134, 0x8090, v132
	v_ashrrev_i32_e32 v135, 31, v134
	v_lshlrev_b64 v[138:139], 10, v[134:135]
	v_add_f32_e32 v133, 1.0, v133
	v_mul_f32_e32 v135, 0xbfb8aa3b, v52
	v_rcp_f32_e32 v134, v133
	v_add_f32_e32 v133, 1.0, v136
	v_exp_f32_e32 v136, v135
	v_mul_f32_e32 v135, 0xbfb8aa3b, v53
	v_exp_f32_e32 v137, v135
	v_rcp_f32_e32 v135, v133
	v_add_f32_e32 v133, 1.0, v136
	v_rcp_f32_e32 v136, v133
	v_add_f32_e32 v133, 1.0, v137
	v_mul_f32_e32 v137, 0xbfb8aa3b, v42
	v_exp_f32_e32 v140, v137
	v_mul_f32_e32 v137, 0xbfb8aa3b, v43
	v_exp_f32_e32 v141, v137
	v_rcp_f32_e32 v137, v133
	v_add_f32_e32 v133, 1.0, v140
	v_rcp_f32_e32 v140, v133
	v_add_f32_e32 v133, 1.0, v141
	v_mul_f32_e32 v141, 0xbfb8aa3b, v44
	v_exp_f32_e32 v142, v141
	v_mul_f32_e32 v141, 0xbfb8aa3b, v45
	v_exp_f32_e32 v143, v141
	v_rcp_f32_e32 v141, v133
	v_add_f32_e32 v133, 1.0, v142
	v_rcp_f32_e32 v142, v133
	v_add_f32_e32 v133, 1.0, v143
	v_rcp_f32_e32 v143, v133
	v_pk_mul_f32 v[134:135], v[50:51], v[134:135]
	v_pk_mul_f32 v[136:137], v[52:53], v[136:137]
	v_pk_mul_f32 v[140:141], v[42:43], v[140:141]
	v_pk_mul_f32 v[142:143], v[44:45], v[142:143]
	v_lshl_add_u64 v[138:139], s[24:25], 0, v[138:139]
	v_mul_f32_e32 v133, 0xbfb8aa3b, v38
	v_cvt_pk_bf16_f32 v134, v134, v135
	v_cvt_pk_bf16_f32 v135, v136, v137
	v_cvt_pk_bf16_f32 v136, v140, v141
	v_cvt_pk_bf16_f32 v137, v142, v143
	v_lshl_add_u64 v[138:139], v[138:139], 0, v[130:131]
	v_exp_f32_e32 v133, v133
	v_mul_f32_e32 v140, 0xbfb8aa3b, v39
	v_exp_f32_e32 v140, v140
	global_store_dwordx4 v[138:139], v[134:137], off nt
	v_add_f32_e32 v133, 1.0, v133
	s_nop 0
	v_mul_f32_e32 v135, 0xbfb8aa3b, v40
	v_exp_f32_e32 v136, v135
	v_mul_f32_e32 v135, 0xbfb8aa3b, v41
	v_exp_f32_e32 v137, v135
	v_rcp_f32_e32 v134, v133
	v_add_f32_e32 v133, 1.0, v140
	v_rcp_f32_e32 v135, v133
	v_add_f32_e32 v133, 1.0, v136
	v_rcp_f32_e32 v136, v133
	v_add_f32_e32 v133, 1.0, v137
	v_mul_f32_e32 v137, 0xbfb8aa3b, v30
	v_exp_f32_e32 v140, v137
	v_mul_f32_e32 v137, 0xbfb8aa3b, v31
	v_exp_f32_e32 v141, v137
	v_rcp_f32_e32 v137, v133
	v_add_f32_e32 v133, 1.0, v140
	v_rcp_f32_e32 v140, v133
	v_add_f32_e32 v133, 1.0, v141
	v_mul_f32_e32 v141, 0xbfb8aa3b, v32
	v_exp_f32_e32 v142, v141
	v_mul_f32_e32 v141, 0xbfb8aa3b, v33
	v_exp_f32_e32 v143, v141
	v_rcp_f32_e32 v141, v133
	v_add_f32_e32 v133, 1.0, v142
	v_rcp_f32_e32 v142, v133
	v_add_f32_e32 v133, 1.0, v143
	v_rcp_f32_e32 v143, v133
	v_pk_mul_f32 v[134:135], v[38:39], v[134:135]
	v_pk_mul_f32 v[136:137], v[40:41], v[136:137]
	v_pk_mul_f32 v[140:141], v[30:31], v[140:141]
	v_pk_mul_f32 v[142:143], v[32:33], v[142:143]
	v_cvt_pk_bf16_f32 v134, v134, v135
	v_cvt_pk_bf16_f32 v135, v136, v137
	v_cvt_pk_bf16_f32 v136, v140, v141
	v_cvt_pk_bf16_f32 v137, v142, v143
	v_mul_f32_e32 v133, 0xbfb8aa3b, v34
	global_store_dwordx4 v[138:139], v[134:137], off offset:256 nt
	v_exp_f32_e32 v133, v133
	s_nop 0
	v_mul_f32_e32 v136, 0xbfb8aa3b, v35
	v_exp_f32_e32 v136, v136
	v_add_u32_e32 v134, 0x80a0, v132
	v_ashrrev_i32_e32 v135, 31, v134
	v_lshlrev_b64 v[138:139], 10, v[134:135]
	v_add_f32_e32 v133, 1.0, v133
	v_mul_f32_e32 v135, 0xbfb8aa3b, v36
	v_rcp_f32_e32 v134, v133
	v_add_f32_e32 v133, 1.0, v136
	v_exp_f32_e32 v136, v135
	v_mul_f32_e32 v135, 0xbfb8aa3b, v37
	v_exp_f32_e32 v137, v135
	v_rcp_f32_e32 v135, v133
	v_add_f32_e32 v133, 1.0, v136
	v_rcp_f32_e32 v136, v133
	v_add_f32_e32 v133, 1.0, v137
	v_mul_f32_e32 v137, 0xbfb8aa3b, v26
	v_exp_f32_e32 v140, v137
	v_mul_f32_e32 v137, 0xbfb8aa3b, v27
	v_exp_f32_e32 v141, v137
	v_rcp_f32_e32 v137, v133
	v_add_f32_e32 v133, 1.0, v140
	v_rcp_f32_e32 v140, v133
	v_add_f32_e32 v133, 1.0, v141
	v_mul_f32_e32 v141, 0xbfb8aa3b, v28
	v_exp_f32_e32 v142, v141
	v_mul_f32_e32 v141, 0xbfb8aa3b, v29
	v_exp_f32_e32 v143, v141
	v_rcp_f32_e32 v141, v133
	v_add_f32_e32 v133, 1.0, v142
	v_rcp_f32_e32 v142, v133
	v_add_f32_e32 v133, 1.0, v143
	v_rcp_f32_e32 v143, v133
	v_pk_mul_f32 v[134:135], v[34:35], v[134:135]
	v_pk_mul_f32 v[136:137], v[36:37], v[136:137]
	v_pk_mul_f32 v[140:141], v[26:27], v[140:141]
	v_pk_mul_f32 v[142:143], v[28:29], v[142:143]
	v_lshl_add_u64 v[138:139], s[24:25], 0, v[138:139]
	v_mul_f32_e32 v133, 0xbfb8aa3b, v22
	v_cvt_pk_bf16_f32 v134, v134, v135
	v_cvt_pk_bf16_f32 v135, v136, v137
	v_cvt_pk_bf16_f32 v136, v140, v141
	v_cvt_pk_bf16_f32 v137, v142, v143
	v_lshl_add_u64 v[138:139], v[138:139], 0, v[130:131]
	v_exp_f32_e32 v133, v133
	v_mul_f32_e32 v140, 0xbfb8aa3b, v23
	v_exp_f32_e32 v140, v140
	global_store_dwordx4 v[138:139], v[134:137], off nt
	v_add_f32_e32 v133, 1.0, v133
	v_add_u32_e32 v132, 0x80b0, v132
	v_mul_f32_e32 v135, 0xbfb8aa3b, v24
	v_exp_f32_e32 v136, v135
	v_mul_f32_e32 v135, 0xbfb8aa3b, v25
	v_exp_f32_e32 v137, v135
	v_rcp_f32_e32 v134, v133
	v_add_f32_e32 v133, 1.0, v140
	v_rcp_f32_e32 v135, v133
	v_add_f32_e32 v133, 1.0, v136
	v_rcp_f32_e32 v136, v133
	v_add_f32_e32 v133, 1.0, v137
	v_mul_f32_e32 v137, 0xbfb8aa3b, v14
	v_exp_f32_e32 v140, v137
	v_mul_f32_e32 v137, 0xbfb8aa3b, v15
	v_exp_f32_e32 v141, v137
	v_rcp_f32_e32 v137, v133
	v_add_f32_e32 v133, 1.0, v140
	v_rcp_f32_e32 v140, v133
	v_add_f32_e32 v133, 1.0, v141
	v_mul_f32_e32 v141, 0xbfb8aa3b, v16
	v_exp_f32_e32 v142, v141
	v_mul_f32_e32 v141, 0xbfb8aa3b, v17
	v_exp_f32_e32 v143, v141
	v_rcp_f32_e32 v141, v133
	v_add_f32_e32 v133, 1.0, v142
	v_rcp_f32_e32 v142, v133
	v_add_f32_e32 v133, 1.0, v143
	v_rcp_f32_e32 v143, v133
	v_pk_mul_f32 v[134:135], v[22:23], v[134:135]
	v_pk_mul_f32 v[136:137], v[24:25], v[136:137]
	v_pk_mul_f32 v[140:141], v[14:15], v[140:141]
	v_pk_mul_f32 v[142:143], v[16:17], v[142:143]
	v_cvt_pk_bf16_f32 v134, v134, v135
	v_cvt_pk_bf16_f32 v135, v136, v137
	v_cvt_pk_bf16_f32 v136, v140, v141
	v_cvt_pk_bf16_f32 v137, v142, v143
	global_store_dwordx4 v[138:139], v[134:137], off offset:256 nt
	v_ashrrev_i32_e32 v133, 31, v132
	v_mul_f32_e32 v138, 0xbfb8aa3b, v10
	v_mul_f32_e32 v134, 0xbfb8aa3b, v18
	v_mul_f32_e32 v135, 0xbfb8aa3b, v19
	v_exp_f32_e32 v134, v134
	v_exp_f32_e32 v135, v135
	v_lshlrev_b64 v[136:137], 10, v[132:133]
	v_mul_f32_e32 v139, 0xbfb8aa3b, v11
	v_add_f32_e32 v132, 1.0, v134
	v_add_f32_e32 v133, 1.0, v135
	v_mul_f32_e32 v134, 0xbfb8aa3b, v20
	v_mul_f32_e32 v135, 0xbfb8aa3b, v21
	v_mul_f32_e32 v140, 0xbfb8aa3b, v12
	v_mul_f32_e32 v141, 0xbfb8aa3b, v13
	v_exp_f32_e32 v134, v134
	v_exp_f32_e32 v135, v135
	v_exp_f32_e32 v138, v138
	v_exp_f32_e32 v139, v139
	v_exp_f32_e32 v140, v140
	v_exp_f32_e32 v141, v141
	v_add_f32_e32 v134, 1.0, v134
	v_add_f32_e32 v135, 1.0, v135
	v_add_f32_e32 v138, 1.0, v138
	v_add_f32_e32 v139, 1.0, v139
	v_add_f32_e32 v140, 1.0, v140
	v_add_f32_e32 v141, 1.0, v141
	v_rcp_f32_e32 v132, v132
	v_rcp_f32_e32 v133, v133
	v_rcp_f32_e32 v134, v134
	v_rcp_f32_e32 v135, v135
	v_rcp_f32_e32 v138, v138
	v_rcp_f32_e32 v139, v139
	v_rcp_f32_e32 v140, v140
	v_rcp_f32_e32 v141, v141
	v_pk_mul_f32 v[132:133], v[18:19], v[132:133]
	v_pk_mul_f32 v[134:135], v[20:21], v[134:135]
	v_pk_mul_f32 v[138:139], v[10:11], v[138:139]
	v_pk_mul_f32 v[140:141], v[12:13], v[140:141]
	v_lshl_add_u64 v[136:137], s[24:25], 0, v[136:137]
	v_cvt_pk_bf16_f32 v132, v132, v133
	v_cvt_pk_bf16_f32 v133, v134, v135
	v_cvt_pk_bf16_f32 v134, v138, v139
	v_cvt_pk_bf16_f32 v135, v140, v141
	v_lshl_add_u64 v[136:137], v[136:137], 0, v[130:131]
	v_mul_f32_e32 v130, 0xbfb8aa3b, v6
	v_mul_f32_e32 v131, 0xbfb8aa3b, v7
	global_store_dwordx4 v[136:137], v[132:135], off nt
	v_mul_f32_e32 v138, 0xbfb8aa3b, v4
	v_mul_f32_e32 v139, 0xbfb8aa3b, v5
	v_mul_f32_e32 v132, 0xbfb8aa3b, v8
	v_mul_f32_e32 v133, 0xbfb8aa3b, v9
	v_mul_f32_e32 v134, 0xbfb8aa3b, v2
	v_mul_f32_e32 v135, 0xbfb8aa3b, v3
	v_exp_f32_e32 v130, v130
	v_exp_f32_e32 v131, v131
	v_exp_f32_e32 v132, v132
	v_exp_f32_e32 v133, v133
	v_exp_f32_e32 v134, v134
	v_exp_f32_e32 v135, v135
	v_exp_f32_e32 v138, v138
	v_exp_f32_e32 v139, v139
	v_add_f32_e32 v130, 1.0, v130
	v_add_f32_e32 v131, 1.0, v131
	v_add_f32_e32 v132, 1.0, v132
	v_add_f32_e32 v133, 1.0, v133
	v_add_f32_e32 v134, 1.0, v134
	v_add_f32_e32 v135, 1.0, v135
	v_add_f32_e32 v138, 1.0, v138
	v_add_f32_e32 v139, 1.0, v139
	v_rcp_f32_e32 v130, v130
	v_rcp_f32_e32 v131, v131
	v_rcp_f32_e32 v132, v132
	v_rcp_f32_e32 v133, v133
	v_rcp_f32_e32 v134, v134
	v_rcp_f32_e32 v135, v135
	v_rcp_f32_e32 v138, v138
	v_rcp_f32_e32 v139, v139
	v_pk_mul_f32 v[130:131], v[6:7], v[130:131]
	v_pk_mul_f32 v[132:133], v[8:9], v[132:133]
	v_pk_mul_f32 v[134:135], v[2:3], v[134:135]
	v_pk_mul_f32 v[138:139], v[4:5], v[138:139]
	v_cvt_pk_bf16_f32 v130, v130, v131
	v_cvt_pk_bf16_f32 v131, v132, v133
	v_cvt_pk_bf16_f32 v132, v134, v135
	v_cvt_pk_bf16_f32 v133, v138, v139
	global_store_dwordx4 v[136:137], v[130:133], off offset:256 nt

.LBB0_297:
	s_and_b64 vcc, exec, s[48:49]
	s_cbranch_vccz .LBB0_309
	s_cmp_gt_i32 s41, 1
	s_mov_b64 s[46:47], -1
	s_cbranch_scc0 .LBB0_304
	s_cmp_gt_i32 s41, 2
	s_cbranch_scc0 .LBB0_301
	s_lshl_b32 s2, s66, 8
	s_and_b32 s2, s2, 0x100
	s_or_b32 s2, s2, s59
	v_add_u32_e32 v134, s2, v173
	s_lshl_b32 s2, s33, 8
	s_add_i32 s2, s2, s58
	v_add_u32_e32 v138, s2, v171
	v_add_u32_e32 v130, 0x8000, v138
	v_ashrrev_i32_e32 v131, 31, v130
	v_lshlrev_b64 v[136:137], 10, v[130:131]
	v_ashrrev_i32_e32 v135, 31, v134
	v_lshl_add_u64 v[136:137], s[26:27], 0, v[136:137]
	v_lshlrev_b64 v[134:135], 1, v[134:135]
	v_cvt_pk_bf16_f32 v130, v126, v127
	v_cvt_pk_bf16_f32 v131, v128, v129
	v_cvt_pk_bf16_f32 v132, v122, v123
	v_cvt_pk_bf16_f32 v133, v124, v125
	v_lshl_add_u64 v[136:137], v[136:137], 0, v[134:135]
	global_store_dwordx4 v[136:137], v[130:133], off nt
	s_mov_b64 s[46:47], 0
	s_nop 0
	v_cvt_pk_bf16_f32 v130, v118, v119
	v_cvt_pk_bf16_f32 v131, v120, v121
	v_cvt_pk_bf16_f32 v132, v110, v111
	v_cvt_pk_bf16_f32 v133, v112, v113
	global_store_dwordx4 v[136:137], v[130:133], off offset:256 nt
	s_nop 1
	v_add_u32_e32 v130, 0x8010, v138
	v_ashrrev_i32_e32 v131, 31, v130
	v_lshlrev_b64 v[136:137], 10, v[130:131]
	v_lshl_add_u64 v[136:137], s[26:27], 0, v[136:137]
	v_cvt_pk_bf16_f32 v130, v114, v115
	v_cvt_pk_bf16_f32 v131, v116, v117
	v_cvt_pk_bf16_f32 v132, v106, v107
	v_cvt_pk_bf16_f32 v133, v108, v109
	v_lshl_add_u64 v[136:137], v[136:137], 0, v[134:135]
	global_store_dwordx4 v[136:137], v[130:133], off nt
	s_nop 1
	v_cvt_pk_bf16_f32 v130, v102, v103
	v_cvt_pk_bf16_f32 v131, v104, v105
	v_cvt_pk_bf16_f32 v132, v94, v95
	v_cvt_pk_bf16_f32 v133, v96, v97
	global_store_dwordx4 v[136:137], v[130:133], off offset:256 nt
	s_nop 1
	v_add_u32_e32 v130, 0x8020, v138
	v_ashrrev_i32_e32 v131, 31, v130
	v_lshlrev_b64 v[136:137], 10, v[130:131]
	v_lshl_add_u64 v[136:137], s[26:27], 0, v[136:137]
	v_cvt_pk_bf16_f32 v130, v98, v99
	v_cvt_pk_bf16_f32 v131, v100, v101
	v_cvt_pk_bf16_f32 v132, v90, v91
	v_cvt_pk_bf16_f32 v133, v92, v93
	v_lshl_add_u64 v[136:137], v[136:137], 0, v[134:135]
	global_store_dwordx4 v[136:137], v[130:133], off nt
	s_nop 1
	v_cvt_pk_bf16_f32 v130, v86, v87
	v_cvt_pk_bf16_f32 v131, v88, v89
	v_cvt_pk_bf16_f32 v132, v78, v79
	v_cvt_pk_bf16_f32 v133, v80, v81
	global_store_dwordx4 v[136:137], v[130:133], off offset:256 nt
	s_nop 1
	v_add_u32_e32 v130, 0x8030, v138
	v_ashrrev_i32_e32 v131, 31, v130
	v_lshlrev_b64 v[136:137], 10, v[130:131]
	v_lshl_add_u64 v[136:137], s[26:27], 0, v[136:137]
	v_cvt_pk_bf16_f32 v130, v82, v83
	v_cvt_pk_bf16_f32 v131, v84, v85
	v_cvt_pk_bf16_f32 v132, v74, v75
	v_cvt_pk_bf16_f32 v133, v76, v77
	v_lshl_add_u64 v[136:137], v[136:137], 0, v[134:135]
	global_store_dwordx4 v[136:137], v[130:133], off nt
	s_nop 1
	v_cvt_pk_bf16_f32 v130, v70, v71
	v_cvt_pk_bf16_f32 v131, v72, v73
	v_cvt_pk_bf16_f32 v132, v66, v67
	v_cvt_pk_bf16_f32 v133, v68, v69
	global_store_dwordx4 v[136:137], v[130:133], off offset:256 nt
	s_nop 1
	v_add_u32_e32 v130, 0x8080, v138
	v_ashrrev_i32_e32 v131, 31, v130
	v_lshlrev_b64 v[136:137], 10, v[130:131]
	v_lshl_add_u64 v[136:137], s[26:27], 0, v[136:137]
	v_cvt_pk_bf16_f32 v130, v62, v63
	v_cvt_pk_bf16_f32 v131, v64, v65
	v_cvt_pk_bf16_f32 v132, v58, v59
	v_cvt_pk_bf16_f32 v133, v60, v61
	v_lshl_add_u64 v[136:137], v[136:137], 0, v[134:135]
	global_store_dwordx4 v[136:137], v[130:133], off nt
	s_nop 1
	v_cvt_pk_bf16_f32 v130, v54, v55
	v_cvt_pk_bf16_f32 v131, v56, v57
	v_cvt_pk_bf16_f32 v132, v46, v47
	v_cvt_pk_bf16_f32 v133, v48, v49
	global_store_dwordx4 v[136:137], v[130:133], off offset:256 nt
	s_nop 1
	v_add_u32_e32 v130, 0x8090, v138
	v_ashrrev_i32_e32 v131, 31, v130
	v_lshlrev_b64 v[136:137], 10, v[130:131]
	v_lshl_add_u64 v[136:137], s[26:27], 0, v[136:137]
	v_cvt_pk_bf16_f32 v130, v50, v51
	v_cvt_pk_bf16_f32 v131, v52, v53
	v_cvt_pk_bf16_f32 v132, v42, v43
	v_cvt_pk_bf16_f32 v133, v44, v45
	v_lshl_add_u64 v[136:137], v[136:137], 0, v[134:135]
	global_store_dwordx4 v[136:137], v[130:133], off nt
	s_nop 1
	v_cvt_pk_bf16_f32 v130, v38, v39
	v_cvt_pk_bf16_f32 v131, v40, v41
	v_cvt_pk_bf16_f32 v132, v30, v31
	v_cvt_pk_bf16_f32 v133, v32, v33
	global_store_dwordx4 v[136:137], v[130:133], off offset:256 nt
	s_nop 1
	v_add_u32_e32 v130, 0x80a0, v138
	v_ashrrev_i32_e32 v131, 31, v130
	v_lshlrev_b64 v[136:137], 10, v[130:131]
	v_lshl_add_u64 v[136:137], s[26:27], 0, v[136:137]
	v_cvt_pk_bf16_f32 v130, v34, v35
	v_cvt_pk_bf16_f32 v131, v36, v37
	v_cvt_pk_bf16_f32 v132, v26, v27
	v_cvt_pk_bf16_f32 v133, v28, v29
	v_lshl_add_u64 v[136:137], v[136:137], 0, v[134:135]
	global_store_dwordx4 v[136:137], v[130:133], off nt
	s_nop 1
	v_cvt_pk_bf16_f32 v130, v22, v23
	v_cvt_pk_bf16_f32 v131, v24, v25
	v_cvt_pk_bf16_f32 v132, v14, v15
	v_cvt_pk_bf16_f32 v133, v16, v17
	global_store_dwordx4 v[136:137], v[130:133], off offset:256 nt
	s_nop 1
	v_add_u32_e32 v130, 0x80b0, v138
	v_ashrrev_i32_e32 v131, 31, v130
	v_lshlrev_b64 v[136:137], 10, v[130:131]
	v_lshl_add_u64 v[136:137], s[26:27], 0, v[136:137]
	v_cvt_pk_bf16_f32 v130, v18, v19
	v_cvt_pk_bf16_f32 v131, v20, v21
	v_cvt_pk_bf16_f32 v132, v10, v11
	v_cvt_pk_bf16_f32 v133, v12, v13
	v_lshl_add_u64 v[134:135], v[136:137], 0, v[134:135]
	global_store_dwordx4 v[134:135], v[130:133], off nt
	s_nop 1
	v_cvt_pk_bf16_f32 v130, v6, v7
	v_cvt_pk_bf16_f32 v131, v8, v9
	v_cvt_pk_bf16_f32 v132, v2, v3
	v_cvt_pk_bf16_f32 v133, v4, v5
	global_store_dwordx4 v[134:135], v[130:133], off offset:256 nt
.LBB0_301:
	s_andn2_b64 vcc, exec, s[46:47]
	s_cbranch_vccnz .LBB0_303
	s_lshl_b32 s2, s33, 8
	v_add_u32_e32 v130, s59, v173
	s_add_i32 s2, s2, 0x8000
	v_add_u32_e32 v138, s2, v130
	v_ashrrev_i32_e32 v131, 3, v138
	s_lshl_b32 s2, s66, 8
	v_and_b32_e32 v131, 0xfffffe00, v131
	s_and_b32 s2, s2, 0x100
	v_add_u32_e32 v140, s58, v171
	v_or_b32_e32 v141, s2, v131
	v_add_u32_e32 v142, v141, v140
	v_lshrrev_b32_e32 v144, 6, v138
	v_and_b32_e32 v139, 56, v130
	v_bfi_b32 v130, s69, v142, v144
	v_ashrrev_i32_e32 v131, 31, v130
	v_lshlrev_b64 v[130:131], 13, v[130:131]
	v_lshlrev_b32_e32 v136, 7, v171
	v_lshl_add_u64 v[130:131], s[28:29], 0, v[130:131]
	v_and_b32_e32 v156, 0x1f80, v136
	v_lshl_add_u64 v[136:137], v[130:131], 0, v[156:157]
	v_lshlrev_b32_e32 v130, 1, v139
	v_mov_b32_e32 v131, v157
	v_cvt_pk_bf16_f32 v132, v126, v127
	v_cvt_pk_bf16_f32 v133, v128, v129
	v_cvt_pk_bf16_f32 v134, v122, v123
	v_cvt_pk_bf16_f32 v135, v124, v125
	v_lshl_add_u64 v[136:137], v[136:137], 0, v[130:131]
	global_store_dwordx4 v[136:137], v[132:135], off nt
	v_add_u32_e32 v136, 0x80, v138
	v_lshrrev_b32_e32 v162, 6, v136
	v_bfe_u32 v163, v136, 6, 6
	v_bfi_b32 v136, s69, v142, v162
	v_ashrrev_i32_e32 v137, 31, v136
	v_lshlrev_b64 v[136:137], 13, v[136:137]
	v_lshl_add_u64 v[136:137], s[28:29], 0, v[136:137]
	v_bfe_u32 v145, v138, 6, 6
	v_lshl_add_u64 v[136:137], v[136:137], 0, v[156:157]
	v_add_u32_e32 v138, 16, v140
	v_and_b32_e32 v143, 0xffffffc0, v142
	v_cvt_pk_bf16_f32 v132, v118, v119
	v_cvt_pk_bf16_f32 v133, v120, v121
	v_cvt_pk_bf16_f32 v134, v110, v111
	v_cvt_pk_bf16_f32 v135, v112, v113
	v_lshl_add_u64 v[136:137], v[136:137], 0, v[130:131]
	v_add_u32_e32 v142, v141, v138
	global_store_dwordx4 v[136:137], v[132:135], off nt
	v_bfi_b32 v136, s69, v142, v144
	v_ashrrev_i32_e32 v137, 31, v136
	v_lshlrev_b64 v[136:137], 13, v[136:137]
	v_lshlrev_b32_e32 v138, 7, v138
	v_lshl_add_u64 v[136:137], s[28:29], 0, v[136:137]
	v_and_b32_e32 v138, 0x1f80, v138
	v_mov_b32_e32 v139, v157
	v_lshl_add_u64 v[136:137], v[136:137], 0, v[138:139]
	v_cvt_pk_bf16_f32 v132, v114, v115
	v_cvt_pk_bf16_f32 v133, v116, v117
	v_cvt_pk_bf16_f32 v134, v106, v107
	v_cvt_pk_bf16_f32 v135, v108, v109
	v_lshl_add_u64 v[136:137], v[136:137], 0, v[130:131]
	global_store_dwordx4 v[136:137], v[132:135], off nt
	v_bfi_b32 v136, s69, v142, v162
	v_ashrrev_i32_e32 v137, 31, v136
	v_lshlrev_b64 v[136:137], 13, v[136:137]
	v_lshl_add_u64 v[136:137], s[28:29], 0, v[136:137]
	v_lshl_add_u64 v[136:137], v[136:137], 0, v[138:139]
	v_add_u32_e32 v138, 32, v140
	v_cvt_pk_bf16_f32 v132, v102, v103
	v_cvt_pk_bf16_f32 v133, v104, v105
	v_cvt_pk_bf16_f32 v134, v94, v95
	v_cvt_pk_bf16_f32 v135, v96, v97
	v_lshl_add_u64 v[136:137], v[136:137], 0, v[130:131]
	v_add_u32_e32 v142, v141, v138
	global_store_dwordx4 v[136:137], v[132:135], off nt
	v_bfi_b32 v136, s69, v142, v144
	v_ashrrev_i32_e32 v137, 31, v136
	v_lshlrev_b64 v[136:137], 13, v[136:137]
	v_lshlrev_b32_e32 v138, 7, v138
	v_lshl_add_u64 v[136:137], s[28:29], 0, v[136:137]
	v_and_b32_e32 v138, 0x1f80, v138
	v_lshl_add_u64 v[136:137], v[136:137], 0, v[138:139]
	v_cvt_pk_bf16_f32 v132, v98, v99
	v_cvt_pk_bf16_f32 v133, v100, v101
	v_cvt_pk_bf16_f32 v134, v90, v91
	v_cvt_pk_bf16_f32 v135, v92, v93
	v_lshl_add_u64 v[136:137], v[136:137], 0, v[130:131]
	global_store_dwordx4 v[136:137], v[132:135], off nt
	v_bfi_b32 v136, s69, v142, v162
	v_ashrrev_i32_e32 v137, 31, v136
	v_lshlrev_b64 v[136:137], 13, v[136:137]
	v_lshl_add_u64 v[136:137], s[28:29], 0, v[136:137]
	v_lshl_add_u64 v[136:137], v[136:137], 0, v[138:139]
	v_add_u32_e32 v138, 48, v140
	v_cvt_pk_bf16_f32 v132, v86, v87
	v_cvt_pk_bf16_f32 v133, v88, v89
	v_cvt_pk_bf16_f32 v134, v78, v79
	v_cvt_pk_bf16_f32 v135, v80, v81
	v_lshl_add_u64 v[136:137], v[136:137], 0, v[130:131]
	v_add_u32_e32 v142, v141, v138
	global_store_dwordx4 v[136:137], v[132:135], off nt
	v_bfi_b32 v136, s69, v142, v144
	v_ashrrev_i32_e32 v137, 31, v136
	v_lshlrev_b64 v[136:137], 13, v[136:137]
	v_lshlrev_b32_e32 v138, 7, v138
	v_lshl_add_u64 v[136:137], s[28:29], 0, v[136:137]
	v_and_b32_e32 v138, 0x1f80, v138
	v_lshl_add_u64 v[136:137], v[136:137], 0, v[138:139]
	v_cvt_pk_bf16_f32 v132, v82, v83
	v_cvt_pk_bf16_f32 v133, v84, v85
	v_cvt_pk_bf16_f32 v134, v74, v75
	v_cvt_pk_bf16_f32 v135, v76, v77
	v_lshl_add_u64 v[136:137], v[136:137], 0, v[130:131]
	global_store_dwordx4 v[136:137], v[132:135], off nt
	v_bfi_b32 v136, s69, v142, v162
	v_ashrrev_i32_e32 v137, 31, v136
	v_lshlrev_b64 v[136:137], 13, v[136:137]
	v_lshl_add_u64 v[136:137], s[28:29], 0, v[136:137]
	v_lshl_add_u64 v[136:137], v[136:137], 0, v[138:139]
	v_cvt_pk_bf16_f32 v132, v70, v71
	v_cvt_pk_bf16_f32 v133, v72, v73
	v_cvt_pk_bf16_f32 v134, v66, v67
	v_cvt_pk_bf16_f32 v135, v68, v69
	v_lshl_add_u64 v[136:137], v[136:137], 0, v[130:131]
	v_add_u32_e32 v138, 0x80, v143
	global_store_dwordx4 v[136:137], v[132:135], off nt
	v_or_b32_e32 v136, v145, v138
	v_ashrrev_i32_e32 v137, 31, v136
	v_lshlrev_b64 v[136:137], 13, v[136:137]
	v_lshl_add_u64 v[136:137], s[28:29], 0, v[136:137]
	v_lshl_add_u64 v[136:137], v[136:137], 0, v[156:157]
	v_cvt_pk_bf16_f32 v132, v62, v63
	v_cvt_pk_bf16_f32 v133, v64, v65
	v_cvt_pk_bf16_f32 v134, v58, v59
	v_cvt_pk_bf16_f32 v135, v60, v61
	v_lshl_add_u64 v[136:137], v[136:137], 0, v[130:131]
	global_store_dwordx4 v[136:137], v[132:135], off nt
	v_or_b32_e32 v136, v163, v138
	v_ashrrev_i32_e32 v137, 31, v136
	v_lshlrev_b64 v[136:137], 13, v[136:137]
	v_lshl_add_u64 v[136:137], s[28:29], 0, v[136:137]
	v_lshl_add_u64 v[136:137], v[136:137], 0, v[156:157]
	v_add_u32_e32 v138, 0x90, v140
	v_cvt_pk_bf16_f32 v132, v54, v55
	v_cvt_pk_bf16_f32 v133, v56, v57
	v_cvt_pk_bf16_f32 v134, v46, v47
	v_cvt_pk_bf16_f32 v135, v48, v49
	v_lshl_add_u64 v[136:137], v[136:137], 0, v[130:131]
	v_add_u32_e32 v139, v141, v138
	global_store_dwordx4 v[136:137], v[132:135], off nt
	v_bfi_b32 v136, s69, v139, v144
	v_ashrrev_i32_e32 v137, 31, v136
	v_lshlrev_b64 v[136:137], 13, v[136:137]
	v_lshlrev_b32_e32 v138, 7, v138
	v_lshl_add_u64 v[136:137], s[28:29], 0, v[136:137]
	v_and_b32_e32 v156, 0x1f80, v138
	v_lshl_add_u64 v[136:137], v[136:137], 0, v[156:157]
	v_cvt_pk_bf16_f32 v132, v50, v51
	v_cvt_pk_bf16_f32 v133, v52, v53
	v_cvt_pk_bf16_f32 v134, v42, v43
	v_cvt_pk_bf16_f32 v135, v44, v45
	v_lshl_add_u64 v[136:137], v[136:137], 0, v[130:131]
	global_store_dwordx4 v[136:137], v[132:135], off nt
	v_bfi_b32 v136, s69, v139, v162
	v_ashrrev_i32_e32 v137, 31, v136
	v_lshlrev_b64 v[136:137], 13, v[136:137]
	v_lshl_add_u64 v[136:137], s[28:29], 0, v[136:137]
	v_lshl_add_u64 v[136:137], v[136:137], 0, v[156:157]
	v_add_u32_e32 v138, 0xa0, v140
	v_cvt_pk_bf16_f32 v132, v38, v39
	v_cvt_pk_bf16_f32 v133, v40, v41
	v_cvt_pk_bf16_f32 v134, v30, v31
	v_cvt_pk_bf16_f32 v135, v32, v33
	v_lshl_add_u64 v[136:137], v[136:137], 0, v[130:131]
	v_add_u32_e32 v139, v141, v138
	global_store_dwordx4 v[136:137], v[132:135], off nt
	v_bfi_b32 v136, s69, v139, v144
	v_ashrrev_i32_e32 v137, 31, v136
	v_lshlrev_b64 v[136:137], 13, v[136:137]
	v_lshlrev_b32_e32 v138, 7, v138
	v_lshl_add_u64 v[136:137], s[28:29], 0, v[136:137]
	v_and_b32_e32 v156, 0x1f80, v138
	v_lshl_add_u64 v[136:137], v[136:137], 0, v[156:157]
	v_cvt_pk_bf16_f32 v132, v34, v35
	v_cvt_pk_bf16_f32 v133, v36, v37
	v_cvt_pk_bf16_f32 v134, v26, v27
	v_cvt_pk_bf16_f32 v135, v28, v29
	v_lshl_add_u64 v[136:137], v[136:137], 0, v[130:131]
	global_store_dwordx4 v[136:137], v[132:135], off nt
	v_bfi_b32 v136, s69, v139, v162
	v_ashrrev_i32_e32 v137, 31, v136
	v_lshlrev_b64 v[136:137], 13, v[136:137]
	v_lshl_add_u64 v[136:137], s[28:29], 0, v[136:137]
	v_lshl_add_u64 v[136:137], v[136:137], 0, v[156:157]
	v_add_u32_e32 v138, 0xb0, v140
	v_cvt_pk_bf16_f32 v132, v22, v23
	v_cvt_pk_bf16_f32 v133, v24, v25
	v_cvt_pk_bf16_f32 v134, v14, v15
	v_cvt_pk_bf16_f32 v135, v16, v17
	v_lshl_add_u64 v[136:137], v[136:137], 0, v[130:131]
	v_add_u32_e32 v139, v141, v138
	global_store_dwordx4 v[136:137], v[132:135], off nt
	v_bfi_b32 v136, s69, v139, v144
	v_ashrrev_i32_e32 v137, 31, v136
	v_lshlrev_b64 v[136:137], 13, v[136:137]
	v_lshlrev_b32_e32 v138, 7, v138
	v_lshl_add_u64 v[136:137], s[28:29], 0, v[136:137]
	v_and_b32_e32 v156, 0x1f80, v138
	v_lshl_add_u64 v[136:137], v[136:137], 0, v[156:157]
	v_cvt_pk_bf16_f32 v132, v18, v19
	v_cvt_pk_bf16_f32 v133, v20, v21
	v_cvt_pk_bf16_f32 v134, v10, v11
	v_cvt_pk_bf16_f32 v135, v12, v13
	v_lshl_add_u64 v[136:137], v[136:137], 0, v[130:131]
	global_store_dwordx4 v[136:137], v[132:135], off nt
	v_bfi_b32 v136, s69, v139, v162
	v_ashrrev_i32_e32 v137, 31, v136
	v_lshlrev_b64 v[136:137], 13, v[136:137]
	v_lshl_add_u64 v[136:137], s[28:29], 0, v[136:137]
	v_lshl_add_u64 v[136:137], v[136:137], 0, v[156:157]
	v_cvt_pk_bf16_f32 v132, v6, v7
	v_cvt_pk_bf16_f32 v133, v8, v9
	v_cvt_pk_bf16_f32 v134, v2, v3
	v_cvt_pk_bf16_f32 v135, v4, v5
	v_lshl_add_u64 v[130:131], v[136:137], 0, v[130:131]
	global_store_dwordx4 v[130:131], v[132:135], off nt

.LBB0_304:
	s_andn2_b64 vcc, exec, s[46:47]
	s_mov_b64 s[46:47], 0
	s_cbranch_vccnz .LBB0_309
	s_cmp_gt_i32 s41, 0
	s_mov_b64 s[46:47], -1
	s_cbranch_scc0 .LBB0_307
	s_lshl_b32 s2, s66, 8
	s_and_b32 s2, s2, 0x100
	s_or_b32 s2, s2, s59
	v_add_u32_e32 v138, s2, v173
	s_lshl_b32 s2, s33, 8
	s_add_i32 s2, s2, s58
	v_add_u32_e32 v139, s2, v171
	v_add_u32_e32 v130, 0x8000, v139
	v_ashrrev_i32_e32 v130, 9, v130
	v_and_b32_e32 v141, -8, v130
	v_ashrrev_i32_e32 v142, 6, v138
	v_add_u32_e32 v130, v141, v142
	v_ashrrev_i32_e32 v131, 31, v130
	v_lshlrev_b64 v[130:131], 19, v[130:131]
	v_lshlrev_b32_e32 v136, 7, v139
	v_and_b32_e32 v140, 56, v138
	v_lshl_add_u64 v[130:131], s[30:31], 0, v[130:131]
	v_and_b32_e32 v156, 0x7ff80, v136
	v_lshl_add_u64 v[136:137], v[130:131], 0, v[156:157]
	v_lshlrev_b32_e32 v130, 1, v140
	v_mov_b32_e32 v131, v157
	v_cvt_pk_bf16_f32 v132, v126, v127
	v_cvt_pk_bf16_f32 v133, v128, v129
	v_cvt_pk_bf16_f32 v134, v122, v123
	v_cvt_pk_bf16_f32 v135, v124, v125
	v_lshl_add_u64 v[136:137], v[136:137], 0, v[130:131]
	global_store_dwordx4 v[136:137], v[132:135], off nt
	v_add_u32_e32 v136, 0x80, v138
	v_ashrrev_i32_e32 v138, 6, v136
	v_add_u32_e32 v136, v141, v138
	v_ashrrev_i32_e32 v137, 31, v136
	v_lshlrev_b64 v[136:137], 19, v[136:137]
	v_lshl_add_u64 v[136:137], s[30:31], 0, v[136:137]
	v_lshl_add_u64 v[136:137], v[136:137], 0, v[156:157]
	v_cvt_pk_bf16_f32 v132, v118, v119
	v_cvt_pk_bf16_f32 v133, v120, v121
	v_cvt_pk_bf16_f32 v134, v110, v111
	v_cvt_pk_bf16_f32 v135, v112, v113
	v_lshl_add_u64 v[136:137], v[136:137], 0, v[130:131]
	v_add_u32_e32 v140, 0x8010, v139
	global_store_dwordx4 v[136:137], v[132:135], off nt
	s_mov_b64 s[46:47], 0
	s_nop 0
	v_ashrrev_i32_e32 v132, 9, v140
	v_and_b32_e32 v141, -8, v132
	v_add_u32_e32 v136, v141, v142
	v_ashrrev_i32_e32 v137, 31, v136
	v_lshlrev_b64 v[136:137], 19, v[136:137]
	v_lshlrev_b32_e32 v140, 7, v140
	v_lshl_add_u64 v[136:137], s[30:31], 0, v[136:137]
	v_and_b32_e32 v156, 0x7ff80, v140
	v_lshl_add_u64 v[136:137], v[136:137], 0, v[156:157]
	v_cvt_pk_bf16_f32 v132, v114, v115
	v_cvt_pk_bf16_f32 v133, v116, v117
	v_cvt_pk_bf16_f32 v134, v106, v107
	v_cvt_pk_bf16_f32 v135, v108, v109
	v_lshl_add_u64 v[136:137], v[136:137], 0, v[130:131]
	global_store_dwordx4 v[136:137], v[132:135], off nt
	v_add_u32_e32 v136, v141, v138
	v_ashrrev_i32_e32 v137, 31, v136
	v_lshlrev_b64 v[136:137], 19, v[136:137]
	v_lshl_add_u64 v[136:137], s[30:31], 0, v[136:137]
	v_lshl_add_u64 v[136:137], v[136:137], 0, v[156:157]
	v_cvt_pk_bf16_f32 v132, v102, v103
	v_cvt_pk_bf16_f32 v133, v104, v105
	v_cvt_pk_bf16_f32 v134, v94, v95
	v_cvt_pk_bf16_f32 v135, v96, v97
	v_lshl_add_u64 v[136:137], v[136:137], 0, v[130:131]
	v_add_u32_e32 v140, 0x8020, v139
	global_store_dwordx4 v[136:137], v[132:135], off nt
	s_nop 1
	v_ashrrev_i32_e32 v132, 9, v140
	v_and_b32_e32 v141, -8, v132
	v_add_u32_e32 v136, v141, v142
	v_ashrrev_i32_e32 v137, 31, v136
	v_lshlrev_b64 v[136:137], 19, v[136:137]
	v_lshlrev_b32_e32 v140, 7, v140
	v_lshl_add_u64 v[136:137], s[30:31], 0, v[136:137]
	v_and_b32_e32 v156, 0x7ff80, v140
	v_lshl_add_u64 v[136:137], v[136:137], 0, v[156:157]
	v_cvt_pk_bf16_f32 v132, v98, v99
	v_cvt_pk_bf16_f32 v133, v100, v101
	v_cvt_pk_bf16_f32 v134, v90, v91
	v_cvt_pk_bf16_f32 v135, v92, v93
	v_lshl_add_u64 v[136:137], v[136:137], 0, v[130:131]
	global_store_dwordx4 v[136:137], v[132:135], off nt
	v_add_u32_e32 v136, v141, v138
	v_ashrrev_i32_e32 v137, 31, v136
	v_lshlrev_b64 v[136:137], 19, v[136:137]
	v_lshl_add_u64 v[136:137], s[30:31], 0, v[136:137]
	v_lshl_add_u64 v[136:137], v[136:137], 0, v[156:157]
	v_cvt_pk_bf16_f32 v132, v86, v87
	v_cvt_pk_bf16_f32 v133, v88, v89
	v_cvt_pk_bf16_f32 v134, v78, v79
	v_cvt_pk_bf16_f32 v135, v80, v81
	v_lshl_add_u64 v[136:137], v[136:137], 0, v[130:131]
	v_add_u32_e32 v140, 0x8030, v139
	global_store_dwordx4 v[136:137], v[132:135], off nt
	s_nop 1
	v_ashrrev_i32_e32 v132, 9, v140
	v_and_b32_e32 v141, -8, v132
	v_add_u32_e32 v136, v141, v142
	v_ashrrev_i32_e32 v137, 31, v136
	v_lshlrev_b64 v[136:137], 19, v[136:137]
	v_lshlrev_b32_e32 v140, 7, v140
	v_lshl_add_u64 v[136:137], s[30:31], 0, v[136:137]
	v_and_b32_e32 v156, 0x7ff80, v140
	v_lshl_add_u64 v[136:137], v[136:137], 0, v[156:157]
	v_cvt_pk_bf16_f32 v132, v82, v83
	v_cvt_pk_bf16_f32 v133, v84, v85
	v_cvt_pk_bf16_f32 v134, v74, v75
	v_cvt_pk_bf16_f32 v135, v76, v77
	v_lshl_add_u64 v[136:137], v[136:137], 0, v[130:131]
	global_store_dwordx4 v[136:137], v[132:135], off nt
	v_add_u32_e32 v136, v141, v138
	v_ashrrev_i32_e32 v137, 31, v136
	v_lshlrev_b64 v[136:137], 19, v[136:137]
	v_lshl_add_u64 v[136:137], s[30:31], 0, v[136:137]
	v_lshl_add_u64 v[136:137], v[136:137], 0, v[156:157]
	v_cvt_pk_bf16_f32 v132, v70, v71
	v_cvt_pk_bf16_f32 v133, v72, v73
	v_cvt_pk_bf16_f32 v134, v66, v67
	v_cvt_pk_bf16_f32 v135, v68, v69
	v_lshl_add_u64 v[136:137], v[136:137], 0, v[130:131]
	v_add_u32_e32 v140, 0x8080, v139
	global_store_dwordx4 v[136:137], v[132:135], off nt
	s_nop 1
	v_ashrrev_i32_e32 v132, 9, v140
	v_and_b32_e32 v141, -8, v132
	v_add_u32_e32 v136, v141, v142
	v_ashrrev_i32_e32 v137, 31, v136
	v_lshlrev_b64 v[136:137], 19, v[136:137]
	v_lshlrev_b32_e32 v140, 7, v140
	v_lshl_add_u64 v[136:137], s[30:31], 0, v[136:137]
	v_and_b32_e32 v156, 0x7ff80, v140
	v_lshl_add_u64 v[136:137], v[136:137], 0, v[156:157]
	v_cvt_pk_bf16_f32 v132, v62, v63
	v_cvt_pk_bf16_f32 v133, v64, v65
	v_cvt_pk_bf16_f32 v134, v58, v59
	v_cvt_pk_bf16_f32 v135, v60, v61
	v_lshl_add_u64 v[136:137], v[136:137], 0, v[130:131]
	global_store_dwordx4 v[136:137], v[132:135], off nt
	v_add_u32_e32 v136, v141, v138
	v_ashrrev_i32_e32 v137, 31, v136
	v_lshlrev_b64 v[136:137], 19, v[136:137]
	v_lshl_add_u64 v[136:137], s[30:31], 0, v[136:137]
	v_lshl_add_u64 v[136:137], v[136:137], 0, v[156:157]
	v_cvt_pk_bf16_f32 v132, v54, v55
	v_cvt_pk_bf16_f32 v133, v56, v57
	v_cvt_pk_bf16_f32 v134, v46, v47
	v_cvt_pk_bf16_f32 v135, v48, v49
	v_lshl_add_u64 v[136:137], v[136:137], 0, v[130:131]
	v_add_u32_e32 v140, 0x8090, v139
	global_store_dwordx4 v[136:137], v[132:135], off nt
	s_nop 1
	v_ashrrev_i32_e32 v132, 9, v140
	v_and_b32_e32 v141, -8, v132
	v_add_u32_e32 v136, v141, v142
	v_ashrrev_i32_e32 v137, 31, v136
	v_lshlrev_b64 v[136:137], 19, v[136:137]
	v_lshlrev_b32_e32 v140, 7, v140
	v_lshl_add_u64 v[136:137], s[30:31], 0, v[136:137]
	v_and_b32_e32 v156, 0x7ff80, v140
	v_lshl_add_u64 v[136:137], v[136:137], 0, v[156:157]
	v_cvt_pk_bf16_f32 v132, v50, v51
	v_cvt_pk_bf16_f32 v133, v52, v53
	v_cvt_pk_bf16_f32 v134, v42, v43
	v_cvt_pk_bf16_f32 v135, v44, v45
	v_lshl_add_u64 v[136:137], v[136:137], 0, v[130:131]
	global_store_dwordx4 v[136:137], v[132:135], off nt
	v_add_u32_e32 v136, v141, v138
	v_ashrrev_i32_e32 v137, 31, v136
	v_lshlrev_b64 v[136:137], 19, v[136:137]
	v_lshl_add_u64 v[136:137], s[30:31], 0, v[136:137]
	v_lshl_add_u64 v[136:137], v[136:137], 0, v[156:157]
	v_cvt_pk_bf16_f32 v132, v38, v39
	v_cvt_pk_bf16_f32 v133, v40, v41
	v_cvt_pk_bf16_f32 v134, v30, v31
	v_cvt_pk_bf16_f32 v135, v32, v33
	v_lshl_add_u64 v[136:137], v[136:137], 0, v[130:131]
	v_add_u32_e32 v140, 0x80a0, v139
	global_store_dwordx4 v[136:137], v[132:135], off nt
	v_add_u32_e32 v139, 0x80b0, v139
	s_nop 0
	v_ashrrev_i32_e32 v132, 9, v140
	v_and_b32_e32 v141, -8, v132
	v_add_u32_e32 v136, v141, v142
	v_ashrrev_i32_e32 v137, 31, v136
	v_lshlrev_b64 v[136:137], 19, v[136:137]
	v_lshlrev_b32_e32 v140, 7, v140
	v_lshl_add_u64 v[136:137], s[30:31], 0, v[136:137]
	v_and_b32_e32 v156, 0x7ff80, v140
	v_lshl_add_u64 v[136:137], v[136:137], 0, v[156:157]
	v_cvt_pk_bf16_f32 v132, v34, v35
	v_cvt_pk_bf16_f32 v133, v36, v37
	v_cvt_pk_bf16_f32 v134, v26, v27
	v_cvt_pk_bf16_f32 v135, v28, v29
	v_lshl_add_u64 v[136:137], v[136:137], 0, v[130:131]
	global_store_dwordx4 v[136:137], v[132:135], off nt
	v_add_u32_e32 v136, v141, v138
	v_ashrrev_i32_e32 v137, 31, v136
	v_lshlrev_b64 v[136:137], 19, v[136:137]
	v_lshl_add_u64 v[136:137], s[30:31], 0, v[136:137]
	v_lshl_add_u64 v[136:137], v[136:137], 0, v[156:157]
	v_cvt_pk_bf16_f32 v132, v22, v23
	v_cvt_pk_bf16_f32 v133, v24, v25
	v_cvt_pk_bf16_f32 v134, v14, v15
	v_cvt_pk_bf16_f32 v135, v16, v17
	v_lshl_add_u64 v[136:137], v[136:137], 0, v[130:131]
	global_store_dwordx4 v[136:137], v[132:135], off nt
	s_nop 1
	v_ashrrev_i32_e32 v132, 9, v139
	v_and_b32_e32 v140, -8, v132
	v_add_u32_e32 v136, v140, v142
	v_ashrrev_i32_e32 v137, 31, v136
	v_lshlrev_b64 v[136:137], 19, v[136:137]
	v_lshlrev_b32_e32 v139, 7, v139
	v_lshl_add_u64 v[136:137], s[30:31], 0, v[136:137]
	v_and_b32_e32 v156, 0x7ff80, v139
	v_lshl_add_u64 v[136:137], v[136:137], 0, v[156:157]
	v_cvt_pk_bf16_f32 v132, v18, v19
	v_cvt_pk_bf16_f32 v133, v20, v21
	v_cvt_pk_bf16_f32 v134, v10, v11
	v_cvt_pk_bf16_f32 v135, v12, v13
	v_lshl_add_u64 v[136:137], v[136:137], 0, v[130:131]
	global_store_dwordx4 v[136:137], v[132:135], off nt
	v_add_u32_e32 v136, v140, v138
	v_ashrrev_i32_e32 v137, 31, v136
	v_lshlrev_b64 v[136:137], 19, v[136:137]
	v_lshl_add_u64 v[136:137], s[30:31], 0, v[136:137]
	v_lshl_add_u64 v[136:137], v[136:137], 0, v[156:157]
	v_cvt_pk_bf16_f32 v132, v6, v7
	v_cvt_pk_bf16_f32 v133, v8, v9
	v_cvt_pk_bf16_f32 v134, v2, v3
	v_cvt_pk_bf16_f32 v135, v4, v5
	v_lshl_add_u64 v[130:131], v[136:137], 0, v[130:131]
	global_store_dwordx4 v[130:131], v[132:135], off nt

.LBB0_309:
	s_and_b64 vcc, exec, s[44:45]
	s_cbranch_vccz .LBB0_311
	s_lshl_b32 s2, s66, 8
	s_and_b32 s2, s2, 0x100
	s_or_b32 s2, s2, s59
	v_add_u32_e32 v134, s2, v173
	s_lshl_b32 s2, s33, 8
	s_add_i32 s2, s2, s58
	v_add_u32_e32 v138, s2, v171
	v_add_u32_e32 v130, 0x8000, v138
	v_ashrrev_i32_e32 v131, 31, v130
	v_lshlrev_b64 v[136:137], 10, v[130:131]
	v_ashrrev_i32_e32 v135, 31, v134
	v_lshl_add_u64 v[136:137], s[36:37], 0, v[136:137]
	v_lshlrev_b64 v[134:135], 1, v[134:135]
	v_cvt_pk_bf16_f32 v130, v126, v127
	v_cvt_pk_bf16_f32 v131, v128, v129
	v_cvt_pk_bf16_f32 v132, v122, v123
	v_cvt_pk_bf16_f32 v133, v124, v125
	v_lshl_add_u64 v[136:137], v[136:137], 0, v[134:135]
	global_store_dwordx4 v[136:137], v[130:133], off nt
	s_mov_b64 s[46:47], 0
	s_nop 0
	v_cvt_pk_bf16_f32 v130, v118, v119
	v_cvt_pk_bf16_f32 v131, v120, v121
	v_cvt_pk_bf16_f32 v132, v110, v111
	v_cvt_pk_bf16_f32 v133, v112, v113
	global_store_dwordx4 v[136:137], v[130:133], off offset:256 nt
	s_nop 1
	v_add_u32_e32 v130, 0x8010, v138
	v_ashrrev_i32_e32 v131, 31, v130
	v_lshlrev_b64 v[136:137], 10, v[130:131]
	v_lshl_add_u64 v[136:137], s[36:37], 0, v[136:137]
	v_cvt_pk_bf16_f32 v130, v114, v115
	v_cvt_pk_bf16_f32 v131, v116, v117
	v_cvt_pk_bf16_f32 v132, v106, v107
	v_cvt_pk_bf16_f32 v133, v108, v109
	v_lshl_add_u64 v[136:137], v[136:137], 0, v[134:135]
	global_store_dwordx4 v[136:137], v[130:133], off nt
	s_nop 1
	v_cvt_pk_bf16_f32 v130, v102, v103
	v_cvt_pk_bf16_f32 v131, v104, v105
	v_cvt_pk_bf16_f32 v132, v94, v95
	v_cvt_pk_bf16_f32 v133, v96, v97
	global_store_dwordx4 v[136:137], v[130:133], off offset:256 nt
	s_nop 1
	v_add_u32_e32 v130, 0x8020, v138
	v_ashrrev_i32_e32 v131, 31, v130
	v_lshlrev_b64 v[136:137], 10, v[130:131]
	v_lshl_add_u64 v[136:137], s[36:37], 0, v[136:137]
	v_cvt_pk_bf16_f32 v130, v98, v99
	v_cvt_pk_bf16_f32 v131, v100, v101
	v_cvt_pk_bf16_f32 v132, v90, v91
	v_cvt_pk_bf16_f32 v133, v92, v93
	v_lshl_add_u64 v[136:137], v[136:137], 0, v[134:135]
	global_store_dwordx4 v[136:137], v[130:133], off nt
	s_nop 1
	v_cvt_pk_bf16_f32 v130, v86, v87
	v_cvt_pk_bf16_f32 v131, v88, v89
	v_cvt_pk_bf16_f32 v132, v78, v79
	v_cvt_pk_bf16_f32 v133, v80, v81
	global_store_dwordx4 v[136:137], v[130:133], off offset:256 nt
	s_nop 1
	v_add_u32_e32 v130, 0x8030, v138
	v_ashrrev_i32_e32 v131, 31, v130
	v_lshlrev_b64 v[136:137], 10, v[130:131]
	v_lshl_add_u64 v[136:137], s[36:37], 0, v[136:137]
	v_cvt_pk_bf16_f32 v130, v82, v83
	v_cvt_pk_bf16_f32 v131, v84, v85
	v_cvt_pk_bf16_f32 v132, v74, v75
	v_cvt_pk_bf16_f32 v133, v76, v77
	v_lshl_add_u64 v[136:137], v[136:137], 0, v[134:135]
	global_store_dwordx4 v[136:137], v[130:133], off nt
	s_nop 1
	v_cvt_pk_bf16_f32 v130, v70, v71
	v_cvt_pk_bf16_f32 v131, v72, v73
	v_cvt_pk_bf16_f32 v132, v66, v67
	v_cvt_pk_bf16_f32 v133, v68, v69
	global_store_dwordx4 v[136:137], v[130:133], off offset:256 nt
	s_nop 1
	v_add_u32_e32 v130, 0x8080, v138
	v_ashrrev_i32_e32 v131, 31, v130
	v_lshlrev_b64 v[136:137], 10, v[130:131]
	v_lshl_add_u64 v[136:137], s[36:37], 0, v[136:137]
	v_cvt_pk_bf16_f32 v130, v62, v63
	v_cvt_pk_bf16_f32 v131, v64, v65
	v_cvt_pk_bf16_f32 v132, v58, v59
	v_cvt_pk_bf16_f32 v133, v60, v61
	v_lshl_add_u64 v[136:137], v[136:137], 0, v[134:135]
	global_store_dwordx4 v[136:137], v[130:133], off nt
	s_nop 1
	v_cvt_pk_bf16_f32 v130, v54, v55
	v_cvt_pk_bf16_f32 v131, v56, v57
	v_cvt_pk_bf16_f32 v132, v46, v47
	v_cvt_pk_bf16_f32 v133, v48, v49
	global_store_dwordx4 v[136:137], v[130:133], off offset:256 nt
	s_nop 1
	v_add_u32_e32 v130, 0x8090, v138
	v_ashrrev_i32_e32 v131, 31, v130
	v_lshlrev_b64 v[136:137], 10, v[130:131]
	v_lshl_add_u64 v[136:137], s[36:37], 0, v[136:137]
	v_cvt_pk_bf16_f32 v130, v50, v51
	v_cvt_pk_bf16_f32 v131, v52, v53
	v_cvt_pk_bf16_f32 v132, v42, v43
	v_cvt_pk_bf16_f32 v133, v44, v45
	v_lshl_add_u64 v[136:137], v[136:137], 0, v[134:135]
	global_store_dwordx4 v[136:137], v[130:133], off nt
	s_nop 1
	v_cvt_pk_bf16_f32 v130, v38, v39
	v_cvt_pk_bf16_f32 v131, v40, v41
	v_cvt_pk_bf16_f32 v132, v30, v31
	v_cvt_pk_bf16_f32 v133, v32, v33
	global_store_dwordx4 v[136:137], v[130:133], off offset:256 nt
	s_nop 1
	v_add_u32_e32 v130, 0x80a0, v138
	v_ashrrev_i32_e32 v131, 31, v130
	v_lshlrev_b64 v[136:137], 10, v[130:131]
	v_lshl_add_u64 v[136:137], s[36:37], 0, v[136:137]
	v_cvt_pk_bf16_f32 v130, v34, v35
	v_cvt_pk_bf16_f32 v131, v36, v37
	v_cvt_pk_bf16_f32 v132, v26, v27
	v_cvt_pk_bf16_f32 v133, v28, v29
	v_lshl_add_u64 v[136:137], v[136:137], 0, v[134:135]
	global_store_dwordx4 v[136:137], v[130:133], off nt
	s_nop 1
	v_cvt_pk_bf16_f32 v130, v22, v23
	v_cvt_pk_bf16_f32 v131, v24, v25
	v_cvt_pk_bf16_f32 v132, v14, v15
	v_cvt_pk_bf16_f32 v133, v16, v17
	global_store_dwordx4 v[136:137], v[130:133], off offset:256 nt
	s_nop 1
	v_add_u32_e32 v130, 0x80b0, v138
	v_ashrrev_i32_e32 v131, 31, v130
	v_lshlrev_b64 v[136:137], 10, v[130:131]
	v_lshl_add_u64 v[136:137], s[36:37], 0, v[136:137]
	v_cvt_pk_bf16_f32 v130, v18, v19
	v_cvt_pk_bf16_f32 v131, v20, v21
	v_cvt_pk_bf16_f32 v132, v10, v11
	v_cvt_pk_bf16_f32 v133, v12, v13
	v_lshl_add_u64 v[134:135], v[136:137], 0, v[134:135]
	global_store_dwordx4 v[134:135], v[130:133], off nt
	s_nop 1
	v_cvt_pk_bf16_f32 v130, v6, v7
	v_cvt_pk_bf16_f32 v131, v8, v9
	v_cvt_pk_bf16_f32 v132, v2, v3
	v_cvt_pk_bf16_f32 v133, v4, v5
	global_store_dwordx4 v[134:135], v[130:133], off offset:256 nt
.LBB0_311:
	s_andn2_b64 vcc, exec, s[46:47]
	s_cbranch_vccnz .LBB0_260
	s_lshl_b32 s2, s66, 8
	s_and_b32 s2, s2, 0x100
	s_or_b32 s2, s2, s59
	v_add_u32_e32 v132, s2, v173
	s_lshl_b32 s2, s33, 8
	s_add_i32 s2, s2, s58
	v_add_u32_e32 v133, s2, v171
	v_add_u32_e32 v130, 0x8000, v133
	v_ashrrev_i32_e32 v130, 9, v130
	v_and_b32_e32 v135, -8, v130
	v_pk_mul_f32 v[126:127], v[126:127], s[38:39] op_sel_hi:[1,0]
	v_pk_mul_f32 v[130:131], v[124:125], s[38:39] op_sel_hi:[1,0]
	v_pk_mul_f32 v[122:123], v[122:123], s[38:39] op_sel_hi:[1,0]
	v_cvt_pk_bf16_f32 v124, v126, v127
	v_cvt_pk_bf16_f32 v127, v130, v131
	v_ashrrev_i32_e32 v130, 6, v132
	v_cvt_pk_bf16_f32 v126, v122, v123
	v_add_u32_e32 v122, v135, v130
	v_pk_mul_f32 v[128:129], v[128:129], s[38:39] op_sel_hi:[1,0]
	v_ashrrev_i32_e32 v123, 31, v122
	v_cvt_pk_bf16_f32 v125, v128, v129
	v_lshlrev_b64 v[122:123], 19, v[122:123]
	v_lshlrev_b32_e32 v128, 7, v133
	v_and_b32_e32 v134, 56, v132
	v_lshl_add_u64 v[122:123], s[34:35], 0, v[122:123]
	v_and_b32_e32 v156, 0x7ff80, v128
	v_lshl_add_u64 v[128:129], v[122:123], 0, v[156:157]
	v_lshlrev_b32_e32 v122, 1, v134
	v_mov_b32_e32 v123, v157
	v_lshl_add_u64 v[128:129], v[128:129], 0, v[122:123]
	global_store_dwordx4 v[128:129], v[124:127], off nt
	v_pk_mul_f32 v[120:121], v[120:121], s[38:39] op_sel_hi:[1,0]
	v_add_u32_e32 v128, 0x80, v132
	v_pk_mul_f32 v[118:119], v[118:119], s[38:39] op_sel_hi:[1,0]
	v_pk_mul_f32 v[124:125], v[110:111], s[38:39] op_sel_hi:[1,0]
	v_cvt_pk_bf16_f32 v111, v120, v121
	v_ashrrev_i32_e32 v120, 6, v128
	v_cvt_pk_bf16_f32 v110, v118, v119
	v_add_u32_e32 v118, v135, v120
	v_ashrrev_i32_e32 v119, 31, v118
	v_lshlrev_b64 v[118:119], 19, v[118:119]
	v_lshl_add_u64 v[118:119], s[34:35], 0, v[118:119]
	v_pk_mul_f32 v[126:127], v[112:113], s[38:39] op_sel_hi:[1,0]
	v_lshl_add_u64 v[118:119], v[118:119], 0, v[156:157]
	v_cvt_pk_bf16_f32 v112, v124, v125
	v_cvt_pk_bf16_f32 v113, v126, v127
	v_lshl_add_u64 v[118:119], v[118:119], 0, v[122:123]
	global_store_dwordx4 v[118:119], v[110:113], off nt
	v_add_u32_e32 v118, 0x8010, v133
	v_pk_mul_f32 v[102:103], v[102:103], s[38:39] op_sel_hi:[1,0]
	v_ashrrev_i32_e32 v110, 9, v118
	v_and_b32_e32 v119, -8, v110
	v_pk_mul_f32 v[110:111], v[114:115], s[38:39] op_sel_hi:[1,0]
	v_pk_mul_f32 v[114:115], v[106:107], s[38:39] op_sel_hi:[1,0]
	v_cvt_pk_bf16_f32 v106, v110, v111
	v_add_u32_e32 v110, v119, v130
	v_pk_mul_f32 v[112:113], v[116:117], s[38:39] op_sel_hi:[1,0]
	v_ashrrev_i32_e32 v111, 31, v110
	v_cvt_pk_bf16_f32 v107, v112, v113
	v_lshlrev_b64 v[110:111], 19, v[110:111]
	v_lshlrev_b32_e32 v112, 7, v118
	v_lshl_add_u64 v[110:111], s[34:35], 0, v[110:111]
	v_and_b32_e32 v156, 0x7ff80, v112
	v_pk_mul_f32 v[116:117], v[108:109], s[38:39] op_sel_hi:[1,0]
	v_lshl_add_u64 v[110:111], v[110:111], 0, v[156:157]
	v_cvt_pk_bf16_f32 v108, v114, v115
	v_cvt_pk_bf16_f32 v109, v116, v117
	v_lshl_add_u64 v[110:111], v[110:111], 0, v[122:123]
	global_store_dwordx4 v[110:111], v[106:109], off nt
	v_pk_mul_f32 v[104:105], v[104:105], s[38:39] op_sel_hi:[1,0]
	v_pk_mul_f32 v[86:87], v[86:87], s[38:39] op_sel_hi:[1,0]
	v_pk_mul_f32 v[106:107], v[94:95], s[38:39] op_sel_hi:[1,0]
	v_cvt_pk_bf16_f32 v94, v102, v103
	v_add_u32_e32 v102, v119, v120
	v_ashrrev_i32_e32 v103, 31, v102
	v_lshlrev_b64 v[102:103], 19, v[102:103]
	v_lshl_add_u64 v[102:103], s[34:35], 0, v[102:103]
	v_pk_mul_f32 v[108:109], v[96:97], s[38:39] op_sel_hi:[1,0]
	v_lshl_add_u64 v[102:103], v[102:103], 0, v[156:157]
	v_cvt_pk_bf16_f32 v95, v104, v105
	v_cvt_pk_bf16_f32 v96, v106, v107
	v_cvt_pk_bf16_f32 v97, v108, v109
	v_lshl_add_u64 v[102:103], v[102:103], 0, v[122:123]
	global_store_dwordx4 v[102:103], v[94:97], off nt
	v_add_u32_e32 v102, 0x8020, v133
	v_pk_mul_f32 v[88:89], v[88:89], s[38:39] op_sel_hi:[1,0]
	v_ashrrev_i32_e32 v94, 9, v102
	v_and_b32_e32 v103, -8, v94
	v_pk_mul_f32 v[94:95], v[98:99], s[38:39] op_sel_hi:[1,0]
	v_pk_mul_f32 v[98:99], v[90:91], s[38:39] op_sel_hi:[1,0]
	v_cvt_pk_bf16_f32 v90, v94, v95
	v_add_u32_e32 v94, v103, v130
	v_pk_mul_f32 v[96:97], v[100:101], s[38:39] op_sel_hi:[1,0]
	v_ashrrev_i32_e32 v95, 31, v94
	v_cvt_pk_bf16_f32 v91, v96, v97
	v_lshlrev_b64 v[94:95], 19, v[94:95]
	v_lshlrev_b32_e32 v96, 7, v102
	v_lshl_add_u64 v[94:95], s[34:35], 0, v[94:95]
	v_and_b32_e32 v156, 0x7ff80, v96
	v_pk_mul_f32 v[100:101], v[92:93], s[38:39] op_sel_hi:[1,0]
	v_lshl_add_u64 v[94:95], v[94:95], 0, v[156:157]
	v_cvt_pk_bf16_f32 v92, v98, v99
	v_cvt_pk_bf16_f32 v93, v100, v101
	v_lshl_add_u64 v[94:95], v[94:95], 0, v[122:123]
	global_store_dwordx4 v[94:95], v[90:93], off nt
	v_pk_mul_f32 v[70:71], v[70:71], s[38:39] op_sel_hi:[1,0]
	v_pk_mul_f32 v[72:73], v[72:73], s[38:39] op_sel_hi:[1,0]
	v_pk_mul_f32 v[90:91], v[78:79], s[38:39] op_sel_hi:[1,0]
	v_cvt_pk_bf16_f32 v78, v86, v87
	v_add_u32_e32 v86, v103, v120
	v_ashrrev_i32_e32 v87, 31, v86
	v_lshlrev_b64 v[86:87], 19, v[86:87]
	v_lshl_add_u64 v[86:87], s[34:35], 0, v[86:87]
	v_pk_mul_f32 v[92:93], v[80:81], s[38:39] op_sel_hi:[1,0]
	v_lshl_add_u64 v[86:87], v[86:87], 0, v[156:157]
	v_cvt_pk_bf16_f32 v79, v88, v89
	v_cvt_pk_bf16_f32 v80, v90, v91
	v_cvt_pk_bf16_f32 v81, v92, v93
	v_lshl_add_u64 v[86:87], v[86:87], 0, v[122:123]
	global_store_dwordx4 v[86:87], v[78:81], off nt
	v_add_u32_e32 v86, 0x8030, v133
	v_pk_mul_f32 v[62:63], v[62:63], s[38:39] op_sel_hi:[1,0]
	v_ashrrev_i32_e32 v78, 9, v86
	v_and_b32_e32 v87, -8, v78
	v_pk_mul_f32 v[78:79], v[82:83], s[38:39] op_sel_hi:[1,0]
	v_pk_mul_f32 v[82:83], v[74:75], s[38:39] op_sel_hi:[1,0]
	v_cvt_pk_bf16_f32 v74, v78, v79
	v_add_u32_e32 v78, v87, v130
	v_pk_mul_f32 v[80:81], v[84:85], s[38:39] op_sel_hi:[1,0]
	v_ashrrev_i32_e32 v79, 31, v78
	v_cvt_pk_bf16_f32 v75, v80, v81
	v_lshlrev_b64 v[78:79], 19, v[78:79]
	v_lshlrev_b32_e32 v80, 7, v86
	v_lshl_add_u64 v[78:79], s[34:35], 0, v[78:79]
	v_and_b32_e32 v156, 0x7ff80, v80
	v_pk_mul_f32 v[84:85], v[76:77], s[38:39] op_sel_hi:[1,0]
	v_lshl_add_u64 v[78:79], v[78:79], 0, v[156:157]
	v_cvt_pk_bf16_f32 v76, v82, v83
	v_cvt_pk_bf16_f32 v77, v84, v85
	v_lshl_add_u64 v[78:79], v[78:79], 0, v[122:123]
	global_store_dwordx4 v[78:79], v[74:77], off nt
	v_pk_mul_f32 v[64:65], v[64:65], s[38:39] op_sel_hi:[1,0]
	v_pk_mul_f32 v[54:55], v[54:55], s[38:39] op_sel_hi:[1,0]
	v_pk_mul_f32 v[74:75], v[66:67], s[38:39] op_sel_hi:[1,0]
	v_cvt_pk_bf16_f32 v66, v70, v71
	v_add_u32_e32 v70, v87, v120
	v_ashrrev_i32_e32 v71, 31, v70
	v_lshlrev_b64 v[70:71], 19, v[70:71]
	v_lshl_add_u64 v[70:71], s[34:35], 0, v[70:71]
	v_pk_mul_f32 v[76:77], v[68:69], s[38:39] op_sel_hi:[1,0]
	v_lshl_add_u64 v[70:71], v[70:71], 0, v[156:157]
	v_cvt_pk_bf16_f32 v67, v72, v73
	v_cvt_pk_bf16_f32 v68, v74, v75
	v_cvt_pk_bf16_f32 v69, v76, v77
	v_lshl_add_u64 v[70:71], v[70:71], 0, v[122:123]
	global_store_dwordx4 v[70:71], v[66:69], off nt
	v_add_u32_e32 v70, 0x8080, v133
	v_pk_mul_f32 v[56:57], v[56:57], s[38:39] op_sel_hi:[1,0]
	v_ashrrev_i32_e32 v66, 9, v70
	v_and_b32_e32 v71, -8, v66
	v_pk_mul_f32 v[66:67], v[58:59], s[38:39] op_sel_hi:[1,0]
	v_cvt_pk_bf16_f32 v58, v62, v63
	v_add_u32_e32 v62, v71, v130
	v_ashrrev_i32_e32 v63, 31, v62
	v_cvt_pk_bf16_f32 v59, v64, v65
	v_lshlrev_b64 v[62:63], 19, v[62:63]
	v_lshlrev_b32_e32 v64, 7, v70
	v_lshl_add_u64 v[62:63], s[34:35], 0, v[62:63]
	v_and_b32_e32 v156, 0x7ff80, v64
	v_pk_mul_f32 v[68:69], v[60:61], s[38:39] op_sel_hi:[1,0]
	v_lshl_add_u64 v[62:63], v[62:63], 0, v[156:157]
	v_cvt_pk_bf16_f32 v60, v66, v67
	v_cvt_pk_bf16_f32 v61, v68, v69
	v_lshl_add_u64 v[62:63], v[62:63], 0, v[122:123]
	global_store_dwordx4 v[62:63], v[58:61], off nt
	v_pk_mul_f32 v[38:39], v[38:39], s[38:39] op_sel_hi:[1,0]
	v_pk_mul_f32 v[40:41], v[40:41], s[38:39] op_sel_hi:[1,0]
	v_pk_mul_f32 v[58:59], v[46:47], s[38:39] op_sel_hi:[1,0]
	v_cvt_pk_bf16_f32 v46, v54, v55
	v_add_u32_e32 v54, v71, v120
	v_ashrrev_i32_e32 v55, 31, v54
	v_lshlrev_b64 v[54:55], 19, v[54:55]
	v_lshl_add_u64 v[54:55], s[34:35], 0, v[54:55]
	v_pk_mul_f32 v[60:61], v[48:49], s[38:39] op_sel_hi:[1,0]
	v_lshl_add_u64 v[54:55], v[54:55], 0, v[156:157]
	v_cvt_pk_bf16_f32 v47, v56, v57
	v_cvt_pk_bf16_f32 v48, v58, v59
	v_cvt_pk_bf16_f32 v49, v60, v61
	v_lshl_add_u64 v[54:55], v[54:55], 0, v[122:123]
	global_store_dwordx4 v[54:55], v[46:49], off nt
	v_add_u32_e32 v54, 0x8090, v133
	v_pk_mul_f32 v[22:23], v[22:23], s[38:39] op_sel_hi:[1,0]
	v_ashrrev_i32_e32 v46, 9, v54
	v_and_b32_e32 v55, -8, v46
	v_pk_mul_f32 v[46:47], v[50:51], s[38:39] op_sel_hi:[1,0]
	v_pk_mul_f32 v[50:51], v[42:43], s[38:39] op_sel_hi:[1,0]
	v_cvt_pk_bf16_f32 v42, v46, v47
	v_add_u32_e32 v46, v55, v130
	v_pk_mul_f32 v[48:49], v[52:53], s[38:39] op_sel_hi:[1,0]
	v_ashrrev_i32_e32 v47, 31, v46
	v_cvt_pk_bf16_f32 v43, v48, v49
	v_lshlrev_b64 v[46:47], 19, v[46:47]
	v_lshlrev_b32_e32 v48, 7, v54
	v_lshl_add_u64 v[46:47], s[34:35], 0, v[46:47]
	v_and_b32_e32 v156, 0x7ff80, v48
	v_pk_mul_f32 v[52:53], v[44:45], s[38:39] op_sel_hi:[1,0]
	v_lshl_add_u64 v[46:47], v[46:47], 0, v[156:157]
	v_cvt_pk_bf16_f32 v44, v50, v51
	v_cvt_pk_bf16_f32 v45, v52, v53
	v_lshl_add_u64 v[46:47], v[46:47], 0, v[122:123]
	global_store_dwordx4 v[46:47], v[42:45], off nt
	v_pk_mul_f32 v[24:25], v[24:25], s[38:39] op_sel_hi:[1,0]
	v_pk_mul_f32 v[6:7], v[6:7], s[38:39] op_sel_hi:[1,0]
	v_pk_mul_f32 v[42:43], v[30:31], s[38:39] op_sel_hi:[1,0]
	v_cvt_pk_bf16_f32 v30, v38, v39
	v_add_u32_e32 v38, v55, v120
	v_ashrrev_i32_e32 v39, 31, v38
	v_lshlrev_b64 v[38:39], 19, v[38:39]
	v_lshl_add_u64 v[38:39], s[34:35], 0, v[38:39]
	v_pk_mul_f32 v[44:45], v[32:33], s[38:39] op_sel_hi:[1,0]
	v_lshl_add_u64 v[38:39], v[38:39], 0, v[156:157]
	v_cvt_pk_bf16_f32 v31, v40, v41
	v_cvt_pk_bf16_f32 v32, v42, v43
	v_cvt_pk_bf16_f32 v33, v44, v45
	v_lshl_add_u64 v[38:39], v[38:39], 0, v[122:123]
	global_store_dwordx4 v[38:39], v[30:33], off nt
	v_add_u32_e32 v38, 0x80a0, v133
	v_pk_mul_f32 v[8:9], v[8:9], s[38:39] op_sel_hi:[1,0]
	v_ashrrev_i32_e32 v30, 9, v38
	v_and_b32_e32 v39, -8, v30
	v_pk_mul_f32 v[30:31], v[34:35], s[38:39] op_sel_hi:[1,0]
	v_pk_mul_f32 v[34:35], v[26:27], s[38:39] op_sel_hi:[1,0]
	v_cvt_pk_bf16_f32 v26, v30, v31
	v_add_u32_e32 v30, v39, v130
	v_pk_mul_f32 v[32:33], v[36:37], s[38:39] op_sel_hi:[1,0]
	v_ashrrev_i32_e32 v31, 31, v30
	v_cvt_pk_bf16_f32 v27, v32, v33
	v_lshlrev_b64 v[30:31], 19, v[30:31]
	v_lshlrev_b32_e32 v32, 7, v38
	v_lshl_add_u64 v[30:31], s[34:35], 0, v[30:31]
	v_and_b32_e32 v156, 0x7ff80, v32
	v_pk_mul_f32 v[36:37], v[28:29], s[38:39] op_sel_hi:[1,0]
	v_lshl_add_u64 v[30:31], v[30:31], 0, v[156:157]
	v_cvt_pk_bf16_f32 v28, v34, v35
	v_cvt_pk_bf16_f32 v29, v36, v37
	v_lshl_add_u64 v[30:31], v[30:31], 0, v[122:123]
	global_store_dwordx4 v[30:31], v[26:29], off nt
	s_nop 1
	v_pk_mul_f32 v[26:27], v[14:15], s[38:39] op_sel_hi:[1,0]
	v_cvt_pk_bf16_f32 v14, v22, v23
	v_add_u32_e32 v22, v39, v120
	v_ashrrev_i32_e32 v23, 31, v22
	v_lshlrev_b64 v[22:23], 19, v[22:23]
	v_lshl_add_u64 v[22:23], s[34:35], 0, v[22:23]
	v_pk_mul_f32 v[28:29], v[16:17], s[38:39] op_sel_hi:[1,0]
	v_lshl_add_u64 v[22:23], v[22:23], 0, v[156:157]
	v_cvt_pk_bf16_f32 v15, v24, v25
	v_cvt_pk_bf16_f32 v16, v26, v27
	v_cvt_pk_bf16_f32 v17, v28, v29
	v_lshl_add_u64 v[22:23], v[22:23], 0, v[122:123]
	global_store_dwordx4 v[22:23], v[14:17], off nt
	v_add_u32_e32 v22, 0x80b0, v133
	s_nop 0
	v_ashrrev_i32_e32 v14, 9, v22
	v_and_b32_e32 v23, -8, v14
	v_pk_mul_f32 v[14:15], v[18:19], s[38:39] op_sel_hi:[1,0]
	v_pk_mul_f32 v[18:19], v[10:11], s[38:39] op_sel_hi:[1,0]
	v_cvt_pk_bf16_f32 v10, v14, v15
	v_add_u32_e32 v14, v23, v130
	v_pk_mul_f32 v[16:17], v[20:21], s[38:39] op_sel_hi:[1,0]
	v_ashrrev_i32_e32 v15, 31, v14
	v_cvt_pk_bf16_f32 v11, v16, v17
	v_lshlrev_b64 v[14:15], 19, v[14:15]
	v_lshlrev_b32_e32 v16, 7, v22
	v_lshl_add_u64 v[14:15], s[34:35], 0, v[14:15]
	v_and_b32_e32 v156, 0x7ff80, v16
	v_pk_mul_f32 v[20:21], v[12:13], s[38:39] op_sel_hi:[1,0]
	v_lshl_add_u64 v[14:15], v[14:15], 0, v[156:157]
	v_cvt_pk_bf16_f32 v12, v18, v19
	v_cvt_pk_bf16_f32 v13, v20, v21
	v_lshl_add_u64 v[14:15], v[14:15], 0, v[122:123]
	global_store_dwordx4 v[14:15], v[10:13], off nt
	s_nop 1
	v_pk_mul_f32 v[10:11], v[2:3], s[38:39] op_sel_hi:[1,0]
	v_cvt_pk_bf16_f32 v2, v6, v7
	v_add_u32_e32 v6, v23, v120
	v_ashrrev_i32_e32 v7, 31, v6
	v_lshlrev_b64 v[6:7], 19, v[6:7]
	v_lshl_add_u64 v[6:7], s[34:35], 0, v[6:7]
	v_pk_mul_f32 v[12:13], v[4:5], s[38:39] op_sel_hi:[1,0]
	v_lshl_add_u64 v[6:7], v[6:7], 0, v[156:157]
	v_cvt_pk_bf16_f32 v3, v8, v9
	v_cvt_pk_bf16_f32 v4, v10, v11
	v_cvt_pk_bf16_f32 v5, v12, v13
	v_lshl_add_u64 v[6:7], v[6:7], 0, v[122:123]
	global_store_dwordx4 v[6:7], v[2:5], off nt
	s_branch .LBB0_260
